# strategy 4: one static s_setprio 1 for waves 4-7 at kernel entry, all per-phase s_setprio flips deleted (on top of v47)
# baseline (speedup 1.0000x reference)
; #define LAS __attribute__((address_space(3)))
; __device__ __forceinline__ unsigned xb_add(unsigned* p, unsigned v) { return __hip_atomic_fetch_add(p, v, __ATOMIC_RELAXED, __HIP_MEMORY_SCOPE_AGENT); }
; __device__ __forceinline__ unsigned xb_xcc_id() { return (unsigned)__builtin_amdgcn_s_getreg((3 << 11) | 20) & 0xFu; }
; #define KWS() ((unsigned char*)karg_u64<136>())
; __device__ __forceinline__ XcdBarrier xcd_barrier_post(unsigned* bar, volatile LAS unsigned* st) {
;     XcdBarrier b; b.bar = bar; b.x = xb_xcc_id(); b.st = st;
;     if (threadIdx.x == 0) (void)xb_add(&bar[XB_XCNT(b.x)], 1u);
;     return b;
; __global__ void __launch_bounds__(NWAVES * 64, 2) fwd_kernel(Args args) {
;     ...
;     const int G = gridDim.x, bx = blockIdx.x;
;     for (int u = threadIdx.x; u < (LDS_BYTES - LDSCTL_OFF) / 4; u += NWAVES * 64) ((LAS unsigned*)(L + LDSCTL_OFF))[u] = 0u;
;     __syncthreads();
;     XcdBarrier bar = xcd_barrier_post((unsigned*)(KWS() + WS_CTL) + CW_BAR, (volatile LAS unsigned*)(L + MISC_OFF) + 8);
_Z10fwd_kernel4Args:
	v_readfirstlane_b32 s98, v0
	s_nop 3
	s_and_b32 s98, s98, 0x3ff
	s_lshr_b32 s98, s98, 6
	s_cmp_ge_u32 s98, 4
	s_cbranch_scc0 .Lprio_done
	s_setprio 1
.Lprio_done:
	s_load_dword s3, s[0:1], 0x90
	v_lshl_add_u32 v1, v0, 2, 0
	s_add_u32 s90, s0, 0x90
	v_add_u32_e32 v1, 0x20000, v1
	v_mov_b32_e32 v2, 0
	s_addc_u32 s91, s1, 0
	ds_write2st64_b32 v1, v2, v2 offset1:8
	ds_write2st64_b32 v1, v2, v2 offset0:16 offset1:24
	v_or_b32_e32 v1, 0x800, v0
	s_mov_b64 s[4:5], -1
	s_and_saveexec_b64 s[6:7], s[4:5]
	v_lshl_add_u32 v3, v1, 2, 0
	v_add_u32_e32 v3, 0x20000, v3
	ds_write_b32 v3, v2
	s_or_b64 exec, exec, s[6:7]
	s_and_saveexec_b64 s[6:7], s[4:5]
	s_add_i32 s4, 0, 0x20000
	v_lshl_add_u32 v1, v1, 2, s4
	v_mov_b32_e32 v2, 0
	ds_write_b32 v1, v2 offset:2048
	s_or_b64 exec, exec, s[6:7]
	v_or_b32_e32 v1, 0xc00, v0
	v_cmp_gt_u32_e64 s[4:5], 7, 6
	v_cmp_gt_u32_e64 s[8:9], 7, 5
	s_and_saveexec_b64 s[6:7], s[8:9]
	v_lshl_add_u32 v2, v1, 2, 0
	v_add_u32_e32 v2, 0x20000, v2
	v_mov_b32_e32 v3, 0
	ds_write_b32 v2, v3
	s_or_b64 exec, exec, s[6:7]
	s_and_saveexec_b64 s[6:7], s[4:5]
	s_add_i32 s4, 0, 0x20000
	v_lshl_add_u32 v1, v1, 2, s4
	v_mov_b32_e32 v2, 0
	ds_write_b32 v1, v2 offset:2048
	s_or_b64 exec, exec, s[6:7]
	s_waitcnt lgkmcnt(0)
	s_barrier
	s_load_dwordx2 s[4:5], s[0:1], 0x88
	s_waitcnt lgkmcnt(0)
	s_add_u32 s85, s4, 0x4000
	v_writelane_b32 v254, s4, 0
	s_addc_u32 s88, s5, 0
	v_cmp_eq_u32_e64 s[6:7], 0, v0
	v_writelane_b32 v254, s5, 1
	s_getreg_b32 s4, hwreg(HW_REG_XCC_ID, 0, 4)
	s_and_b32 s89, s4, 15
	s_mov_b64 s[4:5], exec
	v_writelane_b32 v254, s6, 2
	s_nop 1
	v_writelane_b32 v254, s7, 3
	s_and_b64 s[6:7], s[4:5], s[6:7]
	s_mov_b64 exec, s[6:7]
	s_cbranch_execz .LBB0_10
	s_lshl_b32 s6, s89, 8
	s_add_u32 s6, s85, s6
	s_addc_u32 s7, s88, 0
	v_mov_b32_e32 v1, 1
	v_mov_b64_e32 v[2:3], s[6:7]
	flat_atomic_add v[2:3], v1 offset:1024

; #define PG8_STAGE(bufoff, gbase, voff) do { _Pragma("unroll") for (int _i = 0; _i < 2; ++_i) \
;         __builtin_amdgcn_global_load_lds((const unsigned*)((const char*)(gbase) + (voff)[_i]), (PG8_LAS unsigned*)(lds + (bufoff) + ldsw + _i * 8192), 16, 0, 0); } while (0)
; #define PG8_LDA(dst, b, h) do { _Pragma("unroll") for (int m = 0; m < 4; ++m) _Pragma("unroll") for (int k = 0; k < 2; ++k) dst[m][k] = *(const PG8_LAS bf16x8*)(lds + PG8_SA(b, h) + aoff + m * 2048 + k * 1024); } while (0)
; #define PG8_LDB(dst, b, h) do { _Pragma("unroll") for (int n = 0; n < 2; ++n) _Pragma("unroll") for (int k = 0; k < 2; ++k) dst[n][k] = *(const PG8_LAS bf16x8*)(lds + PG8_SB(b, h) + boff + n * 2048 + k * 1024); } while (0)
; #define PG8_WAIT_V(n) asm volatile("s_waitcnt vmcnt(" #n ")" ::: "memory")
; #define PG8_WAIT_L(n) asm volatile("s_waitcnt lgkmcnt(" #n ")" ::: "memory")
; #define PG8_BAR __builtin_amdgcn_s_barrier()
; #define PG8_SCHED __builtin_amdgcn_sched_barrier(0)
; template <class Epi, class Sched, bool ALIGN_EPI = false, bool SP2 = false, bool F8 = false>
; __device__ __forceinline__ void gemm_phase(PG8_LAS unsigned char* lds, const Gemm g, const Sched& S, const Epi& E) {
;     ...
;             PG8_LDB(B0, 0, 0); PG8_LDB(B1, 0, 1); PG8_SCHED; PG8_LDA(At, 0, 0); PG8_STAGE(PG8_SA(1, 1), a1 + hA, voffA);
;             PG8_WAIT_V(8); PG8_WAIT_L(0); PG8_BAR; PG8_MMA(0, 0, At, B0); PG8_MMA(0, 1, At, B1); PG8_BAR; PG8_SCHED;
;             PG8_LDA(At, 0, 1); PG8_STAGE(PG8_SB(0, 0), b2, voffB); PG8_STAGE(PG8_SB(0, 1), b2 + hB, voffB); PG8_STAGE(PG8_SA(0, 0), a2, voffA);
;             PG8_WAIT_V(8); PG8_WAIT_L(0); PG8_BAR; PG8_MMA(1, 0, At, B0); PG8_MMA(1, 1, At, B1); PG8_BAR; PG8_SCHED;
;             PG8_LDB(B0, 1, 0); PG8_LDB(B1, 1, 1); PG8_SCHED; PG8_LDA(At, 1, 0); PG8_STAGE(PG8_SA(0, 1), a2 + hA, voffA);
;             PG8_WAIT_V(8); PG8_WAIT_L(0); PG8_BAR; PG8_MMA(0, 0, At, B0); PG8_MMA(0, 1, At, B1); PG8_BAR; PG8_SCHED;
;             PG8_LDA(At, 1, 1); PG8_STAGE(PG8_SB(1, 0), b3, voffB); PG8_STAGE(PG8_SB(1, 1), b3 + hB, voffB); PG8_STAGE(PG8_SA(1, 0), a3, voffA);
;             PG8_WAIT_V(8); PG8_WAIT_L(0); PG8_BAR; PG8_MMA(1, 0, At, B0); PG8_MMA(1, 1, At, B1); PG8_BAR; PG8_SCHED;
.LBB0_128:
	ds_read_b128 v[152:155], v149
	ds_read_b128 v[156:159], v149 offset:1024
	ds_read_b128 v[160:163], v149 offset:2048
	ds_read_b128 v[164:167], v149 offset:3072
	ds_read_b128 v[168:171], v150
	ds_read_b128 v[172:175], v150 offset:1024
	ds_read_b128 v[176:179], v150 offset:2048
	ds_read_b128 v[180:183], v150 offset:3072
	s_add_u32 s40, s38, 0xfff00080
	s_addc_u32 s41, s39, -1
	s_cmp_eq_u32 s66, 60
	s_cselect_b32 s43, s31, s41
	s_cselect_b32 s42, s62, s40
	s_cselect_b32 s41, s29, s65
	s_cselect_b32 s40, s63, s64
	v_lshl_add_u64 v[216:217], s[38:39], 0, v[140:141]
	s_add_i32 m0, s27, 0xc000
	ds_read_b128 v[184:187], v151
	ds_read_b128 v[188:191], v151 offset:1024
	ds_read_b128 v[192:195], v151 offset:2048
	ds_read_b128 v[196:199], v151 offset:3072
	ds_read_b128 v[200:203], v151 offset:4096
	ds_read_b128 v[204:207], v151 offset:5120
	ds_read_b128 v[208:211], v151 offset:6144
	ds_read_b128 v[212:215], v151 offset:7168
	global_load_lds_dwordx4 v[216:217], off
	v_lshl_add_u64 v[216:217], s[38:39], 0, v[138:139]
	s_add_i32 m0, s27, 0xe000
	s_nop 0
	global_load_lds_dwordx4 v[216:217], off
	s_waitcnt vmcnt(8)
	s_waitcnt lgkmcnt(0)
	s_barrier
	v_mfma_f32_16x16x32_bf16 v[126:129], v[152:155], v[184:187], v[126:129]
	v_mfma_f32_16x16x32_bf16 v[122:125], v[160:163], v[184:187], v[122:125]
	v_mfma_f32_16x16x32_bf16 v[118:121], v[152:155], v[192:195], v[118:121]
	v_mfma_f32_16x16x32_bf16 v[114:117], v[160:163], v[192:195], v[114:117]
	v_mfma_f32_16x16x32_bf16 v[102:105], v[152:155], v[200:203], v[102:105]
	v_mfma_f32_16x16x32_bf16 v[98:101], v[160:163], v[200:203], v[98:101]
	v_mfma_f32_16x16x32_bf16 v[86:89], v[152:155], v[208:211], v[86:89]
	v_mfma_f32_16x16x32_bf16 v[82:85], v[160:163], v[208:211], v[82:85]
	v_mfma_f32_16x16x32_bf16 v[126:129], v[156:159], v[188:191], v[126:129]
	v_mfma_f32_16x16x32_bf16 v[122:125], v[164:167], v[188:191], v[122:125]
	v_mfma_f32_16x16x32_bf16 v[118:121], v[156:159], v[196:199], v[118:121]
	v_mfma_f32_16x16x32_bf16 v[114:117], v[164:167], v[196:199], v[114:117]
	v_mfma_f32_16x16x32_bf16 v[102:105], v[156:159], v[204:207], v[102:105]
	v_mfma_f32_16x16x32_bf16 v[98:101], v[164:167], v[204:207], v[98:101]
	v_mfma_f32_16x16x32_bf16 v[86:89], v[156:159], v[212:215], v[86:89]
	v_mfma_f32_16x16x32_bf16 v[82:85], v[164:167], v[212:215], v[82:85]
	v_mfma_f32_16x16x32_bf16 v[110:113], v[168:171], v[184:187], v[110:113]
	v_mfma_f32_16x16x32_bf16 v[106:109], v[176:179], v[184:187], v[106:109]
	v_mfma_f32_16x16x32_bf16 v[94:97], v[168:171], v[192:195], v[94:97]
	v_mfma_f32_16x16x32_bf16 v[90:93], v[176:179], v[192:195], v[90:93]
	v_mfma_f32_16x16x32_bf16 v[78:81], v[168:171], v[200:203], v[78:81]
	v_mfma_f32_16x16x32_bf16 v[74:77], v[176:179], v[200:203], v[74:77]
	v_mfma_f32_16x16x32_bf16 v[70:73], v[168:171], v[208:211], v[70:73]
	v_mfma_f32_16x16x32_bf16 v[66:69], v[176:179], v[208:211], v[66:69]
	v_mfma_f32_16x16x32_bf16 v[110:113], v[172:175], v[188:191], v[110:113]
	v_mfma_f32_16x16x32_bf16 v[106:109], v[180:183], v[188:191], v[106:109]
	v_mfma_f32_16x16x32_bf16 v[94:97], v[172:175], v[196:199], v[94:97]
	v_mfma_f32_16x16x32_bf16 v[90:93], v[180:183], v[196:199], v[90:93]
	v_mfma_f32_16x16x32_bf16 v[78:81], v[172:175], v[204:207], v[78:81]
	v_mfma_f32_16x16x32_bf16 v[74:77], v[180:183], v[204:207], v[74:77]
	v_mfma_f32_16x16x32_bf16 v[70:73], v[172:175], v[212:215], v[70:73]
	v_mfma_f32_16x16x32_bf16 v[66:69], v[180:183], v[212:215], v[66:69]
	s_barrier
	s_add_i32 s67, s55, s45
	v_lshl_add_u64 v[216:217], s[40:41], 0, v[134:135]
	s_mov_b32 m0, s67
	ds_read_b128 v[184:187], v151 offset:16384
	ds_read_b128 v[188:191], v151 offset:17408
	ds_read_b128 v[192:195], v151 offset:18432
	ds_read_b128 v[196:199], v151 offset:19456
	ds_read_b128 v[200:203], v151 offset:20480
	ds_read_b128 v[204:207], v151 offset:21504
	ds_read_b128 v[208:211], v151 offset:22528
	ds_read_b128 v[212:215], v151 offset:23552
	global_load_lds_dwordx4 v[216:217], off
	s_add_i32 m0, s67, 0x2000
	s_add_u32 s70, s40, 0x100000
	v_lshl_add_u64 v[218:219], s[40:41], 0, v[130:131]
	s_addc_u32 s71, s41, 0
	s_add_i32 s67, s56, s45
	global_load_lds_dwordx4 v[218:219], off
	v_lshl_add_u64 v[220:221], s[70:71], 0, v[134:135]
	s_mov_b32 m0, s67
	v_lshl_add_u64 v[222:223], s[42:43], 0, v[132:133]
	global_load_lds_dwordx4 v[220:221], off
	v_lshl_add_u64 v[220:221], s[70:71], 0, v[130:131]
	s_add_i32 m0, s67, 0x2000
	s_nop 0
	global_load_lds_dwordx4 v[220:221], off
	v_lshl_add_u64 v[220:221], s[42:43], 0, v[136:137]
	s_mov_b32 m0, s27
	s_nop 0
	global_load_lds_dwordx4 v[220:221], off
	s_mov_b32 m0, s48
	s_nop 0
	global_load_lds_dwordx4 v[222:223], off
	s_waitcnt vmcnt(8)
	s_waitcnt lgkmcnt(0)
	s_barrier
; #define PG8_STAGE(bufoff, gbase, voff) do { _Pragma("unroll") for (int _i = 0; _i < 2; ++_i) \
;         __builtin_amdgcn_global_load_lds((const unsigned*)((const char*)(gbase) + (voff)[_i]), (PG8_LAS unsigned*)(lds + (bufoff) + ldsw + _i * 8192), 16, 0, 0); } while (0)
; #define PG8_LDA(dst, b, h) do { _Pragma("unroll") for (int m = 0; m < 4; ++m) _Pragma("unroll") for (int k = 0; k < 2; ++k) dst[m][k] = *(const PG8_LAS bf16x8*)(lds + PG8_SA(b, h) + aoff + m * 2048 + k * 1024); } while (0)
; #define PG8_LDB(dst, b, h) do { _Pragma("unroll") for (int n = 0; n < 2; ++n) _Pragma("unroll") for (int k = 0; k < 2; ++k) dst[n][k] = *(const PG8_LAS bf16x8*)(lds + PG8_SB(b, h) + boff + n * 2048 + k * 1024); } while (0)
; #define PG8_WAIT_V(n) asm volatile("s_waitcnt vmcnt(" #n ")" ::: "memory")
; #define PG8_WAIT_L(n) asm volatile("s_waitcnt lgkmcnt(" #n ")" ::: "memory")
; #define PG8_BAR __builtin_amdgcn_s_barrier()
; #define PG8_SCHED __builtin_amdgcn_sched_barrier(0)
; template <class Epi, class Sched, bool ALIGN_EPI = false, bool SP2 = false, bool F8 = false>
; __device__ __forceinline__ void gemm_phase(PG8_LAS unsigned char* lds, const Gemm g, const Sched& S, const Epi& E) {
;     ...
;             PG8_WAIT_V(8); PG8_WAIT_L(0); PG8_BAR; PG8_MMA(1, 0, At, B0); PG8_MMA(1, 1, At, B1); PG8_BAR; PG8_SCHED;
;             PG8_LDB(B0, 1, 0); PG8_LDB(B1, 1, 1); PG8_SCHED; PG8_LDA(At, 1, 0); PG8_STAGE(PG8_SA(0, 1), a2 + hA, voffA);
;             PG8_WAIT_V(8); PG8_WAIT_L(0); PG8_BAR; PG8_MMA(0, 0, At, B0); PG8_MMA(0, 1, At, B1); PG8_BAR; PG8_SCHED;
	v_mfma_f32_16x16x32_bf16 v[62:65], v[152:155], v[184:187], v[62:65]
	v_mfma_f32_16x16x32_bf16 v[58:61], v[160:163], v[184:187], v[58:61]
	v_mfma_f32_16x16x32_bf16 v[54:57], v[152:155], v[192:195], v[54:57]
	v_mfma_f32_16x16x32_bf16 v[50:53], v[160:163], v[192:195], v[50:53]
	v_mfma_f32_16x16x32_bf16 v[38:41], v[152:155], v[200:203], v[38:41]
	v_mfma_f32_16x16x32_bf16 v[34:37], v[160:163], v[200:203], v[34:37]
	v_mfma_f32_16x16x32_bf16 v[22:25], v[152:155], v[208:211], v[22:25]
	v_mfma_f32_16x16x32_bf16 v[18:21], v[160:163], v[208:211], v[18:21]
	v_mfma_f32_16x16x32_bf16 v[62:65], v[156:159], v[188:191], v[62:65]
	v_mfma_f32_16x16x32_bf16 v[58:61], v[164:167], v[188:191], v[58:61]
	v_mfma_f32_16x16x32_bf16 v[54:57], v[156:159], v[196:199], v[54:57]
	v_mfma_f32_16x16x32_bf16 v[50:53], v[164:167], v[196:199], v[50:53]
	v_mfma_f32_16x16x32_bf16 v[38:41], v[156:159], v[204:207], v[38:41]
	v_mfma_f32_16x16x32_bf16 v[34:37], v[164:167], v[204:207], v[34:37]
	v_mfma_f32_16x16x32_bf16 v[22:25], v[156:159], v[212:215], v[22:25]
	v_mfma_f32_16x16x32_bf16 v[18:21], v[164:167], v[212:215], v[18:21]
	v_mfma_f32_16x16x32_bf16 v[46:49], v[168:171], v[184:187], v[46:49]
	v_mfma_f32_16x16x32_bf16 v[42:45], v[176:179], v[184:187], v[42:45]
	v_mfma_f32_16x16x32_bf16 v[30:33], v[168:171], v[192:195], v[30:33]
	v_mfma_f32_16x16x32_bf16 v[26:29], v[176:179], v[192:195], v[26:29]
	v_mfma_f32_16x16x32_bf16 v[14:17], v[168:171], v[200:203], v[14:17]
	v_mfma_f32_16x16x32_bf16 v[10:13], v[176:179], v[200:203], v[10:13]
	v_mfma_f32_16x16x32_bf16 v[6:9], v[168:171], v[208:211], v[6:9]
	v_mfma_f32_16x16x32_bf16 v[2:5], v[176:179], v[208:211], v[2:5]
	v_mfma_f32_16x16x32_bf16 v[46:49], v[172:175], v[188:191], v[46:49]
	v_mfma_f32_16x16x32_bf16 v[42:45], v[180:183], v[188:191], v[42:45]
	v_mfma_f32_16x16x32_bf16 v[30:33], v[172:175], v[196:199], v[30:33]
	v_mfma_f32_16x16x32_bf16 v[26:29], v[180:183], v[196:199], v[26:29]
	v_mfma_f32_16x16x32_bf16 v[14:17], v[172:175], v[204:207], v[14:17]
	v_mfma_f32_16x16x32_bf16 v[10:13], v[180:183], v[204:207], v[10:13]
	v_mfma_f32_16x16x32_bf16 v[6:9], v[172:175], v[212:215], v[6:9]
	v_mfma_f32_16x16x32_bf16 v[2:5], v[180:183], v[212:215], v[2:5]
	s_barrier
	s_add_i32 s67, 0, 0x18000
	s_add_i32 s69, 0, 0x1c000
	v_add_u32_e32 v164, s67, v147
	v_add_u32_e32 v180, s69, v147
	ds_read_b128 v[152:155], v164
	ds_read_b128 v[156:159], v164 offset:1024
	ds_read_b128 v[160:163], v164 offset:2048
	ds_read_b128 v[164:167], v164 offset:3072
	ds_read_b128 v[168:171], v180
	ds_read_b128 v[172:175], v180 offset:1024
	ds_read_b128 v[176:179], v180 offset:2048
	ds_read_b128 v[180:183], v180 offset:3072
	s_add_u32 s42, s42, 0x100000
	s_addc_u32 s43, s43, 0
	s_mov_b32 m0, s49
	v_lshl_add_u64 v[224:225], s[42:43], 0, v[136:137]
	ds_read_b128 v[184:187], v151 offset:32768
	ds_read_b128 v[188:191], v151 offset:33792
	ds_read_b128 v[192:195], v151 offset:34816
	ds_read_b128 v[196:199], v151 offset:35840
	ds_read_b128 v[200:203], v151 offset:36864
	ds_read_b128 v[204:207], v151 offset:37888
	ds_read_b128 v[208:211], v151 offset:38912
	ds_read_b128 v[212:215], v151 offset:39936
	global_load_lds_dwordx4 v[224:225], off
	v_lshl_add_u64 v[224:225], s[42:43], 0, v[132:133]
	s_mov_b32 m0, s50
	s_nop 0
	global_load_lds_dwordx4 v[224:225], off
	s_waitcnt vmcnt(8)
	s_waitcnt lgkmcnt(0)
	s_barrier
	v_mfma_f32_16x16x32_bf16 v[126:129], v[152:155], v[184:187], v[126:129]
	v_mfma_f32_16x16x32_bf16 v[122:125], v[160:163], v[184:187], v[122:125]
	v_mfma_f32_16x16x32_bf16 v[118:121], v[152:155], v[192:195], v[118:121]
	v_mfma_f32_16x16x32_bf16 v[114:117], v[160:163], v[192:195], v[114:117]
	v_mfma_f32_16x16x32_bf16 v[102:105], v[152:155], v[200:203], v[102:105]
	v_mfma_f32_16x16x32_bf16 v[98:101], v[160:163], v[200:203], v[98:101]
	v_mfma_f32_16x16x32_bf16 v[86:89], v[152:155], v[208:211], v[86:89]
	v_mfma_f32_16x16x32_bf16 v[82:85], v[160:163], v[208:211], v[82:85]
	v_mfma_f32_16x16x32_bf16 v[126:129], v[156:159], v[188:191], v[126:129]
	v_mfma_f32_16x16x32_bf16 v[122:125], v[164:167], v[188:191], v[122:125]
	v_mfma_f32_16x16x32_bf16 v[118:121], v[156:159], v[196:199], v[118:121]
	v_mfma_f32_16x16x32_bf16 v[114:117], v[164:167], v[196:199], v[114:117]
	v_mfma_f32_16x16x32_bf16 v[102:105], v[156:159], v[204:207], v[102:105]
	v_mfma_f32_16x16x32_bf16 v[98:101], v[164:167], v[204:207], v[98:101]
	v_mfma_f32_16x16x32_bf16 v[86:89], v[156:159], v[212:215], v[86:89]
	v_mfma_f32_16x16x32_bf16 v[82:85], v[164:167], v[212:215], v[82:85]
	v_mfma_f32_16x16x32_bf16 v[110:113], v[168:171], v[184:187], v[110:113]
	v_mfma_f32_16x16x32_bf16 v[106:109], v[176:179], v[184:187], v[106:109]
	v_mfma_f32_16x16x32_bf16 v[94:97], v[168:171], v[192:195], v[94:97]
	v_mfma_f32_16x16x32_bf16 v[90:93], v[176:179], v[192:195], v[90:93]
	v_mfma_f32_16x16x32_bf16 v[78:81], v[168:171], v[200:203], v[78:81]
	v_mfma_f32_16x16x32_bf16 v[74:77], v[176:179], v[200:203], v[74:77]
	v_mfma_f32_16x16x32_bf16 v[70:73], v[168:171], v[208:211], v[70:73]
	v_mfma_f32_16x16x32_bf16 v[66:69], v[176:179], v[208:211], v[66:69]
	v_mfma_f32_16x16x32_bf16 v[110:113], v[172:175], v[188:191], v[110:113]
	v_mfma_f32_16x16x32_bf16 v[106:109], v[180:183], v[188:191], v[106:109]
	v_mfma_f32_16x16x32_bf16 v[94:97], v[172:175], v[196:199], v[94:97]
	v_mfma_f32_16x16x32_bf16 v[90:93], v[180:183], v[196:199], v[90:93]
	v_mfma_f32_16x16x32_bf16 v[78:81], v[172:175], v[204:207], v[78:81]
	v_mfma_f32_16x16x32_bf16 v[74:77], v[180:183], v[204:207], v[74:77]
	v_mfma_f32_16x16x32_bf16 v[70:73], v[172:175], v[212:215], v[70:73]
	v_mfma_f32_16x16x32_bf16 v[66:69], v[180:183], v[212:215], v[66:69]
	s_barrier
; #define PG8_STAGE(bufoff, gbase, voff) do { _Pragma("unroll") for (int _i = 0; _i < 2; ++_i) \
;         __builtin_amdgcn_global_load_lds((const unsigned*)((const char*)(gbase) + (voff)[_i]), (PG8_LAS unsigned*)(lds + (bufoff) + ldsw + _i * 8192), 16, 0, 0); } while (0)
; #define PG8_LDA(dst, b, h) do { _Pragma("unroll") for (int m = 0; m < 4; ++m) _Pragma("unroll") for (int k = 0; k < 2; ++k) dst[m][k] = *(const PG8_LAS bf16x8*)(lds + PG8_SA(b, h) + aoff + m * 2048 + k * 1024); } while (0)
; #define PG8_WAIT_V(n) asm volatile("s_waitcnt vmcnt(" #n ")" ::: "memory")
; #define PG8_WAIT_L(n) asm volatile("s_waitcnt lgkmcnt(" #n ")" ::: "memory")
; #define PG8_BAR __builtin_amdgcn_s_barrier()
; #define PG8_SCHED __builtin_amdgcn_sched_barrier(0)
; template <class Epi, class Sched, bool ALIGN_EPI = false, bool SP2 = false, bool F8 = false>
; __device__ __forceinline__ void gemm_phase(PG8_LAS unsigned char* lds, const Gemm g, const Sched& S, const Epi& E) {
;     ...
;             PG8_LDA(At, 1, 1); PG8_STAGE(PG8_SB(1, 0), b3, voffB); PG8_STAGE(PG8_SB(1, 1), b3 + hB, voffB); PG8_STAGE(PG8_SA(1, 0), a3, voffA);
;             PG8_WAIT_V(8); PG8_WAIT_L(0); PG8_BAR; PG8_MMA(1, 0, At, B0); PG8_MMA(1, 1, At, B1); PG8_BAR; PG8_SCHED;
;     ...
;         if constexpr (ALIGN_EPI) { if (wr == 0) PG8_BAR; }
	s_add_i32 s42, s67, s45
	v_lshl_add_u64 v[216:217], v[216:217], 0, s[12:13]
	s_mov_b32 m0, s42
	ds_read_b128 v[184:187], v151 offset:49152
	ds_read_b128 v[188:191], v151 offset:50176
	ds_read_b128 v[192:195], v151 offset:51200
	ds_read_b128 v[196:199], v151 offset:52224
	ds_read_b128 v[200:203], v151 offset:53248
	ds_read_b128 v[204:207], v151 offset:54272
	ds_read_b128 v[208:211], v151 offset:55296
	ds_read_b128 v[212:215], v151 offset:56320
	global_load_lds_dwordx4 v[216:217], off
	s_add_i32 m0, s42, 0x2000
	s_add_u32 s40, s40, 0x100080
	v_lshl_add_u64 v[216:217], v[218:219], 0, s[12:13]
	s_addc_u32 s41, s41, 0
	s_add_i32 s42, s69, s45
	global_load_lds_dwordx4 v[216:217], off
	v_lshl_add_u64 v[216:217], s[40:41], 0, v[134:135]
	s_mov_b32 m0, s42
	s_nop 0
	global_load_lds_dwordx4 v[216:217], off
	v_lshl_add_u64 v[216:217], s[40:41], 0, v[130:131]
	s_add_i32 m0, s42, 0x2000
	s_nop 0
	global_load_lds_dwordx4 v[216:217], off
	v_lshl_add_u64 v[216:217], v[220:221], 0, s[12:13]
	s_mov_b32 m0, s52
	s_nop 0
	global_load_lds_dwordx4 v[216:217], off
	v_lshl_add_u64 v[216:217], v[222:223], 0, s[12:13]
	s_mov_b32 m0, s53
	s_nop 0
	global_load_lds_dwordx4 v[216:217], off
	s_waitcnt vmcnt(8)
	s_waitcnt lgkmcnt(0)
	s_barrier
	v_mfma_f32_16x16x32_bf16 v[62:65], v[152:155], v[184:187], v[62:65]
	v_mfma_f32_16x16x32_bf16 v[58:61], v[160:163], v[184:187], v[58:61]
	v_mfma_f32_16x16x32_bf16 v[54:57], v[152:155], v[192:195], v[54:57]
	v_mfma_f32_16x16x32_bf16 v[50:53], v[160:163], v[192:195], v[50:53]
	v_mfma_f32_16x16x32_bf16 v[38:41], v[152:155], v[200:203], v[38:41]
	v_mfma_f32_16x16x32_bf16 v[34:37], v[160:163], v[200:203], v[34:37]
	v_mfma_f32_16x16x32_bf16 v[22:25], v[152:155], v[208:211], v[22:25]
	v_mfma_f32_16x16x32_bf16 v[18:21], v[160:163], v[208:211], v[18:21]
	v_mfma_f32_16x16x32_bf16 v[62:65], v[156:159], v[188:191], v[62:65]
	v_mfma_f32_16x16x32_bf16 v[58:61], v[164:167], v[188:191], v[58:61]
	v_mfma_f32_16x16x32_bf16 v[54:57], v[156:159], v[196:199], v[54:57]
	v_mfma_f32_16x16x32_bf16 v[50:53], v[164:167], v[196:199], v[50:53]
	v_mfma_f32_16x16x32_bf16 v[38:41], v[156:159], v[204:207], v[38:41]
	v_mfma_f32_16x16x32_bf16 v[34:37], v[164:167], v[204:207], v[34:37]
	v_mfma_f32_16x16x32_bf16 v[22:25], v[156:159], v[212:215], v[22:25]
	v_mfma_f32_16x16x32_bf16 v[18:21], v[164:167], v[212:215], v[18:21]
	v_mfma_f32_16x16x32_bf16 v[46:49], v[168:171], v[184:187], v[46:49]
	v_mfma_f32_16x16x32_bf16 v[42:45], v[176:179], v[184:187], v[42:45]
	v_mfma_f32_16x16x32_bf16 v[30:33], v[168:171], v[192:195], v[30:33]
	v_mfma_f32_16x16x32_bf16 v[26:29], v[176:179], v[192:195], v[26:29]
	v_mfma_f32_16x16x32_bf16 v[14:17], v[168:171], v[200:203], v[14:17]
	v_mfma_f32_16x16x32_bf16 v[10:13], v[176:179], v[200:203], v[10:13]
	v_mfma_f32_16x16x32_bf16 v[6:9], v[168:171], v[208:211], v[6:9]
	v_mfma_f32_16x16x32_bf16 v[2:5], v[176:179], v[208:211], v[2:5]
	v_mfma_f32_16x16x32_bf16 v[46:49], v[172:175], v[188:191], v[46:49]
	v_mfma_f32_16x16x32_bf16 v[42:45], v[180:183], v[188:191], v[42:45]
	v_mfma_f32_16x16x32_bf16 v[30:33], v[172:175], v[196:199], v[30:33]
	v_mfma_f32_16x16x32_bf16 v[26:29], v[180:183], v[196:199], v[26:29]
	v_mfma_f32_16x16x32_bf16 v[14:17], v[172:175], v[204:207], v[14:17]
	v_mfma_f32_16x16x32_bf16 v[10:13], v[180:183], v[204:207], v[10:13]
	v_mfma_f32_16x16x32_bf16 v[6:9], v[172:175], v[212:215], v[6:9]
	v_mfma_f32_16x16x32_bf16 v[2:5], v[180:183], v[212:215], v[2:5]
	s_barrier
	s_add_i32 s66, s66, 2
	s_add_u32 s64, s64, 0x100
	s_addc_u32 s65, s65, 0
	s_add_u32 s38, s38, 0x100
	s_addc_u32 s39, s39, 0
	s_cmp_gt_u32 s66, 61
	s_cbranch_scc0 .LBB0_128
	s_and_b64 vcc, exec, s[14:15]
	s_cbranch_vccz .LBB0_131
	s_barrier

; #define PG8_STAGE(bufoff, gbase, voff) do { _Pragma("unroll") for (int _i = 0; _i < 2; ++_i) \
;         __builtin_amdgcn_global_load_lds((const unsigned*)((const char*)(gbase) + (voff)[_i]), (PG8_LAS unsigned*)(lds + (bufoff) + ldsw + _i * 8192), 16, 0, 0); } while (0)
; #define PG8_LDA(dst, b, h) do { _Pragma("unroll") for (int m = 0; m < 4; ++m) _Pragma("unroll") for (int k = 0; k < 2; ++k) dst[m][k] = *(const PG8_LAS bf16x8*)(lds + PG8_SA(b, h) + aoff + m * 2048 + k * 1024); } while (0)
; #define PG8_LDB(dst, b, h) do { _Pragma("unroll") for (int n = 0; n < 2; ++n) _Pragma("unroll") for (int k = 0; k < 2; ++k) dst[n][k] = *(const PG8_LAS bf16x8*)(lds + PG8_SB(b, h) + boff + n * 2048 + k * 1024); } while (0)
; #define PG8_WAIT_V(n) asm volatile("s_waitcnt vmcnt(" #n ")" ::: "memory")
; #define PG8_WAIT_L(n) asm volatile("s_waitcnt lgkmcnt(" #n ")" ::: "memory")
; #define PG8_BAR __builtin_amdgcn_s_barrier()
; #define PG8_SCHED __builtin_amdgcn_sched_barrier(0)
; template <class Epi, class Sched, bool ALIGN_EPI = false, bool SP2 = false, bool F8 = false>
; __device__ __forceinline__ void gemm_phase(PG8_LAS unsigned char* lds, const Gemm g, const Sched& S, const Epi& E) {
;     ...
;             PG8_LDB(B0, 0, 0); PG8_LDB(B1, 0, 1); PG8_SCHED; PG8_LDA(At, 0, 0); PG8_STAGE(PG8_SA(1, 1), a1 + hA, voffA);
;             PG8_WAIT_V(8); PG8_WAIT_L(0); PG8_BAR; PG8_MMA(0, 0, At, B0); PG8_MMA(0, 1, At, B1); PG8_BAR; PG8_SCHED;
;             PG8_LDA(At, 0, 1); PG8_STAGE(PG8_SB(0, 0), b2, voffB); PG8_STAGE(PG8_SB(0, 1), b2 + hB, voffB); PG8_STAGE(PG8_SA(0, 0), a2, voffA);
;             PG8_WAIT_V(8); PG8_WAIT_L(0); PG8_BAR; PG8_MMA(1, 0, At, B0); PG8_MMA(1, 1, At, B1); PG8_BAR; PG8_SCHED;
;             PG8_LDB(B0, 1, 0); PG8_LDB(B1, 1, 1); PG8_SCHED; PG8_LDA(At, 1, 0); PG8_STAGE(PG8_SA(0, 1), a2 + hA, voffA);
;             PG8_WAIT_V(8); PG8_WAIT_L(0); PG8_BAR; PG8_MMA(0, 0, At, B0); PG8_MMA(0, 1, At, B1); PG8_BAR; PG8_SCHED;
.LBB0_146:
	ds_read_b128 v[26:29], v190
	ds_read_b128 v[30:33], v190 offset:1024
	ds_read_b128 v[18:21], v190 offset:2048
	ds_read_b128 v[22:25], v190 offset:3072
	ds_read_b128 v[10:13], v191
	ds_read_b128 v[14:17], v191 offset:1024
	ds_read_b128 v[2:5], v191 offset:2048
	ds_read_b128 v[6:9], v191 offset:3072
	s_add_u32 s40, s6, 0xfff80080
	s_addc_u32 s41, s7, -1
	s_cmp_eq_u32 s60, 28
	s_cselect_b32 s43, s29, s41
	s_cselect_b32 s42, s37, s40
	s_cselect_b32 s41, s27, s59
	s_cselect_b32 s40, s44, s45
	v_lshl_add_u64 v[218:219], s[6:7], 0, v[172:173]
	s_add_i32 m0, s39, 0xc000
	ds_read_b128 v[178:181], v192
	ds_read_b128 v[182:185], v192 offset:1024
	ds_read_b128 v[194:197], v192 offset:2048
	ds_read_b128 v[198:201], v192 offset:3072
	ds_read_b128 v[202:205], v192 offset:4096
	ds_read_b128 v[206:209], v192 offset:5120
	ds_read_b128 v[210:213], v192 offset:6144
	ds_read_b128 v[214:217], v192 offset:7168
	global_load_lds_dwordx4 v[218:219], off
	v_lshl_add_u64 v[218:219], s[6:7], 0, v[170:171]
	s_add_i32 m0, s39, 0xe000
	s_nop 0
	global_load_lds_dwordx4 v[218:219], off
	s_waitcnt vmcnt(8)
	s_waitcnt lgkmcnt(0)
	s_barrier
	v_mfma_scale_f32_16x16x128_f8f6f4 v[158:161], v[26:33], v[178:185], v[158:161], v186, v186 op_sel_hi:[0,0,0]
	v_mfma_scale_f32_16x16x128_f8f6f4 v[154:157], v[18:25], v[178:185], v[154:157], v186, v186 op_sel_hi:[0,0,0]
	v_mfma_scale_f32_16x16x128_f8f6f4 v[142:145], v[26:33], v[194:201], v[142:145], v186, v186 op_sel_hi:[0,0,0]
	v_mfma_scale_f32_16x16x128_f8f6f4 v[138:141], v[18:25], v[194:201], v[138:141], v186, v186 op_sel_hi:[0,0,0]
	v_mfma_scale_f32_16x16x128_f8f6f4 v[126:129], v[26:33], v[202:209], v[126:129], v186, v186 op_sel_hi:[0,0,0]
	v_mfma_scale_f32_16x16x128_f8f6f4 v[122:125], v[18:25], v[202:209], v[122:125], v186, v186 op_sel_hi:[0,0,0]
	v_mfma_scale_f32_16x16x128_f8f6f4 v[110:113], v[26:33], v[210:217], v[110:113], v186, v186 op_sel_hi:[0,0,0]
	v_mfma_scale_f32_16x16x128_f8f6f4 v[106:109], v[18:25], v[210:217], v[106:109], v186, v186 op_sel_hi:[0,0,0]
	v_mfma_scale_f32_16x16x128_f8f6f4 v[150:153], v[10:17], v[178:185], v[150:153], v186, v186 op_sel_hi:[0,0,0]
	v_mfma_scale_f32_16x16x128_f8f6f4 v[146:149], v[2:9], v[178:185], v[146:149], v186, v186 op_sel_hi:[0,0,0]
	v_mfma_scale_f32_16x16x128_f8f6f4 v[134:137], v[10:17], v[194:201], v[134:137], v186, v186 op_sel_hi:[0,0,0]
	v_mfma_scale_f32_16x16x128_f8f6f4 v[130:133], v[2:9], v[194:201], v[130:133], v186, v186 op_sel_hi:[0,0,0]
	v_mfma_scale_f32_16x16x128_f8f6f4 v[118:121], v[10:17], v[202:209], v[118:121], v186, v186 op_sel_hi:[0,0,0]
	v_mfma_scale_f32_16x16x128_f8f6f4 v[114:117], v[2:9], v[202:209], v[114:117], v186, v186 op_sel_hi:[0,0,0]
	v_mfma_scale_f32_16x16x128_f8f6f4 v[102:105], v[10:17], v[210:217], v[102:105], v186, v186 op_sel_hi:[0,0,0]
	v_mfma_scale_f32_16x16x128_f8f6f4 v[98:101], v[2:9], v[210:217], v[98:101], v186, v186 op_sel_hi:[0,0,0]
	s_barrier
	s_add_i32 s61, s57, s47
	v_lshl_add_u64 v[178:179], s[40:41], 0, v[164:165]
	s_mov_b32 m0, s61
	ds_read_b128 v[194:197], v192 offset:16384
	ds_read_b128 v[198:201], v192 offset:17408
	ds_read_b128 v[202:205], v192 offset:18432
	ds_read_b128 v[206:209], v192 offset:19456
	ds_read_b128 v[210:213], v192 offset:20480
	ds_read_b128 v[214:217], v192 offset:21504
	ds_read_b128 v[218:221], v192 offset:22528
	ds_read_b128 v[222:225], v192 offset:23552
	global_load_lds_dwordx4 v[178:179], off
	s_add_i32 m0, s61, 0x2000
	s_add_u32 s62, s40, 0x80000
	v_lshl_add_u64 v[180:181], s[40:41], 0, v[168:169]
	s_addc_u32 s63, s41, 0
	s_add_i32 s61, s58, s47
	global_load_lds_dwordx4 v[180:181], off
	v_lshl_add_u64 v[182:183], s[62:63], 0, v[164:165]
	s_mov_b32 m0, s61
	v_lshl_add_u64 v[184:185], s[42:43], 0, v[166:167]
	global_load_lds_dwordx4 v[182:183], off
	v_lshl_add_u64 v[182:183], s[62:63], 0, v[168:169]
	s_add_i32 m0, s61, 0x2000
	s_nop 0
	global_load_lds_dwordx4 v[182:183], off
	v_lshl_add_u64 v[182:183], s[42:43], 0, v[162:163]
	s_mov_b32 m0, s39
	s_nop 0
	global_load_lds_dwordx4 v[182:183], off
	s_mov_b32 m0, s48
	s_nop 0
	global_load_lds_dwordx4 v[184:185], off
	s_waitcnt vmcnt(8)
	s_waitcnt lgkmcnt(0)
	s_barrier
	v_mfma_scale_f32_16x16x128_f8f6f4 v[94:97], v[26:33], v[194:201], v[94:97], v186, v186 op_sel_hi:[0,0,0]
	v_mfma_scale_f32_16x16x128_f8f6f4 v[90:93], v[18:25], v[194:201], v[90:93], v186, v186 op_sel_hi:[0,0,0]
	v_mfma_scale_f32_16x16x128_f8f6f4 v[78:81], v[26:33], v[202:209], v[78:81], v186, v186 op_sel_hi:[0,0,0]
	v_mfma_scale_f32_16x16x128_f8f6f4 v[74:77], v[18:25], v[202:209], v[74:77], v186, v186 op_sel_hi:[0,0,0]
	v_mfma_scale_f32_16x16x128_f8f6f4 v[62:65], v[26:33], v[210:217], v[62:65], v186, v186 op_sel_hi:[0,0,0]
	v_mfma_scale_f32_16x16x128_f8f6f4 v[58:61], v[18:25], v[210:217], v[58:61], v186, v186 op_sel_hi:[0,0,0]
	v_mfma_scale_f32_16x16x128_f8f6f4 v[46:49], v[26:33], v[218:225], v[46:49], v186, v186 op_sel_hi:[0,0,0]
	v_mfma_scale_f32_16x16x128_f8f6f4 v[42:45], v[18:25], v[218:225], v[42:45], v186, v186 op_sel_hi:[0,0,0]
	v_mfma_scale_f32_16x16x128_f8f6f4 v[86:89], v[10:17], v[194:201], v[86:89], v186, v186 op_sel_hi:[0,0,0]
	v_mfma_scale_f32_16x16x128_f8f6f4 v[82:85], v[2:9], v[194:201], v[82:85], v186, v186 op_sel_hi:[0,0,0]
	v_mfma_scale_f32_16x16x128_f8f6f4 v[70:73], v[10:17], v[202:209], v[70:73], v186, v186 op_sel_hi:[0,0,0]
	v_mfma_scale_f32_16x16x128_f8f6f4 v[66:69], v[2:9], v[202:209], v[66:69], v186, v186 op_sel_hi:[0,0,0]
	v_mfma_scale_f32_16x16x128_f8f6f4 v[54:57], v[10:17], v[210:217], v[54:57], v186, v186 op_sel_hi:[0,0,0]
	v_mfma_scale_f32_16x16x128_f8f6f4 v[50:53], v[2:9], v[210:217], v[50:53], v186, v186 op_sel_hi:[0,0,0]
	v_mfma_scale_f32_16x16x128_f8f6f4 v[38:41], v[10:17], v[218:225], v[38:41], v186, v186 op_sel_hi:[0,0,0]
	v_mfma_scale_f32_16x16x128_f8f6f4 v[34:37], v[2:9], v[218:225], v[34:37], v186, v186 op_sel_hi:[0,0,0]
	s_barrier
; #define PG8_STAGE(bufoff, gbase, voff) do { _Pragma("unroll") for (int _i = 0; _i < 2; ++_i) \
;         __builtin_amdgcn_global_load_lds((const unsigned*)((const char*)(gbase) + (voff)[_i]), (PG8_LAS unsigned*)(lds + (bufoff) + ldsw + _i * 8192), 16, 0, 0); } while (0)
; #define PG8_LDA(dst, b, h) do { _Pragma("unroll") for (int m = 0; m < 4; ++m) _Pragma("unroll") for (int k = 0; k < 2; ++k) dst[m][k] = *(const PG8_LAS bf16x8*)(lds + PG8_SA(b, h) + aoff + m * 2048 + k * 1024); } while (0)
; #define PG8_LDB(dst, b, h) do { _Pragma("unroll") for (int n = 0; n < 2; ++n) _Pragma("unroll") for (int k = 0; k < 2; ++k) dst[n][k] = *(const PG8_LAS bf16x8*)(lds + PG8_SB(b, h) + boff + n * 2048 + k * 1024); } while (0)
; #define PG8_WAIT_V(n) asm volatile("s_waitcnt vmcnt(" #n ")" ::: "memory")
; #define PG8_WAIT_L(n) asm volatile("s_waitcnt lgkmcnt(" #n ")" ::: "memory")
; #define PG8_BAR __builtin_amdgcn_s_barrier()
; #define PG8_SCHED __builtin_amdgcn_sched_barrier(0)
; template <class Epi, class Sched, bool ALIGN_EPI = false, bool SP2 = false, bool F8 = false>
; __device__ __forceinline__ void gemm_phase(PG8_LAS unsigned char* lds, const Gemm g, const Sched& S, const Epi& E) {
;     ...
;             PG8_LDB(B0, 1, 0); PG8_LDB(B1, 1, 1); PG8_SCHED; PG8_LDA(At, 1, 0); PG8_STAGE(PG8_SA(0, 1), a2 + hA, voffA);
;             PG8_WAIT_V(8); PG8_WAIT_L(0); PG8_BAR; PG8_MMA(0, 0, At, B0); PG8_MMA(0, 1, At, B1); PG8_BAR; PG8_SCHED;
;             PG8_LDA(At, 1, 1); PG8_STAGE(PG8_SB(1, 0), b3, voffB); PG8_STAGE(PG8_SB(1, 1), b3 + hB, voffB); PG8_STAGE(PG8_SA(1, 0), a3, voffA);
;             PG8_WAIT_V(8); PG8_WAIT_L(0); PG8_BAR; PG8_MMA(1, 0, At, B0); PG8_MMA(1, 1, At, B1); PG8_BAR; PG8_SCHED;
	s_add_i32 s61, 0, 0x18000
	s_add_i32 s62, 0, 0x1c000
	v_add_u32_e32 v14, s61, v188
	v_add_u32_e32 v30, s62, v188
	ds_read_b128 v[2:5], v14
	ds_read_b128 v[6:9], v14 offset:1024
	ds_read_b128 v[10:13], v14 offset:2048
	ds_read_b128 v[14:17], v14 offset:3072
	ds_read_b128 v[18:21], v30
	ds_read_b128 v[22:25], v30 offset:1024
	ds_read_b128 v[26:29], v30 offset:2048
	ds_read_b128 v[30:33], v30 offset:3072
	s_add_u32 s42, s42, 0x80000
	s_addc_u32 s43, s43, 0
	s_mov_b32 m0, s49
	v_lshl_add_u64 v[226:227], s[42:43], 0, v[162:163]
	ds_read_b128 v[194:197], v192 offset:32768
	ds_read_b128 v[198:201], v192 offset:33792
	ds_read_b128 v[202:205], v192 offset:34816
	ds_read_b128 v[206:209], v192 offset:35840
	ds_read_b128 v[210:213], v192 offset:36864
	ds_read_b128 v[214:217], v192 offset:37888
	ds_read_b128 v[218:221], v192 offset:38912
	ds_read_b128 v[222:225], v192 offset:39936
	global_load_lds_dwordx4 v[226:227], off
	v_lshl_add_u64 v[226:227], s[42:43], 0, v[166:167]
	s_mov_b32 m0, s50
	s_nop 0
	global_load_lds_dwordx4 v[226:227], off
	s_waitcnt vmcnt(8)
	s_waitcnt lgkmcnt(0)
	s_barrier
	v_mfma_scale_f32_16x16x128_f8f6f4 v[158:161], v[2:9], v[194:201], v[158:161], v186, v186 op_sel_hi:[0,0,0]
	v_mfma_scale_f32_16x16x128_f8f6f4 v[154:157], v[10:17], v[194:201], v[154:157], v186, v186 op_sel_hi:[0,0,0]
	v_mfma_scale_f32_16x16x128_f8f6f4 v[142:145], v[2:9], v[202:209], v[142:145], v186, v186 op_sel_hi:[0,0,0]
	v_mfma_scale_f32_16x16x128_f8f6f4 v[138:141], v[10:17], v[202:209], v[138:141], v186, v186 op_sel_hi:[0,0,0]
	v_mfma_scale_f32_16x16x128_f8f6f4 v[126:129], v[2:9], v[210:217], v[126:129], v186, v186 op_sel_hi:[0,0,0]
	v_mfma_scale_f32_16x16x128_f8f6f4 v[122:125], v[10:17], v[210:217], v[122:125], v186, v186 op_sel_hi:[0,0,0]
	v_mfma_scale_f32_16x16x128_f8f6f4 v[110:113], v[2:9], v[218:225], v[110:113], v186, v186 op_sel_hi:[0,0,0]
	v_mfma_scale_f32_16x16x128_f8f6f4 v[106:109], v[10:17], v[218:225], v[106:109], v186, v186 op_sel_hi:[0,0,0]
	v_mfma_scale_f32_16x16x128_f8f6f4 v[150:153], v[18:25], v[194:201], v[150:153], v186, v186 op_sel_hi:[0,0,0]
	v_mfma_scale_f32_16x16x128_f8f6f4 v[146:149], v[26:33], v[194:201], v[146:149], v186, v186 op_sel_hi:[0,0,0]
	v_mfma_scale_f32_16x16x128_f8f6f4 v[134:137], v[18:25], v[202:209], v[134:137], v186, v186 op_sel_hi:[0,0,0]
	v_mfma_scale_f32_16x16x128_f8f6f4 v[130:133], v[26:33], v[202:209], v[130:133], v186, v186 op_sel_hi:[0,0,0]
	v_mfma_scale_f32_16x16x128_f8f6f4 v[118:121], v[18:25], v[210:217], v[118:121], v186, v186 op_sel_hi:[0,0,0]
	v_mfma_scale_f32_16x16x128_f8f6f4 v[114:117], v[26:33], v[210:217], v[114:117], v186, v186 op_sel_hi:[0,0,0]
	v_mfma_scale_f32_16x16x128_f8f6f4 v[102:105], v[18:25], v[218:225], v[102:105], v186, v186 op_sel_hi:[0,0,0]
	v_mfma_scale_f32_16x16x128_f8f6f4 v[98:101], v[26:33], v[218:225], v[98:101], v186, v186 op_sel_hi:[0,0,0]
	s_barrier
	s_add_i32 s42, s61, s47
	v_lshl_add_u64 v[178:179], v[178:179], 0, s[22:23]
	s_mov_b32 m0, s42
	ds_read_b128 v[194:197], v192 offset:49152
	ds_read_b128 v[198:201], v192 offset:50176
	ds_read_b128 v[202:205], v192 offset:51200
	ds_read_b128 v[206:209], v192 offset:52224
	ds_read_b128 v[210:213], v192 offset:53248
	ds_read_b128 v[214:217], v192 offset:54272
	ds_read_b128 v[218:221], v192 offset:55296
	ds_read_b128 v[222:225], v192 offset:56320
	global_load_lds_dwordx4 v[178:179], off
	s_add_i32 m0, s42, 0x2000
	s_add_u32 s40, s40, 0x80080
	v_lshl_add_u64 v[178:179], v[180:181], 0, s[22:23]
	s_addc_u32 s41, s41, 0
	s_add_i32 s42, s62, s47
	global_load_lds_dwordx4 v[178:179], off
	v_lshl_add_u64 v[178:179], s[40:41], 0, v[164:165]
	s_mov_b32 m0, s42
	s_nop 0
	global_load_lds_dwordx4 v[178:179], off
	v_lshl_add_u64 v[178:179], s[40:41], 0, v[168:169]
	s_add_i32 m0, s42, 0x2000
	s_nop 0
	global_load_lds_dwordx4 v[178:179], off
	v_lshl_add_u64 v[178:179], v[182:183], 0, s[22:23]
	s_mov_b32 m0, s52
	s_nop 0
	global_load_lds_dwordx4 v[178:179], off
	v_lshl_add_u64 v[178:179], v[184:185], 0, s[22:23]
	s_mov_b32 m0, s53
	s_nop 0
	global_load_lds_dwordx4 v[178:179], off
	s_waitcnt vmcnt(8)
	s_waitcnt lgkmcnt(0)
	s_barrier
	v_mfma_scale_f32_16x16x128_f8f6f4 v[94:97], v[2:9], v[194:201], v[94:97], v186, v186 op_sel_hi:[0,0,0]
	v_mfma_scale_f32_16x16x128_f8f6f4 v[90:93], v[10:17], v[194:201], v[90:93], v186, v186 op_sel_hi:[0,0,0]
	v_mfma_scale_f32_16x16x128_f8f6f4 v[78:81], v[2:9], v[202:209], v[78:81], v186, v186 op_sel_hi:[0,0,0]
	v_mfma_scale_f32_16x16x128_f8f6f4 v[74:77], v[10:17], v[202:209], v[74:77], v186, v186 op_sel_hi:[0,0,0]
	v_mfma_scale_f32_16x16x128_f8f6f4 v[62:65], v[2:9], v[210:217], v[62:65], v186, v186 op_sel_hi:[0,0,0]
	v_mfma_scale_f32_16x16x128_f8f6f4 v[58:61], v[10:17], v[210:217], v[58:61], v186, v186 op_sel_hi:[0,0,0]
	v_mfma_scale_f32_16x16x128_f8f6f4 v[46:49], v[2:9], v[218:225], v[46:49], v186, v186 op_sel_hi:[0,0,0]
	v_mfma_scale_f32_16x16x128_f8f6f4 v[42:45], v[10:17], v[218:225], v[42:45], v186, v186 op_sel_hi:[0,0,0]
	v_mfma_scale_f32_16x16x128_f8f6f4 v[86:89], v[18:25], v[194:201], v[86:89], v186, v186 op_sel_hi:[0,0,0]
	v_mfma_scale_f32_16x16x128_f8f6f4 v[82:85], v[26:33], v[194:201], v[82:85], v186, v186 op_sel_hi:[0,0,0]
	v_mfma_scale_f32_16x16x128_f8f6f4 v[70:73], v[18:25], v[202:209], v[70:73], v186, v186 op_sel_hi:[0,0,0]
	v_mfma_scale_f32_16x16x128_f8f6f4 v[66:69], v[26:33], v[202:209], v[66:69], v186, v186 op_sel_hi:[0,0,0]
	v_mfma_scale_f32_16x16x128_f8f6f4 v[54:57], v[18:25], v[210:217], v[54:57], v186, v186 op_sel_hi:[0,0,0]
	v_mfma_scale_f32_16x16x128_f8f6f4 v[50:53], v[26:33], v[210:217], v[50:53], v186, v186 op_sel_hi:[0,0,0]
	v_mfma_scale_f32_16x16x128_f8f6f4 v[38:41], v[18:25], v[218:225], v[38:41], v186, v186 op_sel_hi:[0,0,0]
	v_mfma_scale_f32_16x16x128_f8f6f4 v[34:37], v[26:33], v[218:225], v[34:37], v186, v186 op_sel_hi:[0,0,0]
	s_barrier
	s_add_i32 s60, s60, 2
	s_add_u32 s45, s45, 0x100
	s_addc_u32 s59, s59, 0
	s_add_u32 s6, s6, 0x100
	s_addc_u32 s7, s7, 0
	s_cmp_gt_u32 s60, 29
	s_cbranch_scc0 .LBB0_146
	s_and_b64 vcc, exec, s[24:25]
	s_cbranch_vccz .LBB0_149
	s_barrier

; __device__ __forceinline__ void attn_unit8(const bf16_t* __restrict__ Qb, const unsigned char* __restrict__ K8h, const unsigned char* __restrict__ VT8h, unsigned char* __restrict__ Ob, int seq, ATT_LAS char* lds, ...
;   int tid_ = threadIdx.x; asm volatile("" : "+v"(tid_));
;   const int tid = tid_, wid = tid >> 6, lane = tid & 63, r32 = lane & 31, hi = lane >> 5;
;   int one = 0x7f7f7f7f; asm volatile("" : "+v"(one));
;   ATT_LAS char* V_lds = lds; ATT_LAS char* K_lds = lds + 3 * 8192;
;   ATT_LAS float* ws = (ATT_LAS float*)(lds + 6 * 8192) + wid * 64; ATT_LAS float* li_l = ws; ATT_LAS float* al_l = ws + 32;
;   float m_reg = -1e30f, l_reg = 0; f32x16 o[4] = {}; i32x8a q8[2];
;   const int krow = tid >> 3, kch = tid & 7, kst = k8_off(krow, kch), vst = v8_off(tid >> 2, tid & 3);
;   const unsigned char* kg = K8h + (long)krow * 512 + kch * 16; const unsigned char* vg = VT8h + tid * 16;
;   i32x4a sk[2], sv[2];
;     ...
;   const int NT = seq / KVBLK;
;   SLOAD8(0, 0);
;   {
;     typedef float f32x4a __attribute__((ext_vector_type(4)));
;     const bf16_t* Qw = Qb + (long)(wid * QBLK + r32) * LDQ + hi * 8;
;     bf16x8 qr[8];
; #pragma unroll
;     for (int d0 = 0; d0 < 8; ++d0) qr[d0] = *reinterpret_cast<const bf16x8*>(Qw + d0 * 16);
;     float x[8][8]; float ss = 0.f;
; #pragma unroll
;     for (int d0 = 0; d0 < 8; ++d0)
; #pragma unroll
;       for (int e = 0; e < 8; ++e) { x[d0][e] = __uint_as_float((unsigned)(unsigned short)qr[d0][e] << 16); ss += x[d0][e] * x[d0][e]; }
;     { auto rr = __builtin_amdgcn_permlane32_swap(__float_as_uint(ss), __float_as_uint(ss), false, false); ss = __uint_as_float(rr[0]) + __uint_as_float(rr[1]); }
;     const float inv = 1.0f / sqrtf(ss * (1.0f / 128.0f) + 1e-6f);
; #pragma unroll
;     for (int d0 = 0; d0 < 8; ++d0) { const f32x4a g0 = *reinterpret_cast<const f32x4a*>(qg + d0 * 16 + hi * 8), g1 = *reinterpret_cast<const f32x4a*>(qg + d0 * 16 + hi * 8 + 4);
; #pragma unroll
;       for (int e = 0; e < 4; ++e) { x[d0][e] = x[d0][e] * inv * g0[e]; x[d0][4 + e] = x[d0][4 + e] * inv * g1[e]; } }
;     const int tq = tpos0 + wid * QBLK + r32;
; #pragma unroll
;     for (int ax = 0; ax < 2; ++ax) { const int pos = ax == 0 ? (tq >> 6) : (tq & 63);
; #pragma unroll
;       for (int h = 0; h < 2; ++h) { const f32x4a* tp = reinterpret_cast<const f32x4a*>(tab + (size_t)(pos * 32 + h * 16 + hi * 8) * 2);
; #pragma unroll
.LBB0_548:
	s_lshl_b32 s27, s25, 8
	s_add_i32 s6, s27, s24
	s_ashr_i32 s7, s6, 31
	s_lshl_b64 s[22:23], s[6:7], 11
	s_lshl_b64 s[6:7], s[6:7], 12
	s_add_u32 s6, s4, s6
	v_mov_b32_e32 v209, v0
	s_addc_u32 s7, s5, s7
	s_lshl_b32 s82, s8, 7
	s_lshl_b32 s8, s8, 8
	s_add_u32 s52, s6, s8
	v_ashrrev_i32_e32 v204, 6, v209
	v_and_b32_e32 v203, 31, v209
	v_lshlrev_b32_e32 v132, 5, v204
	s_addc_u32 s53, s7, 0
	s_ashr_i32 s25, s24, 31
	v_or_b32_e32 v2, v132, v203
	s_lshl_b64 s[8:9], s[24:25], 9
	v_ashrrev_i32_e32 v3, 31, v2
	s_add_u32 s6, s19, s8
	v_bfe_u32 v205, v209, 5, 1
	v_lshlrev_b64 v[2:3], 12, v[2:3]
	s_addc_u32 s7, s28, s9
	s_lshl_b32 s25, s26, 7
	v_lshl_add_u64 v[2:3], s[52:53], 0, v[2:3]
	v_lshlrev_b32_e32 v134, 4, v205
	v_mov_b32_e32 v135, v131
	s_add_u32 s6, s6, s25
	v_lshl_add_u64 v[10:11], v[2:3], 0, v[134:135]
	v_and_b32_e32 v2, 32, v209
	v_mov_b32_e32 v3, v131
	s_addc_u32 s7, s7, 0
	s_ashr_i32 s24, s24, 4
	v_lshl_add_u64 v[12:13], s[12:13], 0, v[2:3]
	v_and_b32_e32 v2, 0x3fffffc0, v209
	v_ashrrev_i32_e32 v14, 3, v209
	s_and_b32 s24, s24, -4
	v_lshl_add_u32 v206, v2, 2, 0
	v_lshrrev_b32_e32 v2, 1, v14
	s_or_b32 s54, s26, s24
	v_xor_b32_e32 v2, v2, v209
	v_ashrrev_i32_e32 v17, 2, v209
	s_ashr_i32 s55, s54, 31
	v_lshlrev_b32_e32 v16, 4, v2
	v_lshrrev_b32_e32 v2, 2, v17
	v_ashrrev_i32_e32 v15, 31, v14
	s_lshl_b64 s[52:53], s[54:55], 13
	v_xor_b32_e32 v2, v2, v209
	v_lshlrev_b64 v[124:125], 9, v[14:15]
	v_lshlrev_b32_e32 v122, 4, v209
	s_add_u32 s52, s29, s52
	v_lshlrev_b32_e32 v18, 4, v2
	v_lshl_add_u64 v[2:3], s[6:7], 0, v[124:125]
	v_and_b32_e32 v130, 0x70, v122
	v_mov_b32_e32 v133, 0x7f7f7f7f
	s_addc_u32 s53, s30, s53
	v_lshl_add_u64 v[118:119], v[2:3], 0, v[130:131]
	v_ashrrev_i32_e32 v123, 31, v122
	flat_load_dwordx4 v[178:181], v[10:11] offset:128
	flat_load_dwordx4 v[152:155], v[10:11] offset:160
	flat_load_dwordx4 v[182:185], v[10:11] offset:192
	flat_load_dwordx4 v[156:159], v[10:11] offset:224
	flat_load_dwordx4 v[160:163], v[12:13] offset:448
	flat_load_dwordx4 v[144:147], v[12:13] offset:464
	flat_load_dwordx4 v[54:57], v[12:13] offset:320
	flat_load_dwordx4 v[50:53], v[12:13] offset:336
	v_lshl_add_u64 v[120:121], s[52:53], 0, v[122:123]
	flat_load_dwordx4 v[6:9], v[118:119]
	flat_load_dwordx4 v[2:5], v[120:121]
	flat_load_dwordx4 v[186:189], v[12:13] offset:384
	flat_load_dwordx4 v[168:171], v[12:13] offset:400
	flat_load_dwordx4 v[86:89], v[12:13] offset:256
	flat_load_dwordx4 v[78:81], v[12:13] offset:272
	flat_load_dwordx4 v[110:113], v[10:11]
	flat_load_dwordx4 v[210:213], v[10:11] offset:32
	flat_load_dwordx4 v[114:117], v[10:11] offset:64
	flat_load_dwordx4 v[214:217], v[10:11] offset:96
	flat_load_dwordx4 v[102:105], v[12:13]
	flat_load_dwordx4 v[98:101], v[12:13] offset:16
	flat_load_dwordx4 v[94:97], v[12:13] offset:64
	flat_load_dwordx4 v[90:93], v[12:13] offset:80
	flat_load_dwordx4 v[106:109], v[12:13] offset:128
	flat_load_dwordx4 v[218:221], v[12:13] offset:144
	flat_load_dwordx4 v[222:225], v[12:13] offset:192
	flat_load_dwordx4 v[194:197], v[12:13] offset:208
	v_lshlrev_b32_e32 v10, 7, v14
	v_and_or_b32 v208, v16, s31, v10
	v_or_b32_e32 v10, s27, v203
	v_add_u32_e32 v14, v10, v132
	v_lshlrev_b32_e32 v15, 3, v205
	v_ashrrev_i32_e32 v10, 1, v14
	v_lshlrev_b32_e32 v11, 6, v17
	v_and_or_b32 v10, v10, s33, v15
	v_and_or_b32 v207, v18, 48, v11
	v_ashrrev_i32_e32 v11, 31, v10
	v_lshl_add_u64 v[12:13], v[10:11], 3, s[14:15]
	flat_load_dwordx4 v[82:85], v[12:13]
	flat_load_dwordx4 v[74:77], v[12:13] offset:16
	flat_load_dwordx4 v[70:73], v[12:13] offset:32
	flat_load_dwordx4 v[66:69], v[12:13] offset:48
	v_or_b32_e32 v10, 16, v10
	v_ashrrev_i32_e32 v11, 31, v10
	v_lshl_add_u64 v[10:11], v[10:11], 3, s[14:15]
	flat_load_dwordx4 v[62:65], v[10:11]
	flat_load_dwordx4 v[58:61], v[10:11] offset:16
	flat_load_dwordx4 v[46:49], v[10:11] offset:32
	flat_load_dwordx4 v[42:45], v[10:11] offset:48
	v_lshlrev_b32_e32 v10, 5, v14
	v_and_or_b32 v10, v10, s34, v15
	v_lshlrev_b32_e32 v10, 3, v10
	v_mov_b32_e32 v11, v131
	v_lshl_add_u64 v[10:11], s[14:15], 0, v[10:11]
	flat_load_dwordx4 v[38:41], v[10:11]
	flat_load_dwordx4 v[34:37], v[10:11] offset:16
	flat_load_dwordx4 v[30:33], v[10:11] offset:32
	flat_load_dwordx4 v[26:29], v[10:11] offset:48
	flat_load_dwordx4 v[22:25], v[10:11] offset:128
	flat_load_dwordx4 v[18:21], v[10:11] offset:144
	flat_load_dwordx4 v[14:17], v[10:11] offset:160
	s_nop 0
	flat_load_dwordx4 v[10:13], v[10:11] offset:176
	s_waitcnt vmcnt(0)
	s_mov_b32 s84, 4
	v_and_b32_e32 v135, 63, v209
	s_mov_b32 s52, 0
	s_waitcnt vmcnt(0) lgkmcnt(0)
; __device__ __forceinline__ void attn_unit8(const bf16_t* __restrict__ Qb, const unsigned char* __restrict__ K8h, const unsigned char* __restrict__ VT8h, unsigned char* __restrict__ Ob, int seq, ATT_LAS char* lds, ...
;     ...
;     float x[8][8]; float ss = 0.f;
; #pragma unroll
;     for (int d0 = 0; d0 < 8; ++d0)
; #pragma unroll
;       for (int e = 0; e < 8; ++e) { x[d0][e] = __uint_as_float((unsigned)(unsigned short)qr[d0][e] << 16); ss += x[d0][e] * x[d0][e]; }
;     { auto rr = __builtin_amdgcn_permlane32_swap(__float_as_uint(ss), __float_as_uint(ss), false, false); ss = __uint_as_float(rr[0]) + __uint_as_float(rr[1]); }
	v_lshlrev_b32_e32 v177, 16, v178
	v_lshlrev_b32_e32 v139, 16, v154
	v_mov_b32_e32 v136, v146
	v_lshlrev_b32_e32 v126, 16, v159
	v_lshlrev_b32_e32 v229, 16, v110
	v_mov_b32_e32 v137, v52
	v_and_b32_e32 v128, 0xffff0000, v159
	v_mov_b32_e32 v52, v147
	v_lshlrev_b32_e32 v138, 16, v158
	v_mov_b32_e32 v142, v144
	v_mov_b32_e32 v143, v50
	v_and_b32_e32 v141, 0xffff0000, v154
	v_and_b32_e32 v140, 0xffff0000, v158
	v_mov_b32_e32 v50, v145
	v_lshlrev_b32_e32 v145, 16, v153
	v_lshlrev_b32_e32 v144, 16, v157
	v_and_b32_e32 v147, 0xffff0000, v153
	v_and_b32_e32 v146, 0xffff0000, v157
	v_lshlrev_b32_e32 v151, 16, v152
	v_lshlrev_b32_e32 v150, 16, v156
	v_mov_b32_e32 v154, v160
	v_and_b32_e32 v153, 0xffff0000, v152
	v_and_b32_e32 v152, 0xffff0000, v156
	v_lshlrev_b32_e32 v157, 16, v181
	v_lshlrev_b32_e32 v156, 16, v185
	v_mov_b32_e32 v160, v170
	v_and_b32_e32 v159, 0xffff0000, v181
	v_and_b32_e32 v158, 0xffff0000, v185
	v_mov_b32_e32 v166, v168
	v_lshlrev_b32_e32 v168, 16, v183
	v_mov_b32_e32 v173, v88
	v_and_b32_e32 v170, 0xffff0000, v183
	v_mov_b32_e32 v88, v189
	v_mov_b32_e32 v181, v86
	v_mov_b32_e32 v86, v187
	v_lshlrev_b32_e32 v183, 16, v213
	v_mov_b32_e32 v187, v92
	v_and_b32_e32 v185, 0xffff0000, v213
	v_mov_b32_e32 v92, v197
	v_lshlrev_b32_e32 v189, 16, v212
	v_mov_b32_e32 v193, v90
	v_and_b32_e32 v191, 0xffff0000, v212
	v_mov_b32_e32 v90, v195
	v_lshlrev_b32_e32 v195, 16, v211
	v_mov_b32_e32 v198, v224
	v_and_b32_e32 v197, 0xffff0000, v211
	v_lshlrev_b32_e32 v213, 16, v210
	v_lshlrev_b32_e32 v212, 16, v214
	v_and_b32_e32 v211, 0xffff0000, v210
	v_and_b32_e32 v210, 0xffff0000, v214
	v_lshlrev_b32_e32 v214, 16, v117
	v_and_b32_e32 v224, 0xffff0000, v117
	v_mov_b32_e32 v227, v98
	v_mov_b32_e32 v98, v219
	v_lshlrev_b32_e32 v117, 16, v111
	v_and_b32_e32 v219, 0xffff0000, v111
	v_lshlrev_b32_e32 v228, 16, v114
	v_and_b32_e32 v111, 0xffff0000, v110
	v_and_b32_e32 v110, 0xffff0000, v114
	v_mul_f32_e32 v114, v229, v229
	v_fmac_f32_e32 v114, v111, v111
	v_fmac_f32_e32 v114, v117, v117
	v_lshlrev_b32_e32 v127, 16, v155
	v_and_b32_e32 v129, 0xffff0000, v155
	v_mov_b32_e32 v148, v162
	v_mov_b32_e32 v155, v54
	v_mov_b32_e32 v54, v161
	v_mov_b32_e32 v161, v80
	v_mov_b32_e32 v80, v171
	v_lshlrev_b32_e32 v162, 16, v184
	v_mov_b32_e32 v167, v78
	v_and_b32_e32 v164, 0xffff0000, v184
	v_mov_b32_e32 v78, v169
	v_lshlrev_b32_e32 v169, 16, v179
	v_and_b32_e32 v171, 0xffff0000, v179
	v_lshlrev_b32_e32 v176, 16, v182
	v_and_b32_e32 v179, 0xffff0000, v178
	v_and_b32_e32 v178, 0xffff0000, v182
	v_lshlrev_b32_e32 v182, 16, v217
	v_and_b32_e32 v184, 0xffff0000, v217
	v_mov_b32_e32 v217, v94
	v_mov_b32_e32 v94, v223
	v_mov_b32_e32 v223, v100
	v_mov_b32_e32 v100, v221
	v_lshlrev_b32_e32 v221, 16, v112
	v_fmac_f32_e32 v114, v219, v219
	v_mov_b32_e32 v149, v56
	v_mov_b32_e32 v56, v163
	v_lshlrev_b32_e32 v163, 16, v180
	v_and_b32_e32 v165, 0xffff0000, v180
	v_mov_b32_e32 v180, v186
	v_mov_b32_e32 v186, v196
	v_mov_b32_e32 v192, v194
	v_lshlrev_b32_e32 v194, 16, v215
	v_mov_b32_e32 v199, v96
	v_and_b32_e32 v196, 0xffff0000, v215
	v_mov_b32_e32 v96, v225
	v_lshlrev_b32_e32 v215, 16, v113
	v_and_b32_e32 v225, 0xffff0000, v113
	v_and_b32_e32 v113, 0xffff0000, v112
	v_fmac_f32_e32 v114, v221, v221
	v_fmac_f32_e32 v114, v113, v113
	v_fmac_f32_e32 v114, v215, v215
	v_fmac_f32_e32 v114, v225, v225
	v_fmac_f32_e32 v114, v213, v213
	v_fmac_f32_e32 v114, v211, v211
	v_fmac_f32_e32 v114, v195, v195
	v_fmac_f32_e32 v114, v197, v197
	v_fmac_f32_e32 v114, v189, v189
	v_fmac_f32_e32 v114, v191, v191
	v_fmac_f32_e32 v114, v183, v183
	v_fmac_f32_e32 v114, v185, v185
	v_mov_b32_e32 v172, v188
	v_lshlrev_b32_e32 v188, 16, v216
	v_and_b32_e32 v190, 0xffff0000, v216
	v_mov_b32_e32 v216, v222
	v_mov_b32_e32 v222, v220
	v_lshlrev_b32_e32 v220, 16, v116
	v_mov_b32_e32 v226, v218
	v_and_b32_e32 v112, 0xffff0000, v116
	v_lshlrev_b32_e32 v116, 16, v115
	v_and_b32_e32 v218, 0xffff0000, v115
	v_pk_fma_f32 v[114:115], v[228:229], v[228:229], v[114:115] op_sel_hi:[1,1,0]
	v_mul_f32_e32 v230, v177, v177
	v_pk_fma_f32 v[114:115], v[110:111], v[110:111], v[114:115]
	v_mov_b32_e32 v174, v128
	v_pk_fma_f32 v[114:115], v[116:117], v[116:117], v[114:115]
	v_mov_b32_e32 v175, v126
	v_pk_fma_f32 v[114:115], v[218:219], v[218:219], v[114:115]
	s_nop 0
	v_pk_fma_f32 v[114:115], v[220:221], v[220:221], v[114:115]
	s_nop 0
	v_pk_fma_f32 v[114:115], v[112:113], v[112:113], v[114:115]
	s_nop 0
	v_pk_fma_f32 v[114:115], v[214:215], v[214:215], v[114:115]
	s_nop 0
	v_pk_fma_f32 v[114:115], v[224:225], v[224:225], v[114:115]
	s_nop 0
	v_pk_fma_f32 v[114:115], v[212:213], v[212:213], v[114:115]
	s_nop 0
	v_pk_fma_f32 v[114:115], v[210:211], v[210:211], v[114:115]
	s_nop 0
	v_pk_fma_f32 v[114:115], v[194:195], v[194:195], v[114:115]
	s_nop 0
	v_pk_fma_f32 v[114:115], v[196:197], v[196:197], v[114:115]
	s_nop 0
	v_pk_fma_f32 v[114:115], v[188:189], v[188:189], v[114:115]
	s_nop 0
	v_pk_fma_f32 v[114:115], v[190:191], v[190:191], v[114:115]
	s_nop 0
	v_pk_fma_f32 v[114:115], v[182:183], v[182:183], v[114:115]
	s_nop 0
	v_pk_fma_f32 v[114:115], v[184:185], v[184:185], v[114:115]
	s_nop 0
	v_pk_add_f32 v[114:115], v[230:231], v[114:115] op_sel_hi:[0,1]
	v_mul_f32_e32 v230, v179, v179
	v_pk_add_f32 v[114:115], v[230:231], v[114:115] op_sel_hi:[0,1]
	v_mul_f32_e32 v230, v169, v169
	v_pk_add_f32 v[114:115], v[230:231], v[114:115] op_sel_hi:[0,1]
	v_mul_f32_e32 v230, v171, v171
	v_pk_add_f32 v[114:115], v[230:231], v[114:115] op_sel_hi:[0,1]
	v_mul_f32_e32 v230, v163, v163
	v_pk_add_f32 v[114:115], v[230:231], v[114:115] op_sel_hi:[0,1]
	v_mul_f32_e32 v230, v165, v165
	v_pk_add_f32 v[114:115], v[230:231], v[114:115] op_sel_hi:[0,1]
; __device__ __forceinline__ void attn_unit8(const bf16_t* __restrict__ Qb, const unsigned char* __restrict__ K8h, const unsigned char* __restrict__ VT8h, unsigned char* __restrict__ Ob, int seq, ATT_LAS char* lds, ...
;     ...
;       for (int e = 0; e < 8; ++e) { x[d0][e] = __uint_as_float((unsigned)(unsigned short)qr[d0][e] << 16); ss += x[d0][e] * x[d0][e]; }
;     { auto rr = __builtin_amdgcn_permlane32_swap(__float_as_uint(ss), __float_as_uint(ss), false, false); ss = __uint_as_float(rr[0]) + __uint_as_float(rr[1]); }
;     const float inv = 1.0f / sqrtf(ss * (1.0f / 128.0f) + 1e-6f);
; #pragma unroll
;     for (int d0 = 0; d0 < 8; ++d0) { const f32x4a g0 = *reinterpret_cast<const f32x4a*>(qg + d0 * 16 + hi * 8), g1 = *reinterpret_cast<const f32x4a*>(qg + d0 * 16 + hi * 8 + 4);
; #pragma unroll
;       for (int e = 0; e < 4; ++e) { x[d0][e] = x[d0][e] * inv * g0[e]; x[d0][4 + e] = x[d0][4 + e] * inv * g1[e]; } }
	v_mul_f32_e32 v230, v157, v157
	v_pk_add_f32 v[114:115], v[230:231], v[114:115] op_sel_hi:[0,1]
	v_mul_f32_e32 v230, v159, v159
	v_pk_add_f32 v[114:115], v[230:231], v[114:115] op_sel_hi:[0,1]
	v_mul_f32_e32 v230, v151, v151
	v_pk_add_f32 v[114:115], v[230:231], v[114:115] op_sel_hi:[0,1]
	v_mul_f32_e32 v230, v153, v153
	v_pk_add_f32 v[114:115], v[230:231], v[114:115] op_sel_hi:[0,1]
	v_mul_f32_e32 v230, v145, v145
	v_pk_add_f32 v[114:115], v[230:231], v[114:115] op_sel_hi:[0,1]
	v_mul_f32_e32 v230, v147, v147
	v_pk_add_f32 v[114:115], v[230:231], v[114:115] op_sel_hi:[0,1]
	v_mul_f32_e32 v230, v139, v139
	v_pk_add_f32 v[114:115], v[230:231], v[114:115] op_sel_hi:[0,1]
	v_mul_f32_e32 v230, v141, v141
	v_pk_add_f32 v[114:115], v[230:231], v[114:115] op_sel_hi:[0,1]
	v_mul_f32_e32 v230, v127, v127
	v_pk_add_f32 v[114:115], v[230:231], v[114:115] op_sel_hi:[0,1]
	v_mul_f32_e32 v230, v129, v129
	v_pk_add_f32 v[114:115], v[230:231], v[114:115] op_sel_hi:[0,1]
	v_pk_fma_f32 v[114:115], v[176:177], v[176:177], v[114:115]
	v_mul_f32_e32 v230, v126, v126
	v_pk_fma_f32 v[114:115], v[178:179], v[178:179], v[114:115]
	s_nop 0
	v_pk_fma_f32 v[114:115], v[168:169], v[168:169], v[114:115]
	s_nop 0
	v_pk_fma_f32 v[114:115], v[170:171], v[170:171], v[114:115]
	s_nop 0
	v_pk_fma_f32 v[114:115], v[162:163], v[162:163], v[114:115]
	s_nop 0
	v_pk_fma_f32 v[114:115], v[164:165], v[164:165], v[114:115]
	s_nop 0
	v_pk_fma_f32 v[114:115], v[156:157], v[156:157], v[114:115]
	s_nop 0
	v_pk_fma_f32 v[114:115], v[158:159], v[158:159], v[114:115]
	s_nop 0
	v_pk_fma_f32 v[114:115], v[150:151], v[150:151], v[114:115]
	s_nop 0
	v_pk_fma_f32 v[114:115], v[152:153], v[152:153], v[114:115]
	s_nop 0
	v_pk_fma_f32 v[114:115], v[144:145], v[144:145], v[114:115]
	s_nop 0
	v_pk_fma_f32 v[114:115], v[146:147], v[146:147], v[114:115]
	s_nop 0
	v_pk_fma_f32 v[114:115], v[138:139], v[138:139], v[114:115]
	s_nop 0
	v_pk_fma_f32 v[114:115], v[140:141], v[140:141], v[114:115]
	s_nop 0
	v_pk_add_f32 v[114:115], v[230:231], v[114:115] op_sel_hi:[0,1]
	v_pk_fma_f32 v[114:115], v[174:175], v[174:175], v[114:115]
	s_nop 0
	v_mov_b32_e32 v115, v114
	s_nop 1
	v_permlane32_swap_b32_e32 v114, v115
	v_add_f32_e32 v114, v114, v115
	v_fmamk_f32 v114, v114, 0x3c000000, v200
	v_mul_f32_e32 v115, 0x4f800000, v114
	v_cmp_gt_f32_e32 vcc, s35, v114
	s_nop 1
	v_cndmask_b32_e32 v174, v114, v115, vcc
	v_sqrt_f32_e32 v175, v174
	v_mov_b32_e32 v114, v108
	v_mov_b32_e32 v115, v104
	v_mov_b32_e32 v104, v109
	v_add_u32_e32 v108, -1, v175
	v_fma_f32 v109, -v108, v175, v174
	v_cmp_ge_f32_e64 s[6:7], 0, v109
	v_add_u32_e32 v109, 1, v175
	s_nop 0
	v_cndmask_b32_e64 v108, v175, v108, s[6:7]
	v_fma_f32 v175, -v109, v175, v174
	v_cmp_lt_f32_e64 s[6:7], 0, v175
	s_nop 1
	v_cndmask_b32_e64 v108, v108, v109, s[6:7]
	v_mul_f32_e32 v109, 0x37800000, v108
	v_cndmask_b32_e32 v108, v108, v109, vcc
	v_cmp_class_f32_e32 vcc, v174, v201
	v_mov_b32_e32 v109, v102
	s_nop 0
	v_cndmask_b32_e32 v174, v108, v174, vcc
	v_div_scale_f32 v175, s[6:7], v174, v174, 1.0
	v_rcp_f32_e32 v230, v175
	v_mov_b32_e32 v108, v106
	v_fma_f32 v102, -v175, v230, 1.0
	v_fmac_f32_e32 v230, v102, v230
	v_div_scale_f32 v102, vcc, 1.0, v174, 1.0
	v_mul_f32_e32 v106, v102, v230
	v_fma_f32 v231, -v175, v106, v102
	v_fmac_f32_e32 v106, v231, v230
	v_fma_f32 v102, -v175, v106, v102
	v_div_fmas_f32 v102, v102, v230, v106
	v_div_fixup_f32 v106, v102, v174, 1.0
	v_pk_mul_f32 v[110:111], v[106:107], v[110:111] op_sel_hi:[0,1]
	v_mov_b32_e32 v102, v107
	v_pk_mul_f32 v[102:103], v[102:103], v[110:111]
	v_pk_mul_f32 v[110:111], v[106:107], v[112:113] op_sel_hi:[0,1]
	v_pk_mul_f32 v[98:99], v[98:99], v[110:111]
	v_pk_mul_f32 v[110:111], v[106:107], v[116:117] op_sel_hi:[0,1]
	v_pk_mul_f32 v[110:111], v[114:115], v[110:111]
	v_pk_mul_f32 v[114:115], v[106:107], v[218:219] op_sel_hi:[0,1]
	v_pk_mul_f32 v[116:117], v[106:107], v[188:189] op_sel_hi:[0,1]
	v_pk_mul_f32 v[188:189], v[106:107], v[210:211] op_sel_hi:[0,1]
	v_pk_mul_f32 v[174:175], v[106:107], v[228:229] op_sel_hi:[0,1]
	v_pk_mul_f32 v[104:105], v[104:105], v[114:115]
	v_pk_mul_f32 v[114:115], v[106:107], v[224:225] op_sel_hi:[0,1]
	v_pk_mul_f32 v[94:95], v[94:95], v[188:189]
	v_pk_mul_f32 v[188:189], v[106:107], v[190:191] op_sel_hi:[0,1]
	v_pk_mul_f32 v[182:183], v[106:107], v[182:183] op_sel_hi:[0,1]
	v_pk_mul_f32 v[162:163], v[106:107], v[162:163] op_sel_hi:[0,1]
	v_pk_mul_f32 v[164:165], v[106:107], v[164:165] op_sel_hi:[0,1]
	v_pk_mul_f32 v[156:157], v[106:107], v[156:157] op_sel_hi:[0,1]
	v_pk_mul_f32 v[138:139], v[106:107], v[138:139] op_sel_hi:[0,1]
	v_pk_mul_f32 v[140:141], v[106:107], v[140:141] op_sel_hi:[0,1]
	v_pk_mul_f32 v[126:127], v[106:107], v[126:127] op_sel_hi:[0,1]
	v_pk_mul_f32 v[108:109], v[108:109], v[174:175]
	v_pk_mul_f32 v[174:175], v[106:107], v[220:221] op_sel_hi:[0,1]
	v_pk_mul_f32 v[112:113], v[106:107], v[214:215] op_sel_hi:[0,1]
	v_pk_mul_f32 v[100:101], v[100:101], v[114:115]
	v_pk_mul_f32 v[114:115], v[106:107], v[212:213] op_sel_hi:[0,1]
	v_pk_mul_f32 v[90:91], v[90:91], v[188:189]
	v_pk_mul_f32 v[188:189], v[106:107], v[194:195] op_sel_hi:[0,1]
	v_pk_mul_f32 v[182:183], v[186:187], v[182:183]
	v_pk_mul_f32 v[186:187], v[106:107], v[196:197] op_sel_hi:[0,1]
	v_pk_mul_f32 v[184:185], v[106:107], v[184:185] op_sel_hi:[0,1]
	v_pk_mul_f32 v[176:177], v[106:107], v[176:177] op_sel_hi:[0,1]
	v_pk_mul_f32 v[162:163], v[162:163], v[166:167]
	v_pk_mul_f32 v[166:167], v[106:107], v[178:179] op_sel_hi:[0,1]
	v_pk_mul_f32 v[78:79], v[164:165], v[78:79]
	v_pk_mul_f32 v[164:165], v[106:107], v[168:169] op_sel_hi:[0,1]
	v_pk_mul_f32 v[156:157], v[156:157], v[160:161]
; __device__ __forceinline__ void attn_unit8(const bf16_t* __restrict__ Qb, const unsigned char* __restrict__ K8h, const unsigned char* __restrict__ VT8h, unsigned char* __restrict__ Ob, int seq, ATT_LAS char* lds, ...
;     ...
;     const int tq = tpos0 + wid * QBLK + r32;
; #pragma unroll
;     for (int ax = 0; ax < 2; ++ax) { const int pos = ax == 0 ? (tq >> 6) : (tq & 63);
; #pragma unroll
;       for (int h = 0; h < 2; ++h) { const f32x4a* tp = reinterpret_cast<const f32x4a*>(tab + (size_t)(pos * 32 + h * 16 + hi * 8) * 2);
; #pragma unroll
;         for (int e2 = 0; e2 < 4; ++e2) { const f32x4a cs = tp[e2];
; #pragma unroll
;           for (int k = 0; k < 2; ++k) { const int e = 2 * e2 + k; const float c = cs[2 * k], s = cs[2 * k + 1]; const float u0 = x[ax * 4 + h][e], u1 = x[ax * 4 + 2 + h][e];
;             x[ax * 4 + h][e] = u0 * c - u1 * s; x[ax * 4 + 2 + h][e] = u1 * c + u0 * s; } } } }
	v_pk_mul_f32 v[160:161], v[106:107], v[170:171] op_sel_hi:[0,1]
	v_pk_mul_f32 v[158:159], v[106:107], v[158:159] op_sel_hi:[0,1]
	v_pk_mul_f32 v[150:151], v[106:107], v[150:151] op_sel_hi:[0,1]
	v_pk_mul_f32 v[138:139], v[138:139], v[142:143]
	v_pk_mul_f32 v[142:143], v[106:107], v[152:153] op_sel_hi:[0,1]
	v_pk_mul_f32 v[50:51], v[140:141], v[50:51]
	v_pk_mul_f32 v[140:141], v[106:107], v[144:145] op_sel_hi:[0,1]
	v_pk_mul_f32 v[126:127], v[126:127], v[136:137]
	v_pk_mul_f32 v[136:137], v[106:107], v[146:147] op_sel_hi:[0,1]
	v_pk_mul_f32 v[106:107], v[106:107], v[128:129] op_sel_hi:[0,1]
	v_pk_mul_f32 v[52:53], v[106:107], v[52:53]
	v_pk_mul_f32 v[106:107], v[108:109], v[82:83] op_sel:[1,0] op_sel_hi:[0,1]
	v_pk_mul_f32 v[82:83], v[108:109], v[82:83]
	v_sub_f32_e32 v106, v106, v107
	v_add_f32_e32 v107, v83, v82
	v_pk_mul_f32 v[82:83], v[102:103], v[84:85] op_sel:[1,0] op_sel_hi:[0,1]
	v_sub_f32_e32 v108, v82, v83
	v_pk_mul_f32 v[82:83], v[102:103], v[84:85]
	v_pk_mul_f32 v[174:175], v[226:227], v[174:175]
	v_add_f32_e32 v84, v83, v82
	v_pk_mul_f32 v[82:83], v[110:111], v[74:75] op_sel:[1,0] op_sel_hi:[0,1]
	v_pk_mul_f32 v[74:75], v[110:111], v[74:75]
	v_sub_f32_e32 v82, v82, v83
	v_add_f32_e32 v83, v75, v74
	v_pk_mul_f32 v[74:75], v[104:105], v[76:77] op_sel:[1,0] op_sel_hi:[0,1]
	v_sub_f32_e32 v85, v74, v75
	v_pk_mul_f32 v[74:75], v[104:105], v[76:77]
	v_pk_mul_f32 v[112:113], v[222:223], v[112:113]
	v_add_f32_e32 v76, v75, v74
	v_pk_mul_f32 v[74:75], v[174:175], v[70:71] op_sel:[1,0] op_sel_hi:[0,1]
	v_pk_mul_f32 v[70:71], v[174:175], v[70:71]
	v_sub_f32_e32 v74, v74, v75
	v_add_f32_e32 v75, v71, v70
	v_pk_mul_f32 v[70:71], v[98:99], v[72:73] op_sel:[1,0] op_sel_hi:[0,1]
	v_sub_f32_e32 v77, v70, v71
	v_pk_mul_f32 v[70:71], v[98:99], v[72:73]
	v_pk_mul_f32 v[114:115], v[216:217], v[114:115]
	v_add_f32_e32 v72, v71, v70
	v_pk_mul_f32 v[70:71], v[112:113], v[66:67] op_sel:[1,0] op_sel_hi:[0,1]
	v_pk_mul_f32 v[66:67], v[112:113], v[66:67]
	v_sub_f32_e32 v70, v70, v71
	v_add_f32_e32 v71, v67, v66
	v_pk_mul_f32 v[66:67], v[100:101], v[68:69] op_sel:[1,0] op_sel_hi:[0,1]
	v_sub_f32_e32 v73, v66, v67
	v_pk_mul_f32 v[66:67], v[100:101], v[68:69]
	v_pk_mul_f32 v[188:189], v[198:199], v[188:189]
	v_add_f32_e32 v68, v67, v66
	v_pk_mul_f32 v[66:67], v[114:115], v[62:63] op_sel:[1,0] op_sel_hi:[0,1]
	v_pk_mul_f32 v[62:63], v[114:115], v[62:63]
	v_sub_f32_e32 v66, v66, v67
	v_add_f32_e32 v67, v63, v62
	v_pk_mul_f32 v[62:63], v[94:95], v[64:65] op_sel:[1,0] op_sel_hi:[0,1]
	v_sub_f32_e32 v69, v62, v63
	v_pk_mul_f32 v[62:63], v[94:95], v[64:65]
	v_pk_mul_f32 v[96:97], v[96:97], v[186:187]
	v_add_f32_e32 v64, v63, v62
	v_pk_mul_f32 v[62:63], v[188:189], v[58:59] op_sel:[1,0] op_sel_hi:[0,1]
	v_pk_mul_f32 v[58:59], v[188:189], v[58:59]
	v_sub_f32_e32 v62, v62, v63
	v_add_f32_e32 v63, v59, v58
	v_pk_mul_f32 v[58:59], v[96:97], v[60:61] op_sel:[1,0] op_sel_hi:[0,1]
	v_pk_mul_f32 v[116:117], v[192:193], v[116:117]
	v_sub_f32_e32 v65, v58, v59
	v_pk_mul_f32 v[58:59], v[96:97], v[60:61]
	v_pk_mul_f32 v[92:93], v[92:93], v[184:185]
	v_add_f32_e32 v60, v59, v58
	v_pk_mul_f32 v[58:59], v[116:117], v[46:47] op_sel:[1,0] op_sel_hi:[0,1]
	v_pk_mul_f32 v[46:47], v[116:117], v[46:47]
	v_sub_f32_e32 v58, v58, v59
	v_add_f32_e32 v59, v47, v46
	v_pk_mul_f32 v[46:47], v[90:91], v[48:49] op_sel:[1,0] op_sel_hi:[0,1]
	v_sub_f32_e32 v61, v46, v47
	v_pk_mul_f32 v[46:47], v[90:91], v[48:49]
	v_pk_mul_f32 v[176:177], v[176:177], v[180:181]
	v_add_f32_e32 v48, v47, v46
	v_pk_mul_f32 v[46:47], v[182:183], v[42:43] op_sel:[1,0] op_sel_hi:[0,1]
	v_pk_mul_f32 v[42:43], v[182:183], v[42:43]
	v_sub_f32_e32 v46, v46, v47
	v_add_f32_e32 v47, v43, v42
	v_pk_mul_f32 v[42:43], v[92:93], v[44:45] op_sel:[1,0] op_sel_hi:[0,1]
	v_sub_f32_e32 v49, v42, v43
	v_pk_mul_f32 v[42:43], v[92:93], v[44:45]
	v_pk_mul_f32 v[86:87], v[166:167], v[86:87]
	v_add_f32_e32 v44, v43, v42
	v_pk_mul_f32 v[42:43], v[176:177], v[38:39] op_sel:[1,0] op_sel_hi:[0,1]
	v_pk_mul_f32 v[38:39], v[176:177], v[38:39]
	v_sub_f32_e32 v42, v42, v43
	v_add_f32_e32 v43, v39, v38
	v_pk_mul_f32 v[38:39], v[86:87], v[40:41] op_sel:[1,0] op_sel_hi:[0,1]
	v_pk_mul_f32 v[164:165], v[164:165], v[172:173]
	v_sub_f32_e32 v45, v38, v39
	v_pk_mul_f32 v[38:39], v[86:87], v[40:41]
	v_pk_mul_f32 v[88:89], v[160:161], v[88:89]
	v_add_f32_e32 v40, v39, v38
	v_pk_mul_f32 v[38:39], v[164:165], v[34:35] op_sel:[1,0] op_sel_hi:[0,1]
	v_pk_mul_f32 v[34:35], v[164:165], v[34:35]
	v_sub_f32_e32 v38, v38, v39
	v_add_f32_e32 v39, v35, v34
	v_pk_mul_f32 v[34:35], v[88:89], v[36:37] op_sel:[1,0] op_sel_hi:[0,1]
	v_sub_f32_e32 v41, v34, v35
	v_pk_mul_f32 v[34:35], v[88:89], v[36:37]
	v_pk_mul_f32 v[80:81], v[158:159], v[80:81]
	v_add_f32_e32 v36, v35, v34
	v_pk_mul_f32 v[34:35], v[162:163], v[30:31] op_sel:[1,0] op_sel_hi:[0,1]
	v_pk_mul_f32 v[30:31], v[162:163], v[30:31]
	v_sub_f32_e32 v34, v34, v35
	v_add_f32_e32 v35, v31, v30
	v_pk_mul_f32 v[30:31], v[78:79], v[32:33] op_sel:[1,0] op_sel_hi:[0,1]
	v_sub_f32_e32 v37, v30, v31
	v_pk_mul_f32 v[30:31], v[78:79], v[32:33]
	v_pk_mul_f32 v[150:151], v[150:151], v[154:155]
	v_add_f32_e32 v32, v31, v30
	v_pk_mul_f32 v[30:31], v[156:157], v[26:27] op_sel:[1,0] op_sel_hi:[0,1]
	v_pk_mul_f32 v[26:27], v[156:157], v[26:27]
	v_sub_f32_e32 v30, v30, v31
	v_add_f32_e32 v31, v27, v26
	v_pk_mul_f32 v[26:27], v[80:81], v[28:29] op_sel:[1,0] op_sel_hi:[0,1]
	v_sub_f32_e32 v33, v26, v27
	v_pk_mul_f32 v[26:27], v[80:81], v[28:29]
	v_pk_mul_f32 v[54:55], v[142:143], v[54:55]
	v_add_f32_e32 v28, v27, v26
	v_pk_mul_f32 v[26:27], v[150:151], v[22:23] op_sel:[1,0] op_sel_hi:[0,1]
	v_pk_mul_f32 v[22:23], v[150:151], v[22:23]
; #define ATT_LAS __attribute__((address_space(3)))
; template <bool WAITSTATES>
; __device__ __forceinline__ void qkt8(f32x16& p0, f32x16& p1, const ATT_LAS char* Ks, const i32x8a (&q8)[2], int r32, int hi, int one) {
;   p0 = f32x16{}; p1 = f32x16{};
;   const i32x8a k00 = ld32(Ks + k8_off(r32, 2 * hi), Ks + k8_off(r32, 2 * hi + 1)), k10 = ld32(Ks + k8_off(32 + r32, 2 * hi), Ks + k8_off(32 + r32, 2 * hi + 1));
;   const i32x8a k01 = ld32(Ks + k8_off(r32, 4 + 2 * hi), Ks + k8_off(r32, 5 + 2 * hi)), k11 = ld32(Ks + k8_off(32 + r32, 4 + 2 * hi), Ks + k8_off(32 + r32, 5 + 2 * hi));
;   asm volatile("s_nop 1" ::: "memory");
;   __builtin_amdgcn_s_setprio(1); MFMA8(p0, k00, q8[0], one); MFMA8(p1, k10, q8[0], one); MFMA8(p0, k01, q8[1], one); MFMA8(p1, k11, q8[1], one); __builtin_amdgcn_s_setprio(0);
; __device__ __forceinline__ void attn_unit8(const bf16_t* __restrict__ Qb, const unsigned char* __restrict__ K8h, const unsigned char* __restrict__ VT8h, unsigned char* __restrict__ Ob, int seq, ATT_LAS char* lds, ...
;     ...
;           for (int k = 0; k < 2; ++k) { const int e = 2 * e2 + k; const float c = cs[2 * k], s = cs[2 * k + 1]; const float u0 = x[ax * 4 + h][e], u1 = x[ax * 4 + 2 + h][e];
;             x[ax * 4 + h][e] = u0 * c - u1 * s; x[ax * 4 + 2 + h][e] = u1 * c + u0 * s; } } } }
; #pragma unroll
;     for (int s = 0; s < 2; ++s)
;       q8[s] = (i32x8a){(int)pk4f8(x[4 * s][0], x[4 * s][1], x[4 * s][2], x[4 * s][3]), (int)pk4f8(x[4 * s][4], x[4 * s][5], x[4 * s][6], x[4 * s][7]),
;                        (int)pk4f8(x[4 * s + 1][0], x[4 * s + 1][1], x[4 * s + 1][2], x[4 * s + 1][3]), (int)pk4f8(x[4 * s + 1][4], x[4 * s + 1][5], x[4 * s + 1][6], x[4 * s + 1][7]),
;                        (int)pk4f8(x[4 * s + 2][0], x[4 * s + 2][1], x[4 * s + 2][2], x[4 * s + 2][3]), (int)pk4f8(x[4 * s + 2][4], x[4 * s + 2][5], x[4 * s + 2][6], x[4 * s + 2][7]),
;                        (int)pk4f8(x[4 * s + 3][0], x[4 * s + 3][1], x[4 * s + 3][2], x[4 * s + 3][3]), (int)pk4f8(x[4 * s + 3][4], x[4 * s + 3][5], x[4 * s + 3][6], x[4 * s + 3][7])};
;   }
;   f32x16 pA0, pA1, pB0, pB1; float mnA, mnB, alA, alB; i32x8a pa;
;   asm volatile("s_waitcnt vmcnt(0)" ::: "memory"); SWRITE8(0, 0); __syncthreads();
;   qkt8<true>(pA0, pA1, K_lds, q8, r32, hi, one); partialSM8(pA0, pA1, m_reg, mnA, alA);
	v_sub_f32_e32 v26, v26, v27
	v_add_f32_e32 v27, v23, v22
	v_pk_mul_f32 v[22:23], v[54:55], v[24:25] op_sel:[1,0] op_sel_hi:[0,1]
	v_pk_mul_f32 v[140:141], v[140:141], v[148:149]
	v_sub_f32_e32 v29, v22, v23
	v_pk_mul_f32 v[22:23], v[54:55], v[24:25]
	v_pk_mul_f32 v[56:57], v[136:137], v[56:57]
	v_add_f32_e32 v24, v23, v22
	v_pk_mul_f32 v[22:23], v[140:141], v[18:19] op_sel:[1,0] op_sel_hi:[0,1]
	v_pk_mul_f32 v[18:19], v[140:141], v[18:19]
	v_sub_f32_e32 v22, v22, v23
	v_add_f32_e32 v23, v19, v18
	v_pk_mul_f32 v[18:19], v[56:57], v[20:21] op_sel:[1,0] op_sel_hi:[0,1]
	v_sub_f32_e32 v25, v18, v19
	v_pk_mul_f32 v[18:19], v[56:57], v[20:21]
	v_mov_b32_e32 v113, v131
	v_add_f32_e32 v20, v19, v18
	v_pk_mul_f32 v[18:19], v[138:139], v[14:15] op_sel:[1,0] op_sel_hi:[0,1]
	v_pk_mul_f32 v[14:15], v[138:139], v[14:15]
	v_sub_f32_e32 v18, v18, v19
	v_add_f32_e32 v19, v15, v14
	v_pk_mul_f32 v[14:15], v[50:51], v[16:17] op_sel:[1,0] op_sel_hi:[0,1]
	v_sub_f32_e32 v21, v14, v15
	v_pk_mul_f32 v[14:15], v[50:51], v[16:17]
	v_mov_b32_e32 v99, v131
	v_add_f32_e32 v16, v15, v14
	v_pk_mul_f32 v[14:15], v[126:127], v[10:11] op_sel:[1,0] op_sel_hi:[0,1]
	v_pk_mul_f32 v[10:11], v[126:127], v[10:11]
	v_cvt_pk_fp8_f32 v113, v19, v16
	v_sub_f32_e32 v14, v14, v15
	v_add_f32_e32 v15, v11, v10
	v_pk_mul_f32 v[10:11], v[52:53], v[12:13] op_sel:[1,0] op_sel_hi:[0,1]
	v_sub_f32_e32 v17, v10, v11
	v_pk_mul_f32 v[10:11], v[52:53], v[12:13]
	v_add_u32_e32 v157, 0, v208
	v_add_u32_e32 v158, 0, v207
	v_add_f32_e32 v10, v11, v10
	v_cvt_pk_fp8_f32 v99, v74, v77
	ds_write_b128 v157, v[6:9] offset:24576
	ds_write_b128 v158, v[2:5]
	v_lshlrev_b32_e32 v74, 1, v205
	v_lshrrev_b32_e32 v2, 1, v209
	v_cvt_pk_fp8_f32 v113, v15, v10 op_sel:[0,0,1]
	v_bfe_u32 v10, v209, 1, 3
	v_bitop3_b32 v2, v74, v2, 7 bitop3:0x78
	v_lshlrev_b32_e32 v159, 4, v2
	v_bitop3_b32 v2, v74, v10, 1 bitop3:0x36
	v_mov_b32_e32 v100, v131
	v_mov_b32_e32 v103, v131
	v_mov_b32_e32 v104, v131
	v_lshlrev_b32_e32 v154, 7, v203
	v_lshlrev_b32_e32 v160, 4, v2
	v_cvt_pk_fp8_f32 v100, v66, v69
	v_cvt_pk_fp8_f32 v103, v75, v72
	v_cvt_pk_fp8_f32 v104, v67, v64
	v_add3_u32 v6, 0, v159, v154
	v_add3_u32 v11, 0, v160, v154
	v_mov_b32_e32 v98, v131
	v_mov_b32_e32 v102, v131
	s_waitcnt lgkmcnt(0)
	s_barrier
	ds_read_b128 v[2:5], v6 offset:24576
	ds_read_b128 v[50:53], v6 offset:28672
	ds_read_b128 v[6:9], v11 offset:24576
	ds_read_b128 v[54:57], v11 offset:28672
	v_bitop3_b32 v11, v74, v10, 4 bitop3:0x36
	v_cvt_pk_fp8_f32 v98, v106, v108
	v_mov_b32_e32 v101, v131
	v_cvt_pk_fp8_f32 v102, v107, v84
	v_mov_b32_e32 v105, v131
	v_mov_b32_e32 v106, v131
	v_mov_b32_e32 v107, v131
	v_mov_b32_e32 v108, v131
	v_mov_b32_e32 v109, v131
	v_mov_b32_e32 v110, v131
	v_mov_b32_e32 v111, v131
	v_mov_b32_e32 v112, v131
	v_lshlrev_b32_e32 v161, 4, v11
	v_bitop3_b32 v10, v74, v10, 5 bitop3:0x36
	v_cvt_pk_fp8_f32 v101, v58, v61
	v_cvt_pk_fp8_f32 v105, v59, v48
	v_cvt_pk_fp8_f32 v106, v42, v45
	v_cvt_pk_fp8_f32 v107, v34, v37
	v_cvt_pk_fp8_f32 v108, v26, v29
	v_cvt_pk_fp8_f32 v109, v18, v21
	v_cvt_pk_fp8_f32 v110, v43, v40
	v_cvt_pk_fp8_f32 v111, v35, v32
	v_cvt_pk_fp8_f32 v112, v27, v24
	v_add3_u32 v11, 0, v161, v154
	v_lshlrev_b32_e32 v162, 4, v10
	v_cvt_pk_fp8_f32 v99, v70, v73 op_sel:[0,0,1]
	v_cvt_pk_fp8_f32 v100, v62, v65 op_sel:[0,0,1]
	v_cvt_pk_fp8_f32 v103, v71, v68 op_sel:[0,0,1]
	v_cvt_pk_fp8_f32 v104, v63, v60 op_sel:[0,0,1]
	v_add3_u32 v10, 0, v162, v154
	ds_read_b128 v[58:61], v11 offset:24576
	ds_read_b128 v[66:69], v11 offset:28672
	ds_read_b128 v[62:65], v10 offset:24576
	ds_read_b128 v[70:73], v10 offset:28672
	v_cvt_pk_fp8_f32 v98, v82, v85 op_sel:[0,0,1]
	v_cvt_pk_fp8_f32 v101, v46, v49 op_sel:[0,0,1]
	v_cvt_pk_fp8_f32 v102, v83, v76 op_sel:[0,0,1]
	v_cvt_pk_fp8_f32 v105, v47, v44 op_sel:[0,0,1]
	v_cvt_pk_fp8_f32 v106, v38, v41 op_sel:[0,0,1]
	v_cvt_pk_fp8_f32 v107, v30, v33 op_sel:[0,0,1]
	v_cvt_pk_fp8_f32 v108, v22, v25 op_sel:[0,0,1]
	v_cvt_pk_fp8_f32 v109, v14, v17 op_sel:[0,0,1]
	v_cvt_pk_fp8_f32 v110, v39, v36 op_sel:[0,0,1]
	v_cvt_pk_fp8_f32 v111, v31, v28 op_sel:[0,0,1]
	v_cvt_pk_fp8_f32 v112, v23, v20 op_sel:[0,0,1]
	s_nop 1
	s_mov_b32 s53, s52
	s_mov_b32 s54, s52
	s_mov_b32 s55, s52
	s_mov_b32 s56, s52
	s_mov_b32 s57, s52
	s_mov_b32 s58, s52
	s_mov_b32 s59, s52
	s_mov_b32 s60, s52
	s_mov_b32 s61, s52
	s_mov_b32 s62, s52
	s_mov_b32 s63, s52
	s_mov_b32 s64, s52
	s_mov_b32 s65, s52
	s_mov_b32 s66, s52
	s_mov_b32 s67, s52
	v_mov_b64_e32 v[34:35], s[52:53]
	v_mov_b64_e32 v[36:37], s[54:55]
	v_mov_b64_e32 v[38:39], s[56:57]
	v_mov_b64_e32 v[40:41], s[58:59]
	v_mov_b64_e32 v[42:43], s[60:61]
	v_mov_b64_e32 v[44:45], s[62:63]
	v_mov_b64_e32 v[46:47], s[64:65]
	v_mov_b64_e32 v[48:49], s[66:67]
	v_mov_b64_e32 v[18:19], v[34:35]
	v_mov_b64_e32 v[20:21], v[36:37]
	v_mov_b64_e32 v[22:23], v[38:39]
	v_mov_b64_e32 v[24:25], v[40:41]
	v_mov_b64_e32 v[26:27], v[42:43]
	v_mov_b64_e32 v[28:29], v[44:45]
	v_mov_b64_e32 v[30:31], v[46:47]
	v_mov_b64_e32 v[32:33], v[48:49]
	s_waitcnt lgkmcnt(5)
	v_mfma_scale_f32_32x32x64_f8f6f4 v[18:33], v[2:9], v[98:105], v[18:33], v133, v133 op_sel_hi:[0,0,0]
	v_mov_b32_e32 v2, v131
	v_mov_b32_e32 v3, v131
	v_mov_b32_e32 v4, v131
	v_mov_b32_e32 v5, v131
	v_mov_b32_e32 v6, v131
	v_mov_b32_e32 v7, v131
	v_mov_b32_e32 v8, v131
	v_mov_b32_e32 v9, v131
	v_mov_b32_e32 v10, v131
	v_mov_b32_e32 v11, v131
	v_mov_b32_e32 v12, v131
	v_mov_b32_e32 v13, v131
	v_mov_b32_e32 v14, v131
	v_mov_b32_e32 v15, v131
	v_mov_b32_e32 v16, v131
	v_mov_b32_e32 v17, v131
	s_waitcnt lgkmcnt(4)
	v_mfma_scale_f32_32x32x64_f8f6f4 v[34:49], v[50:57], v[98:105], v[34:49], v133, v133 op_sel_hi:[0,0,0]
	s_waitcnt lgkmcnt(1)
; #define SLOAD8(i, t) do { sk[i] = *reinterpret_cast<const i32x4a*>(kg + (long)(t) * (64 * 512)); sv[i] = *reinterpret_cast<const i32x4a*>(vg + (long)(t) * VT_STRIDE); } while (0)
; #define SWRITE8(b, i) do { *reinterpret_cast<ATT_LAS i32x4a*>(K_lds + (b) * 8192 + kst) = sk[i]; *reinterpret_cast<ATT_LAS i32x4a*>(V_lds + (b) * 8192 + vst) = sv[i]; } while (0)
; #define SWAIT8() asm volatile("s_waitcnt vmcnt(2)" ::: "memory")
; __device__ __forceinline__ void partialSM8(f32x16& p0, f32x16& p1, float& m_reg, float& mn, float& alpha) {
;   constexpr float C = SCALE * 1.4426950408889634f;
;   float pmax = p0[0];
; #pragma unroll
;   for (int r = 1; r < 16; ++r) pmax = fmaxf(pmax, p0[r]);
; #pragma unroll
;   for (int r = 0; r < 16; ++r) pmax = fmaxf(pmax, p1[r]);
;   { auto rr = __builtin_amdgcn_permlane32_swap(__float_as_uint(pmax), __float_as_uint(pmax), false, false);
;     pmax = fmaxf(__uint_as_float(rr[0]), __uint_as_float(rr[1])); }
;   if (__builtin_expect(__all(pmax - m_reg <= THR8 / SCALE), 1)) { mn = m_reg; alpha = 1.f; }
;   else { mn = fmaxf(m_reg, pmax); alpha = __builtin_amdgcn_exp2f((m_reg - mn) * C); m_reg = mn; }
;   float mnC = -mn * C;
; #pragma unroll
;   for (int r = 0; r < 16; ++r) p0[r] = fmaf(p0[r], C, mnC);
; #pragma unroll
;   for (int r = 0; r < 16; ++r) p1[r] = fmaf(p1[r], C, mnC);
; #pragma unroll
;   for (int r = 0; r < 16; ++r) p0[r] = __builtin_amdgcn_exp2f(p0[r]);
; __device__ __forceinline__ void attn_unit8(const bf16_t* __restrict__ Qb, const unsigned char* __restrict__ K8h, const unsigned char* __restrict__ VT8h, unsigned char* __restrict__ Ob, int seq, ATT_LAS char* lds, ...
;     ...
;   qkt8<true>(pA0, pA1, K_lds, q8, r32, hi, one); partialSM8(pA0, pA1, m_reg, mnA, alA);
;   SLOAD8(1, 1); if (2 < NT) SLOAD8(0, 2);
;   SWAIT8(); SWRITE8(1, 1); __syncthreads();
;   int bK = 8192, bV = 0, bW = 2 * 8192;
	v_mfma_scale_f32_32x32x64_f8f6f4 v[18:33], v[58:65], v[106:113], v[18:33], v133, v133 op_sel_hi:[0,0,0]
	s_waitcnt lgkmcnt(0)
	v_mfma_scale_f32_32x32x64_f8f6f4 v[34:49], v[66:73], v[106:113], v[34:49], v133, v133 op_sel_hi:[0,0,0]
	v_add_co_u32_e32 v50, vcc, s70, v118
	s_nop 15
	s_nop 7
	v_max_f32_e32 v62, v19, v19
	s_nop 0
	v_addc_co_u32_e32 v51, vcc, 0, v119, vcc
	v_add_co_u32_e32 v54, vcc, s70, v120
	v_max_f32_e32 v63, v18, v18
	s_nop 0
	v_addc_co_u32_e32 v55, vcc, 0, v121, vcc
	v_add_co_u32_e32 v58, vcc, s71, v120
	flat_load_dwordx4 v[50:53], v[50:51]
	s_nop 0
	flat_load_dwordx4 v[54:57], v[54:55]
	v_addc_co_u32_e32 v59, vcc, 0, v121, vcc
	v_add_co_u32_e32 v60, vcc, s71, v118
	v_max_f32_e32 v62, v63, v62
	s_nop 0
	v_addc_co_u32_e32 v61, vcc, 0, v119, vcc
	flat_load_dwordx4 v[114:117], v[58:59]
	flat_load_dwordx4 v[118:121], v[60:61]
	v_max3_f32 v58, v62, v20, v21
	v_max3_f32 v58, v58, v22, v23
	v_max3_f32 v58, v58, v24, v25
	v_max3_f32 v58, v58, v26, v27
	v_max3_f32 v58, v58, v28, v29
	v_max3_f32 v58, v58, v30, v31
	v_max3_f32 v58, v58, v32, v33
	v_max3_f32 v58, v58, v34, v35
	v_max3_f32 v58, v58, v36, v37
	v_max3_f32 v58, v58, v38, v39
	v_max3_f32 v58, v58, v40, v41
	v_max3_f32 v58, v58, v42, v43
	v_max3_f32 v58, v58, v44, v45
	v_max3_f32 v58, v58, v46, v47
	v_max3_f32 v58, v58, v48, v49
	v_mov_b32_e32 v59, v58
	s_nop 1
	v_permlane32_swap_b32_e32 v58, v59
	v_max_f32_e32 v59, v59, v59
	v_max_f32_e32 v58, v58, v58
	v_max_f32_e32 v58, v58, v59
	v_add_f32_e32 v59, 0x7149f2ca, v58
	v_cmp_ge_f32_e32 vcc, s69, v59
	s_cmp_eq_u64 vcc, exec
	v_max_f32_e32 v58, 0xf149f2ca, v58
	s_cselect_b64 vcc, -1, 0
	v_cndmask_b32_e32 v167, v58, v202, vcc
	v_sub_f32_e32 v60, 0xf149f2ca, v58
	v_mul_f32_e32 v58, 0xbe0293ee, v167
	v_fmamk_f32 v18, v18, 0x3e0293ee, v58
	v_exp_f32_e32 v176, v18
	v_fmamk_f32 v18, v24, 0x3e0293ee, v58
	v_exp_f32_e32 v174, v18
	v_fmamk_f32 v18, v25, 0x3e0293ee, v58
	v_exp_f32_e32 v175, v18
	v_fmamk_f32 v18, v26, 0x3e0293ee, v58
	v_exp_f32_e32 v182, v18
	v_fmamk_f32 v18, v27, 0x3e0293ee, v58
	v_exp_f32_e32 v184, v18
	v_fmamk_f32 v18, v28, 0x3e0293ee, v58
	v_exp_f32_e32 v178, v18
	v_fmamk_f32 v18, v29, 0x3e0293ee, v58
	v_exp_f32_e32 v181, v18
	v_fmamk_f32 v18, v30, 0x3e0293ee, v58
	v_mul_f32_e32 v60, 0x3e0293ee, v60
	v_exp_f32_e32 v185, v18
	v_fmamk_f32 v18, v31, 0x3e0293ee, v58
	v_exp_f32_e32 v60, v60
	v_exp_f32_e32 v187, v18
	v_fmamk_f32 v18, v32, 0x3e0293ee, v58
	s_add_u32 s8, s25, s8
	v_pk_fma_f32 v[126:127], v[48:49], s[16:17], v[58:59] op_sel_hi:[1,0,0]
	v_pk_fma_f32 v[128:129], v[46:47], s[16:17], v[58:59] op_sel_hi:[1,0,0]
	v_pk_fma_f32 v[140:141], v[44:45], s[16:17], v[58:59] op_sel_hi:[1,0,0]
	v_pk_fma_f32 v[142:143], v[42:43], s[16:17], v[58:59] op_sel_hi:[1,0,0]
	v_pk_fma_f32 v[144:145], v[40:41], s[16:17], v[58:59] op_sel_hi:[1,0,0]
	v_pk_fma_f32 v[146:147], v[38:39], s[16:17], v[58:59] op_sel_hi:[1,0,0]
	v_pk_fma_f32 v[148:149], v[36:37], s[16:17], v[58:59] op_sel_hi:[1,0,0]
	v_pk_fma_f32 v[150:151], v[34:35], s[16:17], v[58:59] op_sel_hi:[1,0,0]
	v_fmamk_f32 v19, v19, 0x3e0293ee, v58
	v_fmamk_f32 v20, v20, 0x3e0293ee, v58
	v_fmamk_f32 v21, v21, 0x3e0293ee, v58
	v_fmamk_f32 v22, v22, 0x3e0293ee, v58
	v_fmamk_f32 v23, v23, 0x3e0293ee, v58
	v_exp_f32_e32 v183, v18
	v_fmac_f32_e32 v58, 0x3e0293ee, v33
	v_lshrrev_b32_e32 v18, 2, v209
	s_addc_u32 s9, 0, s9
	v_exp_f32_e32 v179, v19
	v_exp_f32_e32 v172, v20
	v_exp_f32_e32 v173, v21
	v_exp_f32_e32 v177, v22
	v_exp_f32_e32 v180, v23
	v_exp_f32_e32 v186, v58
	v_bfe_u32 v19, v209, 2, 2
	v_bitop3_b32 v18, v74, v18, 3 bitop3:0x78
	v_lshl_add_u64 v[136:137], s[8:9], 0, v[124:125]
	s_add_i32 s8, s26, s24
	s_waitcnt vmcnt(2)
	v_lshlrev_b32_e32 v164, 4, v18
	v_bitop3_b32 v18, v74, v19, 1 bitop3:0x36
	s_ashr_i32 s9, s8, 31
	v_cndmask_b32_e64 v166, v60, 1.0, vcc
	s_waitcnt vmcnt(0) lgkmcnt(0)
	ds_write_b128 v157, v[50:53] offset:32768
	ds_write_b128 v158, v[54:57] offset:8192
	v_lshlrev_b32_e32 v165, 4, v18
	s_lshl_b64 s[8:9], s[8:9], 13
	v_mov_b64_e32 v[64:65], v[16:17]
	v_mov_b64_e32 v[48:49], v[16:17]
	v_mov_b64_e32 v[32:33], v[16:17]
	v_lshlrev_b32_e32 v163, 6, v203
	v_cmp_gt_u32_e64 s[6:7], 32, v135
	v_lshl_add_u32 v152, v203, 2, v206
	v_or_b32_e32 v136, v136, v130
	v_lshl_add_u64 v[138:139], s[8:9], 0, v[122:123]
	v_mov_b32_e32 v153, 0
	s_movk_i32 s53, 0x2000
	s_movk_i32 s8, 0x4000
	v_mov_b64_e32 v[62:63], v[14:15]
	v_mov_b64_e32 v[60:61], v[12:13]
	v_mov_b64_e32 v[58:59], v[10:11]
	v_mov_b64_e32 v[56:57], v[8:9]
	v_mov_b64_e32 v[54:55], v[6:7]
	v_mov_b64_e32 v[52:53], v[4:5]
	v_mov_b64_e32 v[50:51], v[2:3]
	v_mov_b64_e32 v[46:47], v[14:15]
	v_mov_b64_e32 v[44:45], v[12:13]
	v_mov_b64_e32 v[42:43], v[10:11]
	v_mov_b64_e32 v[40:41], v[8:9]
	v_mov_b64_e32 v[38:39], v[6:7]
	v_mov_b64_e32 v[36:37], v[4:5]
	v_mov_b64_e32 v[34:35], v[2:3]
	v_mov_b64_e32 v[30:31], v[14:15]
	v_mov_b64_e32 v[28:29], v[12:13]
	v_mov_b64_e32 v[26:27], v[10:11]
	v_mov_b64_e32 v[24:25], v[8:9]
	v_mov_b64_e32 v[22:23], v[6:7]
	v_mov_b64_e32 v[20:21], v[4:5]
	v_mov_b64_e32 v[18:19], v[2:3]
	s_waitcnt lgkmcnt(0)
	s_barrier
; #define SBAR() __builtin_amdgcn_sched_barrier(0)
; __device__ __forceinline__ unsigned pk4f8(float a, float b, float c, float d) { unsigned w = 0u; w = __builtin_amdgcn_cvt_pk_fp8_f32(a, b, w, false); w = __builtin_amdgcn_cvt_pk_fp8_f32(c, d, w, true); return w; }
; #define SLOAD8(i, t) do { sk[i] = *reinterpret_cast<const i32x4a*>(kg + (long)(t) * (64 * 512)); sv[i] = *reinterpret_cast<const i32x4a*>(vg + (long)(t) * VT_STRIDE); } while (0)
; #define SWAIT8() asm volatile("s_waitcnt vmcnt(2)" ::: "memory")
; #define SWRITE8R(boff, i) do { *reinterpret_cast<ATT_LAS i32x4a*>(K_lds + (boff) + kst) = sk[i]; *reinterpret_cast<ATT_LAS i32x4a*>(V_lds + (boff) + vst) = sv[i]; } while (0)
; __device__ __forceinline__ void finishSM8(f32x16& p0, f32x16& p1, float alpha, float& l_reg, i32x8a& pa) {
; #pragma unroll
;   for (int r = 0; r < 16; ++r) p1[r] = __builtin_amdgcn_exp2f(p1[r]);
;   float ps = 0;
; #pragma unroll
;   for (int r = 0; r < 16; ++r) ps += p0[r];
; #pragma unroll
;   for (int r = 0; r < 16; ++r) ps += p1[r];
;   { auto rr = __builtin_amdgcn_permlane32_swap(__float_as_uint(ps), __float_as_uint(ps), false, false);
;     ps = __uint_as_float(rr[0]) + __uint_as_float(rr[1]); }
;   l_reg = l_reg * alpha + ps;
;   pa = (i32x8a){(int)pk4f8(p0[0], p0[1], p0[2], p0[3]), (int)pk4f8(p0[4], p0[5], p0[6], p0[7]), (int)pk4f8(p0[8], p0[9], p0[10], p0[11]), (int)pk4f8(p0[12], p0[13], p0[14], p0[15]),
;                 (int)pk4f8(p1[0], p1[1], p1[2], p1[3]), (int)pk4f8(p1[4], p1[5], p1[6], p1[7]), (int)pk4f8(p1[8], p1[9], p1[10], p1[11]), (int)pk4f8(p1[12], p1[13], p1[14], p1[15])};
; }
; __device__ __forceinline__ void attn_unit8(const bf16_t* __restrict__ Qb, const unsigned char* __restrict__ K8h, const unsigned char* __restrict__ VT8h, unsigned char* __restrict__ Ob, int seq, ATT_LAS char* lds, ...
;     ...
;     SBAR(); qkt8<false>(pB0, pB1, K_lds + bK, q8, r32, hi, one);
;     finishSM8(pA0, pA1, alA, l_reg, pa); SBAR();
;     SLOAD8(1, j + 2); SBAR();
;     pv8<false>(o, V_lds + bV, pa, r32, hi, one); partialSM8(pB0, pB1, m_reg, mnB, alB);
;     SWAIT8(); SWRITE8R(bW, 0);
;     RESC8(alB); __syncthreads();
.LBB0_549:
	s_mov_b32 s54, s52
	s_mov_b32 s52, s8
	s_add_i32 s26, s53, 0
	v_add3_u32 v66, s26, v159, v154
	v_add3_u32 v67, s26, v160, v154
	ds_read_b128 v[188:191], v66 offset:24576
	ds_read_b128 v[210:213], v66 offset:28672
	ds_read_b128 v[192:195], v67 offset:24576
	ds_read_b128 v[214:217], v67 offset:28672
	v_add3_u32 v66, s26, v161, v154
	v_add3_u32 v67, s26, v162, v154
	ds_read_b128 v[218:221], v66 offset:24576
	ds_read_b128 v[226:229], v66 offset:28672
	ds_read_b128 v[222:225], v67 offset:24576
	ds_read_b128 v[230:233], v67 offset:28672
	s_nop 1
	v_mov_b64_e32 v[80:81], s[50:51]
	v_mov_b64_e32 v[78:79], s[48:49]
	v_mov_b64_e32 v[76:77], s[46:47]
	v_mov_b64_e32 v[74:75], s[44:45]
	v_mov_b64_e32 v[72:73], s[42:43]
	v_mov_b64_e32 v[70:71], s[40:41]
	v_mov_b64_e32 v[68:69], s[38:39]
	v_mov_b64_e32 v[66:67], s[36:37]
	v_mov_b64_e32 v[96:97], v[80:81]
	v_mov_b64_e32 v[94:95], v[78:79]
	v_mov_b64_e32 v[92:93], v[76:77]
	v_mov_b64_e32 v[90:91], v[74:75]
	v_mov_b64_e32 v[88:89], v[72:73]
	v_mov_b64_e32 v[86:87], v[70:71]
	v_mov_b64_e32 v[84:85], v[68:69]
	v_mov_b64_e32 v[82:83], v[66:67]
	s_waitcnt lgkmcnt(5)
	v_mfma_scale_f32_32x32x64_f8f6f4 v[82:97], v[188:195], v[98:105], v[82:97], v133, v133 op_sel_hi:[0,0,0]
	s_waitcnt lgkmcnt(4)
	v_mfma_scale_f32_32x32x64_f8f6f4 v[66:81], v[210:217], v[98:105], v[66:81], v133, v133 op_sel_hi:[0,0,0]
	s_waitcnt lgkmcnt(1)
	v_mfma_scale_f32_32x32x64_f8f6f4 v[82:97], v[218:225], v[106:113], v[82:97], v133, v133 op_sel_hi:[0,0,0]
	s_waitcnt lgkmcnt(0)
	v_mfma_scale_f32_32x32x64_f8f6f4 v[66:81], v[226:233], v[106:113], v[66:81], v133, v133 op_sel_hi:[0,0,0]
	v_exp_f32_e32 v155, v144
	v_add_f32_e32 v144, 0, v176
	v_add_f32_e32 v144, v179, v144
	v_add_f32_e32 v144, v172, v144
	v_add_f32_e32 v144, v173, v144
	v_add_f32_e32 v144, v177, v144
	v_add_f32_e32 v144, v180, v144
	v_add_f32_e32 v144, v174, v144
	v_add_f32_e32 v144, v175, v144
	v_add_f32_e32 v144, v182, v144
	v_add_f32_e32 v144, v184, v144
	v_add_f32_e32 v144, v178, v144
	v_add_f32_e32 v144, v181, v144
	v_exp_f32_e32 v122, v150
	v_add_f32_e32 v144, v185, v144
	v_exp_f32_e32 v123, v151
	v_add_f32_e32 v144, v187, v144
	v_exp_f32_e32 v124, v148
	v_add_f32_e32 v144, v183, v144
	v_exp_f32_e32 v125, v149
	v_add_f32_e32 v144, v186, v144
	v_exp_f32_e32 v150, v146
	v_add_f32_e32 v144, v122, v144
	v_exp_f32_e32 v151, v147
	v_add_f32_e32 v144, v123, v144
	v_add_f32_e32 v144, v124, v144
	v_exp_f32_e32 v156, v145
	v_add_f32_e32 v144, v125, v144
	v_exp_f32_e32 v142, v142
	v_add_f32_e32 v144, v150, v144
	v_exp_f32_e32 v143, v143
	v_add_f32_e32 v144, v151, v144
	v_exp_f32_e32 v140, v140
	v_add_f32_e32 v144, v155, v144
	v_exp_f32_e32 v141, v141
	v_add_f32_e32 v144, v156, v144
	v_exp_f32_e32 v128, v128
	v_add_f32_e32 v144, v142, v144
	v_exp_f32_e32 v129, v129
	v_add_f32_e32 v144, v143, v144
	v_exp_f32_e32 v126, v126
	v_add_f32_e32 v144, v140, v144
	v_exp_f32_e32 v127, v127
	v_add_f32_e32 v144, v141, v144
	v_add_f32_e32 v144, v128, v144
	v_add_f32_e32 v144, v129, v144
	v_add_f32_e32 v144, v126, v144
	v_add_f32_e32 v169, v127, v144
	v_mov_b32_e32 v144, 0
	v_cvt_pk_fp8_f32 v144, v176, v179
	v_mov_b32_e32 v149, 0
	v_mov_b32_e32 v145, 0
	v_mov_b32_e32 v146, 0
	v_mov_b32_e32 v147, 0
	v_mov_b32_e32 v148, 0
	v_cvt_pk_fp8_f32 v149, v150, v151
	v_mov_b32_e32 v150, 0
	v_mov_b32_e32 v151, 0
	v_cvt_pk_fp8_f32 v145, v177, v180
	v_cvt_pk_fp8_f32 v146, v182, v184
	v_cvt_pk_fp8_f32 v147, v185, v187
	v_cvt_pk_fp8_f32 v144, v172, v173 op_sel:[0,0,1]
	v_cvt_pk_fp8_f32 v148, v122, v123
	v_cvt_pk_fp8_f32 v150, v142, v143
	v_cvt_pk_fp8_f32 v151, v128, v129
	v_mov_b32_e32 v170, v169
	s_nop 1
	v_permlane32_swap_b32_e32 v169, v170
	v_cvt_pk_fp8_f32 v145, v174, v175 op_sel:[0,0,1]
	v_cvt_pk_fp8_f32 v146, v178, v181 op_sel:[0,0,1]
	v_cvt_pk_fp8_f32 v147, v183, v186 op_sel:[0,0,1]
	v_cvt_pk_fp8_f32 v148, v124, v125 op_sel:[0,0,1]
	v_cvt_pk_fp8_f32 v149, v155, v156 op_sel:[0,0,1]
	v_cvt_pk_fp8_f32 v150, v140, v141 op_sel:[0,0,1]
	v_cvt_pk_fp8_f32 v151, v126, v127 op_sel:[0,0,1]
	v_lshl_add_u64 v[142:143], s[10:11], 0, v[136:137]
	v_add_co_u32_e32 v122, vcc, s74, v142
	v_lshl_add_u64 v[140:141], s[10:11], 0, v[138:139]
	s_nop 0
	v_addc_co_u32_e32 v123, vcc, 0, v143, vcc
	v_add_co_u32_e32 v126, vcc, s75, v140
	s_nop 1
	v_addc_co_u32_e32 v127, vcc, 0, v141, vcc
	flat_load_dwordx4 v[122:125], v[122:123]
	s_nop 0
	flat_load_dwordx4 v[126:129], v[126:127]
	s_add_i32 s56, s54, 0
	v_add_u32_e32 v155, s56, v164
	v_add_u32_e32 v155, v155, v163
	v_add_u32_e32 v156, s56, v165
	v_add_u32_e32 v156, v156, v163
	ds_read_b128 v[172:175], v155
	ds_read_b128 v[180:183], v155 offset:2048
	ds_read_b128 v[176:179], v156
	ds_read_b128 v[184:187], v156 offset:2048
	ds_read_b128 v[188:191], v155 offset:4096
	ds_read_b128 v[210:213], v155 offset:6144
	ds_read_b128 v[192:195], v156 offset:4096
	ds_read_b128 v[214:217], v156 offset:6144
	s_waitcnt lgkmcnt(0)
	v_mfma_scale_f32_32x32x64_f8f6f4 v[2:17], v[144:151], v[172:179], v[2:17], v133, v133 op_sel_hi:[0,0,0]
	v_mfma_scale_f32_32x32x64_f8f6f4 v[50:65], v[144:151], v[180:187], v[50:65], v133, v133 op_sel_hi:[0,0,0]
	v_mfma_scale_f32_32x32x64_f8f6f4 v[34:49], v[144:151], v[188:195], v[34:49], v133, v133 op_sel_hi:[0,0,0]
	v_mfma_scale_f32_32x32x64_f8f6f4 v[18:33], v[144:151], v[210:217], v[18:33], v133, v133 op_sel_hi:[0,0,0]
	v_max_f32_e32 v144, v83, v83
	v_max_f32_e32 v145, v82, v82
	v_max_f32_e32 v144, v145, v144
	v_max3_f32 v144, v144, v84, v85
	v_max3_f32 v144, v144, v86, v87
	v_max3_f32 v144, v144, v88, v89
	v_max3_f32 v144, v144, v90, v91
	v_max3_f32 v144, v144, v92, v93
	v_max3_f32 v144, v144, v94, v95
	v_max3_f32 v144, v144, v96, v97
	v_max3_f32 v144, v144, v66, v67
	v_max3_f32 v144, v144, v68, v69
	v_max3_f32 v144, v144, v70, v71
	v_max3_f32 v144, v144, v72, v73
	v_max3_f32 v144, v144, v74, v75
	v_max3_f32 v144, v144, v76, v77
	v_max3_f32 v144, v144, v78, v79
	v_max3_f32 v144, v144, v80, v81
	v_mov_b32_e32 v145, v144
	s_nop 1
	v_permlane32_swap_b32_e32 v144, v145
	v_max_f32_e32 v145, v145, v145
	v_max_f32_e32 v144, v144, v144
	v_max_f32_e32 v144, v144, v145
	v_max_f32_e32 v146, v167, v167
	v_sub_f32_e32 v145, v144, v167
	v_max_f32_e32 v144, v146, v144
	v_sub_f32_e32 v146, v167, v144
	v_mul_f32_e32 v146, 0x3e0293ee, v146
	v_exp_f32_e32 v146, v146
	v_cmp_ge_f32_e32 vcc, s69, v145
	s_cmp_eq_u64 vcc, exec
	s_cselect_b64 s[8:9], -1, 0
	s_waitcnt vmcnt(2)
	s_add_i32 s55, s52, 0
	v_cndmask_b32_e64 v171, v146, 1.0, s[8:9]
	v_add_u32_e32 v145, s55, v208
	ds_write_b128 v145, v[118:121] offset:24576
	v_add_u32_e32 v145, s52, v158
	v_cmp_gt_f32_e32 vcc, 1.0, v171
	ds_write_b128 v145, v[114:117]
	s_cbranch_vccz .LBB0_553
; #define SBAR() __builtin_amdgcn_sched_barrier(0)
; #define SLOAD8(i, t) do { sk[i] = *reinterpret_cast<const i32x4a*>(kg + (long)(t) * (64 * 512)); sv[i] = *reinterpret_cast<const i32x4a*>(vg + (long)(t) * VT_STRIDE); } while (0)
; __device__ __forceinline__ void attn_unit8(const bf16_t* __restrict__ Qb, const unsigned char* __restrict__ K8h, const unsigned char* __restrict__ VT8h, unsigned char* __restrict__ Ob, int seq, ATT_LAS char* lds, ...
;     ...
;     { const int t = bV; bV = bK; bK = bW; bW = t; }
;     SBAR(); qkt8<false>(pA0, pA1, K_lds + bK, q8, r32, hi, one);
;     finishSM8(pB0, pB1, alB, l_reg, pa); SBAR();
;     if (j + 3 < NT) SLOAD8(0, j + 3); SBAR();
	s_and_saveexec_b64 s[24:25], s[6:7]
	ds_write_b32 v152, v171 offset:49280
	s_or_b64 exec, exec, s[24:25]
	s_waitcnt lgkmcnt(0)
	v_add_u32_e32 v145, v206, v134
	ds_read_b128 v[146:149], v145 offset:49376
	ds_read_b128 v[172:175], v145 offset:49344
	ds_read_b128 v[176:179], v145 offset:49312
	ds_read_b128 v[180:183], v145 offset:49280
	s_waitcnt lgkmcnt(0)
	v_pk_mul_f32 v[14:15], v[14:15], v[146:147]
	v_pk_mul_f32 v[10:11], v[10:11], v[172:173]
	v_pk_mul_f32 v[6:7], v[6:7], v[176:177]
	v_pk_mul_f32 v[16:17], v[16:17], v[148:149]
	v_pk_mul_f32 v[12:13], v[12:13], v[174:175]
	v_pk_mul_f32 v[8:9], v[8:9], v[178:179]
	v_pk_mul_f32 v[4:5], v[4:5], v[182:183]
	v_pk_mul_f32 v[2:3], v[2:3], v[180:181]
	v_pk_mul_f32 v[62:63], v[62:63], v[146:147]
	v_pk_mul_f32 v[58:59], v[58:59], v[172:173]
	v_pk_mul_f32 v[54:55], v[54:55], v[176:177]
	v_pk_mul_f32 v[64:65], v[64:65], v[148:149]
	v_pk_mul_f32 v[60:61], v[60:61], v[174:175]
	v_pk_mul_f32 v[56:57], v[56:57], v[178:179]
	v_pk_mul_f32 v[52:53], v[52:53], v[182:183]
	v_pk_mul_f32 v[50:51], v[50:51], v[180:181]
	v_pk_mul_f32 v[46:47], v[46:47], v[146:147]
	v_pk_mul_f32 v[42:43], v[42:43], v[172:173]
	v_pk_mul_f32 v[38:39], v[38:39], v[176:177]
	v_pk_mul_f32 v[48:49], v[48:49], v[148:149]
	v_pk_mul_f32 v[44:45], v[44:45], v[174:175]
	v_pk_mul_f32 v[40:41], v[40:41], v[178:179]
	v_pk_mul_f32 v[36:37], v[36:37], v[182:183]
	v_pk_mul_f32 v[34:35], v[34:35], v[180:181]
	v_pk_mul_f32 v[30:31], v[30:31], v[146:147]
	v_pk_mul_f32 v[26:27], v[26:27], v[172:173]
	v_pk_mul_f32 v[22:23], v[22:23], v[176:177]
	v_pk_mul_f32 v[32:33], v[32:33], v[148:149]
	v_pk_mul_f32 v[28:29], v[28:29], v[174:175]
	v_pk_mul_f32 v[24:25], v[24:25], v[178:179]
	v_pk_mul_f32 v[20:21], v[20:21], v[182:183]
	v_pk_mul_f32 v[18:19], v[18:19], v[180:181]
.LBB0_553:
	v_cndmask_b32_e64 v144, v144, v167, s[8:9]
	v_mul_f32_e32 v197, 0xbe0293ee, v144
	v_fmamk_f32 v82, v82, 0x3e0293ee, v197
	v_fmamk_f32 v83, v83, 0x3e0293ee, v197
	v_fmamk_f32 v84, v84, 0x3e0293ee, v197
	v_fmamk_f32 v85, v85, 0x3e0293ee, v197
	v_fmamk_f32 v86, v86, 0x3e0293ee, v197
	v_fmamk_f32 v87, v87, 0x3e0293ee, v197
	v_fmamk_f32 v88, v88, 0x3e0293ee, v197
	v_fmamk_f32 v89, v89, 0x3e0293ee, v197
	v_fmamk_f32 v90, v90, 0x3e0293ee, v197
	v_fmamk_f32 v91, v91, 0x3e0293ee, v197
	v_fmamk_f32 v92, v92, 0x3e0293ee, v197
	v_fmamk_f32 v93, v93, 0x3e0293ee, v197
	v_fmamk_f32 v94, v94, 0x3e0293ee, v197
	v_fmamk_f32 v95, v95, 0x3e0293ee, v197
	v_fmamk_f32 v96, v96, 0x3e0293ee, v197
	v_fmamk_f32 v97, v97, 0x3e0293ee, v197
	v_exp_f32_e32 v168, v82
	v_exp_f32_e32 v175, v83
	v_exp_f32_e32 v145, v84
	v_exp_f32_e32 v146, v85
	v_exp_f32_e32 v172, v86
	v_exp_f32_e32 v176, v87
	v_exp_f32_e32 v147, v88
	v_exp_f32_e32 v148, v89
	v_exp_f32_e32 v173, v90
	v_exp_f32_e32 v177, v91
	v_exp_f32_e32 v149, v92
	v_exp_f32_e32 v150, v93
	v_exp_f32_e32 v174, v94
	v_exp_f32_e32 v178, v95
	v_exp_f32_e32 v151, v96
	v_exp_f32_e32 v167, v97
	v_fmamk_f32 v179, v66, 0x3e0293ee, v197
	v_fmamk_f32 v196, v67, 0x3e0293ee, v197
	v_fmamk_f32 v198, v68, 0x3e0293ee, v197
	v_fmamk_f32 v199, v69, 0x3e0293ee, v197
	v_fmamk_f32 v209, v70, 0x3e0293ee, v197
	v_fmamk_f32 v226, v71, 0x3e0293ee, v197
	v_fmamk_f32 v227, v72, 0x3e0293ee, v197
	v_fmamk_f32 v228, v73, 0x3e0293ee, v197
	v_fmamk_f32 v229, v74, 0x3e0293ee, v197
	v_fmamk_f32 v230, v75, 0x3e0293ee, v197
	v_fmamk_f32 v231, v76, 0x3e0293ee, v197
	v_fmamk_f32 v232, v77, 0x3e0293ee, v197
	v_fmamk_f32 v233, v78, 0x3e0293ee, v197
	v_fmamk_f32 v234, v79, 0x3e0293ee, v197
	v_fmamk_f32 v235, v80, 0x3e0293ee, v197
	v_fmac_f32_e32 v197, 0x3e0293ee, v81
	s_waitcnt lgkmcnt(0)
	s_barrier
	v_add3_u32 v66, s55, v159, v154
	v_add3_u32 v67, s55, v160, v154
	ds_read_b128 v[180:183], v66 offset:24576
	ds_read_b128 v[188:191], v66 offset:28672
	ds_read_b128 v[184:187], v67 offset:24576
	ds_read_b128 v[192:195], v67 offset:28672
	v_add3_u32 v66, s55, v161, v154
	v_add3_u32 v67, s55, v162, v154
	ds_read_b128 v[210:213], v66 offset:24576
	ds_read_b128 v[218:221], v66 offset:28672
	ds_read_b128 v[214:217], v67 offset:24576
	ds_read_b128 v[222:225], v67 offset:28672
	s_nop 1
	v_mov_b64_e32 v[80:81], s[50:51]
	v_mov_b64_e32 v[78:79], s[48:49]
	v_mov_b64_e32 v[76:77], s[46:47]
	v_mov_b64_e32 v[74:75], s[44:45]
	v_mov_b64_e32 v[72:73], s[42:43]
	v_mov_b64_e32 v[70:71], s[40:41]
	v_mov_b64_e32 v[68:69], s[38:39]
	v_mov_b64_e32 v[66:67], s[36:37]
	v_mov_b64_e32 v[96:97], v[80:81]
	v_mov_b64_e32 v[94:95], v[78:79]
	v_mov_b64_e32 v[92:93], v[76:77]
	v_mov_b64_e32 v[90:91], v[74:75]
	v_mov_b64_e32 v[88:89], v[72:73]
	v_mov_b64_e32 v[86:87], v[70:71]
	v_mov_b64_e32 v[84:85], v[68:69]
	v_mov_b64_e32 v[82:83], v[66:67]
	s_waitcnt lgkmcnt(0)
	v_mfma_scale_f32_32x32x64_f8f6f4 v[82:97], v[180:187], v[98:105], v[82:97], v133, v133 op_sel_hi:[0,0,0]
	v_mfma_scale_f32_32x32x64_f8f6f4 v[66:81], v[188:195], v[98:105], v[66:81], v133, v133 op_sel_hi:[0,0,0]
	s_nop 0
	v_mfma_scale_f32_32x32x64_f8f6f4 v[82:97], v[210:217], v[106:113], v[82:97], v133, v133 op_sel_hi:[0,0,0]
	v_mfma_scale_f32_32x32x64_f8f6f4 v[66:81], v[218:225], v[106:113], v[66:81], v133, v133 op_sel_hi:[0,0,0]
	v_add_f32_e32 v188, 0, v168
	v_add_f32_e32 v188, v175, v188
	v_add_f32_e32 v188, v145, v188
	v_add_f32_e32 v188, v146, v188
	v_add_f32_e32 v188, v172, v188
	v_add_f32_e32 v188, v176, v188
	v_add_f32_e32 v188, v147, v188
	v_add_f32_e32 v188, v148, v188
	v_add_f32_e32 v188, v173, v188
	v_add_f32_e32 v188, v177, v188
	v_add_f32_e32 v188, v149, v188
	v_add_f32_e32 v188, v150, v188
	v_exp_f32_e32 v187, v179
	v_add_f32_e32 v188, v174, v188
	v_exp_f32_e32 v193, v196
	v_add_f32_e32 v188, v178, v188
	v_exp_f32_e32 v179, v198
	v_add_f32_e32 v188, v151, v188
	v_exp_f32_e32 v180, v199
	v_add_f32_e32 v188, v167, v188
	v_exp_f32_e32 v190, v209
	v_add_f32_e32 v188, v187, v188
	v_exp_f32_e32 v194, v226
	v_add_f32_e32 v188, v193, v188
	v_exp_f32_e32 v181, v227
	v_add_f32_e32 v188, v179, v188
	v_exp_f32_e32 v182, v228
	v_add_f32_e32 v188, v180, v188
	v_exp_f32_e32 v191, v229
	v_add_f32_e32 v188, v190, v188
	v_exp_f32_e32 v195, v230
	v_add_f32_e32 v188, v194, v188
	v_exp_f32_e32 v183, v231
	v_add_f32_e32 v188, v181, v188
	v_exp_f32_e32 v184, v232
	v_add_f32_e32 v188, v182, v188
	v_exp_f32_e32 v192, v233
	v_add_f32_e32 v188, v191, v188
	v_exp_f32_e32 v196, v234
	v_add_f32_e32 v188, v195, v188
	v_exp_f32_e32 v185, v235
	v_add_f32_e32 v188, v183, v188
	v_exp_f32_e32 v186, v197
	v_add_f32_e32 v188, v184, v188
	v_add_f32_e32 v188, v192, v188
	v_add_f32_e32 v188, v196, v188
	v_add_f32_e32 v188, v185, v188
	v_add_f32_e32 v188, v186, v188
	v_mov_b32_e32 v189, v188
	s_nop 1
	v_permlane32_swap_b32_e32 v188, v189
	s_cmp_ge_u32 s84, s83
	s_cselect_b64 s[24:25], -1, 0
	s_and_b64 vcc, exec, s[24:25]
	s_cbranch_vccnz .LBB0_555
	v_add_co_u32_e32 v114, vcc, 0x1da20000, v142
	s_nop 1
	v_addc_co_u32_e32 v115, vcc, 0, v143, vcc
	v_add_co_u32_e32 v116, vcc, 0x1e620000, v140
	s_nop 1
	v_addc_co_u32_e32 v117, vcc, 0, v141, vcc
	flat_load_dwordx4 v[118:121], v[114:115]
	s_nop 0
	flat_load_dwordx4 v[114:117], v[116:117]
; #define SBAR() __builtin_amdgcn_sched_barrier(0)
; #define SLOAD8(i, t) do { sk[i] = *reinterpret_cast<const i32x4a*>(kg + (long)(t) * (64 * 512)); sv[i] = *reinterpret_cast<const i32x4a*>(vg + (long)(t) * VT_STRIDE); } while (0)
; #define SWAIT8() asm volatile("s_waitcnt vmcnt(2)" ::: "memory")
; #define SWRITE8R(boff, i) do { *reinterpret_cast<ATT_LAS i32x4a*>(K_lds + (boff) + kst) = sk[i]; *reinterpret_cast<ATT_LAS i32x4a*>(V_lds + (boff) + vst) = sv[i]; } while (0)
; #define RESC8(a) do { if (__any((a) < 1.f)) { if (hi == 0) al_l[r32] = (a); asm volatile("s_waitcnt lgkmcnt(0)" ::: "memory"); \
;     _Pragma("unroll") for (int d = 0; d < 4; ++d) _Pragma("unroll") for (int r = 0; r < 16; ++r) o[d][r] *= al_l[crow(r, hi)]; } } while (0)
; __device__ __forceinline__ void attn_unit8(const bf16_t* __restrict__ Qb, const unsigned char* __restrict__ K8h, const unsigned char* __restrict__ VT8h, unsigned char* __restrict__ Ob, int seq, ATT_LAS char* lds, ...
;     ...
;     if (j + 3 < NT) SLOAD8(0, j + 3); SBAR();
;     pv8<false>(o, V_lds + bV, pa, r32, hi, one); partialSM8(pA0, pA1, m_reg, mnA, alA);
;     SWAIT8(); SWRITE8R(bW, 1);
;     RESC8(alA); __syncthreads();
.LBB0_555:
	v_mov_b32_e32 v210, 0
	v_mov_b32_e32 v211, 0
	v_mov_b32_e32 v212, 0
	v_mov_b32_e32 v213, 0
	v_mov_b32_e32 v214, 0
	v_mov_b32_e32 v215, 0
	v_mov_b32_e32 v216, 0
	v_mov_b32_e32 v217, 0
	v_cvt_pk_fp8_f32 v210, v168, v175
	v_cvt_pk_fp8_f32 v211, v172, v176
	v_cvt_pk_fp8_f32 v212, v173, v177
	v_cvt_pk_fp8_f32 v213, v174, v178
	v_cvt_pk_fp8_f32 v214, v187, v193
	v_cvt_pk_fp8_f32 v215, v190, v194
	v_cvt_pk_fp8_f32 v216, v191, v195
	v_cvt_pk_fp8_f32 v217, v192, v196
	v_cvt_pk_fp8_f32 v210, v145, v146 op_sel:[0,0,1]
	v_cvt_pk_fp8_f32 v211, v147, v148 op_sel:[0,0,1]
	v_cvt_pk_fp8_f32 v212, v149, v150 op_sel:[0,0,1]
	v_cvt_pk_fp8_f32 v213, v151, v167 op_sel:[0,0,1]
	v_cvt_pk_fp8_f32 v214, v179, v180 op_sel:[0,0,1]
	v_cvt_pk_fp8_f32 v215, v181, v182 op_sel:[0,0,1]
	v_cvt_pk_fp8_f32 v216, v183, v184 op_sel:[0,0,1]
	v_cvt_pk_fp8_f32 v217, v185, v186 op_sel:[0,0,1]
	v_add3_u32 v140, s26, v164, v163
	v_add3_u32 v141, s26, v165, v163
	ds_read_b128 v[172:175], v140
	ds_read_b128 v[180:183], v140 offset:2048
	ds_read_b128 v[176:179], v141
	ds_read_b128 v[184:187], v141 offset:2048
	ds_read_b128 v[190:193], v140 offset:4096
	ds_read_b128 v[218:221], v140 offset:6144
	ds_read_b128 v[194:197], v141 offset:4096
	ds_read_b128 v[222:225], v141 offset:6144
	s_waitcnt lgkmcnt(0)
	v_mfma_scale_f32_32x32x64_f8f6f4 v[2:17], v[210:217], v[172:179], v[2:17], v133, v133 op_sel_hi:[0,0,0]
	v_mfma_scale_f32_32x32x64_f8f6f4 v[50:65], v[210:217], v[180:187], v[50:65], v133, v133 op_sel_hi:[0,0,0]
	v_mfma_scale_f32_32x32x64_f8f6f4 v[34:49], v[210:217], v[190:197], v[34:49], v133, v133 op_sel_hi:[0,0,0]
	v_mfma_scale_f32_32x32x64_f8f6f4 v[18:33], v[210:217], v[218:225], v[18:33], v133, v133 op_sel_hi:[0,0,0]
	v_max_f32_e32 v140, v83, v83
	v_max_f32_e32 v141, v82, v82
	v_max_f32_e32 v140, v141, v140
	v_max3_f32 v140, v140, v84, v85
	v_max3_f32 v140, v140, v86, v87
	v_max3_f32 v140, v140, v88, v89
	v_max3_f32 v140, v140, v90, v91
	v_max3_f32 v140, v140, v92, v93
	v_max3_f32 v140, v140, v94, v95
	v_max3_f32 v140, v140, v96, v97
	v_max3_f32 v140, v140, v66, v67
	v_max3_f32 v140, v140, v68, v69
	v_max3_f32 v140, v140, v70, v71
	v_max3_f32 v140, v140, v72, v73
	v_max3_f32 v140, v140, v74, v75
	v_max3_f32 v140, v140, v76, v77
	v_max3_f32 v140, v140, v78, v79
	v_max3_f32 v140, v140, v80, v81
	v_mov_b32_e32 v141, v140
	s_nop 1
	v_permlane32_swap_b32_e32 v140, v141
	v_max_f32_e32 v141, v141, v141
	v_max_f32_e32 v140, v140, v140
	v_max_f32_e32 v140, v140, v141
	v_max_f32_e32 v142, v144, v144
	v_sub_f32_e32 v141, v140, v144
	v_max_f32_e32 v140, v142, v140
	v_sub_f32_e32 v142, v144, v140
	v_mul_f32_e32 v142, 0x3e0293ee, v142
	v_exp_f32_e32 v142, v142
	v_cmp_ge_f32_e32 vcc, s69, v141
	s_cmp_eq_u64 vcc, exec
	s_cselect_b64 s[8:9], -1, 0
	s_waitcnt vmcnt(2)
	v_cndmask_b32_e64 v168, v142, 1.0, s[8:9]
	v_add_u32_e32 v141, s54, v157
	s_waitcnt vmcnt(0)
	ds_write_b128 v141, v[122:125] offset:24576
	v_add_u32_e32 v122, s56, v207
	v_cmp_gt_f32_e32 vcc, 1.0, v168
	ds_write_b128 v122, v[126:129]
	s_cbranch_vccz .LBB0_559
	s_and_saveexec_b64 s[26:27], s[6:7]
	ds_write_b32 v152, v168 offset:49280
	s_or_b64 exec, exec, s[26:27]
	s_waitcnt lgkmcnt(0)
	v_add_u32_e32 v141, v206, v134
	ds_read_b128 v[122:125], v141 offset:49376
	ds_read_b128 v[126:129], v141 offset:49344
	ds_read_b128 v[146:149], v141 offset:49312
	ds_read_b128 v[172:175], v141 offset:49280
	s_waitcnt lgkmcnt(3)
	v_pk_mul_f32 v[14:15], v[14:15], v[122:123]
	s_waitcnt lgkmcnt(2)
	v_pk_mul_f32 v[10:11], v[10:11], v[126:127]
	s_waitcnt lgkmcnt(1)
	v_pk_mul_f32 v[6:7], v[6:7], v[146:147]
	v_pk_mul_f32 v[16:17], v[16:17], v[124:125]
	v_pk_mul_f32 v[12:13], v[12:13], v[128:129]
	v_pk_mul_f32 v[8:9], v[8:9], v[148:149]
	s_waitcnt lgkmcnt(0)
	v_pk_mul_f32 v[4:5], v[4:5], v[174:175]
	v_pk_mul_f32 v[2:3], v[2:3], v[172:173]
	v_pk_mul_f32 v[62:63], v[62:63], v[122:123]
	v_pk_mul_f32 v[58:59], v[58:59], v[126:127]
	v_pk_mul_f32 v[54:55], v[54:55], v[146:147]
	v_pk_mul_f32 v[64:65], v[64:65], v[124:125]
	v_pk_mul_f32 v[60:61], v[60:61], v[128:129]
	v_pk_mul_f32 v[56:57], v[56:57], v[148:149]
	v_pk_mul_f32 v[52:53], v[52:53], v[174:175]
	v_pk_mul_f32 v[50:51], v[50:51], v[172:173]
	v_pk_mul_f32 v[46:47], v[46:47], v[122:123]
	v_pk_mul_f32 v[42:43], v[42:43], v[126:127]
	v_pk_mul_f32 v[38:39], v[38:39], v[146:147]
	v_pk_mul_f32 v[48:49], v[48:49], v[124:125]
	v_pk_mul_f32 v[44:45], v[44:45], v[128:129]
	v_pk_mul_f32 v[40:41], v[40:41], v[148:149]
	v_pk_mul_f32 v[36:37], v[36:37], v[174:175]
	v_pk_mul_f32 v[34:35], v[34:35], v[172:173]
	v_pk_mul_f32 v[30:31], v[30:31], v[122:123]
	v_pk_mul_f32 v[26:27], v[26:27], v[126:127]
	v_pk_mul_f32 v[22:23], v[22:23], v[146:147]
	v_pk_mul_f32 v[32:33], v[32:33], v[124:125]
	v_pk_mul_f32 v[28:29], v[28:29], v[128:129]
	v_pk_mul_f32 v[24:25], v[24:25], v[148:149]
	v_pk_mul_f32 v[20:21], v[20:21], v[174:175]
	v_pk_mul_f32 v[18:19], v[18:19], v[172:173]

; #define SBAR() __builtin_amdgcn_sched_barrier(0)
; __device__ __forceinline__ void attn_unit8(const bf16_t* __restrict__ Qb, const unsigned char* __restrict__ K8h, const unsigned char* __restrict__ VT8h, unsigned char* __restrict__ Ob, int seq, ATT_LAS char* lds, ...
;     ...
;   SBAR(); qkt8<false>(pB0, pB1, K_lds + bK, q8, r32, hi, one);
;   finishSM8(pA0, pA1, alA, l_reg, pa); SBAR();
;   pv8<false>(o, V_lds + bV, pa, r32, hi, one); partialSM8(pB0, pB1, m_reg, mnB, alB);
.LBB0_561:
	v_add3_u32 v66, s56, v159, v154
	v_add3_u32 v67, s56, v160, v154
	ds_read_b128 v[114:117], v66 offset:24576
	ds_read_b128 v[188:191], v66 offset:28672
	ds_read_b128 v[118:121], v67 offset:24576
	ds_read_b128 v[192:195], v67 offset:28672
	v_add3_u32 v66, s56, v161, v154
	v_add3_u32 v67, s56, v162, v154
	ds_read_b128 v[208:211], v66 offset:24576
	ds_read_b128 v[216:219], v66 offset:28672
	ds_read_b128 v[212:215], v67 offset:24576
	ds_read_b128 v[220:223], v67 offset:28672
	s_nop 1
	v_mov_b64_e32 v[80:81], s[50:51]
	v_mov_b64_e32 v[78:79], s[48:49]
	v_mov_b64_e32 v[76:77], s[46:47]
	v_mov_b64_e32 v[74:75], s[44:45]
	v_mov_b64_e32 v[72:73], s[42:43]
	v_mov_b64_e32 v[70:71], s[40:41]
	v_mov_b64_e32 v[68:69], s[38:39]
	v_mov_b64_e32 v[66:67], s[36:37]
	v_mov_b64_e32 v[96:97], v[80:81]
	v_mov_b64_e32 v[94:95], v[78:79]
	v_mov_b64_e32 v[92:93], v[76:77]
	v_mov_b64_e32 v[90:91], v[74:75]
	v_mov_b64_e32 v[88:89], v[72:73]
	v_mov_b64_e32 v[86:87], v[70:71]
	v_mov_b64_e32 v[84:85], v[68:69]
	v_mov_b64_e32 v[82:83], v[66:67]
	s_waitcnt lgkmcnt(5)
	v_mfma_scale_f32_32x32x64_f8f6f4 v[82:97], v[114:121], v[98:105], v[82:97], v133, v133 op_sel_hi:[0,0,0]
	s_waitcnt lgkmcnt(4)
	v_mfma_scale_f32_32x32x64_f8f6f4 v[66:81], v[188:195], v[98:105], v[66:81], v133, v133 op_sel_hi:[0,0,0]
	s_waitcnt lgkmcnt(1)
	v_mfma_scale_f32_32x32x64_f8f6f4 v[82:97], v[208:215], v[106:113], v[82:97], v133, v133 op_sel_hi:[0,0,0]
	s_waitcnt lgkmcnt(0)
	v_mfma_scale_f32_32x32x64_f8f6f4 v[66:81], v[216:223], v[106:113], v[66:81], v133, v133 op_sel_hi:[0,0,0]
	v_add_f32_e32 v98, 0, v176
	v_add_f32_e32 v98, v179, v98
	v_add_f32_e32 v98, v172, v98
	v_add_f32_e32 v98, v173, v98
	v_add_f32_e32 v98, v177, v98
	v_add_f32_e32 v98, v180, v98
	v_add_f32_e32 v98, v174, v98
	v_add_f32_e32 v98, v175, v98
	v_add_f32_e32 v98, v182, v98
	v_add_f32_e32 v98, v184, v98
	v_add_f32_e32 v98, v178, v98
	v_add_f32_e32 v98, v181, v98
	v_exp_f32_e32 v99, v150
	v_add_f32_e32 v98, v185, v98
	v_exp_f32_e32 v105, v151
	v_add_f32_e32 v98, v187, v98
	v_exp_f32_e32 v108, v148
	v_add_f32_e32 v98, v183, v98
	v_exp_f32_e32 v109, v149
	v_add_f32_e32 v98, v186, v98
	v_exp_f32_e32 v106, v146
	v_add_f32_e32 v98, v99, v98
	v_exp_f32_e32 v107, v147
	v_add_f32_e32 v98, v105, v98
	v_exp_f32_e32 v110, v144
	v_add_f32_e32 v98, v108, v98
	v_exp_f32_e32 v111, v145
	v_add_f32_e32 v98, v109, v98
	v_exp_f32_e32 v112, v142
	v_add_f32_e32 v98, v106, v98
	v_exp_f32_e32 v113, v143
	v_add_f32_e32 v98, v107, v98
	v_exp_f32_e32 v114, v140
	v_add_f32_e32 v98, v110, v98
	v_exp_f32_e32 v115, v141
	v_add_f32_e32 v98, v111, v98
	v_exp_f32_e32 v116, v128
	v_add_f32_e32 v98, v112, v98
	v_exp_f32_e32 v117, v129
	v_add_f32_e32 v98, v113, v98
	v_mov_b32_e32 v100, v131
	v_mov_b32_e32 v101, v131
	v_exp_f32_e32 v118, v126
	v_add_f32_e32 v98, v114, v98
	v_cvt_pk_fp8_f32 v100, v176, v179
	v_cvt_pk_fp8_f32 v101, v177, v180
	v_exp_f32_e32 v119, v127
	v_add_f32_e32 v98, v115, v98
	v_mov_b32_e32 v104, v131
	v_add_f32_e32 v98, v116, v98
	v_cvt_pk_fp8_f32 v104, v99, v105
	v_mov_b32_e32 v105, v131
	v_add_f32_e32 v98, v117, v98
	v_mov_b32_e32 v102, v131
	v_mov_b32_e32 v103, v131
	v_cvt_pk_fp8_f32 v105, v106, v107
	v_mov_b32_e32 v106, v131
	v_mov_b32_e32 v107, v131
	v_add_f32_e32 v98, v118, v98
	v_cvt_pk_fp8_f32 v102, v182, v184
	v_cvt_pk_fp8_f32 v103, v185, v187
	v_cvt_pk_fp8_f32 v100, v172, v173 op_sel:[0,0,1]
	v_cvt_pk_fp8_f32 v101, v174, v175 op_sel:[0,0,1]
	v_cvt_pk_fp8_f32 v106, v112, v113
	v_cvt_pk_fp8_f32 v107, v116, v117
	v_add_f32_e32 v98, v119, v98
	v_mov_b32_e32 v99, v98
	s_nop 1
	v_permlane32_swap_b32_e32 v98, v99
	v_cvt_pk_fp8_f32 v102, v178, v181 op_sel:[0,0,1]
	v_cvt_pk_fp8_f32 v103, v183, v186 op_sel:[0,0,1]
	v_cvt_pk_fp8_f32 v104, v108, v109 op_sel:[0,0,1]
	v_cvt_pk_fp8_f32 v105, v110, v111 op_sel:[0,0,1]
	v_cvt_pk_fp8_f32 v106, v114, v115 op_sel:[0,0,1]
	v_cvt_pk_fp8_f32 v107, v118, v119 op_sel:[0,0,1]
	v_add3_u32 v124, s55, v164, v163
	v_add3_u32 v125, s55, v165, v163
	ds_read_b128 v[108:111], v124
	ds_read_b128 v[116:119], v124 offset:2048
	ds_read_b128 v[112:115], v125
	ds_read_b128 v[120:123], v125 offset:2048
	ds_read_b128 v[136:139], v124 offset:4096
	ds_read_b128 v[144:147], v124 offset:6144
	ds_read_b128 v[140:143], v125 offset:4096
	ds_read_b128 v[148:151], v125 offset:6144
	s_waitcnt lgkmcnt(5)
	v_mfma_scale_f32_32x32x64_f8f6f4 v[2:17], v[100:107], v[108:115], v[2:17], v133, v133 op_sel_hi:[0,0,0]
	s_waitcnt lgkmcnt(4)
	v_mfma_scale_f32_32x32x64_f8f6f4 v[50:65], v[100:107], v[116:123], v[50:65], v133, v133 op_sel_hi:[0,0,0]
	s_waitcnt lgkmcnt(1)
	v_mfma_scale_f32_32x32x64_f8f6f4 v[34:49], v[100:107], v[136:143], v[34:49], v133, v133 op_sel_hi:[0,0,0]
	s_waitcnt lgkmcnt(0)
	v_mfma_scale_f32_32x32x64_f8f6f4 v[18:33], v[100:107], v[144:151], v[18:33], v133, v133 op_sel_hi:[0,0,0]
	v_max_f32_e32 v100, v83, v83
	v_max_f32_e32 v101, v82, v82
	v_max_f32_e32 v100, v101, v100
	v_max3_f32 v100, v100, v84, v85
	v_max3_f32 v100, v100, v86, v87
	v_max3_f32 v100, v100, v88, v89
	v_max3_f32 v100, v100, v90, v91
	v_max3_f32 v100, v100, v92, v93
	v_max3_f32 v100, v100, v94, v95
	v_max3_f32 v100, v100, v96, v97
	v_max3_f32 v100, v100, v66, v67
	v_max3_f32 v100, v100, v68, v69
	v_max3_f32 v100, v100, v70, v71
	v_max3_f32 v100, v100, v72, v73
	v_max3_f32 v100, v100, v74, v75
	v_max3_f32 v100, v100, v76, v77
	v_max3_f32 v100, v100, v78, v79
	v_max3_f32 v100, v100, v80, v81
	v_mov_b32_e32 v101, v100
	s_nop 1
	v_permlane32_swap_b32_e32 v100, v101
	v_max_f32_e32 v101, v101, v101
	v_max_f32_e32 v100, v100, v100
	v_max_f32_e32 v100, v100, v101
	v_max_f32_e32 v101, v167, v167
	v_max_f32_e32 v101, v101, v100
	v_sub_f32_e32 v102, v100, v167
	v_sub_f32_e32 v100, v167, v101
	v_mul_f32_e32 v100, 0x3e0293ee, v100
	v_exp_f32_e32 v100, v100
	v_cmp_ge_f32_e32 vcc, s69, v102
	s_cmp_eq_u64 vcc, exec
	s_cselect_b64 s[8:9], -1, 0
	v_cndmask_b32_e64 v100, v100, 1.0, s[8:9]
	v_cmp_gt_f32_e32 vcc, 1.0, v100
	s_cbranch_vccz .LBB0_565
; #define ATT_LAS __attribute__((address_space(3)))
; __device__ __forceinline__ void finishSM8(f32x16& p0, f32x16& p1, float alpha, float& l_reg, i32x8a& pa) {
; #pragma unroll
;   for (int r = 0; r < 16; ++r) p1[r] = __builtin_amdgcn_exp2f(p1[r]);
;   float ps = 0;
; #pragma unroll
;   for (int r = 0; r < 16; ++r) ps += p0[r];
; #pragma unroll
;   for (int r = 0; r < 16; ++r) ps += p1[r];
;   { auto rr = __builtin_amdgcn_permlane32_swap(__float_as_uint(ps), __float_as_uint(ps), false, false);
;     ps = __uint_as_float(rr[0]) + __uint_as_float(rr[1]); }
;   l_reg = l_reg * alpha + ps;
;   pa = (i32x8a){(int)pk4f8(p0[0], p0[1], p0[2], p0[3]), (int)pk4f8(p0[4], p0[5], p0[6], p0[7]), (int)pk4f8(p0[8], p0[9], p0[10], p0[11]), (int)pk4f8(p0[12], p0[13], p0[14], p0[15]),
;                 (int)pk4f8(p1[0], p1[1], p1[2], p1[3]), (int)pk4f8(p1[4], p1[5], p1[6], p1[7]), (int)pk4f8(p1[8], p1[9], p1[10], p1[11]), (int)pk4f8(p1[12], p1[13], p1[14], p1[15])};
; }
; template <bool WAITSTATES>
; __device__ __forceinline__ void qkt8(f32x16& p0, f32x16& p1, const ATT_LAS char* Ks, const i32x8a (&q8)[2], int r32, int hi, int one) {
;   p0 = f32x16{}; p1 = f32x16{};
;   const i32x8a k00 = ld32(Ks + k8_off(r32, 2 * hi), Ks + k8_off(r32, 2 * hi + 1)), k10 = ld32(Ks + k8_off(32 + r32, 2 * hi), Ks + k8_off(32 + r32, 2 * hi + 1));
;   const i32x8a k01 = ld32(Ks + k8_off(r32, 4 + 2 * hi), Ks + k8_off(r32, 5 + 2 * hi)), k11 = ld32(Ks + k8_off(32 + r32, 4 + 2 * hi), Ks + k8_off(32 + r32, 5 + 2 * hi));
;   asm volatile("s_nop 1" ::: "memory");
;   __builtin_amdgcn_s_setprio(1); MFMA8(p0, k00, q8[0], one); MFMA8(p1, k10, q8[0], one); MFMA8(p0, k01, q8[1], one); MFMA8(p1, k11, q8[1], one); __builtin_amdgcn_s_setprio(0);
;   if (WAITSTATES) asm volatile("s_nop 15\n\ts_nop 7" ::: "memory");
; }
; template <bool WAITSTATES>
; __device__ __forceinline__ void pv8(f32x16* o, const ATT_LAS char* Vs, const i32x8a& pa, int r32, int hi, int one) {
; __device__ __forceinline__ void attn_unit8(const bf16_t* __restrict__ Qb, const unsigned char* __restrict__ K8h, const unsigned char* __restrict__ VT8h, unsigned char* __restrict__ Ob, int seq, ATT_LAS char* lds, ...
;     ...
;   RESC8(alB);
;   finishSM8(pB0, pB1, alB, l_reg, pa); SBAR();
;   pv8<true>(o, V_lds + bK, pa, r32, hi, one);
;   if (hi == 0) li_l[r32] = l_reg; asm volatile("s_waitcnt lgkmcnt(0)" ::: "memory");
	s_and_saveexec_b64 s[24:25], s[6:7]
	ds_write_b32 v152, v100 offset:49280
	s_or_b64 exec, exec, s[24:25]
	s_waitcnt lgkmcnt(0)
	v_add_u32_e32 v114, v206, v134
	ds_read_b128 v[102:105], v114 offset:49376
	ds_read_b128 v[106:109], v114 offset:49344
	ds_read_b128 v[110:113], v114 offset:49312
	ds_read_b128 v[114:117], v114 offset:49280
	s_waitcnt lgkmcnt(3)
	v_pk_mul_f32 v[14:15], v[14:15], v[102:103]
	s_waitcnt lgkmcnt(2)
	v_pk_mul_f32 v[10:11], v[10:11], v[106:107]
	s_waitcnt lgkmcnt(1)
	v_pk_mul_f32 v[6:7], v[6:7], v[110:111]
	v_pk_mul_f32 v[16:17], v[16:17], v[104:105]
	v_pk_mul_f32 v[12:13], v[12:13], v[108:109]
	v_pk_mul_f32 v[8:9], v[8:9], v[112:113]
	s_waitcnt lgkmcnt(0)
	v_pk_mul_f32 v[4:5], v[4:5], v[116:117]
	v_pk_mul_f32 v[2:3], v[2:3], v[114:115]
	v_pk_mul_f32 v[62:63], v[62:63], v[102:103]
	v_pk_mul_f32 v[58:59], v[58:59], v[106:107]
	v_pk_mul_f32 v[54:55], v[54:55], v[110:111]
	v_pk_mul_f32 v[64:65], v[64:65], v[104:105]
	v_pk_mul_f32 v[60:61], v[60:61], v[108:109]
	v_pk_mul_f32 v[56:57], v[56:57], v[112:113]
	v_pk_mul_f32 v[52:53], v[52:53], v[116:117]
	v_pk_mul_f32 v[50:51], v[50:51], v[114:115]
	v_pk_mul_f32 v[46:47], v[46:47], v[102:103]
	v_pk_mul_f32 v[42:43], v[42:43], v[106:107]
	v_pk_mul_f32 v[38:39], v[38:39], v[110:111]
	v_pk_mul_f32 v[48:49], v[48:49], v[104:105]
	v_pk_mul_f32 v[44:45], v[44:45], v[108:109]
	v_pk_mul_f32 v[40:41], v[40:41], v[112:113]
	v_pk_mul_f32 v[36:37], v[36:37], v[116:117]
	v_pk_mul_f32 v[34:35], v[34:35], v[114:115]
	v_pk_mul_f32 v[30:31], v[30:31], v[102:103]
	v_pk_mul_f32 v[26:27], v[26:27], v[106:107]
	v_pk_mul_f32 v[22:23], v[22:23], v[110:111]
	v_pk_mul_f32 v[32:33], v[32:33], v[104:105]
	v_pk_mul_f32 v[28:29], v[28:29], v[108:109]
	v_pk_mul_f32 v[24:25], v[24:25], v[112:113]
	v_pk_mul_f32 v[20:21], v[20:21], v[116:117]
	v_pk_mul_f32 v[18:19], v[18:19], v[114:115]
.LBB0_565:
	v_cndmask_b32_e64 v101, v101, v167, s[8:9]
	v_mul_f32_e32 v101, 0xbe0293ee, v101
	v_fmamk_f32 v82, v82, 0x3e0293ee, v101
	v_fmamk_f32 v83, v83, 0x3e0293ee, v101
	v_fmamk_f32 v84, v84, 0x3e0293ee, v101
	v_fmamk_f32 v85, v85, 0x3e0293ee, v101
	v_fmamk_f32 v86, v86, 0x3e0293ee, v101
	v_fmamk_f32 v87, v87, 0x3e0293ee, v101
	v_fmamk_f32 v88, v88, 0x3e0293ee, v101
	v_fmamk_f32 v89, v89, 0x3e0293ee, v101
	v_fmamk_f32 v90, v90, 0x3e0293ee, v101
	v_fmamk_f32 v91, v91, 0x3e0293ee, v101
	v_fmamk_f32 v92, v92, 0x3e0293ee, v101
	v_fmamk_f32 v93, v93, 0x3e0293ee, v101
	v_fmamk_f32 v94, v94, 0x3e0293ee, v101
	v_fmamk_f32 v95, v95, 0x3e0293ee, v101
	v_fmamk_f32 v96, v96, 0x3e0293ee, v101
	v_fmamk_f32 v97, v97, 0x3e0293ee, v101
	v_fmamk_f32 v66, v66, 0x3e0293ee, v101
	v_fmamk_f32 v67, v67, 0x3e0293ee, v101
	v_fmamk_f32 v68, v68, 0x3e0293ee, v101
	v_fmamk_f32 v69, v69, 0x3e0293ee, v101
	v_fmamk_f32 v70, v70, 0x3e0293ee, v101
	v_fmamk_f32 v71, v71, 0x3e0293ee, v101
	v_fmamk_f32 v72, v72, 0x3e0293ee, v101
	v_fmamk_f32 v73, v73, 0x3e0293ee, v101
	v_fmamk_f32 v74, v74, 0x3e0293ee, v101
	v_fmamk_f32 v75, v75, 0x3e0293ee, v101
	v_fmamk_f32 v76, v76, 0x3e0293ee, v101
	v_fmamk_f32 v77, v77, 0x3e0293ee, v101
	v_fmamk_f32 v78, v78, 0x3e0293ee, v101
	v_fmamk_f32 v79, v79, 0x3e0293ee, v101
	v_fmamk_f32 v80, v80, 0x3e0293ee, v101
	v_fmac_f32_e32 v101, 0x3e0293ee, v81
	v_exp_f32_e32 v81, v82
	v_exp_f32_e32 v82, v83
	v_exp_f32_e32 v83, v84
	v_exp_f32_e32 v84, v85
	v_exp_f32_e32 v85, v86
	v_exp_f32_e32 v86, v87
	v_exp_f32_e32 v87, v88
	v_exp_f32_e32 v88, v89
	v_exp_f32_e32 v89, v90
	v_exp_f32_e32 v90, v91
	v_exp_f32_e32 v91, v92
	v_exp_f32_e32 v92, v93
	v_exp_f32_e32 v93, v94
	v_exp_f32_e32 v94, v95
	v_exp_f32_e32 v95, v96
	v_exp_f32_e32 v96, v97
	v_exp_f32_e32 v97, v66
	v_add_f32_e32 v66, 0, v81
	v_add_f32_e32 v66, v82, v66
	v_add_f32_e32 v66, v83, v66
	v_add_f32_e32 v66, v84, v66
	v_add_f32_e32 v66, v85, v66
	v_add_f32_e32 v66, v86, v66
	v_add_f32_e32 v66, v87, v66
	v_add_f32_e32 v66, v88, v66
	v_add_f32_e32 v66, v89, v66
	v_add_f32_e32 v66, v90, v66
	v_add_f32_e32 v66, v91, v66
	v_add_f32_e32 v66, v92, v66
	v_add_f32_e32 v66, v93, v66
	v_exp_f32_e32 v67, v67
	v_add_f32_e32 v66, v94, v66
	v_exp_f32_e32 v102, v68
	v_add_f32_e32 v66, v95, v66
	v_exp_f32_e32 v103, v69
	v_add_f32_e32 v66, v96, v66
	v_exp_f32_e32 v104, v70
	v_add_f32_e32 v66, v97, v66
	v_exp_f32_e32 v105, v71
	v_add_f32_e32 v66, v67, v66
	v_exp_f32_e32 v106, v72
	v_add_f32_e32 v66, v102, v66
	v_exp_f32_e32 v107, v73
	v_add_f32_e32 v66, v103, v66
	v_exp_f32_e32 v108, v74
	v_add_f32_e32 v66, v104, v66
	v_exp_f32_e32 v75, v75
	v_add_f32_e32 v66, v105, v66
	v_exp_f32_e32 v76, v76
	v_add_f32_e32 v66, v106, v66
	v_exp_f32_e32 v77, v77
	v_add_f32_e32 v66, v107, v66
	v_exp_f32_e32 v78, v78
	v_add_f32_e32 v66, v108, v66
	v_exp_f32_e32 v79, v79
	v_add_f32_e32 v66, v75, v66
	v_exp_f32_e32 v80, v80
	v_add_f32_e32 v66, v76, v66
	v_exp_f32_e32 v101, v101
	v_add_f32_e32 v66, v77, v66
	v_add_f32_e32 v66, v78, v66
	v_mov_b32_e32 v74, v131
	v_add_f32_e32 v66, v79, v66
	v_mov_b32_e32 v68, v131
	v_mov_b32_e32 v69, v131
	v_mov_b32_e32 v70, v131
	v_mov_b32_e32 v71, v131
	v_mov_b32_e32 v72, v131
	v_mov_b32_e32 v73, v131
	v_cvt_pk_fp8_f32 v74, v108, v75
	v_mov_b32_e32 v75, v131
	v_add_f32_e32 v66, v80, v66
	v_cvt_pk_fp8_f32 v68, v81, v82
	v_cvt_pk_fp8_f32 v69, v85, v86
	v_cvt_pk_fp8_f32 v70, v89, v90
	v_cvt_pk_fp8_f32 v71, v93, v94
	v_cvt_pk_fp8_f32 v72, v97, v67
	v_cvt_pk_fp8_f32 v73, v104, v105
	v_cvt_pk_fp8_f32 v75, v78, v79
	v_add_f32_e32 v66, v101, v66
	v_mov_b32_e32 v67, v66
	s_nop 1
	v_permlane32_swap_b32_e32 v66, v67
	v_cvt_pk_fp8_f32 v68, v83, v84 op_sel:[0,0,1]
	v_cvt_pk_fp8_f32 v69, v87, v88 op_sel:[0,0,1]
	v_cvt_pk_fp8_f32 v70, v91, v92 op_sel:[0,0,1]
	v_cvt_pk_fp8_f32 v71, v95, v96 op_sel:[0,0,1]
	v_cvt_pk_fp8_f32 v72, v102, v103 op_sel:[0,0,1]
	v_cvt_pk_fp8_f32 v73, v106, v107 op_sel:[0,0,1]
	v_cvt_pk_fp8_f32 v74, v76, v77 op_sel:[0,0,1]
	v_cvt_pk_fp8_f32 v75, v80, v101 op_sel:[0,0,1]
	ds_read_b128 v[76:79], v155
	ds_read_b128 v[84:87], v155 offset:2048
	ds_read_b128 v[80:83], v156
	ds_read_b128 v[88:91], v156 offset:2048
	ds_read_b128 v[102:105], v155 offset:4096
	ds_read_b128 v[110:113], v155 offset:6144
	ds_read_b128 v[106:109], v156 offset:4096
	ds_read_b128 v[114:117], v156 offset:6144
	s_waitcnt lgkmcnt(5)
	v_mfma_scale_f32_32x32x64_f8f6f4 v[2:17], v[68:75], v[76:83], v[2:17], v133, v133 op_sel_hi:[0,0,0]
	s_waitcnt lgkmcnt(4)
	v_mfma_scale_f32_32x32x64_f8f6f4 v[50:65], v[68:75], v[84:91], v[50:65], v133, v133 op_sel_hi:[0,0,0]
	s_waitcnt lgkmcnt(1)
	v_mfma_scale_f32_32x32x64_f8f6f4 v[34:49], v[68:75], v[102:109], v[34:49], v133, v133 op_sel_hi:[0,0,0]
	s_waitcnt lgkmcnt(0)
	v_mfma_scale_f32_32x32x64_f8f6f4 v[18:33], v[68:75], v[110:117], v[18:33], v133, v133 op_sel_hi:[0,0,0]
	s_nop 15
	s_nop 7
	s_and_saveexec_b64 s[8:9], s[6:7]
	s_cbranch_execz .LBB0_543
	v_add_f32_e32 v68, v98, v99
	v_fmac_f32_e32 v68, v153, v168
	v_add_f32_e32 v66, v66, v67
	v_fmac_f32_e32 v66, v68, v100
	ds_write_b32 v152, v66 offset:49152
	s_branch .LBB0_543

; #define PG8_STAGE(bufoff, gbase, voff) do { _Pragma("unroll") for (int _i = 0; _i < 2; ++_i) \
;         __builtin_amdgcn_global_load_lds((const unsigned*)((const char*)(gbase) + (voff)[_i]), (PG8_LAS unsigned*)(lds + (bufoff) + ldsw + _i * 8192), 16, 0, 0); } while (0)
; #define PG8_LDA(dst, b, h) do { _Pragma("unroll") for (int m = 0; m < 4; ++m) _Pragma("unroll") for (int k = 0; k < 2; ++k) dst[m][k] = *(const PG8_LAS bf16x8*)(lds + PG8_SA(b, h) + aoff + m * 2048 + k * 1024); } while (0)
; #define PG8_LDB(dst, b, h) do { _Pragma("unroll") for (int n = 0; n < 2; ++n) _Pragma("unroll") for (int k = 0; k < 2; ++k) dst[n][k] = *(const PG8_LAS bf16x8*)(lds + PG8_SB(b, h) + boff + n * 2048 + k * 1024); } while (0)
; #define PG8_WAIT_V(n) asm volatile("s_waitcnt vmcnt(" #n ")" ::: "memory")
; #define PG8_WAIT_L(n) asm volatile("s_waitcnt lgkmcnt(" #n ")" ::: "memory")
; #define PG8_BAR __builtin_amdgcn_s_barrier()
; #define PG8_SCHED __builtin_amdgcn_sched_barrier(0)
; template <class Epi, class Sched, bool ALIGN_EPI = false, bool SP2 = false, bool F8 = false>
; __device__ __forceinline__ void gemm_phase(PG8_LAS unsigned char* lds, const Gemm g, const Sched& S, const Epi& E) {
;     ...
;             PG8_LDB(B0, 0, 0); PG8_LDB(B1, 0, 1); PG8_SCHED; PG8_LDA(At, 0, 0); PG8_STAGE(PG8_SA(1, 1), a1 + hA, voffA);
;             PG8_WAIT_V(8); PG8_WAIT_L(0); PG8_BAR; PG8_MMA(0, 0, At, B0); PG8_MMA(0, 1, At, B1); PG8_BAR; PG8_SCHED;
;             PG8_LDA(At, 0, 1); PG8_STAGE(PG8_SB(0, 0), b2, voffB); PG8_STAGE(PG8_SB(0, 1), b2 + hB, voffB); PG8_STAGE(PG8_SA(0, 0), a2, voffA);
;             PG8_WAIT_V(8); PG8_WAIT_L(0); PG8_BAR; PG8_MMA(1, 0, At, B0); PG8_MMA(1, 1, At, B1); PG8_BAR; PG8_SCHED;
.LBB0_618:
	ds_read_b128 v[130:133], v185
	ds_read_b128 v[134:137], v185 offset:1024
	ds_read_b128 v[138:141], v185 offset:2048
	ds_read_b128 v[142:145], v185 offset:3072
	ds_read_b128 v[146:149], v186
	ds_read_b128 v[150:153], v186 offset:1024
	ds_read_b128 v[154:157], v186 offset:2048
	ds_read_b128 v[174:177], v186 offset:3072
	s_add_u32 s40, s38, 0xfff80080
	s_addc_u32 s41, s39, -1
	s_cmp_eq_u32 s59, 4
	s_cselect_b32 s43, s29, s41
	s_cselect_b32 s42, s55, s40
	s_cselect_b32 s41, s27, s58
	s_cselect_b32 s40, s56, s57
	v_lshl_add_u64 v[216:217], s[38:39], 0, v[168:169]
	s_add_i32 m0, s37, 0xc000
	ds_read_b128 v[178:181], v187
	ds_read_b128 v[188:191], v187 offset:1024
	ds_read_b128 v[192:195], v187 offset:2048
	ds_read_b128 v[196:199], v187 offset:3072
	ds_read_b128 v[200:203], v187 offset:4096
	ds_read_b128 v[204:207], v187 offset:5120
	ds_read_b128 v[208:211], v187 offset:6144
	ds_read_b128 v[212:215], v187 offset:7168
	global_load_lds_dwordx4 v[216:217], off
	v_lshl_add_u64 v[216:217], s[38:39], 0, v[166:167]
	s_add_i32 m0, s37, 0xe000
	s_nop 0
	global_load_lds_dwordx4 v[216:217], off
	s_waitcnt vmcnt(8)
	s_waitcnt lgkmcnt(0)
	s_barrier
	v_mfma_f32_16x16x32_bf16 v[126:129], v[130:133], v[178:181], v[126:129]
	v_mfma_f32_16x16x32_bf16 v[122:125], v[138:141], v[178:181], v[122:125]
	v_mfma_f32_16x16x32_bf16 v[110:113], v[130:133], v[192:195], v[110:113]
	v_mfma_f32_16x16x32_bf16 v[106:109], v[138:141], v[192:195], v[106:109]
	v_mfma_f32_16x16x32_bf16 v[94:97], v[130:133], v[200:203], v[94:97]
	v_mfma_f32_16x16x32_bf16 v[90:93], v[138:141], v[200:203], v[90:93]
	v_mfma_f32_16x16x32_bf16 v[78:81], v[130:133], v[208:211], v[78:81]
	v_mfma_f32_16x16x32_bf16 v[74:77], v[138:141], v[208:211], v[74:77]
	v_mfma_f32_16x16x32_bf16 v[126:129], v[134:137], v[188:191], v[126:129]
	v_mfma_f32_16x16x32_bf16 v[122:125], v[142:145], v[188:191], v[122:125]
	v_mfma_f32_16x16x32_bf16 v[110:113], v[134:137], v[196:199], v[110:113]
	v_mfma_f32_16x16x32_bf16 v[106:109], v[142:145], v[196:199], v[106:109]
	v_mfma_f32_16x16x32_bf16 v[94:97], v[134:137], v[204:207], v[94:97]
	v_mfma_f32_16x16x32_bf16 v[90:93], v[142:145], v[204:207], v[90:93]
	v_mfma_f32_16x16x32_bf16 v[78:81], v[134:137], v[212:215], v[78:81]
	v_mfma_f32_16x16x32_bf16 v[74:77], v[142:145], v[212:215], v[74:77]
	v_mfma_f32_16x16x32_bf16 v[118:121], v[146:149], v[178:181], v[118:121]
	v_mfma_f32_16x16x32_bf16 v[114:117], v[154:157], v[178:181], v[114:117]
	v_mfma_f32_16x16x32_bf16 v[102:105], v[146:149], v[192:195], v[102:105]
	v_mfma_f32_16x16x32_bf16 v[98:101], v[154:157], v[192:195], v[98:101]
	v_mfma_f32_16x16x32_bf16 v[86:89], v[146:149], v[200:203], v[86:89]
	v_mfma_f32_16x16x32_bf16 v[82:85], v[154:157], v[200:203], v[82:85]
	v_mfma_f32_16x16x32_bf16 v[70:73], v[146:149], v[208:211], v[70:73]
	v_mfma_f32_16x16x32_bf16 v[66:69], v[154:157], v[208:211], v[66:69]
	v_mfma_f32_16x16x32_bf16 v[118:121], v[150:153], v[188:191], v[118:121]
	v_mfma_f32_16x16x32_bf16 v[114:117], v[174:177], v[188:191], v[114:117]
	v_mfma_f32_16x16x32_bf16 v[102:105], v[150:153], v[196:199], v[102:105]
	v_mfma_f32_16x16x32_bf16 v[98:101], v[174:177], v[196:199], v[98:101]
	v_mfma_f32_16x16x32_bf16 v[86:89], v[150:153], v[204:207], v[86:89]
	v_mfma_f32_16x16x32_bf16 v[82:85], v[174:177], v[204:207], v[82:85]
	v_mfma_f32_16x16x32_bf16 v[70:73], v[150:153], v[212:215], v[70:73]
	v_mfma_f32_16x16x32_bf16 v[66:69], v[174:177], v[212:215], v[66:69]
	s_barrier
	s_add_i32 s60, s52, s19
	v_lshl_add_u64 v[216:217], s[40:41], 0, v[162:163]
	s_mov_b32 m0, s60
	ds_read_b128 v[178:181], v187 offset:16384
	ds_read_b128 v[188:191], v187 offset:17408
	ds_read_b128 v[192:195], v187 offset:18432
	ds_read_b128 v[196:199], v187 offset:19456
	ds_read_b128 v[200:203], v187 offset:20480
	ds_read_b128 v[204:207], v187 offset:21504
	ds_read_b128 v[208:211], v187 offset:22528
	ds_read_b128 v[212:215], v187 offset:23552
	global_load_lds_dwordx4 v[216:217], off
	s_add_i32 m0, s60, 0x2000
	s_add_u32 s60, s40, 0x20000
	v_lshl_add_u64 v[218:219], s[40:41], 0, v[158:159]
	s_addc_u32 s61, s41, 0
	s_add_i32 s62, s53, s19
	global_load_lds_dwordx4 v[218:219], off
	v_lshl_add_u64 v[220:221], s[60:61], 0, v[162:163]
	s_mov_b32 m0, s62
	v_lshl_add_u64 v[222:223], s[42:43], 0, v[160:161]
	global_load_lds_dwordx4 v[220:221], off
	v_lshl_add_u64 v[220:221], s[60:61], 0, v[158:159]
	s_add_i32 m0, s62, 0x2000
	s_nop 0
	global_load_lds_dwordx4 v[220:221], off
	v_lshl_add_u64 v[220:221], s[42:43], 0, v[164:165]
	s_mov_b32 m0, s37
	s_nop 0
	global_load_lds_dwordx4 v[220:221], off
	s_mov_b32 m0, s45
	s_nop 0
	global_load_lds_dwordx4 v[222:223], off
	s_waitcnt vmcnt(8)
	s_waitcnt lgkmcnt(0)
	s_barrier
; #define PG8_STAGE(bufoff, gbase, voff) do { _Pragma("unroll") for (int _i = 0; _i < 2; ++_i) \
;         __builtin_amdgcn_global_load_lds((const unsigned*)((const char*)(gbase) + (voff)[_i]), (PG8_LAS unsigned*)(lds + (bufoff) + ldsw + _i * 8192), 16, 0, 0); } while (0)
; #define PG8_LDA(dst, b, h) do { _Pragma("unroll") for (int m = 0; m < 4; ++m) _Pragma("unroll") for (int k = 0; k < 2; ++k) dst[m][k] = *(const PG8_LAS bf16x8*)(lds + PG8_SA(b, h) + aoff + m * 2048 + k * 1024); } while (0)
; #define PG8_LDB(dst, b, h) do { _Pragma("unroll") for (int n = 0; n < 2; ++n) _Pragma("unroll") for (int k = 0; k < 2; ++k) dst[n][k] = *(const PG8_LAS bf16x8*)(lds + PG8_SB(b, h) + boff + n * 2048 + k * 1024); } while (0)
; #define PG8_WAIT_V(n) asm volatile("s_waitcnt vmcnt(" #n ")" ::: "memory")
; #define PG8_WAIT_L(n) asm volatile("s_waitcnt lgkmcnt(" #n ")" ::: "memory")
; #define PG8_BAR __builtin_amdgcn_s_barrier()
; #define PG8_SCHED __builtin_amdgcn_sched_barrier(0)
; template <class Epi, class Sched, bool ALIGN_EPI = false, bool SP2 = false, bool F8 = false>
; __device__ __forceinline__ void gemm_phase(PG8_LAS unsigned char* lds, const Gemm g, const Sched& S, const Epi& E) {
;     ...
;             PG8_WAIT_V(8); PG8_WAIT_L(0); PG8_BAR; PG8_MMA(1, 0, At, B0); PG8_MMA(1, 1, At, B1); PG8_BAR; PG8_SCHED;
;             PG8_LDB(B0, 1, 0); PG8_LDB(B1, 1, 1); PG8_SCHED; PG8_LDA(At, 1, 0); PG8_STAGE(PG8_SA(0, 1), a2 + hA, voffA);
;             PG8_WAIT_V(8); PG8_WAIT_L(0); PG8_BAR; PG8_MMA(0, 0, At, B0); PG8_MMA(0, 1, At, B1); PG8_BAR; PG8_SCHED;
	v_mfma_f32_16x16x32_bf16 v[62:65], v[130:133], v[178:181], v[62:65]
	v_mfma_f32_16x16x32_bf16 v[58:61], v[138:141], v[178:181], v[58:61]
	v_mfma_f32_16x16x32_bf16 v[46:49], v[130:133], v[192:195], v[46:49]
	v_mfma_f32_16x16x32_bf16 v[42:45], v[138:141], v[192:195], v[42:45]
	v_mfma_f32_16x16x32_bf16 v[30:33], v[130:133], v[200:203], v[30:33]
	v_mfma_f32_16x16x32_bf16 v[26:29], v[138:141], v[200:203], v[26:29]
	v_mfma_f32_16x16x32_bf16 v[14:17], v[130:133], v[208:211], v[14:17]
	v_mfma_f32_16x16x32_bf16 v[10:13], v[138:141], v[208:211], v[10:13]
	v_mfma_f32_16x16x32_bf16 v[62:65], v[134:137], v[188:191], v[62:65]
	v_mfma_f32_16x16x32_bf16 v[58:61], v[142:145], v[188:191], v[58:61]
	v_mfma_f32_16x16x32_bf16 v[46:49], v[134:137], v[196:199], v[46:49]
	v_mfma_f32_16x16x32_bf16 v[42:45], v[142:145], v[196:199], v[42:45]
	v_mfma_f32_16x16x32_bf16 v[30:33], v[134:137], v[204:207], v[30:33]
	v_mfma_f32_16x16x32_bf16 v[26:29], v[142:145], v[204:207], v[26:29]
	v_mfma_f32_16x16x32_bf16 v[14:17], v[134:137], v[212:215], v[14:17]
	v_mfma_f32_16x16x32_bf16 v[10:13], v[142:145], v[212:215], v[10:13]
	v_mfma_f32_16x16x32_bf16 v[54:57], v[146:149], v[178:181], v[54:57]
	v_mfma_f32_16x16x32_bf16 v[50:53], v[154:157], v[178:181], v[50:53]
	v_mfma_f32_16x16x32_bf16 v[38:41], v[146:149], v[192:195], v[38:41]
	v_mfma_f32_16x16x32_bf16 v[34:37], v[154:157], v[192:195], v[34:37]
	v_mfma_f32_16x16x32_bf16 v[22:25], v[146:149], v[200:203], v[22:25]
	v_mfma_f32_16x16x32_bf16 v[18:21], v[154:157], v[200:203], v[18:21]
	v_mfma_f32_16x16x32_bf16 v[6:9], v[146:149], v[208:211], v[6:9]
	v_mfma_f32_16x16x32_bf16 v[2:5], v[154:157], v[208:211], v[2:5]
	v_mfma_f32_16x16x32_bf16 v[54:57], v[150:153], v[188:191], v[54:57]
	v_mfma_f32_16x16x32_bf16 v[50:53], v[174:177], v[188:191], v[50:53]
	v_mfma_f32_16x16x32_bf16 v[38:41], v[150:153], v[196:199], v[38:41]
	v_mfma_f32_16x16x32_bf16 v[34:37], v[174:177], v[196:199], v[34:37]
	v_mfma_f32_16x16x32_bf16 v[22:25], v[150:153], v[204:207], v[22:25]
	v_mfma_f32_16x16x32_bf16 v[18:21], v[174:177], v[204:207], v[18:21]
	v_mfma_f32_16x16x32_bf16 v[6:9], v[150:153], v[212:215], v[6:9]
	v_mfma_f32_16x16x32_bf16 v[2:5], v[174:177], v[212:215], v[2:5]
	s_barrier
	s_add_i32 s60, 0, 0x18000
	s_add_i32 s61, 0, 0x1c000
	v_add_u32_e32 v142, s60, v183
	v_add_u32_e32 v174, s61, v183
	ds_read_b128 v[130:133], v142
	ds_read_b128 v[134:137], v142 offset:1024
	ds_read_b128 v[138:141], v142 offset:2048
	ds_read_b128 v[142:145], v142 offset:3072
	ds_read_b128 v[146:149], v174
	ds_read_b128 v[150:153], v174 offset:1024
	ds_read_b128 v[154:157], v174 offset:2048
	ds_read_b128 v[174:177], v174 offset:3072
	s_add_u32 s42, s42, 0x80000
	s_addc_u32 s43, s43, 0
	s_mov_b32 m0, s46
	v_lshl_add_u64 v[224:225], s[42:43], 0, v[164:165]
	ds_read_b128 v[178:181], v187 offset:32768
	ds_read_b128 v[188:191], v187 offset:33792
	ds_read_b128 v[192:195], v187 offset:34816
	ds_read_b128 v[196:199], v187 offset:35840
	ds_read_b128 v[200:203], v187 offset:36864
	ds_read_b128 v[204:207], v187 offset:37888
	ds_read_b128 v[208:211], v187 offset:38912
	ds_read_b128 v[212:215], v187 offset:39936
	global_load_lds_dwordx4 v[224:225], off
	v_lshl_add_u64 v[224:225], s[42:43], 0, v[160:161]
	s_mov_b32 m0, s47
	s_nop 0
	global_load_lds_dwordx4 v[224:225], off
	s_waitcnt vmcnt(8)
	s_waitcnt lgkmcnt(0)
	s_barrier
	v_mfma_f32_16x16x32_bf16 v[126:129], v[130:133], v[178:181], v[126:129]
	v_mfma_f32_16x16x32_bf16 v[122:125], v[138:141], v[178:181], v[122:125]
	v_mfma_f32_16x16x32_bf16 v[110:113], v[130:133], v[192:195], v[110:113]
	v_mfma_f32_16x16x32_bf16 v[106:109], v[138:141], v[192:195], v[106:109]
	v_mfma_f32_16x16x32_bf16 v[94:97], v[130:133], v[200:203], v[94:97]
	v_mfma_f32_16x16x32_bf16 v[90:93], v[138:141], v[200:203], v[90:93]
	v_mfma_f32_16x16x32_bf16 v[78:81], v[130:133], v[208:211], v[78:81]
	v_mfma_f32_16x16x32_bf16 v[74:77], v[138:141], v[208:211], v[74:77]
	v_mfma_f32_16x16x32_bf16 v[126:129], v[134:137], v[188:191], v[126:129]
	v_mfma_f32_16x16x32_bf16 v[122:125], v[142:145], v[188:191], v[122:125]
	v_mfma_f32_16x16x32_bf16 v[110:113], v[134:137], v[196:199], v[110:113]
	v_mfma_f32_16x16x32_bf16 v[106:109], v[142:145], v[196:199], v[106:109]
	v_mfma_f32_16x16x32_bf16 v[94:97], v[134:137], v[204:207], v[94:97]
	v_mfma_f32_16x16x32_bf16 v[90:93], v[142:145], v[204:207], v[90:93]
	v_mfma_f32_16x16x32_bf16 v[78:81], v[134:137], v[212:215], v[78:81]
	v_mfma_f32_16x16x32_bf16 v[74:77], v[142:145], v[212:215], v[74:77]
	v_mfma_f32_16x16x32_bf16 v[118:121], v[146:149], v[178:181], v[118:121]
	v_mfma_f32_16x16x32_bf16 v[114:117], v[154:157], v[178:181], v[114:117]
	v_mfma_f32_16x16x32_bf16 v[102:105], v[146:149], v[192:195], v[102:105]
	v_mfma_f32_16x16x32_bf16 v[98:101], v[154:157], v[192:195], v[98:101]
	v_mfma_f32_16x16x32_bf16 v[86:89], v[146:149], v[200:203], v[86:89]
	v_mfma_f32_16x16x32_bf16 v[82:85], v[154:157], v[200:203], v[82:85]
	v_mfma_f32_16x16x32_bf16 v[70:73], v[146:149], v[208:211], v[70:73]
	v_mfma_f32_16x16x32_bf16 v[66:69], v[154:157], v[208:211], v[66:69]
	v_mfma_f32_16x16x32_bf16 v[118:121], v[150:153], v[188:191], v[118:121]
	v_mfma_f32_16x16x32_bf16 v[114:117], v[174:177], v[188:191], v[114:117]
	v_mfma_f32_16x16x32_bf16 v[102:105], v[150:153], v[196:199], v[102:105]
	v_mfma_f32_16x16x32_bf16 v[98:101], v[174:177], v[196:199], v[98:101]
	v_mfma_f32_16x16x32_bf16 v[86:89], v[150:153], v[204:207], v[86:89]
	v_mfma_f32_16x16x32_bf16 v[82:85], v[174:177], v[204:207], v[82:85]
	v_mfma_f32_16x16x32_bf16 v[70:73], v[150:153], v[212:215], v[70:73]
	v_mfma_f32_16x16x32_bf16 v[66:69], v[174:177], v[212:215], v[66:69]
	s_barrier
; #define PG8_GAS __attribute__((address_space(1)))
; #define PG8_STAGE(bufoff, gbase, voff) do { _Pragma("unroll") for (int _i = 0; _i < 2; ++_i) \
;         __builtin_amdgcn_global_load_lds((const unsigned*)((const char*)(gbase) + (voff)[_i]), (PG8_LAS unsigned*)(lds + (bufoff) + ldsw + _i * 8192), 16, 0, 0); } while (0)
; #define PG8_LDA(dst, b, h) do { _Pragma("unroll") for (int m = 0; m < 4; ++m) _Pragma("unroll") for (int k = 0; k < 2; ++k) dst[m][k] = *(const PG8_LAS bf16x8*)(lds + PG8_SA(b, h) + aoff + m * 2048 + k * 1024); } while (0)
; #define PG8_WAIT_V(n) asm volatile("s_waitcnt vmcnt(" #n ")" ::: "memory")
; #define PG8_WAIT_L(n) asm volatile("s_waitcnt lgkmcnt(" #n ")" ::: "memory")
; #define PG8_BAR __builtin_amdgcn_s_barrier()
; #define PG8_SCHED __builtin_amdgcn_sched_barrier(0)
;     __device__ __forceinline__ void operator()(const f32x4 (&acc)[2][2][4][2], const Unit& un, int wr, int wc, int fr, int fq) const {
;         const int row0 = un.pm * BM + wr * 64 + fr, col0 = un.pn * BM + wc * 32 + 8 * fq;
;         f32x4 sc[2][2];
; #pragma unroll
;         for (int bj = 0; bj < 2; ++bj)
; #pragma unroll
;             for (int n = 0; n < 2; ++n) sc[bj][n] = *(const PG8_GAS f32x4*)(ps + col0 + bj * HALF + 4 * n);
; #pragma unroll
;         for (int ai = 0; ai < 2; ++ai) {
;             u32x4 gg[4][2];
; #pragma unroll
;             for (int m = 0; m < 4; ++m)
; #pragma unroll
;                 for (int bj = 0; bj < 2; ++bj) gg[m][bj] = *(const PG8_GAS u32x4*)(sp + (size_t)(row0 + ai * HALF + m * 16) * 4096 + col0 + bj * HALF);
; template <class Epi, class Sched, bool ALIGN_EPI = false, bool SP2 = false, bool F8 = false>
; __device__ __forceinline__ void gemm_phase(PG8_LAS unsigned char* lds, const Gemm g, const Sched& S, const Epi& E) {
;     ...
;             PG8_LDA(At, 1, 1); PG8_STAGE(PG8_SB(1, 0), b3, voffB); PG8_STAGE(PG8_SB(1, 1), b3 + hB, voffB); PG8_STAGE(PG8_SA(1, 0), a3, voffA);
;             PG8_WAIT_V(8); PG8_WAIT_L(0); PG8_BAR; PG8_MMA(1, 0, At, B0); PG8_MMA(1, 1, At, B1); PG8_BAR; PG8_SCHED;
	s_add_i32 s42, s60, s19
	v_lshl_add_u64 v[216:217], v[216:217], 0, s[14:15]
	s_mov_b32 m0, s42
	ds_read_b128 v[178:181], v187 offset:49152
	ds_read_b128 v[188:191], v187 offset:50176
	ds_read_b128 v[192:195], v187 offset:51200
	ds_read_b128 v[196:199], v187 offset:52224
	ds_read_b128 v[200:203], v187 offset:53248
	ds_read_b128 v[204:207], v187 offset:54272
	ds_read_b128 v[208:211], v187 offset:55296
	ds_read_b128 v[212:215], v187 offset:56320
	global_load_lds_dwordx4 v[216:217], off
	s_add_i32 m0, s42, 0x2000
	s_add_u32 s40, s40, 0x20080
	v_lshl_add_u64 v[216:217], v[218:219], 0, s[14:15]
	s_addc_u32 s41, s41, 0
	s_add_i32 s42, s61, s19
	global_load_lds_dwordx4 v[216:217], off
	v_lshl_add_u64 v[216:217], s[40:41], 0, v[162:163]
	s_mov_b32 m0, s42
	s_nop 0
	global_load_lds_dwordx4 v[216:217], off
	v_lshl_add_u64 v[216:217], s[40:41], 0, v[158:159]
	s_add_i32 m0, s42, 0x2000
	s_nop 0
	global_load_lds_dwordx4 v[216:217], off
	v_lshl_add_u64 v[216:217], v[220:221], 0, s[14:15]
	s_mov_b32 m0, s49
	s_nop 0
	global_load_lds_dwordx4 v[216:217], off
	v_lshl_add_u64 v[216:217], v[222:223], 0, s[14:15]
	s_mov_b32 m0, s50
	s_nop 0
	global_load_lds_dwordx4 v[216:217], off
	s_waitcnt vmcnt(8)
	s_waitcnt lgkmcnt(0)
	s_barrier
	v_mfma_f32_16x16x32_bf16 v[62:65], v[130:133], v[178:181], v[62:65]
	v_mfma_f32_16x16x32_bf16 v[58:61], v[138:141], v[178:181], v[58:61]
	v_mfma_f32_16x16x32_bf16 v[46:49], v[130:133], v[192:195], v[46:49]
	v_mfma_f32_16x16x32_bf16 v[42:45], v[138:141], v[192:195], v[42:45]
	v_mfma_f32_16x16x32_bf16 v[30:33], v[130:133], v[200:203], v[30:33]
	v_mfma_f32_16x16x32_bf16 v[26:29], v[138:141], v[200:203], v[26:29]
	v_mfma_f32_16x16x32_bf16 v[14:17], v[130:133], v[208:211], v[14:17]
	v_mfma_f32_16x16x32_bf16 v[10:13], v[138:141], v[208:211], v[10:13]
	v_mfma_f32_16x16x32_bf16 v[62:65], v[134:137], v[188:191], v[62:65]
	v_mfma_f32_16x16x32_bf16 v[58:61], v[142:145], v[188:191], v[58:61]
	v_mfma_f32_16x16x32_bf16 v[46:49], v[134:137], v[196:199], v[46:49]
	v_mfma_f32_16x16x32_bf16 v[42:45], v[142:145], v[196:199], v[42:45]
	v_mfma_f32_16x16x32_bf16 v[30:33], v[134:137], v[204:207], v[30:33]
	v_mfma_f32_16x16x32_bf16 v[26:29], v[142:145], v[204:207], v[26:29]
	v_mfma_f32_16x16x32_bf16 v[14:17], v[134:137], v[212:215], v[14:17]
	v_mfma_f32_16x16x32_bf16 v[10:13], v[142:145], v[212:215], v[10:13]
	v_mfma_f32_16x16x32_bf16 v[54:57], v[146:149], v[178:181], v[54:57]
	v_mfma_f32_16x16x32_bf16 v[50:53], v[154:157], v[178:181], v[50:53]
	v_mfma_f32_16x16x32_bf16 v[38:41], v[146:149], v[192:195], v[38:41]
	v_mfma_f32_16x16x32_bf16 v[34:37], v[154:157], v[192:195], v[34:37]
	v_mfma_f32_16x16x32_bf16 v[22:25], v[146:149], v[200:203], v[22:25]
	v_mfma_f32_16x16x32_bf16 v[18:21], v[154:157], v[200:203], v[18:21]
	v_mfma_f32_16x16x32_bf16 v[6:9], v[146:149], v[208:211], v[6:9]
	v_mfma_f32_16x16x32_bf16 v[2:5], v[154:157], v[208:211], v[2:5]
	v_mfma_f32_16x16x32_bf16 v[54:57], v[150:153], v[188:191], v[54:57]
	v_mfma_f32_16x16x32_bf16 v[50:53], v[174:177], v[188:191], v[50:53]
	v_mfma_f32_16x16x32_bf16 v[38:41], v[150:153], v[196:199], v[38:41]
	v_mfma_f32_16x16x32_bf16 v[34:37], v[174:177], v[196:199], v[34:37]
	v_mfma_f32_16x16x32_bf16 v[22:25], v[150:153], v[204:207], v[22:25]
	v_mfma_f32_16x16x32_bf16 v[18:21], v[174:177], v[204:207], v[18:21]
	v_mfma_f32_16x16x32_bf16 v[6:9], v[150:153], v[212:215], v[6:9]
	v_mfma_f32_16x16x32_bf16 v[2:5], v[174:177], v[212:215], v[2:5]
	s_barrier
	s_add_i32 s59, s59, 2
	s_add_u32 s57, s57, 0x100
	s_addc_u32 s58, s58, 0
	s_add_u32 s38, s38, 0x100
	s_addc_u32 s39, s39, 0
	s_cmp_gt_u32 s59, 5
	s_cbranch_scc0 .LBB0_618
	v_lshl_or_b32 v146, s54, 8, v184
	v_ashrrev_i32_e32 v147, 31, v146
	v_lshl_add_u32 v148, s36, 8, v182
	v_ashrrev_i32_e32 v149, 31, v148
	v_lshlrev_b64 v[174:175], 1, v[146:147]
	v_lshlrev_b64 v[178:179], 13, v[148:149]
	v_lshl_add_u64 v[176:177], s[12:13], 0, v[174:175]
	v_lshl_add_u64 v[130:131], v[146:147], 2, s[10:11]
	v_lshl_add_u64 v[146:147], v[176:177], 0, v[178:179]
	global_load_dwordx4 v[142:145], v[130:131], off
	global_load_dwordx4 v[138:141], v[130:131], off offset:16
	global_load_dwordx4 v[134:137], v[130:131], off offset:512
	s_nop 0
	global_load_dwordx4 v[130:133], v[130:131], off offset:528
	s_nop 0
	global_load_dwordx4 v[188:191], v[146:147], off
	global_load_dwordx4 v[192:195], v[146:147], off offset:256
	v_or_b32_e32 v146, 16, v148
	v_ashrrev_i32_e32 v147, 31, v146
	v_lshlrev_b64 v[208:209], 13, v[146:147]
	v_lshl_add_u64 v[146:147], v[176:177], 0, v[208:209]
	global_load_dwordx4 v[196:199], v[146:147], off
	global_load_dwordx4 v[200:203], v[146:147], off offset:256
	v_or_b32_e32 v150, 32, v148
	v_or_b32_e32 v148, 48, v148
	v_ashrrev_i32_e32 v151, 31, v150
	v_ashrrev_i32_e32 v149, 31, v148
	v_lshlrev_b64 v[210:211], 13, v[150:151]
	v_lshlrev_b64 v[180:181], 13, v[148:149]
	v_lshl_add_u64 v[146:147], s[12:13], 0, v[178:179]
	v_lshl_add_u64 v[148:149], v[176:177], 0, v[210:211]
	v_lshl_add_u64 v[212:213], v[176:177], 0, v[180:181]
	v_lshl_add_u64 v[214:215], v[146:147], 0, v[174:175]
	global_load_dwordx4 v[204:207], v[148:149], off
	global_load_dwordx4 v[154:157], v[148:149], off offset:256
	global_load_dwordx4 v[150:153], v[212:213], off
	s_nop 0
	global_load_dwordx4 v[146:149], v[212:213], off offset:256
	s_and_b64 vcc, exec, s[8:9]
	s_mov_b32 s54, s26
	s_mov_b32 s36, s28
	s_mov_b64 s[38:39], s[34:35]
	s_mov_b64 s[40:41], s[30:31]
	s_waitcnt vmcnt(0)
; #define PG8_GAS __attribute__((address_space(1)))
; __device__ __forceinline__ unsigned cvt_pk_bf16(float lo, float hi) { const f32x2c v = {lo, hi}; return __builtin_bit_cast(unsigned, __builtin_convertvector(v, bf16x2c)); }
; __device__ __forceinline__ float bf_lo(unsigned w) { return __uint_as_float(w << 16); }
; __device__ __forceinline__ float bf_hi(unsigned w) { return __uint_as_float(w & 0xffff0000u); }
;     __device__ __forceinline__ void operator()(const f32x4 (&acc)[2][2][4][2], const Unit& un, int wr, int wc, int fr, int fq) const {
;     ...
;             for (int m = 0; m < 4; ++m)
; #pragma unroll
;                 for (int bj = 0; bj < 2; ++bj) { const u32x4 g = gg[m][bj];
;                     const f32x4 v0 = acc[ai][bj][m][0] * sc[bj][0], v1 = acc[ai][bj][m][1] * sc[bj][1];
;                     u32x4 w; w.x = cvt_pk_bf16(v0[0] * bf_lo(g.x), v0[1] * bf_hi(g.x)); w.y = cvt_pk_bf16(v0[2] * bf_lo(g.y), v0[3] * bf_hi(g.y));
;                     w.z = cvt_pk_bf16(v1[0] * bf_lo(g.z), v1[1] * bf_hi(g.z)); w.w = cvt_pk_bf16(v1[2] * bf_lo(g.w), v1[3] * bf_hi(g.w));
;                     *(PG8_GAS u32x4*)(sp + (size_t)(row0 + ai * HALF + m * 16) * 4096 + col0 + bj * HALF) = w; }
	v_pk_mul_f32 v[128:129], v[128:129], v[144:145]
	v_pk_mul_f32 v[126:127], v[126:127], v[142:143]
	v_pk_mul_f32 v[124:125], v[124:125], v[140:141]
	v_pk_mul_f32 v[122:123], v[122:123], v[138:139]
	v_pk_mul_f32 v[212:213], v[108:109], v[140:141]
	v_pk_mul_f32 v[216:217], v[106:107], v[138:139]
	v_lshlrev_b32_e32 v106, 16, v188
	v_and_b32_e32 v107, 0xffff0000, v188
	v_lshlrev_b32_e32 v108, 16, v189
	v_and_b32_e32 v109, 0xffff0000, v189
	v_lshlrev_b32_e32 v188, 16, v190
	v_and_b32_e32 v189, 0xffff0000, v190
	v_lshlrev_b32_e32 v190, 16, v191
	v_and_b32_e32 v191, 0xffff0000, v191
	v_pk_mul_f32 v[120:121], v[120:121], v[136:137]
	v_pk_mul_f32 v[118:119], v[118:119], v[134:135]
	v_pk_mul_f32 v[116:117], v[116:117], v[132:133]
	v_pk_mul_f32 v[114:115], v[114:115], v[130:131]
	v_lshlrev_b32_e32 v218, 16, v192
	v_and_b32_e32 v219, 0xffff0000, v192
	v_lshlrev_b32_e32 v192, 16, v193
	v_and_b32_e32 v193, 0xffff0000, v193
	v_lshlrev_b32_e32 v220, 16, v194
	v_and_b32_e32 v221, 0xffff0000, v194
	v_lshlrev_b32_e32 v194, 16, v195
	v_and_b32_e32 v195, 0xffff0000, v195
	v_pk_mul_f32 v[106:107], v[126:127], v[106:107]
	v_pk_mul_f32 v[108:109], v[128:129], v[108:109]
	v_pk_mul_f32 v[122:123], v[122:123], v[188:189]
	v_pk_mul_f32 v[124:125], v[124:125], v[190:191]
	v_pk_mul_f32 v[112:113], v[112:113], v[144:145]
	v_pk_mul_f32 v[110:111], v[110:111], v[142:143]
	v_lshlrev_b32_e32 v222, 16, v196
	v_and_b32_e32 v223, 0xffff0000, v196
	v_lshlrev_b32_e32 v196, 16, v197
	v_and_b32_e32 v197, 0xffff0000, v197
	v_pk_mul_f32 v[118:119], v[118:119], v[218:219]
	v_pk_mul_f32 v[120:121], v[120:121], v[192:193]
	v_pk_mul_f32 v[114:115], v[114:115], v[220:221]
	v_pk_mul_f32 v[116:117], v[116:117], v[194:195]
	v_cvt_pk_bf16_f32 v106, v106, v107
	v_cvt_pk_bf16_f32 v107, v108, v109
	v_cvt_pk_bf16_f32 v108, v122, v123
	v_cvt_pk_bf16_f32 v109, v124, v125
	v_pk_mul_f32 v[126:127], v[110:111], v[222:223]
	v_pk_mul_f32 v[128:129], v[112:113], v[196:197]
	v_cvt_pk_bf16_f32 v110, v118, v119
	v_cvt_pk_bf16_f32 v111, v120, v121
	v_cvt_pk_bf16_f32 v112, v114, v115
	v_cvt_pk_bf16_f32 v113, v116, v117
	global_store_dwordx4 v[214:215], v[106:109], off
	global_store_dwordx4 v[214:215], v[110:113], off offset:256
	v_pk_mul_f32 v[102:103], v[102:103], v[134:135]
	v_pk_mul_f32 v[108:109], v[100:101], v[132:133]
	v_pk_mul_f32 v[100:101], v[98:99], v[130:131]
	v_lshlrev_b32_e32 v98, 16, v200
	v_and_b32_e32 v99, 0xffff0000, v200
	v_lshlrev_b32_e32 v106, 16, v198
	v_and_b32_e32 v107, 0xffff0000, v198
	v_pk_mul_f32 v[104:105], v[104:105], v[136:137]
	v_pk_mul_f32 v[98:99], v[102:103], v[98:99]
	v_lshlrev_b32_e32 v102, 16, v201
	v_and_b32_e32 v103, 0xffff0000, v201
	v_pk_mul_f32 v[106:107], v[216:217], v[106:107]
	v_pk_mul_f32 v[102:103], v[104:105], v[102:103]
	v_cvt_pk_bf16_f32 v116, v106, v107
	v_lshlrev_b32_e32 v106, 16, v199
	v_and_b32_e32 v107, 0xffff0000, v199
	v_cvt_pk_bf16_f32 v98, v98, v99
	v_cvt_pk_bf16_f32 v99, v102, v103
	v_lshlrev_b32_e32 v102, 16, v202
	v_and_b32_e32 v103, 0xffff0000, v202
	v_pk_mul_f32 v[106:107], v[212:213], v[106:107]
	v_pk_mul_f32 v[100:101], v[100:101], v[102:103]
	v_lshlrev_b32_e32 v102, 16, v203
	v_and_b32_e32 v103, 0xffff0000, v203
	v_cvt_pk_bf16_f32 v117, v106, v107
	v_lshl_add_u64 v[106:107], s[12:13], 0, v[208:209]
	v_pk_mul_f32 v[102:103], v[108:109], v[102:103]
	v_lshl_add_u64 v[106:107], v[106:107], 0, v[174:175]
	v_cvt_pk_bf16_f32 v100, v100, v101
	v_cvt_pk_bf16_f32 v101, v102, v103
	global_store_dwordx4 v[106:107], v[98:101], off offset:256
	v_pk_mul_f32 v[94:95], v[94:95], v[142:143]
	v_pk_mul_f32 v[96:97], v[96:97], v[144:145]
	v_pk_mul_f32 v[98:99], v[92:93], v[140:141]
	v_pk_mul_f32 v[92:93], v[90:91], v[138:139]
	v_lshlrev_b32_e32 v90, 16, v204
	v_and_b32_e32 v91, 0xffff0000, v204
	v_pk_mul_f32 v[90:91], v[94:95], v[90:91]
	v_lshlrev_b32_e32 v94, 16, v205
	v_and_b32_e32 v95, 0xffff0000, v205
	v_pk_mul_f32 v[94:95], v[96:97], v[94:95]
	v_cvt_pk_bf16_f32 v90, v90, v91
	v_cvt_pk_bf16_f32 v91, v94, v95
	v_lshlrev_b32_e32 v94, 16, v206
	v_and_b32_e32 v95, 0xffff0000, v206
	v_pk_mul_f32 v[92:93], v[92:93], v[94:95]
	v_lshlrev_b32_e32 v94, 16, v207
	v_and_b32_e32 v95, 0xffff0000, v207
	v_pk_mul_f32 v[94:95], v[98:99], v[94:95]
	v_cvt_pk_bf16_f32 v92, v92, v93
	v_cvt_pk_bf16_f32 v93, v94, v95
	v_lshl_add_u64 v[94:95], s[12:13], 0, v[210:211]
	v_lshl_add_u64 v[102:103], v[178:179], 0, s[16:17]
	v_lshl_add_u64 v[94:95], v[94:95], 0, v[174:175]
	v_pk_mul_f32 v[86:87], v[86:87], v[134:135]
	v_lshl_add_u64 v[96:97], v[176:177], 0, v[102:103]
	v_lshlrev_b32_e32 v98, 16, v154
	v_and_b32_e32 v99, 0xffff0000, v154
	global_store_dwordx4 v[94:95], v[90:93], off
	v_pk_mul_f32 v[88:89], v[88:89], v[136:137]
	v_pk_mul_f32 v[86:87], v[86:87], v[98:99]
	v_pk_mul_f32 v[90:91], v[84:85], v[132:133]
	v_pk_mul_f32 v[92:93], v[82:83], v[130:131]
	global_load_dwordx4 v[82:85], v[96:97], off
	v_lshlrev_b32_e32 v98, 16, v155
	v_and_b32_e32 v99, 0xffff0000, v155
	v_pk_mul_f32 v[88:89], v[88:89], v[98:99]
	v_cvt_pk_bf16_f32 v86, v86, v87
	v_cvt_pk_bf16_f32 v87, v88, v89
	v_lshlrev_b32_e32 v88, 16, v156
	v_and_b32_e32 v89, 0xffff0000, v156
	v_pk_mul_f32 v[88:89], v[92:93], v[88:89]
	v_lshlrev_b32_e32 v92, 16, v157
	v_and_b32_e32 v93, 0xffff0000, v157
	v_pk_mul_f32 v[90:91], v[90:91], v[92:93]
	v_cvt_pk_bf16_f32 v88, v88, v89
	v_cvt_pk_bf16_f32 v89, v90, v91
	global_store_dwordx4 v[94:95], v[86:89], off offset:256
	v_pk_mul_f32 v[80:81], v[80:81], v[144:145]
	v_pk_mul_f32 v[90:91], v[76:77], v[140:141]
	v_pk_mul_f32 v[86:87], v[78:79], v[142:143]
	v_lshlrev_b32_e32 v88, 16, v150
	v_and_b32_e32 v89, 0xffff0000, v150
	v_pk_mul_f32 v[86:87], v[86:87], v[88:89]
	v_lshlrev_b32_e32 v88, 16, v151
; #define PG8_GAS __attribute__((address_space(1)))
; __device__ __forceinline__ unsigned cvt_pk_bf16(float lo, float hi) { const f32x2c v = {lo, hi}; return __builtin_bit_cast(unsigned, __builtin_convertvector(v, bf16x2c)); }
; __device__ __forceinline__ float bf_lo(unsigned w) { return __uint_as_float(w << 16); }
; __device__ __forceinline__ float bf_hi(unsigned w) { return __uint_as_float(w & 0xffff0000u); }
;     __device__ __forceinline__ void operator()(const f32x4 (&acc)[2][2][4][2], const Unit& un, int wr, int wc, int fr, int fq) const {
;     ...
;         for (int ai = 0; ai < 2; ++ai) {
;             u32x4 gg[4][2];
; #pragma unroll
;             for (int m = 0; m < 4; ++m)
; #pragma unroll
;                 for (int bj = 0; bj < 2; ++bj) gg[m][bj] = *(const PG8_GAS u32x4*)(sp + (size_t)(row0 + ai * HALF + m * 16) * 4096 + col0 + bj * HALF);
;             asm volatile("" ::: "memory");
; #pragma unroll
;             for (int m = 0; m < 4; ++m)
; #pragma unroll
;                 for (int bj = 0; bj < 2; ++bj) { const u32x4 g = gg[m][bj];
;                     const f32x4 v0 = acc[ai][bj][m][0] * sc[bj][0], v1 = acc[ai][bj][m][1] * sc[bj][1];
;                     u32x4 w; w.x = cvt_pk_bf16(v0[0] * bf_lo(g.x), v0[1] * bf_hi(g.x)); w.y = cvt_pk_bf16(v0[2] * bf_lo(g.y), v0[3] * bf_hi(g.y));
;                     w.z = cvt_pk_bf16(v1[0] * bf_lo(g.z), v1[1] * bf_hi(g.z)); w.w = cvt_pk_bf16(v1[2] * bf_lo(g.w), v1[3] * bf_hi(g.w));
;                     *(PG8_GAS u32x4*)(sp + (size_t)(row0 + ai * HALF + m * 16) * 4096 + col0 + bj * HALF) = w; }
	v_and_b32_e32 v89, 0xffff0000, v151
	global_load_dwordx4 v[76:79], v[96:97], off offset:256
	v_pk_mul_f32 v[80:81], v[80:81], v[88:89]
	v_pk_mul_f32 v[74:75], v[74:75], v[138:139]
	v_cvt_pk_bf16_f32 v86, v86, v87
	v_cvt_pk_bf16_f32 v87, v80, v81
	v_lshlrev_b32_e32 v80, 16, v152
	v_and_b32_e32 v81, 0xffff0000, v152
	v_pk_mul_f32 v[74:75], v[74:75], v[80:81]
	v_lshl_add_u64 v[80:81], v[178:179], 0, s[20:21]
	v_cvt_pk_bf16_f32 v88, v74, v75
	v_lshlrev_b32_e32 v74, 16, v153
	v_and_b32_e32 v75, 0xffff0000, v153
	v_pk_mul_f32 v[74:75], v[90:91], v[74:75]
	v_lshl_add_u64 v[90:91], v[176:177], 0, v[80:81]
	v_cvt_pk_bf16_f32 v89, v74, v75
	v_lshl_add_u64 v[74:75], s[12:13], 0, v[180:181]
	v_lshl_add_u64 v[74:75], v[74:75], 0, v[174:175]
	global_store_dwordx4 v[74:75], v[86:89], off
	global_load_dwordx4 v[86:89], v[90:91], off
	v_pk_mul_f32 v[70:71], v[70:71], v[134:135]
	v_pk_mul_f32 v[92:93], v[68:69], v[132:133]
	v_pk_mul_f32 v[68:69], v[66:67], v[130:131]
	v_lshlrev_b32_e32 v66, 16, v146
	v_and_b32_e32 v67, 0xffff0000, v146
	v_pk_mul_f32 v[72:73], v[72:73], v[136:137]
	v_pk_mul_f32 v[66:67], v[70:71], v[66:67]
	v_lshlrev_b32_e32 v70, 16, v147
	v_and_b32_e32 v71, 0xffff0000, v147
	v_pk_mul_f32 v[70:71], v[72:73], v[70:71]
	v_cvt_pk_bf16_f32 v66, v66, v67
	v_cvt_pk_bf16_f32 v67, v70, v71
	v_lshlrev_b32_e32 v70, 16, v148
	v_and_b32_e32 v71, 0xffff0000, v148
	v_pk_mul_f32 v[68:69], v[68:69], v[70:71]
	v_lshlrev_b32_e32 v70, 16, v149
	v_and_b32_e32 v71, 0xffff0000, v149
	v_pk_mul_f32 v[70:71], v[92:93], v[70:71]
	global_load_dwordx4 v[90:93], v[90:91], off offset:256
	v_cvt_pk_bf16_f32 v114, v126, v127
	v_cvt_pk_bf16_f32 v115, v128, v129
	v_cvt_pk_bf16_f32 v68, v68, v69
	v_cvt_pk_bf16_f32 v69, v70, v71
	v_lshl_add_u64 v[104:105], v[178:179], 0, s[22:23]
	global_store_dwordx4 v[106:107], v[114:117], off
	global_store_dwordx4 v[74:75], v[66:69], off offset:256
	v_lshl_add_u64 v[74:75], v[178:179], 0, s[24:25]
	v_pk_mul_f32 v[62:63], v[62:63], v[142:143]
	v_lshl_add_u64 v[66:67], v[176:177], 0, v[104:105]
	global_load_dwordx4 v[94:97], v[66:67], off
	global_load_dwordx4 v[98:101], v[66:67], off offset:256
	v_lshl_add_u64 v[66:67], v[176:177], 0, v[74:75]
	global_load_dwordx4 v[70:73], v[66:67], off
	s_nop 0
	global_load_dwordx4 v[66:69], v[66:67], off offset:256
	v_pk_mul_f32 v[106:107], v[60:61], v[140:141]
	v_pk_mul_f32 v[60:61], v[58:59], v[138:139]
	v_pk_mul_f32 v[64:65], v[64:65], v[144:145]
	v_pk_mul_f32 v[54:55], v[54:55], v[134:135]
	v_pk_mul_f32 v[56:57], v[56:57], v[136:137]
	s_waitcnt vmcnt(11)
	v_lshlrev_b32_e32 v58, 16, v82
	v_and_b32_e32 v59, 0xffff0000, v82
	v_pk_mul_f32 v[58:59], v[62:63], v[58:59]
	v_lshlrev_b32_e32 v62, 16, v83
	v_and_b32_e32 v63, 0xffff0000, v83
	v_pk_mul_f32 v[62:63], v[64:65], v[62:63]
	v_cvt_pk_bf16_f32 v58, v58, v59
	v_cvt_pk_bf16_f32 v59, v62, v63
	v_lshlrev_b32_e32 v62, 16, v84
	v_and_b32_e32 v63, 0xffff0000, v84
	v_pk_mul_f32 v[60:61], v[60:61], v[62:63]
	v_lshlrev_b32_e32 v62, 16, v85
	v_and_b32_e32 v63, 0xffff0000, v85
	v_pk_mul_f32 v[62:63], v[106:107], v[62:63]
	v_cvt_pk_bf16_f32 v60, v60, v61
	v_cvt_pk_bf16_f32 v61, v62, v63
	v_lshl_add_u64 v[62:63], s[12:13], 0, v[102:103]
	v_lshl_add_u64 v[62:63], v[62:63], 0, v[174:175]
	global_store_dwordx4 v[62:63], v[58:61], off
	v_pk_mul_f32 v[46:47], v[46:47], v[142:143]
	v_pk_mul_f32 v[48:49], v[48:49], v[144:145]
	v_pk_mul_f32 v[58:59], v[52:53], v[132:133]
	v_pk_mul_f32 v[52:53], v[50:51], v[130:131]
	s_waitcnt vmcnt(10)
	v_lshlrev_b32_e32 v50, 16, v76
	v_and_b32_e32 v51, 0xffff0000, v76
	v_pk_mul_f32 v[50:51], v[54:55], v[50:51]
	v_lshlrev_b32_e32 v54, 16, v77
	v_and_b32_e32 v55, 0xffff0000, v77
	v_pk_mul_f32 v[54:55], v[56:57], v[54:55]
	v_cvt_pk_bf16_f32 v50, v50, v51
	v_cvt_pk_bf16_f32 v51, v54, v55
	v_lshlrev_b32_e32 v54, 16, v78
	v_and_b32_e32 v55, 0xffff0000, v78
	v_pk_mul_f32 v[52:53], v[52:53], v[54:55]
	v_lshlrev_b32_e32 v54, 16, v79
	v_and_b32_e32 v55, 0xffff0000, v79
	v_pk_mul_f32 v[54:55], v[58:59], v[54:55]
	v_cvt_pk_bf16_f32 v52, v52, v53
	v_cvt_pk_bf16_f32 v53, v54, v55
	global_store_dwordx4 v[62:63], v[50:53], off offset:256
	v_pk_mul_f32 v[38:39], v[38:39], v[134:135]
	v_pk_mul_f32 v[40:41], v[40:41], v[136:137]
	v_pk_mul_f32 v[50:51], v[44:45], v[140:141]
	v_pk_mul_f32 v[44:45], v[42:43], v[138:139]
	s_waitcnt vmcnt(9)
; #define PG8_GAS __attribute__((address_space(1)))
; __device__ __forceinline__ unsigned cvt_pk_bf16(float lo, float hi) { const f32x2c v = {lo, hi}; return __builtin_bit_cast(unsigned, __builtin_convertvector(v, bf16x2c)); }
; __device__ __forceinline__ float bf_lo(unsigned w) { return __uint_as_float(w << 16); }
; __device__ __forceinline__ float bf_hi(unsigned w) { return __uint_as_float(w & 0xffff0000u); }
; #define PG8_WAIT_V(n) asm volatile("s_waitcnt vmcnt(" #n ")" ::: "memory")
; #define PG8_BAR __builtin_amdgcn_s_barrier()
;     __device__ __forceinline__ void operator()(const f32x4 (&acc)[2][2][4][2], const Unit& un, int wr, int wc, int fr, int fq) const {
;     ...
;             for (int m = 0; m < 4; ++m)
; #pragma unroll
;                 for (int bj = 0; bj < 2; ++bj) { const u32x4 g = gg[m][bj];
;                     const f32x4 v0 = acc[ai][bj][m][0] * sc[bj][0], v1 = acc[ai][bj][m][1] * sc[bj][1];
;                     u32x4 w; w.x = cvt_pk_bf16(v0[0] * bf_lo(g.x), v0[1] * bf_hi(g.x)); w.y = cvt_pk_bf16(v0[2] * bf_lo(g.y), v0[3] * bf_hi(g.y));
;                     w.z = cvt_pk_bf16(v1[0] * bf_lo(g.z), v1[1] * bf_hi(g.z)); w.w = cvt_pk_bf16(v1[2] * bf_lo(g.w), v1[3] * bf_hi(g.w));
;                     *(PG8_GAS u32x4*)(sp + (size_t)(row0 + ai * HALF + m * 16) * 4096 + col0 + bj * HALF) = w; }
; template <class Epi, class Sched, bool ALIGN_EPI = false, bool SP2 = false, bool F8 = false>
; __device__ __forceinline__ void gemm_phase(PG8_LAS unsigned char* lds, const Gemm g, const Sched& S, const Epi& E) {
;     ...
;     PG8_WAIT_V(0);
;     if constexpr (!ALIGN_EPI) { if (wr == 0) PG8_BAR; }
;     PG8_BAR;
	v_lshlrev_b32_e32 v42, 16, v86
	v_and_b32_e32 v43, 0xffff0000, v86
	v_pk_mul_f32 v[42:43], v[46:47], v[42:43]
	v_lshlrev_b32_e32 v46, 16, v87
	v_and_b32_e32 v47, 0xffff0000, v87
	v_pk_mul_f32 v[46:47], v[48:49], v[46:47]
	v_cvt_pk_bf16_f32 v42, v42, v43
	v_cvt_pk_bf16_f32 v43, v46, v47
	v_lshlrev_b32_e32 v46, 16, v88
	v_and_b32_e32 v47, 0xffff0000, v88
	v_pk_mul_f32 v[44:45], v[44:45], v[46:47]
	v_lshlrev_b32_e32 v46, 16, v89
	v_and_b32_e32 v47, 0xffff0000, v89
	v_pk_mul_f32 v[46:47], v[50:51], v[46:47]
	v_cvt_pk_bf16_f32 v44, v44, v45
	v_cvt_pk_bf16_f32 v45, v46, v47
	v_lshl_add_u64 v[46:47], s[12:13], 0, v[80:81]
	v_lshl_add_u64 v[46:47], v[46:47], 0, v[174:175]
	global_store_dwordx4 v[46:47], v[42:45], off
	v_pk_mul_f32 v[30:31], v[30:31], v[142:143]
	v_pk_mul_f32 v[32:33], v[32:33], v[144:145]
	v_pk_mul_f32 v[42:43], v[36:37], v[132:133]
	v_pk_mul_f32 v[36:37], v[34:35], v[130:131]
	s_waitcnt vmcnt(9)
	v_lshlrev_b32_e32 v34, 16, v90
	v_and_b32_e32 v35, 0xffff0000, v90
	v_pk_mul_f32 v[34:35], v[38:39], v[34:35]
	v_lshlrev_b32_e32 v38, 16, v91
	v_and_b32_e32 v39, 0xffff0000, v91
	v_pk_mul_f32 v[38:39], v[40:41], v[38:39]
	v_cvt_pk_bf16_f32 v34, v34, v35
	v_cvt_pk_bf16_f32 v35, v38, v39
	v_lshlrev_b32_e32 v38, 16, v92
	v_and_b32_e32 v39, 0xffff0000, v92
	v_pk_mul_f32 v[36:37], v[36:37], v[38:39]
	v_lshlrev_b32_e32 v38, 16, v93
	v_and_b32_e32 v39, 0xffff0000, v93
	v_pk_mul_f32 v[38:39], v[42:43], v[38:39]
	v_cvt_pk_bf16_f32 v36, v36, v37
	v_cvt_pk_bf16_f32 v37, v38, v39
	global_store_dwordx4 v[46:47], v[34:37], off offset:256
	v_pk_mul_f32 v[22:23], v[22:23], v[134:135]
	v_pk_mul_f32 v[24:25], v[24:25], v[136:137]
	v_pk_mul_f32 v[34:35], v[28:29], v[140:141]
	v_pk_mul_f32 v[28:29], v[26:27], v[138:139]
	s_waitcnt vmcnt(7)
	v_lshlrev_b32_e32 v26, 16, v94
	v_and_b32_e32 v27, 0xffff0000, v94
	v_pk_mul_f32 v[26:27], v[30:31], v[26:27]
	v_lshlrev_b32_e32 v30, 16, v95
	v_and_b32_e32 v31, 0xffff0000, v95
	v_pk_mul_f32 v[30:31], v[32:33], v[30:31]
	v_cvt_pk_bf16_f32 v26, v26, v27
	v_cvt_pk_bf16_f32 v27, v30, v31
	v_lshlrev_b32_e32 v30, 16, v96
	v_and_b32_e32 v31, 0xffff0000, v96
	v_pk_mul_f32 v[28:29], v[28:29], v[30:31]
	v_lshlrev_b32_e32 v30, 16, v97
	v_and_b32_e32 v31, 0xffff0000, v97
	v_pk_mul_f32 v[30:31], v[34:35], v[30:31]
	v_cvt_pk_bf16_f32 v28, v28, v29
	v_cvt_pk_bf16_f32 v29, v30, v31
	v_lshl_add_u64 v[30:31], s[12:13], 0, v[104:105]
	v_lshl_add_u64 v[30:31], v[30:31], 0, v[174:175]
	global_store_dwordx4 v[30:31], v[26:29], off
	v_pk_mul_f32 v[14:15], v[14:15], v[142:143]
	v_pk_mul_f32 v[16:17], v[16:17], v[144:145]
	v_pk_mul_f32 v[26:27], v[20:21], v[132:133]
	v_pk_mul_f32 v[20:21], v[18:19], v[130:131]
	s_waitcnt vmcnt(7)
	v_lshlrev_b32_e32 v18, 16, v98
	v_and_b32_e32 v19, 0xffff0000, v98
	v_pk_mul_f32 v[18:19], v[22:23], v[18:19]
	v_lshlrev_b32_e32 v22, 16, v99
	v_and_b32_e32 v23, 0xffff0000, v99
	v_pk_mul_f32 v[22:23], v[24:25], v[22:23]
	v_cvt_pk_bf16_f32 v18, v18, v19
	v_cvt_pk_bf16_f32 v19, v22, v23
	v_lshlrev_b32_e32 v22, 16, v100
	v_and_b32_e32 v23, 0xffff0000, v100
	v_pk_mul_f32 v[20:21], v[20:21], v[22:23]
	v_lshlrev_b32_e32 v22, 16, v101
	v_and_b32_e32 v23, 0xffff0000, v101
	v_pk_mul_f32 v[22:23], v[26:27], v[22:23]
	v_cvt_pk_bf16_f32 v20, v20, v21
	v_cvt_pk_bf16_f32 v21, v22, v23
	global_store_dwordx4 v[30:31], v[18:21], off offset:256
	v_pk_mul_f32 v[6:7], v[6:7], v[134:135]
	v_pk_mul_f32 v[8:9], v[8:9], v[136:137]
	v_pk_mul_f32 v[18:19], v[12:13], v[140:141]
	v_pk_mul_f32 v[12:13], v[10:11], v[138:139]
	s_waitcnt vmcnt(7)
	v_lshlrev_b32_e32 v10, 16, v70
	v_and_b32_e32 v11, 0xffff0000, v70
	v_pk_mul_f32 v[10:11], v[14:15], v[10:11]
	v_lshlrev_b32_e32 v14, 16, v71
	v_and_b32_e32 v15, 0xffff0000, v71
	v_pk_mul_f32 v[14:15], v[16:17], v[14:15]
	v_cvt_pk_bf16_f32 v10, v10, v11
	v_cvt_pk_bf16_f32 v11, v14, v15
	v_lshlrev_b32_e32 v14, 16, v72
	v_and_b32_e32 v15, 0xffff0000, v72
	v_pk_mul_f32 v[12:13], v[12:13], v[14:15]
	v_lshlrev_b32_e32 v14, 16, v73
	v_and_b32_e32 v15, 0xffff0000, v73
	v_pk_mul_f32 v[14:15], v[18:19], v[14:15]
	v_cvt_pk_bf16_f32 v12, v12, v13
	v_cvt_pk_bf16_f32 v13, v14, v15
	v_lshl_add_u64 v[14:15], s[12:13], 0, v[74:75]
	v_lshl_add_u64 v[14:15], v[14:15], 0, v[174:175]
	global_store_dwordx4 v[14:15], v[10:13], off
	s_nop 1
	v_pk_mul_f32 v[10:11], v[4:5], v[132:133]
	v_pk_mul_f32 v[4:5], v[2:3], v[130:131]
	s_waitcnt vmcnt(7)
	v_lshlrev_b32_e32 v2, 16, v66
	v_and_b32_e32 v3, 0xffff0000, v66
	v_pk_mul_f32 v[2:3], v[6:7], v[2:3]
	v_lshlrev_b32_e32 v6, 16, v67
	v_and_b32_e32 v7, 0xffff0000, v67
	v_pk_mul_f32 v[6:7], v[8:9], v[6:7]
	v_cvt_pk_bf16_f32 v2, v2, v3
	v_cvt_pk_bf16_f32 v3, v6, v7
	v_lshlrev_b32_e32 v6, 16, v68
	v_and_b32_e32 v7, 0xffff0000, v68
	v_pk_mul_f32 v[4:5], v[4:5], v[6:7]
	v_lshlrev_b32_e32 v6, 16, v69
	v_and_b32_e32 v7, 0xffff0000, v69
	v_pk_mul_f32 v[6:7], v[10:11], v[6:7]
	v_cvt_pk_bf16_f32 v4, v4, v5
	v_cvt_pk_bf16_f32 v5, v6, v7
	global_store_dwordx4 v[14:15], v[2:5], off offset:256
	s_cbranch_vccz .LBB0_615
	s_waitcnt vmcnt(0)
	s_cmpk_gt_u32 s4, 0xff
	s_cbranch_scc1 .LBB0_622
	s_barrier

; #define PG8_STAGE(bufoff, gbase, voff) do { _Pragma("unroll") for (int _i = 0; _i < 2; ++_i) \
;         __builtin_amdgcn_global_load_lds((const unsigned*)((const char*)(gbase) + (voff)[_i]), (PG8_LAS unsigned*)(lds + (bufoff) + ldsw + _i * 8192), 16, 0, 0); } while (0)
; #define PG8_LDA(dst, b, h) do { _Pragma("unroll") for (int m = 0; m < 4; ++m) _Pragma("unroll") for (int k = 0; k < 2; ++k) dst[m][k] = *(const PG8_LAS bf16x8*)(lds + PG8_SA(b, h) + aoff + m * 2048 + k * 1024); } while (0)
; #define PG8_LDB(dst, b, h) do { _Pragma("unroll") for (int n = 0; n < 2; ++n) _Pragma("unroll") for (int k = 0; k < 2; ++k) dst[n][k] = *(const PG8_LAS bf16x8*)(lds + PG8_SB(b, h) + boff + n * 2048 + k * 1024); } while (0)
; #define PG8_WAIT_V(n) asm volatile("s_waitcnt vmcnt(" #n ")" ::: "memory")
; #define PG8_WAIT_L(n) asm volatile("s_waitcnt lgkmcnt(" #n ")" ::: "memory")
; #define PG8_BAR __builtin_amdgcn_s_barrier()
; #define PG8_SCHED __builtin_amdgcn_sched_barrier(0)
; template <class Epi, class Sched, bool ALIGN_EPI = false, bool SP2 = false, bool F8 = false>
; __device__ __forceinline__ void gemm_phase(PG8_LAS unsigned char* lds, const Gemm g, const Sched& S, const Epi& E) {
;     ...
;             PG8_LDB(B0, 0, 0); PG8_LDB(B1, 0, 1); PG8_SCHED; PG8_LDA(At, 0, 0); PG8_STAGE(PG8_SA(1, 1), a1 + hA, voffA);
;             PG8_WAIT_V(8); PG8_WAIT_L(0); PG8_BAR; PG8_MMA(0, 0, At, B0); PG8_MMA(0, 1, At, B1); PG8_BAR; PG8_SCHED;
;             PG8_LDA(At, 0, 1); PG8_STAGE(PG8_SB(0, 0), b2, voffB); PG8_STAGE(PG8_SB(0, 1), b2 + hB, voffB); PG8_STAGE(PG8_SA(0, 0), a2, voffA);
;             PG8_WAIT_V(8); PG8_WAIT_L(0); PG8_BAR; PG8_MMA(1, 0, At, B0); PG8_MMA(1, 1, At, B1); PG8_BAR; PG8_SCHED;
.LBB0_630:
	ds_read_b128 v[26:29], v190
	ds_read_b128 v[30:33], v190 offset:1024
	ds_read_b128 v[18:21], v190 offset:2048
	ds_read_b128 v[22:25], v190 offset:3072
	ds_read_b128 v[10:13], v191
	ds_read_b128 v[14:17], v191 offset:1024
	ds_read_b128 v[2:5], v191 offset:2048
	ds_read_b128 v[6:9], v191 offset:3072
	s_add_u32 s30, s28, 0xfffc0080
	s_addc_u32 s31, s29, -1
	s_cmp_eq_u32 s51, 12
	s_cselect_b32 s35, s21, s31
	s_cselect_b32 s34, s47, s30
	s_cselect_b32 s31, s17, s50
	s_cselect_b32 s30, s48, s49
	v_lshl_add_u64 v[218:219], s[28:29], 0, v[172:173]
	s_add_i32 m0, s27, 0xc000
	ds_read_b128 v[178:181], v192
	ds_read_b128 v[182:185], v192 offset:1024
	ds_read_b128 v[194:197], v192 offset:2048
	ds_read_b128 v[198:201], v192 offset:3072
	ds_read_b128 v[202:205], v192 offset:4096
	ds_read_b128 v[206:209], v192 offset:5120
	ds_read_b128 v[210:213], v192 offset:6144
	ds_read_b128 v[214:217], v192 offset:7168
	global_load_lds_dwordx4 v[218:219], off
	v_lshl_add_u64 v[218:219], s[28:29], 0, v[170:171]
	s_add_i32 m0, s27, 0xe000
	s_nop 0
	global_load_lds_dwordx4 v[218:219], off
	s_waitcnt vmcnt(8)
	s_waitcnt lgkmcnt(0)
	s_barrier
	v_mfma_scale_f32_16x16x128_f8f6f4 v[158:161], v[26:33], v[178:185], v[158:161], v186, v186 op_sel_hi:[0,0,0]
	v_mfma_scale_f32_16x16x128_f8f6f4 v[154:157], v[18:25], v[178:185], v[154:157], v186, v186 op_sel_hi:[0,0,0]
	v_mfma_scale_f32_16x16x128_f8f6f4 v[146:149], v[26:33], v[194:201], v[146:149], v186, v186 op_sel_hi:[0,0,0]
	v_mfma_scale_f32_16x16x128_f8f6f4 v[138:141], v[18:25], v[194:201], v[138:141], v186, v186 op_sel_hi:[0,0,0]
	v_mfma_scale_f32_16x16x128_f8f6f4 v[130:133], v[26:33], v[202:209], v[130:133], v186, v186 op_sel_hi:[0,0,0]
	v_mfma_scale_f32_16x16x128_f8f6f4 v[122:125], v[18:25], v[202:209], v[122:125], v186, v186 op_sel_hi:[0,0,0]
	v_mfma_scale_f32_16x16x128_f8f6f4 v[114:117], v[26:33], v[210:217], v[114:117], v186, v186 op_sel_hi:[0,0,0]
	v_mfma_scale_f32_16x16x128_f8f6f4 v[106:109], v[18:25], v[210:217], v[106:109], v186, v186 op_sel_hi:[0,0,0]
	v_mfma_scale_f32_16x16x128_f8f6f4 v[150:153], v[10:17], v[178:185], v[150:153], v186, v186 op_sel_hi:[0,0,0]
	v_mfma_scale_f32_16x16x128_f8f6f4 v[142:145], v[2:9], v[178:185], v[142:145], v186, v186 op_sel_hi:[0,0,0]
	v_mfma_scale_f32_16x16x128_f8f6f4 v[134:137], v[10:17], v[194:201], v[134:137], v186, v186 op_sel_hi:[0,0,0]
	v_mfma_scale_f32_16x16x128_f8f6f4 v[126:129], v[2:9], v[194:201], v[126:129], v186, v186 op_sel_hi:[0,0,0]
	v_mfma_scale_f32_16x16x128_f8f6f4 v[118:121], v[10:17], v[202:209], v[118:121], v186, v186 op_sel_hi:[0,0,0]
	v_mfma_scale_f32_16x16x128_f8f6f4 v[110:113], v[2:9], v[202:209], v[110:113], v186, v186 op_sel_hi:[0,0,0]
	v_mfma_scale_f32_16x16x128_f8f6f4 v[102:105], v[10:17], v[210:217], v[102:105], v186, v186 op_sel_hi:[0,0,0]
	v_mfma_scale_f32_16x16x128_f8f6f4 v[98:101], v[2:9], v[210:217], v[98:101], v186, v186 op_sel_hi:[0,0,0]
	s_barrier
	s_add_i32 s52, s44, s19
	v_lshl_add_u64 v[178:179], s[30:31], 0, v[166:167]
	s_mov_b32 m0, s52
	ds_read_b128 v[194:197], v192 offset:16384
	ds_read_b128 v[198:201], v192 offset:17408
	ds_read_b128 v[202:205], v192 offset:18432
	ds_read_b128 v[206:209], v192 offset:19456
	ds_read_b128 v[210:213], v192 offset:20480
	ds_read_b128 v[214:217], v192 offset:21504
	ds_read_b128 v[218:221], v192 offset:22528
	ds_read_b128 v[222:225], v192 offset:23552
	global_load_lds_dwordx4 v[178:179], off
	s_add_i32 m0, s52, 0x2000
	s_add_u32 s52, s30, 0x40000
	v_lshl_add_u64 v[180:181], s[30:31], 0, v[162:163]
	s_addc_u32 s53, s31, 0
	s_add_i32 s54, s45, s19
	global_load_lds_dwordx4 v[180:181], off
	v_lshl_add_u64 v[182:183], s[52:53], 0, v[166:167]
	s_mov_b32 m0, s54
	v_lshl_add_u64 v[184:185], s[34:35], 0, v[164:165]
	global_load_lds_dwordx4 v[182:183], off
	v_lshl_add_u64 v[182:183], s[52:53], 0, v[162:163]
	s_add_i32 m0, s54, 0x2000
	s_nop 0
	global_load_lds_dwordx4 v[182:183], off
	v_lshl_add_u64 v[182:183], s[34:35], 0, v[168:169]
	s_mov_b32 m0, s27
	s_nop 0
	global_load_lds_dwordx4 v[182:183], off
	s_mov_b32 m0, s37
	s_nop 0
	global_load_lds_dwordx4 v[184:185], off
	s_waitcnt vmcnt(8)
	s_waitcnt lgkmcnt(0)
	s_barrier
	v_mfma_scale_f32_16x16x128_f8f6f4 v[94:97], v[26:33], v[194:201], v[94:97], v186, v186 op_sel_hi:[0,0,0]
	v_mfma_scale_f32_16x16x128_f8f6f4 v[90:93], v[18:25], v[194:201], v[90:93], v186, v186 op_sel_hi:[0,0,0]
	v_mfma_scale_f32_16x16x128_f8f6f4 v[82:85], v[26:33], v[202:209], v[82:85], v186, v186 op_sel_hi:[0,0,0]
	v_mfma_scale_f32_16x16x128_f8f6f4 v[74:77], v[18:25], v[202:209], v[74:77], v186, v186 op_sel_hi:[0,0,0]
	v_mfma_scale_f32_16x16x128_f8f6f4 v[66:69], v[26:33], v[210:217], v[66:69], v186, v186 op_sel_hi:[0,0,0]
	v_mfma_scale_f32_16x16x128_f8f6f4 v[58:61], v[18:25], v[210:217], v[58:61], v186, v186 op_sel_hi:[0,0,0]
	v_mfma_scale_f32_16x16x128_f8f6f4 v[50:53], v[26:33], v[218:225], v[50:53], v186, v186 op_sel_hi:[0,0,0]
	v_mfma_scale_f32_16x16x128_f8f6f4 v[42:45], v[18:25], v[218:225], v[42:45], v186, v186 op_sel_hi:[0,0,0]
	v_mfma_scale_f32_16x16x128_f8f6f4 v[86:89], v[10:17], v[194:201], v[86:89], v186, v186 op_sel_hi:[0,0,0]
	v_mfma_scale_f32_16x16x128_f8f6f4 v[78:81], v[2:9], v[194:201], v[78:81], v186, v186 op_sel_hi:[0,0,0]
	v_mfma_scale_f32_16x16x128_f8f6f4 v[70:73], v[10:17], v[202:209], v[70:73], v186, v186 op_sel_hi:[0,0,0]
	v_mfma_scale_f32_16x16x128_f8f6f4 v[62:65], v[2:9], v[202:209], v[62:65], v186, v186 op_sel_hi:[0,0,0]
	v_mfma_scale_f32_16x16x128_f8f6f4 v[54:57], v[10:17], v[210:217], v[54:57], v186, v186 op_sel_hi:[0,0,0]
	v_mfma_scale_f32_16x16x128_f8f6f4 v[46:49], v[2:9], v[210:217], v[46:49], v186, v186 op_sel_hi:[0,0,0]
	v_mfma_scale_f32_16x16x128_f8f6f4 v[38:41], v[10:17], v[218:225], v[38:41], v186, v186 op_sel_hi:[0,0,0]
	v_mfma_scale_f32_16x16x128_f8f6f4 v[34:37], v[2:9], v[218:225], v[34:37], v186, v186 op_sel_hi:[0,0,0]
	s_barrier
; #define PG8_STAGE(bufoff, gbase, voff) do { _Pragma("unroll") for (int _i = 0; _i < 2; ++_i) \
;         __builtin_amdgcn_global_load_lds((const unsigned*)((const char*)(gbase) + (voff)[_i]), (PG8_LAS unsigned*)(lds + (bufoff) + ldsw + _i * 8192), 16, 0, 0); } while (0)
; #define PG8_LDA(dst, b, h) do { _Pragma("unroll") for (int m = 0; m < 4; ++m) _Pragma("unroll") for (int k = 0; k < 2; ++k) dst[m][k] = *(const PG8_LAS bf16x8*)(lds + PG8_SA(b, h) + aoff + m * 2048 + k * 1024); } while (0)
; #define PG8_LDB(dst, b, h) do { _Pragma("unroll") for (int n = 0; n < 2; ++n) _Pragma("unroll") for (int k = 0; k < 2; ++k) dst[n][k] = *(const PG8_LAS bf16x8*)(lds + PG8_SB(b, h) + boff + n * 2048 + k * 1024); } while (0)
; #define PG8_WAIT_V(n) asm volatile("s_waitcnt vmcnt(" #n ")" ::: "memory")
; #define PG8_WAIT_L(n) asm volatile("s_waitcnt lgkmcnt(" #n ")" ::: "memory")
; #define PG8_BAR __builtin_amdgcn_s_barrier()
; #define PG8_SCHED __builtin_amdgcn_sched_barrier(0)
; template <class Epi, class Sched, bool ALIGN_EPI = false, bool SP2 = false, bool F8 = false>
; __device__ __forceinline__ void gemm_phase(PG8_LAS unsigned char* lds, const Gemm g, const Sched& S, const Epi& E) {
;     ...
;             PG8_LDB(B0, 1, 0); PG8_LDB(B1, 1, 1); PG8_SCHED; PG8_LDA(At, 1, 0); PG8_STAGE(PG8_SA(0, 1), a2 + hA, voffA);
;             PG8_WAIT_V(8); PG8_WAIT_L(0); PG8_BAR; PG8_MMA(0, 0, At, B0); PG8_MMA(0, 1, At, B1); PG8_BAR; PG8_SCHED;
;             PG8_LDA(At, 1, 1); PG8_STAGE(PG8_SB(1, 0), b3, voffB); PG8_STAGE(PG8_SB(1, 1), b3 + hB, voffB); PG8_STAGE(PG8_SA(1, 0), a3, voffA);
;             PG8_WAIT_V(8); PG8_WAIT_L(0); PG8_BAR; PG8_MMA(1, 0, At, B0); PG8_MMA(1, 1, At, B1); PG8_BAR; PG8_SCHED;
	s_add_i32 s52, 0, 0x18000
	s_add_i32 s53, 0, 0x1c000
	v_add_u32_e32 v14, s52, v188
	v_add_u32_e32 v30, s53, v188
	ds_read_b128 v[2:5], v14
	ds_read_b128 v[6:9], v14 offset:1024
	ds_read_b128 v[10:13], v14 offset:2048
	ds_read_b128 v[14:17], v14 offset:3072
	ds_read_b128 v[18:21], v30
	ds_read_b128 v[22:25], v30 offset:1024
	ds_read_b128 v[26:29], v30 offset:2048
	ds_read_b128 v[30:33], v30 offset:3072
	s_add_u32 s34, s34, 0x40000
	s_addc_u32 s35, s35, 0
	s_mov_b32 m0, s38
	v_lshl_add_u64 v[226:227], s[34:35], 0, v[168:169]
	ds_read_b128 v[194:197], v192 offset:32768
	ds_read_b128 v[198:201], v192 offset:33792
	ds_read_b128 v[202:205], v192 offset:34816
	ds_read_b128 v[206:209], v192 offset:35840
	ds_read_b128 v[210:213], v192 offset:36864
	ds_read_b128 v[214:217], v192 offset:37888
	ds_read_b128 v[218:221], v192 offset:38912
	ds_read_b128 v[222:225], v192 offset:39936
	global_load_lds_dwordx4 v[226:227], off
	v_lshl_add_u64 v[226:227], s[34:35], 0, v[164:165]
	s_mov_b32 m0, s39
	s_nop 0
	global_load_lds_dwordx4 v[226:227], off
	s_waitcnt vmcnt(8)
	s_waitcnt lgkmcnt(0)
	s_barrier
	v_mfma_scale_f32_16x16x128_f8f6f4 v[158:161], v[2:9], v[194:201], v[158:161], v186, v186 op_sel_hi:[0,0,0]
	v_mfma_scale_f32_16x16x128_f8f6f4 v[154:157], v[10:17], v[194:201], v[154:157], v186, v186 op_sel_hi:[0,0,0]
	v_mfma_scale_f32_16x16x128_f8f6f4 v[146:149], v[2:9], v[202:209], v[146:149], v186, v186 op_sel_hi:[0,0,0]
	v_mfma_scale_f32_16x16x128_f8f6f4 v[138:141], v[10:17], v[202:209], v[138:141], v186, v186 op_sel_hi:[0,0,0]
	v_mfma_scale_f32_16x16x128_f8f6f4 v[130:133], v[2:9], v[210:217], v[130:133], v186, v186 op_sel_hi:[0,0,0]
	v_mfma_scale_f32_16x16x128_f8f6f4 v[122:125], v[10:17], v[210:217], v[122:125], v186, v186 op_sel_hi:[0,0,0]
	v_mfma_scale_f32_16x16x128_f8f6f4 v[114:117], v[2:9], v[218:225], v[114:117], v186, v186 op_sel_hi:[0,0,0]
	v_mfma_scale_f32_16x16x128_f8f6f4 v[106:109], v[10:17], v[218:225], v[106:109], v186, v186 op_sel_hi:[0,0,0]
	v_mfma_scale_f32_16x16x128_f8f6f4 v[150:153], v[18:25], v[194:201], v[150:153], v186, v186 op_sel_hi:[0,0,0]
	v_mfma_scale_f32_16x16x128_f8f6f4 v[142:145], v[26:33], v[194:201], v[142:145], v186, v186 op_sel_hi:[0,0,0]
	v_mfma_scale_f32_16x16x128_f8f6f4 v[134:137], v[18:25], v[202:209], v[134:137], v186, v186 op_sel_hi:[0,0,0]
	v_mfma_scale_f32_16x16x128_f8f6f4 v[126:129], v[26:33], v[202:209], v[126:129], v186, v186 op_sel_hi:[0,0,0]
	v_mfma_scale_f32_16x16x128_f8f6f4 v[118:121], v[18:25], v[210:217], v[118:121], v186, v186 op_sel_hi:[0,0,0]
	v_mfma_scale_f32_16x16x128_f8f6f4 v[110:113], v[26:33], v[210:217], v[110:113], v186, v186 op_sel_hi:[0,0,0]
	v_mfma_scale_f32_16x16x128_f8f6f4 v[102:105], v[18:25], v[218:225], v[102:105], v186, v186 op_sel_hi:[0,0,0]
	v_mfma_scale_f32_16x16x128_f8f6f4 v[98:101], v[26:33], v[218:225], v[98:101], v186, v186 op_sel_hi:[0,0,0]
	s_barrier
	s_add_i32 s34, s52, s19
	v_lshl_add_u64 v[178:179], v[178:179], 0, s[14:15]
	s_mov_b32 m0, s34
	ds_read_b128 v[194:197], v192 offset:49152
	ds_read_b128 v[198:201], v192 offset:50176
	ds_read_b128 v[202:205], v192 offset:51200
	ds_read_b128 v[206:209], v192 offset:52224
	ds_read_b128 v[210:213], v192 offset:53248
	ds_read_b128 v[214:217], v192 offset:54272
	ds_read_b128 v[218:221], v192 offset:55296
	ds_read_b128 v[222:225], v192 offset:56320
	global_load_lds_dwordx4 v[178:179], off
	s_add_i32 m0, s34, 0x2000
	s_add_u32 s30, s30, 0x40080
	v_lshl_add_u64 v[178:179], v[180:181], 0, s[14:15]
	s_addc_u32 s31, s31, 0
	s_add_i32 s34, s53, s19
	global_load_lds_dwordx4 v[178:179], off
	v_lshl_add_u64 v[178:179], s[30:31], 0, v[166:167]
	s_mov_b32 m0, s34
	s_nop 0
	global_load_lds_dwordx4 v[178:179], off
	v_lshl_add_u64 v[178:179], s[30:31], 0, v[162:163]
	s_add_i32 m0, s34, 0x2000
	s_nop 0
	global_load_lds_dwordx4 v[178:179], off
	v_lshl_add_u64 v[178:179], v[182:183], 0, s[14:15]
	s_mov_b32 m0, s41
	s_nop 0
	global_load_lds_dwordx4 v[178:179], off
	v_lshl_add_u64 v[178:179], v[184:185], 0, s[14:15]
	s_mov_b32 m0, s42
	s_nop 0
	global_load_lds_dwordx4 v[178:179], off
	s_waitcnt vmcnt(8)
	s_waitcnt lgkmcnt(0)
	s_barrier
	v_mfma_scale_f32_16x16x128_f8f6f4 v[94:97], v[2:9], v[194:201], v[94:97], v186, v186 op_sel_hi:[0,0,0]
	v_mfma_scale_f32_16x16x128_f8f6f4 v[90:93], v[10:17], v[194:201], v[90:93], v186, v186 op_sel_hi:[0,0,0]
	v_mfma_scale_f32_16x16x128_f8f6f4 v[82:85], v[2:9], v[202:209], v[82:85], v186, v186 op_sel_hi:[0,0,0]
	v_mfma_scale_f32_16x16x128_f8f6f4 v[74:77], v[10:17], v[202:209], v[74:77], v186, v186 op_sel_hi:[0,0,0]
	v_mfma_scale_f32_16x16x128_f8f6f4 v[66:69], v[2:9], v[210:217], v[66:69], v186, v186 op_sel_hi:[0,0,0]
	v_mfma_scale_f32_16x16x128_f8f6f4 v[58:61], v[10:17], v[210:217], v[58:61], v186, v186 op_sel_hi:[0,0,0]
	v_mfma_scale_f32_16x16x128_f8f6f4 v[50:53], v[2:9], v[218:225], v[50:53], v186, v186 op_sel_hi:[0,0,0]
	v_mfma_scale_f32_16x16x128_f8f6f4 v[42:45], v[10:17], v[218:225], v[42:45], v186, v186 op_sel_hi:[0,0,0]
	v_mfma_scale_f32_16x16x128_f8f6f4 v[86:89], v[18:25], v[194:201], v[86:89], v186, v186 op_sel_hi:[0,0,0]
	v_mfma_scale_f32_16x16x128_f8f6f4 v[78:81], v[26:33], v[194:201], v[78:81], v186, v186 op_sel_hi:[0,0,0]
	v_mfma_scale_f32_16x16x128_f8f6f4 v[70:73], v[18:25], v[202:209], v[70:73], v186, v186 op_sel_hi:[0,0,0]
	v_mfma_scale_f32_16x16x128_f8f6f4 v[62:65], v[26:33], v[202:209], v[62:65], v186, v186 op_sel_hi:[0,0,0]
	v_mfma_scale_f32_16x16x128_f8f6f4 v[54:57], v[18:25], v[210:217], v[54:57], v186, v186 op_sel_hi:[0,0,0]
	v_mfma_scale_f32_16x16x128_f8f6f4 v[46:49], v[26:33], v[210:217], v[46:49], v186, v186 op_sel_hi:[0,0,0]
	v_mfma_scale_f32_16x16x128_f8f6f4 v[38:41], v[18:25], v[218:225], v[38:41], v186, v186 op_sel_hi:[0,0,0]
	v_mfma_scale_f32_16x16x128_f8f6f4 v[34:37], v[26:33], v[218:225], v[34:37], v186, v186 op_sel_hi:[0,0,0]
	s_barrier
; #define PG8_GAS __attribute__((address_space(1)))
; __device__ __forceinline__ unsigned cvt_pk_bf16(float lo, float hi) { const f32x2c v = {lo, hi}; return __builtin_bit_cast(unsigned, __builtin_convertvector(v, bf16x2c)); }
; __device__ __forceinline__ float bf_lo(unsigned w) { return __uint_as_float(w << 16); }
; __device__ __forceinline__ float bf_hi(unsigned w) { return __uint_as_float(w & 0xffff0000u); }
;     __device__ __forceinline__ void operator()(const f32x4 (&acc)[2][2][4][2], const Unit& un, int wr, int wc, int fr, int fq) const {
;         const int row0 = un.pm * BM + wr * 64 + fr, col0 = un.pn * BM + wc * 32 + 8 * fq;
; #pragma unroll
;         for (int ai = 0; ai < 2; ++ai) {
;             u32x4 gg[4][2], pp[4][2];
; #pragma unroll
;             for (int m = 0; m < 4; ++m)
; #pragma unroll
;                 for (int bj = 0; bj < 2; ++bj) { const size_t off = (size_t)(row0 + ai * HALF + m * 16) * 4096 + col0 + bj * HALF; gg[m][bj] = *(const PG8_GAS u32x4*)(sa + off); pp[m][bj] = *(const PG8_GAS u32x4*)(P + off); }
;             asm volatile("" ::: "memory");
; #pragma unroll
;             for (int m = 0; m < 4; ++m)
; #pragma unroll
;                 for (int bj = 0; bj < 2; ++bj) { const u32x4 g = gg[m][bj], p = pp[m][bj]; const f32x4 v0 = acc[ai][bj][m][0], v1 = acc[ai][bj][m][1];
;                     u32x4 w; w.x = cvt_pk_bf16(v0[0] * bf_lo(g.x) + bf_lo(p.x), v0[1] * bf_hi(g.x) + bf_hi(p.x)); w.y = cvt_pk_bf16(v0[2] * bf_lo(g.y) + bf_lo(p.y), v0[3] * bf_hi(g.y) + bf_hi(p.y));
;                     w.z = cvt_pk_bf16(v1[0] * bf_lo(g.z) + bf_lo(p.z), v1[1] * bf_hi(g.z) + bf_hi(p.z)); w.w = cvt_pk_bf16(v1[2] * bf_lo(g.w) + bf_lo(p.w), v1[3] * bf_hi(g.w) + bf_hi(p.w));
;                     *(PG8_GAS u32x4*)(sa + (size_t)(row0 + ai * HALF + m * 16) * 4096 + col0 + bj * HALF) = w; }
; template <class Epi, class Sched, bool ALIGN_EPI = false, bool SP2 = false, bool F8 = false>
; __device__ __forceinline__ void gemm_phase(PG8_LAS unsigned char* lds, const Gemm g, const Sched& S, const Epi& E) {
;     ...
;         if constexpr (F8) asm volatile("s_nop 15\n\ts_nop 15\n\ts_nop 7" ::: "memory");
	s_add_i32 s51, s51, 2
	s_add_u32 s49, s49, 0x100
	s_addc_u32 s50, s50, 0
	s_add_u32 s28, s28, 0x100
	s_addc_u32 s29, s29, 0
	s_cmp_gt_u32 s51, 13
	s_cbranch_scc0 .LBB0_630
	v_lshl_add_u32 v182, s26, 8, v187
	v_lshl_or_b32 v180, s46, 8, v189
	v_ashrrev_i32_e32 v183, 31, v182
	v_ashrrev_i32_e32 v181, 31, v180
	v_lshlrev_b64 v[2:3], 12, v[182:183]
	v_lshl_add_u64 v[2:3], v[2:3], 0, v[180:181]
	v_lshlrev_b64 v[2:3], 1, v[2:3]
	s_nop 15
	s_nop 15
	s_nop 7
	v_lshl_add_u64 v[4:5], s[10:11], 0, v[2:3]
	global_load_dwordx4 v[30:33], v[4:5], off
	v_lshl_add_u64 v[4:5], s[12:13], 0, v[2:3]
	global_load_dwordx4 v[194:197], v[4:5], off
	v_or_b32_e32 v2, 0x100, v2
	v_lshl_add_u64 v[4:5], s[10:11], 0, v[2:3]
	v_lshl_add_u64 v[2:3], s[12:13], 0, v[2:3]
	global_load_dwordx4 v[198:201], v[4:5], off
	global_load_dwordx4 v[202:205], v[2:3], off
	v_or_b32_e32 v184, 16, v182
	v_ashrrev_i32_e32 v185, 31, v184
	v_lshlrev_b64 v[2:3], 13, v[182:183]
	v_lshlrev_b64 v[4:5], 12, v[184:185]
	v_lshlrev_b64 v[178:179], 1, v[180:181]
	v_lshl_add_u64 v[2:3], s[10:11], 0, v[2:3]
	v_lshl_add_u64 v[4:5], v[4:5], 0, v[180:181]
	v_lshl_add_u64 v[230:231], v[2:3], 0, v[178:179]
	v_lshlrev_b64 v[2:3], 1, v[4:5]
	v_lshl_add_u64 v[4:5], s[10:11], 0, v[2:3]
	global_load_dwordx4 v[206:209], v[4:5], off
	v_lshl_add_u64 v[4:5], s[12:13], 0, v[2:3]
	global_load_dwordx4 v[210:213], v[4:5], off
	v_or_b32_e32 v28, 32, v182
	v_or_b32_e32 v26, 48, v182
	v_ashrrev_i32_e32 v29, 31, v28
	v_ashrrev_i32_e32 v27, 31, v26
	v_lshlrev_b64 v[6:7], 12, v[28:29]
	v_lshlrev_b64 v[8:9], 12, v[26:27]
	v_lshl_add_u64 v[6:7], v[6:7], 0, v[180:181]
	v_lshl_add_u64 v[8:9], v[8:9], 0, v[180:181]
	v_lshlrev_b64 v[4:5], 1, v[6:7]
	v_lshlrev_b64 v[6:7], 1, v[8:9]
	v_or_b32_e32 v2, 0x100, v2
	v_lshl_add_u64 v[8:9], s[10:11], 0, v[4:5]
	v_lshl_add_u64 v[10:11], s[12:13], 0, v[4:5]
	v_or_b32_e32 v4, 0x100, v4
	v_lshl_add_u64 v[12:13], s[10:11], 0, v[6:7]
	v_lshl_add_u64 v[18:19], s[12:13], 0, v[6:7]
	v_or_b32_e32 v6, 0x100, v6
	v_lshl_add_u64 v[20:21], s[10:11], 0, v[2:3]
	v_lshl_add_u64 v[2:3], s[12:13], 0, v[2:3]
	global_load_dwordx4 v[214:217], v[8:9], off
	global_load_dwordx4 v[218:221], v[10:11], off
	v_lshl_add_u64 v[8:9], s[10:11], 0, v[4:5]
	v_lshl_add_u64 v[4:5], s[12:13], 0, v[4:5]
	global_load_dwordx4 v[14:17], v[12:13], off
	s_nop 0
	global_load_dwordx4 v[10:13], v[18:19], off
	v_lshl_add_u64 v[232:233], s[10:11], 0, v[6:7]
	v_lshl_add_u64 v[234:235], s[12:13], 0, v[6:7]
	global_load_dwordx4 v[222:225], v[20:21], off
	global_load_dwordx4 v[226:229], v[2:3], off
	global_load_dwordx4 v[22:25], v[8:9], off
	s_nop 0
	global_load_dwordx4 v[18:21], v[4:5], off
	global_load_dwordx4 v[6:9], v[232:233], off
	s_nop 0
	global_load_dwordx4 v[2:5], v[234:235], off
	s_and_b64 vcc, exec, s[8:9]
	s_mov_b32 s46, s16
	s_mov_b32 s26, s20
	s_mov_b64 s[28:29], s[24:25]
	s_mov_b64 s[30:31], s[22:23]
	s_waitcnt vmcnt(0)
	v_lshlrev_b32_e32 v232, 16, v30
	v_and_b32_e32 v233, 0xffff0000, v30
	v_lshlrev_b32_e32 v234, 16, v194
	v_and_b32_e32 v235, 0xffff0000, v194
	v_lshlrev_b32_e32 v30, 16, v31
	v_and_b32_e32 v31, 0xffff0000, v31
	v_lshlrev_b32_e32 v194, 16, v195
	v_and_b32_e32 v195, 0xffff0000, v195
	v_lshlrev_b32_e32 v236, 16, v32
	v_and_b32_e32 v237, 0xffff0000, v32
	v_lshlrev_b32_e32 v238, 16, v196
	v_and_b32_e32 v239, 0xffff0000, v196
	v_lshlrev_b32_e32 v32, 16, v33
	v_and_b32_e32 v33, 0xffff0000, v33
	v_lshlrev_b32_e32 v196, 16, v197
	v_and_b32_e32 v197, 0xffff0000, v197
	v_pk_fma_f32 v[158:159], v[158:159], v[232:233], v[234:235]
	v_pk_fma_f32 v[160:161], v[160:161], v[30:31], v[194:195]
	v_pk_fma_f32 v[154:155], v[154:155], v[236:237], v[238:239]
	v_pk_fma_f32 v[156:157], v[156:157], v[32:33], v[196:197]
	v_cvt_pk_bf16_f32 v30, v158, v159
	v_cvt_pk_bf16_f32 v31, v160, v161
	v_cvt_pk_bf16_f32 v32, v154, v155
	v_cvt_pk_bf16_f32 v33, v156, v157
	v_lshlrev_b32_e32 v194, 16, v198
	global_store_dwordx4 v[230:231], v[30:33], off
	v_and_b32_e32 v195, 0xffff0000, v198
	s_nop 0
	v_lshlrev_b32_e32 v30, 16, v202
	v_and_b32_e32 v31, 0xffff0000, v202
	v_pk_fma_f32 v[30:31], v[150:151], v[194:195], v[30:31]
	v_lshlrev_b32_e32 v32, 16, v199
	v_and_b32_e32 v33, 0xffff0000, v199
	v_lshlrev_b32_e32 v150, 16, v203
	v_and_b32_e32 v151, 0xffff0000, v203
	v_pk_fma_f32 v[32:33], v[152:153], v[32:33], v[150:151]
	v_cvt_pk_bf16_f32 v30, v30, v31
	v_cvt_pk_bf16_f32 v31, v32, v33
	v_lshlrev_b32_e32 v32, 16, v200
	v_and_b32_e32 v33, 0xffff0000, v200
	v_lshlrev_b32_e32 v150, 16, v204
	v_and_b32_e32 v151, 0xffff0000, v204
	v_pk_fma_f32 v[32:33], v[142:143], v[32:33], v[150:151]
	v_lshlrev_b32_e32 v142, 16, v201
	v_and_b32_e32 v143, 0xffff0000, v201
	v_lshlrev_b32_e32 v150, 16, v205
	v_and_b32_e32 v151, 0xffff0000, v205
	v_pk_fma_f32 v[142:143], v[144:145], v[142:143], v[150:151]
	v_cvt_pk_bf16_f32 v32, v32, v33
	v_cvt_pk_bf16_f32 v33, v142, v143
	global_store_dwordx4 v[230:231], v[30:33], off offset:256
	v_lshlrev_b32_e32 v144, 16, v211
	v_and_b32_e32 v145, 0xffff0000, v211
	v_lshlrev_b32_e32 v30, 16, v206
	v_and_b32_e32 v31, 0xffff0000, v206
	v_lshlrev_b32_e32 v32, 16, v210
	v_and_b32_e32 v33, 0xffff0000, v210
	v_pk_fma_f32 v[30:31], v[146:147], v[30:31], v[32:33]
	v_lshlrev_b32_e32 v32, 16, v207
	v_and_b32_e32 v33, 0xffff0000, v207
	v_pk_fma_f32 v[32:33], v[148:149], v[32:33], v[144:145]
	v_cvt_pk_bf16_f32 v30, v30, v31
	v_cvt_pk_bf16_f32 v31, v32, v33
	v_lshlrev_b32_e32 v32, 16, v208
	v_and_b32_e32 v33, 0xffff0000, v208
	v_lshlrev_b32_e32 v144, 16, v212
	v_and_b32_e32 v145, 0xffff0000, v212
	v_pk_fma_f32 v[32:33], v[138:139], v[32:33], v[144:145]
	v_lshlrev_b32_e32 v138, 16, v209
	v_and_b32_e32 v139, 0xffff0000, v209
	v_lshlrev_b32_e32 v144, 16, v213
; #define PG8_GAS __attribute__((address_space(1)))
; __device__ __forceinline__ unsigned cvt_pk_bf16(float lo, float hi) { const f32x2c v = {lo, hi}; return __builtin_bit_cast(unsigned, __builtin_convertvector(v, bf16x2c)); }
; __device__ __forceinline__ float bf_lo(unsigned w) { return __uint_as_float(w << 16); }
; __device__ __forceinline__ float bf_hi(unsigned w) { return __uint_as_float(w & 0xffff0000u); }
;     __device__ __forceinline__ void operator()(const f32x4 (&acc)[2][2][4][2], const Unit& un, int wr, int wc, int fr, int fq) const {
;     ...
;             for (int m = 0; m < 4; ++m)
; #pragma unroll
;                 for (int bj = 0; bj < 2; ++bj) { const u32x4 g = gg[m][bj], p = pp[m][bj]; const f32x4 v0 = acc[ai][bj][m][0], v1 = acc[ai][bj][m][1];
;                     u32x4 w; w.x = cvt_pk_bf16(v0[0] * bf_lo(g.x) + bf_lo(p.x), v0[1] * bf_hi(g.x) + bf_hi(p.x)); w.y = cvt_pk_bf16(v0[2] * bf_lo(g.y) + bf_lo(p.y), v0[3] * bf_hi(g.y) + bf_hi(p.y));
;                     w.z = cvt_pk_bf16(v1[0] * bf_lo(g.z) + bf_lo(p.z), v1[1] * bf_hi(g.z) + bf_hi(p.z)); w.w = cvt_pk_bf16(v1[2] * bf_lo(g.w) + bf_lo(p.w), v1[3] * bf_hi(g.w) + bf_hi(p.w));
;                     *(PG8_GAS u32x4*)(sa + (size_t)(row0 + ai * HALF + m * 16) * 4096 + col0 + bj * HALF) = w; }
	v_and_b32_e32 v145, 0xffff0000, v213
	v_lshlrev_b64 v[142:143], 13, v[184:185]
	v_pk_fma_f32 v[138:139], v[140:141], v[138:139], v[144:145]
	v_cvt_pk_bf16_f32 v32, v32, v33
	v_cvt_pk_bf16_f32 v33, v138, v139
	v_lshl_add_u64 v[138:139], s[10:11], 0, v[142:143]
	v_lshl_add_u64 v[138:139], v[138:139], 0, v[178:179]
	global_store_dwordx4 v[138:139], v[30:33], off
	s_nop 1
	v_lshlrev_b32_e32 v30, 16, v222
	v_and_b32_e32 v31, 0xffff0000, v222
	v_lshlrev_b32_e32 v32, 16, v226
	v_and_b32_e32 v33, 0xffff0000, v226
	v_pk_fma_f32 v[30:31], v[134:135], v[30:31], v[32:33]
	v_lshlrev_b32_e32 v32, 16, v223
	v_and_b32_e32 v33, 0xffff0000, v223
	v_lshlrev_b32_e32 v134, 16, v227
	v_and_b32_e32 v135, 0xffff0000, v227
	v_pk_fma_f32 v[32:33], v[136:137], v[32:33], v[134:135]
	v_cvt_pk_bf16_f32 v30, v30, v31
	v_cvt_pk_bf16_f32 v31, v32, v33
	v_lshlrev_b32_e32 v32, 16, v224
	v_and_b32_e32 v33, 0xffff0000, v224
	v_lshlrev_b32_e32 v134, 16, v228
	v_and_b32_e32 v135, 0xffff0000, v228
	v_pk_fma_f32 v[32:33], v[126:127], v[32:33], v[134:135]
	v_lshlrev_b32_e32 v126, 16, v225
	v_and_b32_e32 v127, 0xffff0000, v225
	v_lshlrev_b32_e32 v134, 16, v229
	v_and_b32_e32 v135, 0xffff0000, v229
	v_pk_fma_f32 v[126:127], v[128:129], v[126:127], v[134:135]
	v_cvt_pk_bf16_f32 v32, v32, v33
	v_cvt_pk_bf16_f32 v33, v126, v127
	global_store_dwordx4 v[138:139], v[30:33], off offset:256
	v_lshlrev_b32_e32 v126, 16, v219
	v_and_b32_e32 v127, 0xffff0000, v219
	v_lshlrev_b64 v[32:33], 13, v[28:29]
	v_lshlrev_b32_e32 v28, 16, v214
	v_and_b32_e32 v29, 0xffff0000, v214
	v_lshlrev_b32_e32 v30, 16, v218
	v_and_b32_e32 v31, 0xffff0000, v218
	v_pk_fma_f32 v[28:29], v[130:131], v[28:29], v[30:31]
	v_lshlrev_b32_e32 v30, 16, v215
	v_and_b32_e32 v31, 0xffff0000, v215
	v_pk_fma_f32 v[30:31], v[132:133], v[30:31], v[126:127]
	v_cvt_pk_bf16_f32 v28, v28, v29
	v_cvt_pk_bf16_f32 v29, v30, v31
	v_lshlrev_b32_e32 v30, 16, v216
	v_and_b32_e32 v31, 0xffff0000, v216
	v_lshlrev_b32_e32 v126, 16, v220
	v_and_b32_e32 v127, 0xffff0000, v220
	v_pk_fma_f32 v[30:31], v[122:123], v[30:31], v[126:127]
	v_lshlrev_b32_e32 v122, 16, v217
	v_and_b32_e32 v123, 0xffff0000, v217
	v_lshlrev_b32_e32 v126, 16, v221
	v_and_b32_e32 v127, 0xffff0000, v221
	v_pk_fma_f32 v[122:123], v[124:125], v[122:123], v[126:127]
	v_lshl_add_u64 v[32:33], s[10:11], 0, v[32:33]
	v_cvt_pk_bf16_f32 v30, v30, v31
	v_cvt_pk_bf16_f32 v31, v122, v123
	v_lshl_add_u64 v[32:33], v[32:33], 0, v[178:179]
	global_store_dwordx4 v[32:33], v[28:31], off
	v_add_u32_e32 v132, 0x80, v182
	v_ashrrev_i32_e32 v133, 31, v132
	v_lshlrev_b32_e32 v28, 16, v22
	v_and_b32_e32 v29, 0xffff0000, v22
	v_lshlrev_b32_e32 v30, 16, v18
	v_and_b32_e32 v31, 0xffff0000, v18
	v_pk_fma_f32 v[28:29], v[118:119], v[28:29], v[30:31]
	v_lshlrev_b32_e32 v22, 16, v23
	v_cvt_pk_bf16_f32 v18, v28, v29
	v_and_b32_e32 v23, 0xffff0000, v23
	v_lshlrev_b32_e32 v28, 16, v19
	v_and_b32_e32 v29, 0xffff0000, v19
	v_pk_fma_f32 v[22:23], v[120:121], v[22:23], v[28:29]
	v_lshlrev_b32_e32 v28, 16, v20
	v_cvt_pk_bf16_f32 v19, v22, v23
	v_lshlrev_b32_e32 v22, 16, v24
	v_and_b32_e32 v23, 0xffff0000, v24
	v_and_b32_e32 v29, 0xffff0000, v20
	v_pk_fma_f32 v[22:23], v[110:111], v[22:23], v[28:29]
	v_lshlrev_b32_e32 v24, 16, v21
	v_cvt_pk_bf16_f32 v20, v22, v23
	v_lshlrev_b32_e32 v22, 16, v25
	v_and_b32_e32 v23, 0xffff0000, v25
	v_and_b32_e32 v25, 0xffff0000, v21
	v_pk_fma_f32 v[22:23], v[112:113], v[22:23], v[24:25]
	v_add_u32_e32 v134, 0x90, v182
	v_cvt_pk_bf16_f32 v21, v22, v23
	global_store_dwordx4 v[32:33], v[18:21], off offset:256
	v_lshlrev_b32_e32 v22, 16, v10
	v_and_b32_e32 v23, 0xffff0000, v10
	v_lshlrev_b32_e32 v20, 16, v14
	v_and_b32_e32 v21, 0xffff0000, v14
	v_pk_fma_f32 v[20:21], v[114:115], v[20:21], v[22:23]
	v_lshlrev_b32_e32 v14, 16, v15
	v_cvt_pk_bf16_f32 v10, v20, v21
	v_and_b32_e32 v15, 0xffff0000, v15
	v_lshlrev_b32_e32 v20, 16, v11
	v_and_b32_e32 v21, 0xffff0000, v11
	v_pk_fma_f32 v[14:15], v[116:117], v[14:15], v[20:21]
	v_lshlrev_b32_e32 v20, 16, v12
	v_cvt_pk_bf16_f32 v11, v14, v15
	v_lshlrev_b32_e32 v14, 16, v16
	v_and_b32_e32 v15, 0xffff0000, v16
	v_and_b32_e32 v21, 0xffff0000, v12
	v_pk_fma_f32 v[14:15], v[106:107], v[14:15], v[20:21]
	v_lshlrev_b32_e32 v16, 16, v13
	v_cvt_pk_bf16_f32 v12, v14, v15
	v_lshlrev_b32_e32 v14, 16, v17
	v_and_b32_e32 v15, 0xffff0000, v17
	v_and_b32_e32 v17, 0xffff0000, v13
	v_lshlrev_b64 v[18:19], 13, v[26:27]
	v_pk_fma_f32 v[14:15], v[108:109], v[14:15], v[16:17]
	v_ashrrev_i32_e32 v135, 31, v134
	v_cvt_pk_bf16_f32 v13, v14, v15
	v_lshl_add_u64 v[14:15], s[10:11], 0, v[18:19]
	v_lshl_add_u64 v[14:15], v[14:15], 0, v[178:179]
	global_store_dwordx4 v[14:15], v[10:13], off
	v_add_u32_e32 v136, 0xa0, v182
	v_ashrrev_i32_e32 v137, 31, v136
	v_lshlrev_b32_e32 v10, 16, v6
	v_and_b32_e32 v11, 0xffff0000, v6
	v_lshlrev_b32_e32 v12, 16, v2
	v_and_b32_e32 v13, 0xffff0000, v2
	v_pk_fma_f32 v[10:11], v[102:103], v[10:11], v[12:13]
	v_lshlrev_b32_e32 v6, 16, v7
	v_cvt_pk_bf16_f32 v2, v10, v11
	v_and_b32_e32 v7, 0xffff0000, v7
	v_lshlrev_b32_e32 v10, 16, v3
	v_and_b32_e32 v11, 0xffff0000, v3
	v_pk_fma_f32 v[6:7], v[104:105], v[6:7], v[10:11]
	v_lshlrev_b32_e32 v10, 16, v4
	v_cvt_pk_bf16_f32 v3, v6, v7
	v_lshlrev_b32_e32 v6, 16, v8
	v_and_b32_e32 v7, 0xffff0000, v8
	v_and_b32_e32 v11, 0xffff0000, v4
	v_pk_fma_f32 v[6:7], v[98:99], v[6:7], v[10:11]
	v_lshlrev_b32_e32 v8, 16, v5
	v_cvt_pk_bf16_f32 v4, v6, v7
	v_lshlrev_b32_e32 v6, 16, v9
	v_and_b32_e32 v7, 0xffff0000, v9
	v_and_b32_e32 v9, 0xffff0000, v5
	v_pk_fma_f32 v[6:7], v[100:101], v[6:7], v[8:9]
	v_add_u32_e32 v98, 0xb0, v182
	v_cvt_pk_bf16_f32 v5, v6, v7
	global_store_dwordx4 v[14:15], v[2:5], off offset:256
; #define PG8_GAS __attribute__((address_space(1)))
; __device__ __forceinline__ unsigned cvt_pk_bf16(float lo, float hi) { const f32x2c v = {lo, hi}; return __builtin_bit_cast(unsigned, __builtin_convertvector(v, bf16x2c)); }
; __device__ __forceinline__ float bf_lo(unsigned w) { return __uint_as_float(w << 16); }
; __device__ __forceinline__ float bf_hi(unsigned w) { return __uint_as_float(w & 0xffff0000u); }
;     __device__ __forceinline__ void operator()(const f32x4 (&acc)[2][2][4][2], const Unit& un, int wr, int wc, int fr, int fq) const {
;     ...
;         for (int ai = 0; ai < 2; ++ai) {
;             u32x4 gg[4][2], pp[4][2];
; #pragma unroll
;             for (int m = 0; m < 4; ++m)
; #pragma unroll
;                 for (int bj = 0; bj < 2; ++bj) { const size_t off = (size_t)(row0 + ai * HALF + m * 16) * 4096 + col0 + bj * HALF; gg[m][bj] = *(const PG8_GAS u32x4*)(sa + off); pp[m][bj] = *(const PG8_GAS u32x4*)(P + off); }
;             asm volatile("" ::: "memory");
; #pragma unroll
;             for (int m = 0; m < 4; ++m)
; #pragma unroll
;                 for (int bj = 0; bj < 2; ++bj) { const u32x4 g = gg[m][bj], p = pp[m][bj]; const f32x4 v0 = acc[ai][bj][m][0], v1 = acc[ai][bj][m][1];
;                     u32x4 w; w.x = cvt_pk_bf16(v0[0] * bf_lo(g.x) + bf_lo(p.x), v0[1] * bf_hi(g.x) + bf_hi(p.x)); w.y = cvt_pk_bf16(v0[2] * bf_lo(g.y) + bf_lo(p.y), v0[3] * bf_hi(g.y) + bf_hi(p.y));
;                     w.z = cvt_pk_bf16(v1[0] * bf_lo(g.z) + bf_lo(p.z), v1[1] * bf_hi(g.z) + bf_hi(p.z)); w.w = cvt_pk_bf16(v1[2] * bf_lo(g.w) + bf_lo(p.w), v1[3] * bf_hi(g.w) + bf_hi(p.w));
;                     *(PG8_GAS u32x4*)(sa + (size_t)(row0 + ai * HALF + m * 16) * 4096 + col0 + bj * HALF) = w; }
	v_ashrrev_i32_e32 v99, 31, v98
	s_nop 0
	v_lshlrev_b64 v[2:3], 12, v[132:133]
	v_lshl_add_u64 v[2:3], v[2:3], 0, v[180:181]
	v_lshlrev_b64 v[2:3], 1, v[2:3]
	v_lshl_add_u64 v[4:5], s[10:11], 0, v[2:3]
	global_load_dwordx4 v[100:103], v[4:5], off
	v_lshl_add_u64 v[4:5], s[12:13], 0, v[2:3]
	global_load_dwordx4 v[104:107], v[4:5], off
	v_or_b32_e32 v2, 0x100, v2
	v_lshl_add_u64 v[4:5], s[10:11], 0, v[2:3]
	v_lshl_add_u64 v[2:3], s[12:13], 0, v[2:3]
	global_load_dwordx4 v[108:111], v[4:5], off
	global_load_dwordx4 v[112:115], v[2:3], off
	v_lshlrev_b64 v[2:3], 12, v[134:135]
	v_lshl_add_u64 v[2:3], v[2:3], 0, v[180:181]
	v_lshlrev_b64 v[2:3], 1, v[2:3]
	v_lshl_add_u64 v[4:5], s[10:11], 0, v[2:3]
	v_lshl_add_u64 v[6:7], s[12:13], 0, v[2:3]
	global_load_dwordx4 v[116:119], v[4:5], off
	global_load_dwordx4 v[120:123], v[6:7], off
	v_or_b32_e32 v2, 0x100, v2
	v_lshl_add_u64 v[4:5], s[10:11], 0, v[2:3]
	v_lshl_add_u64 v[2:3], s[12:13], 0, v[2:3]
	global_load_dwordx4 v[124:127], v[4:5], off
	global_load_dwordx4 v[128:131], v[2:3], off
	v_lshlrev_b64 v[2:3], 12, v[136:137]
	v_lshl_add_u64 v[2:3], v[2:3], 0, v[180:181]
	v_lshlrev_b64 v[2:3], 1, v[2:3]
	v_lshl_add_u64 v[4:5], s[10:11], 0, v[2:3]
	v_lshl_add_u64 v[6:7], s[12:13], 0, v[2:3]
	global_load_dwordx4 v[30:33], v[4:5], off
	global_load_dwordx4 v[26:29], v[6:7], off
	v_or_b32_e32 v2, 0x100, v2
	v_lshl_add_u64 v[4:5], s[10:11], 0, v[2:3]
	v_lshl_add_u64 v[2:3], s[12:13], 0, v[2:3]
	global_load_dwordx4 v[22:25], v[4:5], off
	global_load_dwordx4 v[18:21], v[2:3], off
	v_lshlrev_b64 v[2:3], 12, v[98:99]
	v_lshl_add_u64 v[2:3], v[2:3], 0, v[180:181]
	v_lshlrev_b64 v[2:3], 1, v[2:3]
	v_lshl_add_u64 v[4:5], s[10:11], 0, v[2:3]
	v_lshl_add_u64 v[6:7], s[12:13], 0, v[2:3]
	global_load_dwordx4 v[14:17], v[4:5], off
	global_load_dwordx4 v[10:13], v[6:7], off
	v_or_b32_e32 v2, 0x100, v2
	v_lshl_add_u64 v[4:5], s[10:11], 0, v[2:3]
	v_lshl_add_u64 v[2:3], s[12:13], 0, v[2:3]
	global_load_dwordx4 v[6:9], v[4:5], off
	s_nop 0
	global_load_dwordx4 v[2:5], v[2:3], off
	v_lshlrev_b64 v[132:133], 13, v[132:133]
	s_waitcnt vmcnt(15)
	v_lshlrev_b32_e32 v138, 16, v100
	v_and_b32_e32 v139, 0xffff0000, v100
	s_waitcnt vmcnt(14)
	v_lshlrev_b32_e32 v140, 16, v104
	v_and_b32_e32 v141, 0xffff0000, v104
	v_lshlrev_b32_e32 v100, 16, v101
	v_and_b32_e32 v101, 0xffff0000, v101
	v_lshlrev_b32_e32 v104, 16, v105
	v_and_b32_e32 v105, 0xffff0000, v105
	v_pk_fma_f32 v[94:95], v[94:95], v[138:139], v[140:141]
	v_pk_fma_f32 v[96:97], v[96:97], v[100:101], v[104:105]
	v_cvt_pk_bf16_f32 v94, v94, v95
	v_cvt_pk_bf16_f32 v95, v96, v97
	v_lshlrev_b32_e32 v96, 16, v102
	v_and_b32_e32 v97, 0xffff0000, v102
	v_lshlrev_b32_e32 v100, 16, v106
	v_and_b32_e32 v101, 0xffff0000, v106
	v_pk_fma_f32 v[90:91], v[90:91], v[96:97], v[100:101]
	v_lshlrev_b32_e32 v100, 16, v107
	v_cvt_pk_bf16_f32 v96, v90, v91
	v_lshlrev_b32_e32 v90, 16, v103
	v_and_b32_e32 v91, 0xffff0000, v103
	v_and_b32_e32 v101, 0xffff0000, v107
	v_pk_fma_f32 v[90:91], v[92:93], v[90:91], v[100:101]
	s_waitcnt vmcnt(13)
	v_lshlrev_b32_e32 v92, 16, v108
	v_cvt_pk_bf16_f32 v97, v90, v91
	v_lshl_add_u64 v[90:91], s[10:11], 0, v[132:133]
	v_lshl_add_u64 v[90:91], v[90:91], 0, v[178:179]
	global_store_dwordx4 v[90:91], v[94:97], off
	v_and_b32_e32 v93, 0xffff0000, v108
	s_waitcnt vmcnt(13)
	v_lshlrev_b32_e32 v94, 16, v112
	v_and_b32_e32 v95, 0xffff0000, v112
	v_pk_fma_f32 v[86:87], v[86:87], v[92:93], v[94:95]
	v_lshlrev_b32_e32 v92, 16, v109
	v_and_b32_e32 v93, 0xffff0000, v109
	v_lshlrev_b32_e32 v94, 16, v113
	v_and_b32_e32 v95, 0xffff0000, v113
	v_pk_fma_f32 v[88:89], v[88:89], v[92:93], v[94:95]
	v_cvt_pk_bf16_f32 v86, v86, v87
	v_cvt_pk_bf16_f32 v87, v88, v89
	v_lshlrev_b32_e32 v88, 16, v110
	v_and_b32_e32 v89, 0xffff0000, v110
	v_lshlrev_b32_e32 v92, 16, v114
	v_and_b32_e32 v93, 0xffff0000, v114
	v_pk_fma_f32 v[78:79], v[78:79], v[88:89], v[92:93]
	v_lshlrev_b32_e32 v92, 16, v115
	v_cvt_pk_bf16_f32 v88, v78, v79
	v_lshlrev_b32_e32 v78, 16, v111
	v_and_b32_e32 v79, 0xffff0000, v111
	v_and_b32_e32 v93, 0xffff0000, v115
	v_pk_fma_f32 v[78:79], v[80:81], v[78:79], v[92:93]
	s_waitcnt vmcnt(11)
	v_lshlrev_b32_e32 v80, 16, v120
	v_cvt_pk_bf16_f32 v89, v78, v79
	v_lshlrev_b32_e32 v78, 16, v116
	v_and_b32_e32 v79, 0xffff0000, v116
	v_and_b32_e32 v81, 0xffff0000, v120
	v_pk_fma_f32 v[78:79], v[82:83], v[78:79], v[80:81]
	v_lshlrev_b32_e32 v80, 16, v117
	v_and_b32_e32 v81, 0xffff0000, v117
	v_lshlrev_b32_e32 v82, 16, v121
	v_and_b32_e32 v83, 0xffff0000, v121
	v_pk_fma_f32 v[80:81], v[84:85], v[80:81], v[82:83]
	v_cvt_pk_bf16_f32 v78, v78, v79
	v_cvt_pk_bf16_f32 v79, v80, v81
	v_lshlrev_b32_e32 v80, 16, v118
	v_and_b32_e32 v81, 0xffff0000, v118
	v_lshlrev_b32_e32 v82, 16, v122
	v_and_b32_e32 v83, 0xffff0000, v122
	v_pk_fma_f32 v[74:75], v[74:75], v[80:81], v[82:83]
	v_lshlrev_b32_e32 v82, 16, v123
	v_cvt_pk_bf16_f32 v80, v74, v75
	v_lshlrev_b32_e32 v74, 16, v119
	v_and_b32_e32 v75, 0xffff0000, v119
	v_and_b32_e32 v83, 0xffff0000, v123
	global_store_dwordx4 v[90:91], v[86:89], off offset:256
	v_pk_fma_f32 v[74:75], v[76:77], v[74:75], v[82:83]
	s_waitcnt vmcnt(11)
	v_lshlrev_b32_e32 v76, 16, v124
	v_lshlrev_b64 v[86:87], 13, v[134:135]
	v_cvt_pk_bf16_f32 v81, v74, v75
	v_lshl_add_u64 v[74:75], s[10:11], 0, v[86:87]
	v_lshl_add_u64 v[74:75], v[74:75], 0, v[178:179]
	global_store_dwordx4 v[74:75], v[78:81], off
	v_and_b32_e32 v77, 0xffff0000, v124
	s_waitcnt vmcnt(11)
; #define PG8_GAS __attribute__((address_space(1)))
; __device__ __forceinline__ unsigned cvt_pk_bf16(float lo, float hi) { const f32x2c v = {lo, hi}; return __builtin_bit_cast(unsigned, __builtin_convertvector(v, bf16x2c)); }
; __device__ __forceinline__ float bf_lo(unsigned w) { return __uint_as_float(w << 16); }
; __device__ __forceinline__ float bf_hi(unsigned w) { return __uint_as_float(w & 0xffff0000u); }
; #define PG8_WAIT_V(n) asm volatile("s_waitcnt vmcnt(" #n ")" ::: "memory")
; #define PG8_BAR __builtin_amdgcn_s_barrier()
;     __device__ __forceinline__ void operator()(const f32x4 (&acc)[2][2][4][2], const Unit& un, int wr, int wc, int fr, int fq) const {
;     ...
;             for (int m = 0; m < 4; ++m)
; #pragma unroll
;                 for (int bj = 0; bj < 2; ++bj) { const u32x4 g = gg[m][bj], p = pp[m][bj]; const f32x4 v0 = acc[ai][bj][m][0], v1 = acc[ai][bj][m][1];
;                     u32x4 w; w.x = cvt_pk_bf16(v0[0] * bf_lo(g.x) + bf_lo(p.x), v0[1] * bf_hi(g.x) + bf_hi(p.x)); w.y = cvt_pk_bf16(v0[2] * bf_lo(g.y) + bf_lo(p.y), v0[3] * bf_hi(g.y) + bf_hi(p.y));
;                     w.z = cvt_pk_bf16(v1[0] * bf_lo(g.z) + bf_lo(p.z), v1[1] * bf_hi(g.z) + bf_hi(p.z)); w.w = cvt_pk_bf16(v1[2] * bf_lo(g.w) + bf_lo(p.w), v1[3] * bf_hi(g.w) + bf_hi(p.w));
;                     *(PG8_GAS u32x4*)(sa + (size_t)(row0 + ai * HALF + m * 16) * 4096 + col0 + bj * HALF) = w; }
; template <class Epi, class Sched, bool ALIGN_EPI = false, bool SP2 = false, bool F8 = false>
; __device__ __forceinline__ void gemm_phase(PG8_LAS unsigned char* lds, const Gemm g, const Sched& S, const Epi& E) {
;     ...
;         if (!has_next) break;
;     ...
;     PG8_WAIT_V(0);
;     if constexpr (!ALIGN_EPI) { if (wr == 0) PG8_BAR; }
;     PG8_BAR;
	v_lshlrev_b32_e32 v78, 16, v128
	v_and_b32_e32 v79, 0xffff0000, v128
	v_pk_fma_f32 v[70:71], v[70:71], v[76:77], v[78:79]
	v_lshlrev_b32_e32 v76, 16, v125
	v_and_b32_e32 v77, 0xffff0000, v125
	v_lshlrev_b32_e32 v78, 16, v129
	v_and_b32_e32 v79, 0xffff0000, v129
	v_pk_fma_f32 v[72:73], v[72:73], v[76:77], v[78:79]
	v_cvt_pk_bf16_f32 v70, v70, v71
	v_cvt_pk_bf16_f32 v71, v72, v73
	v_lshlrev_b32_e32 v72, 16, v126
	v_and_b32_e32 v73, 0xffff0000, v126
	v_lshlrev_b32_e32 v76, 16, v130
	v_and_b32_e32 v77, 0xffff0000, v130
	v_pk_fma_f32 v[62:63], v[62:63], v[72:73], v[76:77]
	v_lshlrev_b32_e32 v76, 16, v131
	v_cvt_pk_bf16_f32 v72, v62, v63
	v_lshlrev_b32_e32 v62, 16, v127
	v_and_b32_e32 v63, 0xffff0000, v127
	v_and_b32_e32 v77, 0xffff0000, v131
	v_pk_fma_f32 v[62:63], v[64:65], v[62:63], v[76:77]
	s_waitcnt vmcnt(10)
	v_lshlrev_b32_e32 v64, 16, v30
	v_cvt_pk_bf16_f32 v73, v62, v63
	global_store_dwordx4 v[74:75], v[70:73], off offset:256
	v_and_b32_e32 v65, 0xffff0000, v30
	v_lshlrev_b32_e32 v30, 16, v31
	s_waitcnt vmcnt(10)
	v_lshlrev_b32_e32 v70, 16, v26
	v_and_b32_e32 v71, 0xffff0000, v26
	v_pk_fma_f32 v[64:65], v[66:67], v[64:65], v[70:71]
	v_and_b32_e32 v31, 0xffff0000, v31
	v_cvt_pk_bf16_f32 v26, v64, v65
	v_lshlrev_b32_e32 v64, 16, v27
	v_and_b32_e32 v65, 0xffff0000, v27
	v_pk_fma_f32 v[30:31], v[68:69], v[30:31], v[64:65]
	v_lshlrev_b32_e32 v64, 16, v28
	v_cvt_pk_bf16_f32 v27, v30, v31
	v_lshlrev_b32_e32 v30, 16, v32
	v_and_b32_e32 v31, 0xffff0000, v32
	v_and_b32_e32 v65, 0xffff0000, v28
	v_pk_fma_f32 v[30:31], v[58:59], v[30:31], v[64:65]
	v_lshlrev_b32_e32 v32, 16, v29
	v_cvt_pk_bf16_f32 v28, v30, v31
	v_lshlrev_b32_e32 v30, 16, v33
	v_and_b32_e32 v31, 0xffff0000, v33
	v_and_b32_e32 v33, 0xffff0000, v29
	v_lshlrev_b64 v[62:63], 13, v[136:137]
	v_pk_fma_f32 v[30:31], v[60:61], v[30:31], v[32:33]
	s_nop 0
	v_cvt_pk_bf16_f32 v29, v30, v31
	v_lshl_add_u64 v[30:31], s[10:11], 0, v[62:63]
	v_lshl_add_u64 v[30:31], v[30:31], 0, v[178:179]
	global_store_dwordx4 v[30:31], v[26:29], off
	s_waitcnt vmcnt(10)
	s_nop 0
	v_lshlrev_b32_e32 v26, 16, v22
	v_and_b32_e32 v27, 0xffff0000, v22
	s_waitcnt vmcnt(9)
	v_lshlrev_b32_e32 v28, 16, v18
	v_and_b32_e32 v29, 0xffff0000, v18
	v_pk_fma_f32 v[26:27], v[54:55], v[26:27], v[28:29]
	v_lshlrev_b32_e32 v22, 16, v23
	v_cvt_pk_bf16_f32 v18, v26, v27
	v_and_b32_e32 v23, 0xffff0000, v23
	v_lshlrev_b32_e32 v26, 16, v19
	v_and_b32_e32 v27, 0xffff0000, v19
	v_pk_fma_f32 v[22:23], v[56:57], v[22:23], v[26:27]
	v_lshlrev_b32_e32 v26, 16, v20
	v_cvt_pk_bf16_f32 v19, v22, v23
	v_lshlrev_b32_e32 v22, 16, v24
	v_and_b32_e32 v23, 0xffff0000, v24
	v_and_b32_e32 v27, 0xffff0000, v20
	v_pk_fma_f32 v[22:23], v[46:47], v[22:23], v[26:27]
	v_lshlrev_b32_e32 v24, 16, v21
	v_cvt_pk_bf16_f32 v20, v22, v23
	v_lshlrev_b32_e32 v22, 16, v25
	v_and_b32_e32 v23, 0xffff0000, v25
	v_and_b32_e32 v25, 0xffff0000, v21
	v_pk_fma_f32 v[22:23], v[48:49], v[22:23], v[24:25]
	s_nop 0
	v_cvt_pk_bf16_f32 v21, v22, v23
	global_store_dwordx4 v[30:31], v[18:21], off offset:256
	s_waitcnt vmcnt(8)
	v_lshlrev_b32_e32 v22, 16, v10
	v_and_b32_e32 v23, 0xffff0000, v10
	v_lshlrev_b32_e32 v20, 16, v14
	v_and_b32_e32 v21, 0xffff0000, v14
	v_pk_fma_f32 v[20:21], v[50:51], v[20:21], v[22:23]
	v_lshlrev_b32_e32 v14, 16, v15
	v_cvt_pk_bf16_f32 v10, v20, v21
	v_and_b32_e32 v15, 0xffff0000, v15
	v_lshlrev_b32_e32 v20, 16, v11
	v_and_b32_e32 v21, 0xffff0000, v11
	v_pk_fma_f32 v[14:15], v[52:53], v[14:15], v[20:21]
	v_lshlrev_b32_e32 v20, 16, v12
	v_cvt_pk_bf16_f32 v11, v14, v15
	v_lshlrev_b32_e32 v14, 16, v16
	v_and_b32_e32 v15, 0xffff0000, v16
	v_and_b32_e32 v21, 0xffff0000, v12
	v_pk_fma_f32 v[14:15], v[42:43], v[14:15], v[20:21]
	v_lshlrev_b32_e32 v16, 16, v13
	v_cvt_pk_bf16_f32 v12, v14, v15
	v_lshlrev_b32_e32 v14, 16, v17
	v_and_b32_e32 v15, 0xffff0000, v17
	v_and_b32_e32 v17, 0xffff0000, v13
	v_lshlrev_b64 v[18:19], 13, v[98:99]
	v_pk_fma_f32 v[14:15], v[44:45], v[14:15], v[16:17]
	s_nop 0
	v_cvt_pk_bf16_f32 v13, v14, v15
	v_lshl_add_u64 v[14:15], s[10:11], 0, v[18:19]
	v_lshl_add_u64 v[14:15], v[14:15], 0, v[178:179]
	global_store_dwordx4 v[14:15], v[10:13], off
	s_waitcnt vmcnt(8)
	s_nop 0
	v_lshlrev_b32_e32 v10, 16, v6
	v_and_b32_e32 v11, 0xffff0000, v6
	s_waitcnt vmcnt(7)
	v_lshlrev_b32_e32 v12, 16, v2
	v_and_b32_e32 v13, 0xffff0000, v2
	v_pk_fma_f32 v[10:11], v[38:39], v[10:11], v[12:13]
	v_lshlrev_b32_e32 v6, 16, v7
	v_cvt_pk_bf16_f32 v2, v10, v11
	v_and_b32_e32 v7, 0xffff0000, v7
	v_lshlrev_b32_e32 v10, 16, v3
	v_and_b32_e32 v11, 0xffff0000, v3
	v_pk_fma_f32 v[6:7], v[40:41], v[6:7], v[10:11]
	v_lshlrev_b32_e32 v10, 16, v4
	v_cvt_pk_bf16_f32 v3, v6, v7
	v_lshlrev_b32_e32 v6, 16, v8
	v_and_b32_e32 v7, 0xffff0000, v8
	v_and_b32_e32 v11, 0xffff0000, v4
	v_pk_fma_f32 v[6:7], v[34:35], v[6:7], v[10:11]
	v_lshlrev_b32_e32 v8, 16, v5
	v_cvt_pk_bf16_f32 v4, v6, v7
	v_lshlrev_b32_e32 v6, 16, v9
	v_and_b32_e32 v7, 0xffff0000, v9
	v_and_b32_e32 v9, 0xffff0000, v5
	v_pk_fma_f32 v[6:7], v[36:37], v[6:7], v[8:9]
	s_nop 0
	v_cvt_pk_bf16_f32 v5, v6, v7
	global_store_dwordx4 v[14:15], v[2:5], off offset:256
	s_cbranch_vccz .LBB0_627
	s_waitcnt vmcnt(0)
	s_cmpk_gt_u32 s4, 0xff
	s_cbranch_scc1 .LBB0_634
	s_barrier

; #define PG8_STAGE(bufoff, gbase, voff) do { _Pragma("unroll") for (int _i = 0; _i < 2; ++_i) \
;         __builtin_amdgcn_global_load_lds((const unsigned*)((const char*)(gbase) + (voff)[_i]), (PG8_LAS unsigned*)(lds + (bufoff) + ldsw + _i * 8192), 16, 0, 0); } while (0)
; #define PG8_LDA(dst, b, h) do { _Pragma("unroll") for (int m = 0; m < 4; ++m) _Pragma("unroll") for (int k = 0; k < 2; ++k) dst[m][k] = *(const PG8_LAS bf16x8*)(lds + PG8_SA(b, h) + aoff + m * 2048 + k * 1024); } while (0)
; #define PG8_LDB(dst, b, h) do { _Pragma("unroll") for (int n = 0; n < 2; ++n) _Pragma("unroll") for (int k = 0; k < 2; ++k) dst[n][k] = *(const PG8_LAS bf16x8*)(lds + PG8_SB(b, h) + boff + n * 2048 + k * 1024); } while (0)
; #define PG8_WAIT_V(n) asm volatile("s_waitcnt vmcnt(" #n ")" ::: "memory")
; #define PG8_WAIT_L(n) asm volatile("s_waitcnt lgkmcnt(" #n ")" ::: "memory")
; #define PG8_BAR __builtin_amdgcn_s_barrier()
; #define PG8_SCHED __builtin_amdgcn_sched_barrier(0)
; template <class Epi, class Sched, bool ALIGN_EPI = false, bool SP2 = false, bool F8 = false>
; __device__ __forceinline__ void gemm_phase(PG8_LAS unsigned char* lds, const Gemm g, const Sched& S, const Epi& E) {
;     ...
;             PG8_LDB(B0, 0, 0); PG8_LDB(B1, 0, 1); PG8_SCHED; PG8_LDA(At, 0, 0); PG8_STAGE(PG8_SA(1, 1), a1 + hA, voffA);
;             PG8_WAIT_V(8); PG8_WAIT_L(0); PG8_BAR; PG8_MMA(0, 0, At, B0); PG8_MMA(0, 1, At, B1); PG8_BAR; PG8_SCHED;
;             PG8_LDA(At, 0, 1); PG8_STAGE(PG8_SB(0, 0), b2, voffB); PG8_STAGE(PG8_SB(0, 1), b2 + hB, voffB); PG8_STAGE(PG8_SA(0, 0), a2, voffA);
;             PG8_WAIT_V(8); PG8_WAIT_L(0); PG8_BAR; PG8_MMA(1, 0, At, B0); PG8_MMA(1, 1, At, B1); PG8_BAR; PG8_SCHED;
.LBB0_689:
	ds_read_b128 v[130:133], v210
	ds_read_b128 v[134:137], v210 offset:1024
	ds_read_b128 v[138:141], v210 offset:2048
	ds_read_b128 v[142:145], v210 offset:3072
	ds_read_b128 v[146:149], v211
	ds_read_b128 v[150:153], v211 offset:1024
	ds_read_b128 v[154:157], v211 offset:2048
	ds_read_b128 v[158:161], v211 offset:3072
	s_add_u32 s38, s36, 0xfff00080
	s_addc_u32 s39, s37, -1
	s_cmp_eq_u32 s61, 60
	s_cselect_b32 s41, s17, s39
	s_cselect_b32 s40, s20, s38
	s_cselect_b32 s39, s25, s60
	s_cselect_b32 s38, s27, s35
	v_lshl_add_u64 v[218:219], s[36:37], 0, v[188:189]
	s_add_i32 m0, s33, 0xc000
	ds_read_b128 v[162:165], v212
	ds_read_b128 v[166:169], v212 offset:1024
	ds_read_b128 v[170:173], v212 offset:2048
	ds_read_b128 v[174:177], v212 offset:3072
	ds_read_b128 v[194:197], v212 offset:4096
	ds_read_b128 v[198:201], v212 offset:5120
	ds_read_b128 v[202:205], v212 offset:6144
	ds_read_b128 v[214:217], v212 offset:7168
	global_load_lds_dwordx4 v[218:219], off
	v_lshl_add_u64 v[218:219], s[36:37], 0, v[186:187]
	s_add_i32 m0, s33, 0xe000
	s_nop 0
	global_load_lds_dwordx4 v[218:219], off
	s_waitcnt vmcnt(8)
	s_waitcnt lgkmcnt(0)
	s_barrier
	v_mfma_f32_16x16x32_bf16 v[126:129], v[130:133], v[162:165], v[126:129]
	v_mfma_f32_16x16x32_bf16 v[122:125], v[138:141], v[162:165], v[122:125]
	v_mfma_f32_16x16x32_bf16 v[110:113], v[130:133], v[170:173], v[110:113]
	v_mfma_f32_16x16x32_bf16 v[106:109], v[138:141], v[170:173], v[106:109]
	v_mfma_f32_16x16x32_bf16 v[94:97], v[130:133], v[194:197], v[94:97]
	v_mfma_f32_16x16x32_bf16 v[90:93], v[138:141], v[194:197], v[90:93]
	v_mfma_f32_16x16x32_bf16 v[78:81], v[130:133], v[202:205], v[78:81]
	v_mfma_f32_16x16x32_bf16 v[74:77], v[138:141], v[202:205], v[74:77]
	v_mfma_f32_16x16x32_bf16 v[126:129], v[134:137], v[166:169], v[126:129]
	v_mfma_f32_16x16x32_bf16 v[122:125], v[142:145], v[166:169], v[122:125]
	v_mfma_f32_16x16x32_bf16 v[110:113], v[134:137], v[174:177], v[110:113]
	v_mfma_f32_16x16x32_bf16 v[106:109], v[142:145], v[174:177], v[106:109]
	v_mfma_f32_16x16x32_bf16 v[94:97], v[134:137], v[198:201], v[94:97]
	v_mfma_f32_16x16x32_bf16 v[90:93], v[142:145], v[198:201], v[90:93]
	v_mfma_f32_16x16x32_bf16 v[78:81], v[134:137], v[214:217], v[78:81]
	v_mfma_f32_16x16x32_bf16 v[74:77], v[142:145], v[214:217], v[74:77]
	v_mfma_f32_16x16x32_bf16 v[118:121], v[146:149], v[162:165], v[118:121]
	v_mfma_f32_16x16x32_bf16 v[114:117], v[154:157], v[162:165], v[114:117]
	v_mfma_f32_16x16x32_bf16 v[102:105], v[146:149], v[170:173], v[102:105]
	v_mfma_f32_16x16x32_bf16 v[98:101], v[154:157], v[170:173], v[98:101]
	v_mfma_f32_16x16x32_bf16 v[86:89], v[146:149], v[194:197], v[86:89]
	v_mfma_f32_16x16x32_bf16 v[82:85], v[154:157], v[194:197], v[82:85]
	v_mfma_f32_16x16x32_bf16 v[70:73], v[146:149], v[202:205], v[70:73]
	v_mfma_f32_16x16x32_bf16 v[66:69], v[154:157], v[202:205], v[66:69]
	v_mfma_f32_16x16x32_bf16 v[118:121], v[150:153], v[166:169], v[118:121]
	v_mfma_f32_16x16x32_bf16 v[114:117], v[158:161], v[166:169], v[114:117]
	v_mfma_f32_16x16x32_bf16 v[102:105], v[150:153], v[174:177], v[102:105]
	v_mfma_f32_16x16x32_bf16 v[98:101], v[158:161], v[174:177], v[98:101]
	v_mfma_f32_16x16x32_bf16 v[86:89], v[150:153], v[198:201], v[86:89]
	v_mfma_f32_16x16x32_bf16 v[82:85], v[158:161], v[198:201], v[82:85]
	v_mfma_f32_16x16x32_bf16 v[70:73], v[150:153], v[214:217], v[70:73]
	v_mfma_f32_16x16x32_bf16 v[66:69], v[158:161], v[214:217], v[66:69]
	s_barrier
	s_add_i32 s62, s56, s19
	v_lshl_add_u64 v[218:219], s[38:39], 0, v[180:181]
	s_mov_b32 m0, s62
	ds_read_b128 v[162:165], v212 offset:16384
	ds_read_b128 v[166:169], v212 offset:17408
	ds_read_b128 v[170:173], v212 offset:18432
	ds_read_b128 v[174:177], v212 offset:19456
	ds_read_b128 v[194:197], v212 offset:20480
	ds_read_b128 v[198:201], v212 offset:21504
	ds_read_b128 v[202:205], v212 offset:22528
	ds_read_b128 v[214:217], v212 offset:23552
	global_load_lds_dwordx4 v[218:219], off
	s_add_i32 m0, s62, 0x2000
	s_add_u32 s62, s38, 0x100000
	v_lshl_add_u64 v[220:221], s[38:39], 0, v[184:185]
	s_addc_u32 s63, s39, 0
	s_add_i32 s64, s57, s19
	global_load_lds_dwordx4 v[220:221], off
	v_lshl_add_u64 v[222:223], s[62:63], 0, v[180:181]
	s_mov_b32 m0, s64
	v_lshl_add_u64 v[224:225], s[40:41], 0, v[182:183]
	global_load_lds_dwordx4 v[222:223], off
	v_lshl_add_u64 v[222:223], s[62:63], 0, v[184:185]
	s_add_i32 m0, s64, 0x2000
	s_nop 0
	global_load_lds_dwordx4 v[222:223], off
	v_lshl_add_u64 v[222:223], s[40:41], 0, v[178:179]
	s_mov_b32 m0, s33
	s_nop 0
	global_load_lds_dwordx4 v[222:223], off
	s_mov_b32 m0, s42
	s_nop 0
	global_load_lds_dwordx4 v[224:225], off
	s_waitcnt vmcnt(8)
	s_waitcnt lgkmcnt(0)
	s_barrier
; #define PG8_STAGE(bufoff, gbase, voff) do { _Pragma("unroll") for (int _i = 0; _i < 2; ++_i) \
;         __builtin_amdgcn_global_load_lds((const unsigned*)((const char*)(gbase) + (voff)[_i]), (PG8_LAS unsigned*)(lds + (bufoff) + ldsw + _i * 8192), 16, 0, 0); } while (0)
; #define PG8_LDA(dst, b, h) do { _Pragma("unroll") for (int m = 0; m < 4; ++m) _Pragma("unroll") for (int k = 0; k < 2; ++k) dst[m][k] = *(const PG8_LAS bf16x8*)(lds + PG8_SA(b, h) + aoff + m * 2048 + k * 1024); } while (0)
; #define PG8_LDB(dst, b, h) do { _Pragma("unroll") for (int n = 0; n < 2; ++n) _Pragma("unroll") for (int k = 0; k < 2; ++k) dst[n][k] = *(const PG8_LAS bf16x8*)(lds + PG8_SB(b, h) + boff + n * 2048 + k * 1024); } while (0)
; #define PG8_WAIT_V(n) asm volatile("s_waitcnt vmcnt(" #n ")" ::: "memory")
; #define PG8_WAIT_L(n) asm volatile("s_waitcnt lgkmcnt(" #n ")" ::: "memory")
; #define PG8_BAR __builtin_amdgcn_s_barrier()
; #define PG8_SCHED __builtin_amdgcn_sched_barrier(0)
; template <class Epi, class Sched, bool ALIGN_EPI = false, bool SP2 = false, bool F8 = false>
; __device__ __forceinline__ void gemm_phase(PG8_LAS unsigned char* lds, const Gemm g, const Sched& S, const Epi& E) {
;     ...
;             PG8_WAIT_V(8); PG8_WAIT_L(0); PG8_BAR; PG8_MMA(1, 0, At, B0); PG8_MMA(1, 1, At, B1); PG8_BAR; PG8_SCHED;
;             PG8_LDB(B0, 1, 0); PG8_LDB(B1, 1, 1); PG8_SCHED; PG8_LDA(At, 1, 0); PG8_STAGE(PG8_SA(0, 1), a2 + hA, voffA);
;             PG8_WAIT_V(8); PG8_WAIT_L(0); PG8_BAR; PG8_MMA(0, 0, At, B0); PG8_MMA(0, 1, At, B1); PG8_BAR; PG8_SCHED;
	v_mfma_f32_16x16x32_bf16 v[62:65], v[130:133], v[162:165], v[62:65]
	v_mfma_f32_16x16x32_bf16 v[58:61], v[138:141], v[162:165], v[58:61]
	v_mfma_f32_16x16x32_bf16 v[46:49], v[130:133], v[170:173], v[46:49]
	v_mfma_f32_16x16x32_bf16 v[42:45], v[138:141], v[170:173], v[42:45]
	v_mfma_f32_16x16x32_bf16 v[30:33], v[130:133], v[194:197], v[30:33]
	v_mfma_f32_16x16x32_bf16 v[26:29], v[138:141], v[194:197], v[26:29]
	v_mfma_f32_16x16x32_bf16 v[14:17], v[130:133], v[202:205], v[14:17]
	v_mfma_f32_16x16x32_bf16 v[10:13], v[138:141], v[202:205], v[10:13]
	v_mfma_f32_16x16x32_bf16 v[62:65], v[134:137], v[166:169], v[62:65]
	v_mfma_f32_16x16x32_bf16 v[58:61], v[142:145], v[166:169], v[58:61]
	v_mfma_f32_16x16x32_bf16 v[46:49], v[134:137], v[174:177], v[46:49]
	v_mfma_f32_16x16x32_bf16 v[42:45], v[142:145], v[174:177], v[42:45]
	v_mfma_f32_16x16x32_bf16 v[30:33], v[134:137], v[198:201], v[30:33]
	v_mfma_f32_16x16x32_bf16 v[26:29], v[142:145], v[198:201], v[26:29]
	v_mfma_f32_16x16x32_bf16 v[14:17], v[134:137], v[214:217], v[14:17]
	v_mfma_f32_16x16x32_bf16 v[10:13], v[142:145], v[214:217], v[10:13]
	v_mfma_f32_16x16x32_bf16 v[54:57], v[146:149], v[162:165], v[54:57]
	v_mfma_f32_16x16x32_bf16 v[50:53], v[154:157], v[162:165], v[50:53]
	v_mfma_f32_16x16x32_bf16 v[38:41], v[146:149], v[170:173], v[38:41]
	v_mfma_f32_16x16x32_bf16 v[34:37], v[154:157], v[170:173], v[34:37]
	v_mfma_f32_16x16x32_bf16 v[22:25], v[146:149], v[194:197], v[22:25]
	v_mfma_f32_16x16x32_bf16 v[18:21], v[154:157], v[194:197], v[18:21]
	v_mfma_f32_16x16x32_bf16 v[6:9], v[146:149], v[202:205], v[6:9]
	v_mfma_f32_16x16x32_bf16 v[2:5], v[154:157], v[202:205], v[2:5]
	v_mfma_f32_16x16x32_bf16 v[54:57], v[150:153], v[166:169], v[54:57]
	v_mfma_f32_16x16x32_bf16 v[50:53], v[158:161], v[166:169], v[50:53]
	v_mfma_f32_16x16x32_bf16 v[38:41], v[150:153], v[174:177], v[38:41]
	v_mfma_f32_16x16x32_bf16 v[34:37], v[158:161], v[174:177], v[34:37]
	v_mfma_f32_16x16x32_bf16 v[22:25], v[150:153], v[198:201], v[22:25]
	v_mfma_f32_16x16x32_bf16 v[18:21], v[158:161], v[198:201], v[18:21]
	v_mfma_f32_16x16x32_bf16 v[6:9], v[150:153], v[214:217], v[6:9]
	v_mfma_f32_16x16x32_bf16 v[2:5], v[158:161], v[214:217], v[2:5]
	s_barrier
	s_add_i32 s62, 0, 0x18000
	s_add_i32 s63, 0, 0x1c000
	v_add_u32_e32 v142, s62, v207
	v_add_u32_e32 v158, s63, v207
	ds_read_b128 v[130:133], v142
	ds_read_b128 v[134:137], v142 offset:1024
	ds_read_b128 v[138:141], v142 offset:2048
	ds_read_b128 v[142:145], v142 offset:3072
	ds_read_b128 v[146:149], v158
	ds_read_b128 v[150:153], v158 offset:1024
	ds_read_b128 v[154:157], v158 offset:2048
	ds_read_b128 v[158:161], v158 offset:3072
	s_add_u32 s40, s40, 0x100000
	s_addc_u32 s41, s41, 0
	s_mov_b32 m0, s43
	v_lshl_add_u64 v[226:227], s[40:41], 0, v[178:179]
	ds_read_b128 v[162:165], v212 offset:32768
	ds_read_b128 v[166:169], v212 offset:33792
	ds_read_b128 v[170:173], v212 offset:34816
	ds_read_b128 v[174:177], v212 offset:35840
	ds_read_b128 v[194:197], v212 offset:36864
	ds_read_b128 v[198:201], v212 offset:37888
	ds_read_b128 v[202:205], v212 offset:38912
	ds_read_b128 v[214:217], v212 offset:39936
	global_load_lds_dwordx4 v[226:227], off
	v_lshl_add_u64 v[226:227], s[40:41], 0, v[182:183]
	s_mov_b32 m0, s44
	s_nop 0
	global_load_lds_dwordx4 v[226:227], off
	s_waitcnt vmcnt(8)
	s_waitcnt lgkmcnt(0)
	s_barrier
	v_mfma_f32_16x16x32_bf16 v[126:129], v[130:133], v[162:165], v[126:129]
	v_mfma_f32_16x16x32_bf16 v[122:125], v[138:141], v[162:165], v[122:125]
	v_mfma_f32_16x16x32_bf16 v[110:113], v[130:133], v[170:173], v[110:113]
	v_mfma_f32_16x16x32_bf16 v[106:109], v[138:141], v[170:173], v[106:109]
	v_mfma_f32_16x16x32_bf16 v[94:97], v[130:133], v[194:197], v[94:97]
	v_mfma_f32_16x16x32_bf16 v[90:93], v[138:141], v[194:197], v[90:93]
	v_mfma_f32_16x16x32_bf16 v[78:81], v[130:133], v[202:205], v[78:81]
	v_mfma_f32_16x16x32_bf16 v[74:77], v[138:141], v[202:205], v[74:77]
	v_mfma_f32_16x16x32_bf16 v[126:129], v[134:137], v[166:169], v[126:129]
	v_mfma_f32_16x16x32_bf16 v[122:125], v[142:145], v[166:169], v[122:125]
	v_mfma_f32_16x16x32_bf16 v[110:113], v[134:137], v[174:177], v[110:113]
	v_mfma_f32_16x16x32_bf16 v[106:109], v[142:145], v[174:177], v[106:109]
	v_mfma_f32_16x16x32_bf16 v[94:97], v[134:137], v[198:201], v[94:97]
	v_mfma_f32_16x16x32_bf16 v[90:93], v[142:145], v[198:201], v[90:93]
	v_mfma_f32_16x16x32_bf16 v[78:81], v[134:137], v[214:217], v[78:81]
	v_mfma_f32_16x16x32_bf16 v[74:77], v[142:145], v[214:217], v[74:77]
	v_mfma_f32_16x16x32_bf16 v[118:121], v[146:149], v[162:165], v[118:121]
	v_mfma_f32_16x16x32_bf16 v[114:117], v[154:157], v[162:165], v[114:117]
	v_mfma_f32_16x16x32_bf16 v[102:105], v[146:149], v[170:173], v[102:105]
	v_mfma_f32_16x16x32_bf16 v[98:101], v[154:157], v[170:173], v[98:101]
	v_mfma_f32_16x16x32_bf16 v[86:89], v[146:149], v[194:197], v[86:89]
	v_mfma_f32_16x16x32_bf16 v[82:85], v[154:157], v[194:197], v[82:85]
	v_mfma_f32_16x16x32_bf16 v[70:73], v[146:149], v[202:205], v[70:73]
	v_mfma_f32_16x16x32_bf16 v[66:69], v[154:157], v[202:205], v[66:69]
	v_mfma_f32_16x16x32_bf16 v[118:121], v[150:153], v[166:169], v[118:121]
	v_mfma_f32_16x16x32_bf16 v[114:117], v[158:161], v[166:169], v[114:117]
	v_mfma_f32_16x16x32_bf16 v[102:105], v[150:153], v[174:177], v[102:105]
	v_mfma_f32_16x16x32_bf16 v[98:101], v[158:161], v[174:177], v[98:101]
	v_mfma_f32_16x16x32_bf16 v[86:89], v[150:153], v[198:201], v[86:89]
	v_mfma_f32_16x16x32_bf16 v[82:85], v[158:161], v[198:201], v[82:85]
	v_mfma_f32_16x16x32_bf16 v[70:73], v[150:153], v[214:217], v[70:73]
	v_mfma_f32_16x16x32_bf16 v[66:69], v[158:161], v[214:217], v[66:69]
	s_barrier
; #define PG8_STAGE(bufoff, gbase, voff) do { _Pragma("unroll") for (int _i = 0; _i < 2; ++_i) \
;         __builtin_amdgcn_global_load_lds((const unsigned*)((const char*)(gbase) + (voff)[_i]), (PG8_LAS unsigned*)(lds + (bufoff) + ldsw + _i * 8192), 16, 0, 0); } while (0)
; #define PG8_LDA(dst, b, h) do { _Pragma("unroll") for (int m = 0; m < 4; ++m) _Pragma("unroll") for (int k = 0; k < 2; ++k) dst[m][k] = *(const PG8_LAS bf16x8*)(lds + PG8_SA(b, h) + aoff + m * 2048 + k * 1024); } while (0)
; #define PG8_WAIT_V(n) asm volatile("s_waitcnt vmcnt(" #n ")" ::: "memory")
; #define PG8_WAIT_L(n) asm volatile("s_waitcnt lgkmcnt(" #n ")" ::: "memory")
; #define PG8_BAR __builtin_amdgcn_s_barrier()
; #define PG8_SCHED __builtin_amdgcn_sched_barrier(0)
;     __device__ __forceinline__ void run(const f32x4 (&acc)[2][2][4][2], const Unit& un, int wr, int wc, int fr, int fq, PG8_LAS unsigned char* xl) const {
;     ...
;         const float* bs = un.pm < split_pm ? base + (size_t)un.pm * BM * 4096 : base2 + (size_t)(un.pm - split_pm) * BM * 4096;
; template <class Epi, class Sched, bool ALIGN_EPI = false, bool SP2 = false, bool F8 = false>
; __device__ __forceinline__ void gemm_phase(PG8_LAS unsigned char* lds, const Gemm g, const Sched& S, const Epi& E) {
;     ...
;             PG8_LDA(At, 1, 1); PG8_STAGE(PG8_SB(1, 0), b3, voffB); PG8_STAGE(PG8_SB(1, 1), b3 + hB, voffB); PG8_STAGE(PG8_SA(1, 0), a3, voffA);
;             PG8_WAIT_V(8); PG8_WAIT_L(0); PG8_BAR; PG8_MMA(1, 0, At, B0); PG8_MMA(1, 1, At, B1); PG8_BAR; PG8_SCHED;
	s_add_i32 s40, s62, s19
	v_lshl_add_u64 v[218:219], v[218:219], 0, s[22:23]
	s_mov_b32 m0, s40
	ds_read_b128 v[162:165], v212 offset:49152
	ds_read_b128 v[166:169], v212 offset:50176
	ds_read_b128 v[170:173], v212 offset:51200
	ds_read_b128 v[174:177], v212 offset:52224
	ds_read_b128 v[194:197], v212 offset:53248
	ds_read_b128 v[198:201], v212 offset:54272
	ds_read_b128 v[202:205], v212 offset:55296
	ds_read_b128 v[214:217], v212 offset:56320
	global_load_lds_dwordx4 v[218:219], off
	s_add_i32 m0, s40, 0x2000
	s_add_u32 s38, s38, 0x100080
	v_lshl_add_u64 v[218:219], v[220:221], 0, s[22:23]
	s_addc_u32 s39, s39, 0
	s_add_i32 s40, s63, s19
	global_load_lds_dwordx4 v[218:219], off
	v_lshl_add_u64 v[218:219], s[38:39], 0, v[180:181]
	s_mov_b32 m0, s40
	s_nop 0
	global_load_lds_dwordx4 v[218:219], off
	v_lshl_add_u64 v[218:219], s[38:39], 0, v[184:185]
	s_add_i32 m0, s40, 0x2000
	s_nop 0
	global_load_lds_dwordx4 v[218:219], off
	v_lshl_add_u64 v[218:219], v[222:223], 0, s[22:23]
	s_mov_b32 m0, s50
	s_nop 0
	global_load_lds_dwordx4 v[218:219], off
	v_lshl_add_u64 v[218:219], v[224:225], 0, s[22:23]
	s_mov_b32 m0, s51
	s_nop 0
	global_load_lds_dwordx4 v[218:219], off
	s_waitcnt vmcnt(8)
	s_waitcnt lgkmcnt(0)
	s_barrier
	v_mfma_f32_16x16x32_bf16 v[62:65], v[130:133], v[162:165], v[62:65]
	v_mfma_f32_16x16x32_bf16 v[58:61], v[138:141], v[162:165], v[58:61]
	v_mfma_f32_16x16x32_bf16 v[46:49], v[130:133], v[170:173], v[46:49]
	v_mfma_f32_16x16x32_bf16 v[42:45], v[138:141], v[170:173], v[42:45]
	v_mfma_f32_16x16x32_bf16 v[30:33], v[130:133], v[194:197], v[30:33]
	v_mfma_f32_16x16x32_bf16 v[26:29], v[138:141], v[194:197], v[26:29]
	v_mfma_f32_16x16x32_bf16 v[14:17], v[130:133], v[202:205], v[14:17]
	v_mfma_f32_16x16x32_bf16 v[10:13], v[138:141], v[202:205], v[10:13]
	v_mfma_f32_16x16x32_bf16 v[62:65], v[134:137], v[166:169], v[62:65]
	v_mfma_f32_16x16x32_bf16 v[58:61], v[142:145], v[166:169], v[58:61]
	v_mfma_f32_16x16x32_bf16 v[46:49], v[134:137], v[174:177], v[46:49]
	v_mfma_f32_16x16x32_bf16 v[42:45], v[142:145], v[174:177], v[42:45]
	v_mfma_f32_16x16x32_bf16 v[30:33], v[134:137], v[198:201], v[30:33]
	v_mfma_f32_16x16x32_bf16 v[26:29], v[142:145], v[198:201], v[26:29]
	v_mfma_f32_16x16x32_bf16 v[14:17], v[134:137], v[214:217], v[14:17]
	v_mfma_f32_16x16x32_bf16 v[10:13], v[142:145], v[214:217], v[10:13]
	v_mfma_f32_16x16x32_bf16 v[54:57], v[146:149], v[162:165], v[54:57]
	v_mfma_f32_16x16x32_bf16 v[50:53], v[154:157], v[162:165], v[50:53]
	v_mfma_f32_16x16x32_bf16 v[38:41], v[146:149], v[170:173], v[38:41]
	v_mfma_f32_16x16x32_bf16 v[34:37], v[154:157], v[170:173], v[34:37]
	v_mfma_f32_16x16x32_bf16 v[22:25], v[146:149], v[194:197], v[22:25]
	v_mfma_f32_16x16x32_bf16 v[18:21], v[154:157], v[194:197], v[18:21]
	v_mfma_f32_16x16x32_bf16 v[6:9], v[146:149], v[202:205], v[6:9]
	v_mfma_f32_16x16x32_bf16 v[2:5], v[154:157], v[202:205], v[2:5]
	v_mfma_f32_16x16x32_bf16 v[54:57], v[150:153], v[166:169], v[54:57]
	v_mfma_f32_16x16x32_bf16 v[50:53], v[158:161], v[166:169], v[50:53]
	v_mfma_f32_16x16x32_bf16 v[38:41], v[150:153], v[174:177], v[38:41]
	v_mfma_f32_16x16x32_bf16 v[34:37], v[158:161], v[174:177], v[34:37]
	v_mfma_f32_16x16x32_bf16 v[22:25], v[150:153], v[198:201], v[22:25]
	v_mfma_f32_16x16x32_bf16 v[18:21], v[158:161], v[198:201], v[18:21]
	v_mfma_f32_16x16x32_bf16 v[6:9], v[150:153], v[214:217], v[6:9]
	v_mfma_f32_16x16x32_bf16 v[2:5], v[158:161], v[214:217], v[2:5]
	s_barrier
	s_add_i32 s61, s61, 2
	s_add_u32 s35, s35, 0x100
	s_addc_u32 s60, s60, 0
	s_add_u32 s36, s36, 0x100
	s_addc_u32 s37, s37, 0
	s_cmp_gt_u32 s61, 61
	s_cbranch_scc0 .LBB0_689
	v_mov_b32_e32 v214, v206
	s_cmp_gt_i32 s16, 63
	s_mov_b64 s[38:39], -1
	s_cbranch_scc0 .LBB0_692
	s_sub_i32 s20, s16, 64
	s_lshl_b64 s[36:37], s[20:21], 22
	s_add_u32 s36, s14, s36
	s_addc_u32 s37, s15, s37
	s_mov_b32 s17, s21
	s_mov_b64 s[38:39], 0

; #define PG8_STAGE(bufoff, gbase, voff) do { _Pragma("unroll") for (int _i = 0; _i < 2; ++_i) \
;         __builtin_amdgcn_global_load_lds((const unsigned*)((const char*)(gbase) + (voff)[_i]), (PG8_LAS unsigned*)(lds + (bufoff) + ldsw + _i * 8192), 16, 0, 0); } while (0)
; #define PG8_LDA(dst, b, h) do { _Pragma("unroll") for (int m = 0; m < 4; ++m) _Pragma("unroll") for (int k = 0; k < 2; ++k) dst[m][k] = *(const PG8_LAS bf16x8*)(lds + PG8_SA(b, h) + aoff + m * 2048 + k * 1024); } while (0)
; #define PG8_LDB(dst, b, h) do { _Pragma("unroll") for (int n = 0; n < 2; ++n) _Pragma("unroll") for (int k = 0; k < 2; ++k) dst[n][k] = *(const PG8_LAS bf16x8*)(lds + PG8_SB(b, h) + boff + n * 2048 + k * 1024); } while (0)
; #define PG8_WAIT_V(n) asm volatile("s_waitcnt vmcnt(" #n ")" ::: "memory")
; #define PG8_WAIT_L(n) asm volatile("s_waitcnt lgkmcnt(" #n ")" ::: "memory")
; #define PG8_BAR __builtin_amdgcn_s_barrier()
; #define PG8_SCHED __builtin_amdgcn_sched_barrier(0)
; template <class Epi, class Sched, bool ALIGN_EPI = false, bool SP2 = false, bool F8 = false>
; __device__ __forceinline__ void gemm_phase(PG8_LAS unsigned char* lds, const Gemm g, const Sched& S, const Epi& E) {
;     ...
;             PG8_LDB(B0, 0, 0); PG8_LDB(B1, 0, 1); PG8_SCHED; PG8_LDA(At, 0, 0); PG8_STAGE(PG8_SA(1, 1), a1 + hA, voffA);
;             PG8_WAIT_V(8); PG8_WAIT_L(0); PG8_BAR; PG8_MMA(0, 0, At, B0); PG8_MMA(0, 1, At, B1); PG8_BAR; PG8_SCHED;
;             PG8_LDA(At, 0, 1); PG8_STAGE(PG8_SB(0, 0), b2, voffB); PG8_STAGE(PG8_SB(0, 1), b2 + hB, voffB); PG8_STAGE(PG8_SA(0, 0), a2, voffA);
;             PG8_WAIT_V(8); PG8_WAIT_L(0); PG8_BAR; PG8_MMA(1, 0, At, B0); PG8_MMA(1, 1, At, B1); PG8_BAR; PG8_SCHED;
.LBB0_770:
	ds_read_b128 v[130:133], v241
	ds_read_b128 v[134:137], v241 offset:1024
	ds_read_b128 v[138:141], v241 offset:2048
	ds_read_b128 v[142:145], v241 offset:3072
	ds_read_b128 v[146:149], v242
	ds_read_b128 v[150:153], v242 offset:1024
	ds_read_b128 v[154:157], v242 offset:2048
	ds_read_b128 v[158:161], v242 offset:3072
	s_add_u32 s14, s12, 0xfff00080
	s_addc_u32 s15, s13, -1
	s_cmp_eq_u32 s80, 60
	s_cselect_b32 s17, s11, s15
	s_cselect_b32 s16, s63, s14
	s_cselect_b32 s15, s61, s79
	s_cselect_b32 s14, s77, s78
	v_lshl_add_u64 v[208:209], s[12:13], 0, v[188:189]
	s_add_i32 m0, s7, 0xc000
	ds_read_b128 v[162:165], v243
	ds_read_b128 v[166:169], v243 offset:1024
	ds_read_b128 v[170:173], v243 offset:2048
	ds_read_b128 v[174:177], v243 offset:3072
	ds_read_b128 v[192:195], v243 offset:4096
	ds_read_b128 v[196:199], v243 offset:5120
	ds_read_b128 v[200:203], v243 offset:6144
	ds_read_b128 v[204:207], v243 offset:7168
	global_load_lds_dwordx4 v[208:209], off
	v_lshl_add_u64 v[208:209], s[12:13], 0, v[186:187]
	s_add_i32 m0, s7, 0xe000
	s_nop 0
	global_load_lds_dwordx4 v[208:209], off
	s_waitcnt vmcnt(8)
	s_waitcnt lgkmcnt(0)
	s_barrier
	v_mfma_f32_16x16x32_bf16 v[126:129], v[130:133], v[162:165], v[126:129]
	v_mfma_f32_16x16x32_bf16 v[90:93], v[138:141], v[162:165], v[90:93]
	v_mfma_f32_16x16x32_bf16 v[110:113], v[130:133], v[170:173], v[110:113]
	v_mfma_f32_16x16x32_bf16 v[86:89], v[138:141], v[170:173], v[86:89]
	v_mfma_f32_16x16x32_bf16 v[106:109], v[130:133], v[192:195], v[106:109]
	v_mfma_f32_16x16x32_bf16 v[82:85], v[138:141], v[192:195], v[82:85]
	v_mfma_f32_16x16x32_bf16 v[118:121], v[130:133], v[200:203], v[118:121]
	v_mfma_f32_16x16x32_bf16 v[122:125], v[138:141], v[200:203], v[122:125]
	v_mfma_f32_16x16x32_bf16 v[126:129], v[134:137], v[166:169], v[126:129]
	v_mfma_f32_16x16x32_bf16 v[90:93], v[142:145], v[166:169], v[90:93]
	v_mfma_f32_16x16x32_bf16 v[110:113], v[134:137], v[174:177], v[110:113]
	v_mfma_f32_16x16x32_bf16 v[86:89], v[142:145], v[174:177], v[86:89]
	v_mfma_f32_16x16x32_bf16 v[106:109], v[134:137], v[196:199], v[106:109]
	v_mfma_f32_16x16x32_bf16 v[82:85], v[142:145], v[196:199], v[82:85]
	v_mfma_f32_16x16x32_bf16 v[118:121], v[134:137], v[204:207], v[118:121]
	v_mfma_f32_16x16x32_bf16 v[122:125], v[142:145], v[204:207], v[122:125]
	v_mfma_f32_16x16x32_bf16 v[94:97], v[146:149], v[162:165], v[94:97]
	v_mfma_f32_16x16x32_bf16 v[66:69], v[154:157], v[162:165], v[66:69]
	v_mfma_f32_16x16x32_bf16 v[102:105], v[146:149], v[170:173], v[102:105]
	v_mfma_f32_16x16x32_bf16 v[78:81], v[154:157], v[170:173], v[78:81]
	v_mfma_f32_16x16x32_bf16 v[98:101], v[146:149], v[192:195], v[98:101]
	v_mfma_f32_16x16x32_bf16 v[74:77], v[154:157], v[192:195], v[74:77]
	v_mfma_f32_16x16x32_bf16 v[70:73], v[146:149], v[200:203], v[70:73]
	v_mfma_f32_16x16x32_bf16 v[58:61], v[154:157], v[200:203], v[58:61]
	v_mfma_f32_16x16x32_bf16 v[94:97], v[150:153], v[166:169], v[94:97]
	v_mfma_f32_16x16x32_bf16 v[66:69], v[158:161], v[166:169], v[66:69]
	v_mfma_f32_16x16x32_bf16 v[102:105], v[150:153], v[174:177], v[102:105]
	v_mfma_f32_16x16x32_bf16 v[78:81], v[158:161], v[174:177], v[78:81]
	v_mfma_f32_16x16x32_bf16 v[98:101], v[150:153], v[196:199], v[98:101]
	v_mfma_f32_16x16x32_bf16 v[74:77], v[158:161], v[196:199], v[74:77]
	v_mfma_f32_16x16x32_bf16 v[70:73], v[150:153], v[204:207], v[70:73]
	v_mfma_f32_16x16x32_bf16 v[58:61], v[158:161], v[204:207], v[58:61]
	s_barrier
	s_add_i32 s81, s97, s6
	v_lshl_add_u64 v[208:209], s[14:15], 0, v[180:181]
	s_mov_b32 m0, s81
	ds_read_b128 v[162:165], v243 offset:16384
	ds_read_b128 v[166:169], v243 offset:17408
	ds_read_b128 v[170:173], v243 offset:18432
	ds_read_b128 v[174:177], v243 offset:19456
	ds_read_b128 v[192:195], v243 offset:20480
	ds_read_b128 v[196:199], v243 offset:21504
	ds_read_b128 v[200:203], v243 offset:22528
	ds_read_b128 v[204:207], v243 offset:23552
	global_load_lds_dwordx4 v[208:209], off
	s_add_i32 m0, s81, 0x2000
	s_add_u32 vcc_lo, s14, 0x100000
	v_lshl_add_u64 v[210:211], s[14:15], 0, v[184:185]
	s_addc_u32 vcc_hi, s15, 0
	s_add_i32 s81, s86, s6
	global_load_lds_dwordx4 v[210:211], off
	v_lshl_add_u64 v[212:213], vcc, 0, v[180:181]
	s_mov_b32 m0, s81
	v_lshl_add_u64 v[214:215], s[16:17], 0, v[182:183]
	global_load_lds_dwordx4 v[212:213], off
	v_lshl_add_u64 v[212:213], vcc, 0, v[184:185]
	s_add_i32 m0, s81, 0x2000
	s_nop 0
	global_load_lds_dwordx4 v[212:213], off
	v_lshl_add_u64 v[212:213], s[16:17], 0, v[178:179]
	s_mov_b32 m0, s7
	s_nop 0
	global_load_lds_dwordx4 v[212:213], off
	s_mov_b32 m0, s18
	s_nop 0
	global_load_lds_dwordx4 v[214:215], off
	s_waitcnt vmcnt(8)
	s_waitcnt lgkmcnt(0)
	s_barrier
; #define PG8_STAGE(bufoff, gbase, voff) do { _Pragma("unroll") for (int _i = 0; _i < 2; ++_i) \
;         __builtin_amdgcn_global_load_lds((const unsigned*)((const char*)(gbase) + (voff)[_i]), (PG8_LAS unsigned*)(lds + (bufoff) + ldsw + _i * 8192), 16, 0, 0); } while (0)
; #define PG8_LDA(dst, b, h) do { _Pragma("unroll") for (int m = 0; m < 4; ++m) _Pragma("unroll") for (int k = 0; k < 2; ++k) dst[m][k] = *(const PG8_LAS bf16x8*)(lds + PG8_SA(b, h) + aoff + m * 2048 + k * 1024); } while (0)
; #define PG8_LDB(dst, b, h) do { _Pragma("unroll") for (int n = 0; n < 2; ++n) _Pragma("unroll") for (int k = 0; k < 2; ++k) dst[n][k] = *(const PG8_LAS bf16x8*)(lds + PG8_SB(b, h) + boff + n * 2048 + k * 1024); } while (0)
; #define PG8_WAIT_V(n) asm volatile("s_waitcnt vmcnt(" #n ")" ::: "memory")
; #define PG8_WAIT_L(n) asm volatile("s_waitcnt lgkmcnt(" #n ")" ::: "memory")
; #define PG8_BAR __builtin_amdgcn_s_barrier()
; #define PG8_SCHED __builtin_amdgcn_sched_barrier(0)
; template <class Epi, class Sched, bool ALIGN_EPI = false, bool SP2 = false, bool F8 = false>
; __device__ __forceinline__ void gemm_phase(PG8_LAS unsigned char* lds, const Gemm g, const Sched& S, const Epi& E) {
;     ...
;             PG8_WAIT_V(8); PG8_WAIT_L(0); PG8_BAR; PG8_MMA(1, 0, At, B0); PG8_MMA(1, 1, At, B1); PG8_BAR; PG8_SCHED;
;             PG8_LDB(B0, 1, 0); PG8_LDB(B1, 1, 1); PG8_SCHED; PG8_LDA(At, 1, 0); PG8_STAGE(PG8_SA(0, 1), a2 + hA, voffA);
;             PG8_WAIT_V(8); PG8_WAIT_L(0); PG8_BAR; PG8_MMA(0, 0, At, B0); PG8_MMA(0, 1, At, B1); PG8_BAR; PG8_SCHED;
	v_mfma_f32_16x16x32_bf16 v[62:65], v[130:133], v[162:165], v[62:65]
	v_mfma_f32_16x16x32_bf16 v[38:41], v[138:141], v[162:165], v[38:41]
	v_mfma_f32_16x16x32_bf16 v[42:45], v[130:133], v[170:173], v[42:45]
	v_mfma_f32_16x16x32_bf16 v[14:17], v[138:141], v[170:173], v[14:17]
	v_mfma_f32_16x16x32_bf16 v[34:37], v[130:133], v[192:195], v[34:37]
	v_mfma_f32_16x16x32_bf16 v[10:13], v[138:141], v[192:195], v[10:13]
	v_mfma_f32_16x16x32_bf16 v[50:53], v[130:133], v[200:203], v[50:53]
	v_mfma_f32_16x16x32_bf16 v[114:117], v[138:141], v[200:203], v[114:117]
	v_mfma_f32_16x16x32_bf16 v[62:65], v[134:137], v[166:169], v[62:65]
	v_mfma_f32_16x16x32_bf16 v[38:41], v[142:145], v[166:169], v[38:41]
	v_mfma_f32_16x16x32_bf16 v[42:45], v[134:137], v[174:177], v[42:45]
	v_mfma_f32_16x16x32_bf16 v[14:17], v[142:145], v[174:177], v[14:17]
	v_mfma_f32_16x16x32_bf16 v[34:37], v[134:137], v[196:199], v[34:37]
	v_mfma_f32_16x16x32_bf16 v[10:13], v[142:145], v[196:199], v[10:13]
	v_mfma_f32_16x16x32_bf16 v[50:53], v[134:137], v[204:207], v[50:53]
	v_mfma_f32_16x16x32_bf16 v[114:117], v[142:145], v[204:207], v[114:117]
	v_mfma_f32_16x16x32_bf16 v[46:49], v[146:149], v[162:165], v[46:49]
	v_mfma_f32_16x16x32_bf16 v[22:25], v[154:157], v[162:165], v[22:25]
	v_mfma_f32_16x16x32_bf16 v[30:33], v[146:149], v[170:173], v[30:33]
	v_mfma_f32_16x16x32_bf16 v[6:9], v[154:157], v[170:173], v[6:9]
	v_mfma_f32_16x16x32_bf16 v[26:29], v[146:149], v[192:195], v[26:29]
	v_mfma_f32_16x16x32_bf16 v[2:5], v[154:157], v[192:195], v[2:5]
	v_mfma_f32_16x16x32_bf16 v[54:57], v[146:149], v[200:203], v[54:57]
	v_mfma_f32_16x16x32_bf16 v[18:21], v[154:157], v[200:203], v[18:21]
	v_mfma_f32_16x16x32_bf16 v[46:49], v[150:153], v[166:169], v[46:49]
	v_mfma_f32_16x16x32_bf16 v[22:25], v[158:161], v[166:169], v[22:25]
	v_mfma_f32_16x16x32_bf16 v[30:33], v[150:153], v[174:177], v[30:33]
	v_mfma_f32_16x16x32_bf16 v[6:9], v[158:161], v[174:177], v[6:9]
	v_mfma_f32_16x16x32_bf16 v[26:29], v[150:153], v[196:199], v[26:29]
	v_mfma_f32_16x16x32_bf16 v[2:5], v[158:161], v[196:199], v[2:5]
	v_mfma_f32_16x16x32_bf16 v[54:57], v[150:153], v[204:207], v[54:57]
	v_mfma_f32_16x16x32_bf16 v[18:21], v[158:161], v[204:207], v[18:21]
	s_barrier
	s_add_i32 s81, 0, 0x18000
	s_add_i32 vcc_lo, 0, 0x1c000
	v_add_u32_e32 v142, s81, v240
	v_add_u32_e32 v158, vcc_lo, v240
	ds_read_b128 v[130:133], v142
	ds_read_b128 v[134:137], v142 offset:1024
	ds_read_b128 v[138:141], v142 offset:2048
	ds_read_b128 v[142:145], v142 offset:3072
	ds_read_b128 v[146:149], v158
	ds_read_b128 v[150:153], v158 offset:1024
	ds_read_b128 v[154:157], v158 offset:2048
	ds_read_b128 v[158:161], v158 offset:3072
	s_add_u32 s16, s16, 0x100000
	s_addc_u32 s17, s17, 0
	s_mov_b32 m0, s19
	v_lshl_add_u64 v[216:217], s[16:17], 0, v[178:179]
	ds_read_b128 v[162:165], v243 offset:32768
	ds_read_b128 v[166:169], v243 offset:33792
	ds_read_b128 v[170:173], v243 offset:34816
	ds_read_b128 v[174:177], v243 offset:35840
	ds_read_b128 v[192:195], v243 offset:36864
	ds_read_b128 v[196:199], v243 offset:37888
	ds_read_b128 v[200:203], v243 offset:38912
	ds_read_b128 v[204:207], v243 offset:39936
	global_load_lds_dwordx4 v[216:217], off
	v_lshl_add_u64 v[216:217], s[16:17], 0, v[182:183]
	s_mov_b32 m0, s33
	s_nop 0
	global_load_lds_dwordx4 v[216:217], off
	s_waitcnt vmcnt(8)
	s_waitcnt lgkmcnt(0)
	s_barrier
	v_mfma_f32_16x16x32_bf16 v[126:129], v[130:133], v[162:165], v[126:129]
	v_mfma_f32_16x16x32_bf16 v[90:93], v[138:141], v[162:165], v[90:93]
	v_mfma_f32_16x16x32_bf16 v[110:113], v[130:133], v[170:173], v[110:113]
	v_mfma_f32_16x16x32_bf16 v[86:89], v[138:141], v[170:173], v[86:89]
	v_mfma_f32_16x16x32_bf16 v[106:109], v[130:133], v[192:195], v[106:109]
	v_mfma_f32_16x16x32_bf16 v[82:85], v[138:141], v[192:195], v[82:85]
	v_mfma_f32_16x16x32_bf16 v[118:121], v[130:133], v[200:203], v[118:121]
	v_mfma_f32_16x16x32_bf16 v[122:125], v[138:141], v[200:203], v[122:125]
	v_mfma_f32_16x16x32_bf16 v[126:129], v[134:137], v[166:169], v[126:129]
	v_mfma_f32_16x16x32_bf16 v[90:93], v[142:145], v[166:169], v[90:93]
	v_mfma_f32_16x16x32_bf16 v[110:113], v[134:137], v[174:177], v[110:113]
	v_mfma_f32_16x16x32_bf16 v[86:89], v[142:145], v[174:177], v[86:89]
	v_mfma_f32_16x16x32_bf16 v[106:109], v[134:137], v[196:199], v[106:109]
	v_mfma_f32_16x16x32_bf16 v[82:85], v[142:145], v[196:199], v[82:85]
	v_mfma_f32_16x16x32_bf16 v[118:121], v[134:137], v[204:207], v[118:121]
	v_mfma_f32_16x16x32_bf16 v[122:125], v[142:145], v[204:207], v[122:125]
	v_mfma_f32_16x16x32_bf16 v[94:97], v[146:149], v[162:165], v[94:97]
	v_mfma_f32_16x16x32_bf16 v[66:69], v[154:157], v[162:165], v[66:69]
	v_mfma_f32_16x16x32_bf16 v[102:105], v[146:149], v[170:173], v[102:105]
	v_mfma_f32_16x16x32_bf16 v[78:81], v[154:157], v[170:173], v[78:81]
	v_mfma_f32_16x16x32_bf16 v[98:101], v[146:149], v[192:195], v[98:101]
	v_mfma_f32_16x16x32_bf16 v[74:77], v[154:157], v[192:195], v[74:77]
	v_mfma_f32_16x16x32_bf16 v[70:73], v[146:149], v[200:203], v[70:73]
	v_mfma_f32_16x16x32_bf16 v[58:61], v[154:157], v[200:203], v[58:61]
	v_mfma_f32_16x16x32_bf16 v[94:97], v[150:153], v[166:169], v[94:97]
	v_mfma_f32_16x16x32_bf16 v[66:69], v[158:161], v[166:169], v[66:69]
	v_mfma_f32_16x16x32_bf16 v[102:105], v[150:153], v[174:177], v[102:105]
	v_mfma_f32_16x16x32_bf16 v[78:81], v[158:161], v[174:177], v[78:81]
	v_mfma_f32_16x16x32_bf16 v[98:101], v[150:153], v[196:199], v[98:101]
	v_mfma_f32_16x16x32_bf16 v[74:77], v[158:161], v[196:199], v[74:77]
	v_mfma_f32_16x16x32_bf16 v[70:73], v[150:153], v[204:207], v[70:73]
	v_mfma_f32_16x16x32_bf16 v[58:61], v[158:161], v[204:207], v[58:61]
	s_barrier
; #define PG8_STAGE(bufoff, gbase, voff) do { _Pragma("unroll") for (int _i = 0; _i < 2; ++_i) \
;         __builtin_amdgcn_global_load_lds((const unsigned*)((const char*)(gbase) + (voff)[_i]), (PG8_LAS unsigned*)(lds + (bufoff) + ldsw + _i * 8192), 16, 0, 0); } while (0)
; #define PG8_LDA(dst, b, h) do { _Pragma("unroll") for (int m = 0; m < 4; ++m) _Pragma("unroll") for (int k = 0; k < 2; ++k) dst[m][k] = *(const PG8_LAS bf16x8*)(lds + PG8_SA(b, h) + aoff + m * 2048 + k * 1024); } while (0)
; #define PG8_WAIT_V(n) asm volatile("s_waitcnt vmcnt(" #n ")" ::: "memory")
; #define PG8_WAIT_L(n) asm volatile("s_waitcnt lgkmcnt(" #n ")" ::: "memory")
; #define PG8_BAR __builtin_amdgcn_s_barrier()
; #define PG8_SCHED __builtin_amdgcn_sched_barrier(0)
; template <class Epi, class Sched, bool ALIGN_EPI = false, bool SP2 = false, bool F8 = false>
; __device__ __forceinline__ void gemm_phase(PG8_LAS unsigned char* lds, const Gemm g, const Sched& S, const Epi& E) {
;     ...
;             PG8_LDA(At, 1, 1); PG8_STAGE(PG8_SB(1, 0), b3, voffB); PG8_STAGE(PG8_SB(1, 1), b3 + hB, voffB); PG8_STAGE(PG8_SA(1, 0), a3, voffA);
;             PG8_WAIT_V(8); PG8_WAIT_L(0); PG8_BAR; PG8_MMA(1, 0, At, B0); PG8_MMA(1, 1, At, B1); PG8_BAR; PG8_SCHED;
;     ...
;         if constexpr (ALIGN_EPI) { if (wr == 0) PG8_BAR; }
	s_add_i32 s16, s81, s6
	v_lshl_add_u64 v[208:209], v[208:209], 0, s[36:37]
	s_mov_b32 m0, s16
	ds_read_b128 v[162:165], v243 offset:49152
	ds_read_b128 v[166:169], v243 offset:50176
	ds_read_b128 v[170:173], v243 offset:51200
	ds_read_b128 v[174:177], v243 offset:52224
	ds_read_b128 v[192:195], v243 offset:53248
	ds_read_b128 v[196:199], v243 offset:54272
	ds_read_b128 v[200:203], v243 offset:55296
	ds_read_b128 v[204:207], v243 offset:56320
	global_load_lds_dwordx4 v[208:209], off
	s_add_i32 m0, s16, 0x2000
	s_add_u32 s14, s14, 0x100080
	v_lshl_add_u64 v[208:209], v[210:211], 0, s[36:37]
	s_addc_u32 s15, s15, 0
	s_add_i32 s16, vcc_lo, s6
	global_load_lds_dwordx4 v[208:209], off
	v_lshl_add_u64 v[208:209], s[14:15], 0, v[180:181]
	s_mov_b32 m0, s16
	s_nop 0
	global_load_lds_dwordx4 v[208:209], off
	v_lshl_add_u64 v[208:209], s[14:15], 0, v[184:185]
	s_add_i32 m0, s16, 0x2000
	s_nop 0
	global_load_lds_dwordx4 v[208:209], off
	v_lshl_add_u64 v[208:209], v[212:213], 0, s[36:37]
	s_mov_b32 m0, s71
	s_nop 0
	global_load_lds_dwordx4 v[208:209], off
	v_lshl_add_u64 v[208:209], v[214:215], 0, s[36:37]
	s_mov_b32 m0, s74
	s_nop 0
	global_load_lds_dwordx4 v[208:209], off
	s_waitcnt vmcnt(8)
	s_waitcnt lgkmcnt(0)
	s_barrier
	v_mfma_f32_16x16x32_bf16 v[62:65], v[130:133], v[162:165], v[62:65]
	v_mfma_f32_16x16x32_bf16 v[38:41], v[138:141], v[162:165], v[38:41]
	v_mfma_f32_16x16x32_bf16 v[42:45], v[130:133], v[170:173], v[42:45]
	v_mfma_f32_16x16x32_bf16 v[14:17], v[138:141], v[170:173], v[14:17]
	v_mfma_f32_16x16x32_bf16 v[34:37], v[130:133], v[192:195], v[34:37]
	v_mfma_f32_16x16x32_bf16 v[10:13], v[138:141], v[192:195], v[10:13]
	v_mfma_f32_16x16x32_bf16 v[50:53], v[130:133], v[200:203], v[50:53]
	v_mfma_f32_16x16x32_bf16 v[114:117], v[138:141], v[200:203], v[114:117]
	v_mfma_f32_16x16x32_bf16 v[62:65], v[134:137], v[166:169], v[62:65]
	v_mfma_f32_16x16x32_bf16 v[38:41], v[142:145], v[166:169], v[38:41]
	v_mfma_f32_16x16x32_bf16 v[42:45], v[134:137], v[174:177], v[42:45]
	v_mfma_f32_16x16x32_bf16 v[14:17], v[142:145], v[174:177], v[14:17]
	v_mfma_f32_16x16x32_bf16 v[34:37], v[134:137], v[196:199], v[34:37]
	v_mfma_f32_16x16x32_bf16 v[10:13], v[142:145], v[196:199], v[10:13]
	v_mfma_f32_16x16x32_bf16 v[50:53], v[134:137], v[204:207], v[50:53]
	v_mfma_f32_16x16x32_bf16 v[114:117], v[142:145], v[204:207], v[114:117]
	v_mfma_f32_16x16x32_bf16 v[46:49], v[146:149], v[162:165], v[46:49]
	v_mfma_f32_16x16x32_bf16 v[22:25], v[154:157], v[162:165], v[22:25]
	v_mfma_f32_16x16x32_bf16 v[30:33], v[146:149], v[170:173], v[30:33]
	v_mfma_f32_16x16x32_bf16 v[6:9], v[154:157], v[170:173], v[6:9]
	v_mfma_f32_16x16x32_bf16 v[26:29], v[146:149], v[192:195], v[26:29]
	v_mfma_f32_16x16x32_bf16 v[2:5], v[154:157], v[192:195], v[2:5]
	v_mfma_f32_16x16x32_bf16 v[54:57], v[146:149], v[200:203], v[54:57]
	v_mfma_f32_16x16x32_bf16 v[18:21], v[154:157], v[200:203], v[18:21]
	v_mfma_f32_16x16x32_bf16 v[46:49], v[150:153], v[166:169], v[46:49]
	v_mfma_f32_16x16x32_bf16 v[22:25], v[158:161], v[166:169], v[22:25]
	v_mfma_f32_16x16x32_bf16 v[30:33], v[150:153], v[174:177], v[30:33]
	v_mfma_f32_16x16x32_bf16 v[6:9], v[158:161], v[174:177], v[6:9]
	v_mfma_f32_16x16x32_bf16 v[26:29], v[150:153], v[196:199], v[26:29]
	v_mfma_f32_16x16x32_bf16 v[2:5], v[158:161], v[196:199], v[2:5]
	v_mfma_f32_16x16x32_bf16 v[54:57], v[150:153], v[204:207], v[54:57]
	v_mfma_f32_16x16x32_bf16 v[18:21], v[158:161], v[204:207], v[18:21]
	s_barrier
	s_add_i32 s80, s80, 2
	s_add_u32 s78, s78, 0x100
	s_addc_u32 s79, s79, 0
	s_add_u32 s12, s12, 0x100
	s_addc_u32 s13, s13, 0
	s_cmp_gt_u32 s80, 61
	s_cbranch_scc0 .LBB0_770
	s_and_b64 vcc, exec, s[38:39]
	s_cbranch_vccz .LBB0_773
	s_barrier

; #define PG8_STAGE(bufoff, gbase, voff) do { _Pragma("unroll") for (int _i = 0; _i < 2; ++_i) \
;         __builtin_amdgcn_global_load_lds((const unsigned*)((const char*)(gbase) + (voff)[_i]), (PG8_LAS unsigned*)(lds + (bufoff) + ldsw + _i * 8192), 16, 0, 0); } while (0)
; #define PG8_LDA(dst, b, h) do { _Pragma("unroll") for (int m = 0; m < 4; ++m) _Pragma("unroll") for (int k = 0; k < 2; ++k) dst[m][k] = *(const PG8_LAS bf16x8*)(lds + PG8_SA(b, h) + aoff + m * 2048 + k * 1024); } while (0)
; #define PG8_LDB(dst, b, h) do { _Pragma("unroll") for (int n = 0; n < 2; ++n) _Pragma("unroll") for (int k = 0; k < 2; ++k) dst[n][k] = *(const PG8_LAS bf16x8*)(lds + PG8_SB(b, h) + boff + n * 2048 + k * 1024); } while (0)
; #define PG8_WAIT_V(n) asm volatile("s_waitcnt vmcnt(" #n ")" ::: "memory")
; #define PG8_WAIT_L(n) asm volatile("s_waitcnt lgkmcnt(" #n ")" ::: "memory")
; #define PG8_BAR __builtin_amdgcn_s_barrier()
; #define PG8_SCHED __builtin_amdgcn_sched_barrier(0)
; template <class Epi, class Sched, bool ALIGN_EPI = false, bool SP2 = false, bool F8 = false>
; __device__ __forceinline__ void gemm_phase(PG8_LAS unsigned char* lds, const Gemm g, const Sched& S, const Epi& E) {
;     ...
;             PG8_LDB(B0, 0, 0); PG8_LDB(B1, 0, 1); PG8_SCHED; PG8_LDA(At, 0, 0); PG8_STAGE(PG8_SA(1, 1), a1 + hA, voffA);
;             PG8_WAIT_V(8); PG8_WAIT_L(0); PG8_BAR; PG8_MMA(0, 0, At, B0); PG8_MMA(0, 1, At, B1); PG8_BAR; PG8_SCHED;
;             PG8_LDA(At, 0, 1); PG8_STAGE(PG8_SB(0, 0), b2, voffB); PG8_STAGE(PG8_SB(0, 1), b2 + hB, voffB); PG8_STAGE(PG8_SA(0, 0), a2, voffA);
;             PG8_WAIT_V(8); PG8_WAIT_L(0); PG8_BAR; PG8_MMA(1, 0, At, B0); PG8_MMA(1, 1, At, B1); PG8_BAR; PG8_SCHED;
.LBB0_825:
	ds_read_b128 v[130:133], v241
	ds_read_b128 v[134:137], v241 offset:1024
	ds_read_b128 v[138:141], v241 offset:2048
	ds_read_b128 v[142:145], v241 offset:3072
	ds_read_b128 v[146:149], v242
	ds_read_b128 v[150:153], v242 offset:1024
	ds_read_b128 v[154:157], v242 offset:2048
	ds_read_b128 v[158:161], v242 offset:3072
	s_add_u32 s14, s12, 0xfff00080
	s_addc_u32 s15, s13, -1
	s_cmp_eq_u32 s82, 60
	s_cselect_b32 s17, s11, s15
	s_cselect_b32 s16, s63, s14
	s_cselect_b32 s15, s65, s81
	s_cselect_b32 s14, s79, s80
	v_lshl_add_u64 v[208:209], s[12:13], 0, v[188:189]
	s_add_i32 m0, s7, 0xc000
	ds_read_b128 v[162:165], v243
	ds_read_b128 v[166:169], v243 offset:1024
	ds_read_b128 v[170:173], v243 offset:2048
	ds_read_b128 v[174:177], v243 offset:3072
	ds_read_b128 v[192:195], v243 offset:4096
	ds_read_b128 v[196:199], v243 offset:5120
	ds_read_b128 v[200:203], v243 offset:6144
	ds_read_b128 v[204:207], v243 offset:7168
	global_load_lds_dwordx4 v[208:209], off
	v_lshl_add_u64 v[208:209], s[12:13], 0, v[186:187]
	s_add_i32 m0, s7, 0xe000
	s_nop 0
	global_load_lds_dwordx4 v[208:209], off
	s_waitcnt vmcnt(8)
	s_waitcnt lgkmcnt(0)
	s_barrier
	v_mfma_f32_16x16x32_bf16 v[126:129], v[130:133], v[162:165], v[126:129]
	v_mfma_f32_16x16x32_bf16 v[90:93], v[138:141], v[162:165], v[90:93]
	v_mfma_f32_16x16x32_bf16 v[110:113], v[130:133], v[170:173], v[110:113]
	v_mfma_f32_16x16x32_bf16 v[86:89], v[138:141], v[170:173], v[86:89]
	v_mfma_f32_16x16x32_bf16 v[106:109], v[130:133], v[192:195], v[106:109]
	v_mfma_f32_16x16x32_bf16 v[82:85], v[138:141], v[192:195], v[82:85]
	v_mfma_f32_16x16x32_bf16 v[118:121], v[130:133], v[200:203], v[118:121]
	v_mfma_f32_16x16x32_bf16 v[122:125], v[138:141], v[200:203], v[122:125]
	v_mfma_f32_16x16x32_bf16 v[126:129], v[134:137], v[166:169], v[126:129]
	v_mfma_f32_16x16x32_bf16 v[90:93], v[142:145], v[166:169], v[90:93]
	v_mfma_f32_16x16x32_bf16 v[110:113], v[134:137], v[174:177], v[110:113]
	v_mfma_f32_16x16x32_bf16 v[86:89], v[142:145], v[174:177], v[86:89]
	v_mfma_f32_16x16x32_bf16 v[106:109], v[134:137], v[196:199], v[106:109]
	v_mfma_f32_16x16x32_bf16 v[82:85], v[142:145], v[196:199], v[82:85]
	v_mfma_f32_16x16x32_bf16 v[118:121], v[134:137], v[204:207], v[118:121]
	v_mfma_f32_16x16x32_bf16 v[122:125], v[142:145], v[204:207], v[122:125]
	v_mfma_f32_16x16x32_bf16 v[94:97], v[146:149], v[162:165], v[94:97]
	v_mfma_f32_16x16x32_bf16 v[66:69], v[154:157], v[162:165], v[66:69]
	v_mfma_f32_16x16x32_bf16 v[102:105], v[146:149], v[170:173], v[102:105]
	v_mfma_f32_16x16x32_bf16 v[78:81], v[154:157], v[170:173], v[78:81]
	v_mfma_f32_16x16x32_bf16 v[98:101], v[146:149], v[192:195], v[98:101]
	v_mfma_f32_16x16x32_bf16 v[74:77], v[154:157], v[192:195], v[74:77]
	v_mfma_f32_16x16x32_bf16 v[70:73], v[146:149], v[200:203], v[70:73]
	v_mfma_f32_16x16x32_bf16 v[58:61], v[154:157], v[200:203], v[58:61]
	v_mfma_f32_16x16x32_bf16 v[94:97], v[150:153], v[166:169], v[94:97]
	v_mfma_f32_16x16x32_bf16 v[66:69], v[158:161], v[166:169], v[66:69]
	v_mfma_f32_16x16x32_bf16 v[102:105], v[150:153], v[174:177], v[102:105]
	v_mfma_f32_16x16x32_bf16 v[78:81], v[158:161], v[174:177], v[78:81]
	v_mfma_f32_16x16x32_bf16 v[98:101], v[150:153], v[196:199], v[98:101]
	v_mfma_f32_16x16x32_bf16 v[74:77], v[158:161], v[196:199], v[74:77]
	v_mfma_f32_16x16x32_bf16 v[70:73], v[150:153], v[204:207], v[70:73]
	v_mfma_f32_16x16x32_bf16 v[58:61], v[158:161], v[204:207], v[58:61]
	s_barrier
	s_add_i32 s83, s30, s5
	v_lshl_add_u64 v[208:209], s[14:15], 0, v[180:181]
	s_mov_b32 m0, s83
	ds_read_b128 v[162:165], v243 offset:16384
	ds_read_b128 v[166:169], v243 offset:17408
	ds_read_b128 v[170:173], v243 offset:18432
	ds_read_b128 v[174:177], v243 offset:19456
	ds_read_b128 v[192:195], v243 offset:20480
	ds_read_b128 v[196:199], v243 offset:21504
	ds_read_b128 v[200:203], v243 offset:22528
	ds_read_b128 v[204:207], v243 offset:23552
	global_load_lds_dwordx4 v[208:209], off
	s_add_i32 m0, s83, 0x2000
	s_add_u32 vcc_lo, s14, 0x100000
	v_lshl_add_u64 v[210:211], s[14:15], 0, v[184:185]
	s_addc_u32 vcc_hi, s15, 0
	s_add_i32 s83, s86, s5
	global_load_lds_dwordx4 v[210:211], off
	v_lshl_add_u64 v[212:213], vcc, 0, v[180:181]
	s_mov_b32 m0, s83
	v_lshl_add_u64 v[214:215], s[16:17], 0, v[182:183]
	global_load_lds_dwordx4 v[212:213], off
	v_lshl_add_u64 v[212:213], vcc, 0, v[184:185]
	s_add_i32 m0, s83, 0x2000
	s_nop 0
	global_load_lds_dwordx4 v[212:213], off
	v_lshl_add_u64 v[212:213], s[16:17], 0, v[178:179]
	s_mov_b32 m0, s7
	s_nop 0
	global_load_lds_dwordx4 v[212:213], off
	s_mov_b32 m0, s18
	s_nop 0
	global_load_lds_dwordx4 v[214:215], off
	s_waitcnt vmcnt(8)
	s_waitcnt lgkmcnt(0)
	s_barrier
; #define PG8_STAGE(bufoff, gbase, voff) do { _Pragma("unroll") for (int _i = 0; _i < 2; ++_i) \
;         __builtin_amdgcn_global_load_lds((const unsigned*)((const char*)(gbase) + (voff)[_i]), (PG8_LAS unsigned*)(lds + (bufoff) + ldsw + _i * 8192), 16, 0, 0); } while (0)
; #define PG8_LDA(dst, b, h) do { _Pragma("unroll") for (int m = 0; m < 4; ++m) _Pragma("unroll") for (int k = 0; k < 2; ++k) dst[m][k] = *(const PG8_LAS bf16x8*)(lds + PG8_SA(b, h) + aoff + m * 2048 + k * 1024); } while (0)
; #define PG8_LDB(dst, b, h) do { _Pragma("unroll") for (int n = 0; n < 2; ++n) _Pragma("unroll") for (int k = 0; k < 2; ++k) dst[n][k] = *(const PG8_LAS bf16x8*)(lds + PG8_SB(b, h) + boff + n * 2048 + k * 1024); } while (0)
; #define PG8_WAIT_V(n) asm volatile("s_waitcnt vmcnt(" #n ")" ::: "memory")
; #define PG8_WAIT_L(n) asm volatile("s_waitcnt lgkmcnt(" #n ")" ::: "memory")
; #define PG8_BAR __builtin_amdgcn_s_barrier()
; #define PG8_SCHED __builtin_amdgcn_sched_barrier(0)
; template <class Epi, class Sched, bool ALIGN_EPI = false, bool SP2 = false, bool F8 = false>
; __device__ __forceinline__ void gemm_phase(PG8_LAS unsigned char* lds, const Gemm g, const Sched& S, const Epi& E) {
;     ...
;             PG8_WAIT_V(8); PG8_WAIT_L(0); PG8_BAR; PG8_MMA(1, 0, At, B0); PG8_MMA(1, 1, At, B1); PG8_BAR; PG8_SCHED;
;             PG8_LDB(B0, 1, 0); PG8_LDB(B1, 1, 1); PG8_SCHED; PG8_LDA(At, 1, 0); PG8_STAGE(PG8_SA(0, 1), a2 + hA, voffA);
;             PG8_WAIT_V(8); PG8_WAIT_L(0); PG8_BAR; PG8_MMA(0, 0, At, B0); PG8_MMA(0, 1, At, B1); PG8_BAR; PG8_SCHED;
	v_mfma_f32_16x16x32_bf16 v[62:65], v[130:133], v[162:165], v[62:65]
	v_mfma_f32_16x16x32_bf16 v[38:41], v[138:141], v[162:165], v[38:41]
	v_mfma_f32_16x16x32_bf16 v[42:45], v[130:133], v[170:173], v[42:45]
	v_mfma_f32_16x16x32_bf16 v[14:17], v[138:141], v[170:173], v[14:17]
	v_mfma_f32_16x16x32_bf16 v[34:37], v[130:133], v[192:195], v[34:37]
	v_mfma_f32_16x16x32_bf16 v[10:13], v[138:141], v[192:195], v[10:13]
	v_mfma_f32_16x16x32_bf16 v[50:53], v[130:133], v[200:203], v[50:53]
	v_mfma_f32_16x16x32_bf16 v[114:117], v[138:141], v[200:203], v[114:117]
	v_mfma_f32_16x16x32_bf16 v[62:65], v[134:137], v[166:169], v[62:65]
	v_mfma_f32_16x16x32_bf16 v[38:41], v[142:145], v[166:169], v[38:41]
	v_mfma_f32_16x16x32_bf16 v[42:45], v[134:137], v[174:177], v[42:45]
	v_mfma_f32_16x16x32_bf16 v[14:17], v[142:145], v[174:177], v[14:17]
	v_mfma_f32_16x16x32_bf16 v[34:37], v[134:137], v[196:199], v[34:37]
	v_mfma_f32_16x16x32_bf16 v[10:13], v[142:145], v[196:199], v[10:13]
	v_mfma_f32_16x16x32_bf16 v[50:53], v[134:137], v[204:207], v[50:53]
	v_mfma_f32_16x16x32_bf16 v[114:117], v[142:145], v[204:207], v[114:117]
	v_mfma_f32_16x16x32_bf16 v[46:49], v[146:149], v[162:165], v[46:49]
	v_mfma_f32_16x16x32_bf16 v[22:25], v[154:157], v[162:165], v[22:25]
	v_mfma_f32_16x16x32_bf16 v[30:33], v[146:149], v[170:173], v[30:33]
	v_mfma_f32_16x16x32_bf16 v[6:9], v[154:157], v[170:173], v[6:9]
	v_mfma_f32_16x16x32_bf16 v[26:29], v[146:149], v[192:195], v[26:29]
	v_mfma_f32_16x16x32_bf16 v[2:5], v[154:157], v[192:195], v[2:5]
	v_mfma_f32_16x16x32_bf16 v[54:57], v[146:149], v[200:203], v[54:57]
	v_mfma_f32_16x16x32_bf16 v[18:21], v[154:157], v[200:203], v[18:21]
	v_mfma_f32_16x16x32_bf16 v[46:49], v[150:153], v[166:169], v[46:49]
	v_mfma_f32_16x16x32_bf16 v[22:25], v[158:161], v[166:169], v[22:25]
	v_mfma_f32_16x16x32_bf16 v[30:33], v[150:153], v[174:177], v[30:33]
	v_mfma_f32_16x16x32_bf16 v[6:9], v[158:161], v[174:177], v[6:9]
	v_mfma_f32_16x16x32_bf16 v[26:29], v[150:153], v[196:199], v[26:29]
	v_mfma_f32_16x16x32_bf16 v[2:5], v[158:161], v[196:199], v[2:5]
	v_mfma_f32_16x16x32_bf16 v[54:57], v[150:153], v[204:207], v[54:57]
	v_mfma_f32_16x16x32_bf16 v[18:21], v[158:161], v[204:207], v[18:21]
	s_barrier
	s_add_i32 s83, 0, 0x18000
	s_add_i32 vcc_lo, 0, 0x1c000
	v_add_u32_e32 v142, s83, v240
	v_add_u32_e32 v158, vcc_lo, v240
	ds_read_b128 v[130:133], v142
	ds_read_b128 v[134:137], v142 offset:1024
	ds_read_b128 v[138:141], v142 offset:2048
	ds_read_b128 v[142:145], v142 offset:3072
	ds_read_b128 v[146:149], v158
	ds_read_b128 v[150:153], v158 offset:1024
	ds_read_b128 v[154:157], v158 offset:2048
	ds_read_b128 v[158:161], v158 offset:3072
	s_add_u32 s16, s16, 0x100000
	s_addc_u32 s17, s17, 0
	s_mov_b32 m0, s19
	v_lshl_add_u64 v[216:217], s[16:17], 0, v[178:179]
	ds_read_b128 v[162:165], v243 offset:32768
	ds_read_b128 v[166:169], v243 offset:33792
	ds_read_b128 v[170:173], v243 offset:34816
	ds_read_b128 v[174:177], v243 offset:35840
	ds_read_b128 v[192:195], v243 offset:36864
	ds_read_b128 v[196:199], v243 offset:37888
	ds_read_b128 v[200:203], v243 offset:38912
	ds_read_b128 v[204:207], v243 offset:39936
	global_load_lds_dwordx4 v[216:217], off
	v_lshl_add_u64 v[216:217], s[16:17], 0, v[182:183]
	s_mov_b32 m0, s29
	s_nop 0
	global_load_lds_dwordx4 v[216:217], off
	s_waitcnt vmcnt(8)
	s_waitcnt lgkmcnt(0)
	s_barrier
	v_mfma_f32_16x16x32_bf16 v[126:129], v[130:133], v[162:165], v[126:129]
	v_mfma_f32_16x16x32_bf16 v[90:93], v[138:141], v[162:165], v[90:93]
	v_mfma_f32_16x16x32_bf16 v[110:113], v[130:133], v[170:173], v[110:113]
	v_mfma_f32_16x16x32_bf16 v[86:89], v[138:141], v[170:173], v[86:89]
	v_mfma_f32_16x16x32_bf16 v[106:109], v[130:133], v[192:195], v[106:109]
	v_mfma_f32_16x16x32_bf16 v[82:85], v[138:141], v[192:195], v[82:85]
	v_mfma_f32_16x16x32_bf16 v[118:121], v[130:133], v[200:203], v[118:121]
	v_mfma_f32_16x16x32_bf16 v[122:125], v[138:141], v[200:203], v[122:125]
	v_mfma_f32_16x16x32_bf16 v[126:129], v[134:137], v[166:169], v[126:129]
	v_mfma_f32_16x16x32_bf16 v[90:93], v[142:145], v[166:169], v[90:93]
	v_mfma_f32_16x16x32_bf16 v[110:113], v[134:137], v[174:177], v[110:113]
	v_mfma_f32_16x16x32_bf16 v[86:89], v[142:145], v[174:177], v[86:89]
	v_mfma_f32_16x16x32_bf16 v[106:109], v[134:137], v[196:199], v[106:109]
	v_mfma_f32_16x16x32_bf16 v[82:85], v[142:145], v[196:199], v[82:85]
	v_mfma_f32_16x16x32_bf16 v[118:121], v[134:137], v[204:207], v[118:121]
	v_mfma_f32_16x16x32_bf16 v[122:125], v[142:145], v[204:207], v[122:125]
	v_mfma_f32_16x16x32_bf16 v[94:97], v[146:149], v[162:165], v[94:97]
	v_mfma_f32_16x16x32_bf16 v[66:69], v[154:157], v[162:165], v[66:69]
	v_mfma_f32_16x16x32_bf16 v[102:105], v[146:149], v[170:173], v[102:105]
	v_mfma_f32_16x16x32_bf16 v[78:81], v[154:157], v[170:173], v[78:81]
	v_mfma_f32_16x16x32_bf16 v[98:101], v[146:149], v[192:195], v[98:101]
	v_mfma_f32_16x16x32_bf16 v[74:77], v[154:157], v[192:195], v[74:77]
	v_mfma_f32_16x16x32_bf16 v[70:73], v[146:149], v[200:203], v[70:73]
	v_mfma_f32_16x16x32_bf16 v[58:61], v[154:157], v[200:203], v[58:61]
	v_mfma_f32_16x16x32_bf16 v[94:97], v[150:153], v[166:169], v[94:97]
	v_mfma_f32_16x16x32_bf16 v[66:69], v[158:161], v[166:169], v[66:69]
	v_mfma_f32_16x16x32_bf16 v[102:105], v[150:153], v[174:177], v[102:105]
	v_mfma_f32_16x16x32_bf16 v[78:81], v[158:161], v[174:177], v[78:81]
	v_mfma_f32_16x16x32_bf16 v[98:101], v[150:153], v[196:199], v[98:101]
	v_mfma_f32_16x16x32_bf16 v[74:77], v[158:161], v[196:199], v[74:77]
	v_mfma_f32_16x16x32_bf16 v[70:73], v[150:153], v[204:207], v[70:73]
	v_mfma_f32_16x16x32_bf16 v[58:61], v[158:161], v[204:207], v[58:61]
	s_barrier
; #define PG8_STAGE(bufoff, gbase, voff) do { _Pragma("unroll") for (int _i = 0; _i < 2; ++_i) \
;         __builtin_amdgcn_global_load_lds((const unsigned*)((const char*)(gbase) + (voff)[_i]), (PG8_LAS unsigned*)(lds + (bufoff) + ldsw + _i * 8192), 16, 0, 0); } while (0)
; #define PG8_LDA(dst, b, h) do { _Pragma("unroll") for (int m = 0; m < 4; ++m) _Pragma("unroll") for (int k = 0; k < 2; ++k) dst[m][k] = *(const PG8_LAS bf16x8*)(lds + PG8_SA(b, h) + aoff + m * 2048 + k * 1024); } while (0)
; #define PG8_WAIT_V(n) asm volatile("s_waitcnt vmcnt(" #n ")" ::: "memory")
; #define PG8_WAIT_L(n) asm volatile("s_waitcnt lgkmcnt(" #n ")" ::: "memory")
; #define PG8_BAR __builtin_amdgcn_s_barrier()
; #define PG8_SCHED __builtin_amdgcn_sched_barrier(0)
; template <class Epi, class Sched, bool ALIGN_EPI = false, bool SP2 = false, bool F8 = false>
; __device__ __forceinline__ void gemm_phase(PG8_LAS unsigned char* lds, const Gemm g, const Sched& S, const Epi& E) {
;     ...
;             PG8_LDA(At, 1, 1); PG8_STAGE(PG8_SB(1, 0), b3, voffB); PG8_STAGE(PG8_SB(1, 1), b3 + hB, voffB); PG8_STAGE(PG8_SA(1, 0), a3, voffA);
;             PG8_WAIT_V(8); PG8_WAIT_L(0); PG8_BAR; PG8_MMA(1, 0, At, B0); PG8_MMA(1, 1, At, B1); PG8_BAR; PG8_SCHED;
;     ...
;         if constexpr (ALIGN_EPI) { if (wr == 0) PG8_BAR; }
	s_add_i32 s16, s83, s5
	v_lshl_add_u64 v[208:209], v[208:209], 0, s[38:39]
	s_mov_b32 m0, s16
	ds_read_b128 v[162:165], v243 offset:49152
	ds_read_b128 v[166:169], v243 offset:50176
	ds_read_b128 v[170:173], v243 offset:51200
	ds_read_b128 v[174:177], v243 offset:52224
	ds_read_b128 v[192:195], v243 offset:53248
	ds_read_b128 v[196:199], v243 offset:54272
	ds_read_b128 v[200:203], v243 offset:55296
	ds_read_b128 v[204:207], v243 offset:56320
	global_load_lds_dwordx4 v[208:209], off
	s_add_i32 m0, s16, 0x2000
	s_add_u32 s14, s14, 0x100080
	v_lshl_add_u64 v[208:209], v[210:211], 0, s[38:39]
	s_addc_u32 s15, s15, 0
	s_add_i32 s16, vcc_lo, s5
	global_load_lds_dwordx4 v[208:209], off
	v_lshl_add_u64 v[208:209], s[14:15], 0, v[180:181]
	s_mov_b32 m0, s16
	s_nop 0
	global_load_lds_dwordx4 v[208:209], off
	v_lshl_add_u64 v[208:209], s[14:15], 0, v[184:185]
	s_add_i32 m0, s16, 0x2000
	s_nop 0
	global_load_lds_dwordx4 v[208:209], off
	v_lshl_add_u64 v[208:209], v[212:213], 0, s[38:39]
	s_mov_b32 m0, s70
	s_nop 0
	global_load_lds_dwordx4 v[208:209], off
	v_lshl_add_u64 v[208:209], v[214:215], 0, s[38:39]
	s_mov_b32 m0, s71
	s_nop 0
	global_load_lds_dwordx4 v[208:209], off
	s_waitcnt vmcnt(8)
	s_waitcnt lgkmcnt(0)
	s_barrier
	v_mfma_f32_16x16x32_bf16 v[62:65], v[130:133], v[162:165], v[62:65]
	v_mfma_f32_16x16x32_bf16 v[38:41], v[138:141], v[162:165], v[38:41]
	v_mfma_f32_16x16x32_bf16 v[42:45], v[130:133], v[170:173], v[42:45]
	v_mfma_f32_16x16x32_bf16 v[14:17], v[138:141], v[170:173], v[14:17]
	v_mfma_f32_16x16x32_bf16 v[34:37], v[130:133], v[192:195], v[34:37]
	v_mfma_f32_16x16x32_bf16 v[10:13], v[138:141], v[192:195], v[10:13]
	v_mfma_f32_16x16x32_bf16 v[50:53], v[130:133], v[200:203], v[50:53]
	v_mfma_f32_16x16x32_bf16 v[114:117], v[138:141], v[200:203], v[114:117]
	v_mfma_f32_16x16x32_bf16 v[62:65], v[134:137], v[166:169], v[62:65]
	v_mfma_f32_16x16x32_bf16 v[38:41], v[142:145], v[166:169], v[38:41]
	v_mfma_f32_16x16x32_bf16 v[42:45], v[134:137], v[174:177], v[42:45]
	v_mfma_f32_16x16x32_bf16 v[14:17], v[142:145], v[174:177], v[14:17]
	v_mfma_f32_16x16x32_bf16 v[34:37], v[134:137], v[196:199], v[34:37]
	v_mfma_f32_16x16x32_bf16 v[10:13], v[142:145], v[196:199], v[10:13]
	v_mfma_f32_16x16x32_bf16 v[50:53], v[134:137], v[204:207], v[50:53]
	v_mfma_f32_16x16x32_bf16 v[114:117], v[142:145], v[204:207], v[114:117]
	v_mfma_f32_16x16x32_bf16 v[46:49], v[146:149], v[162:165], v[46:49]
	v_mfma_f32_16x16x32_bf16 v[22:25], v[154:157], v[162:165], v[22:25]
	v_mfma_f32_16x16x32_bf16 v[30:33], v[146:149], v[170:173], v[30:33]
	v_mfma_f32_16x16x32_bf16 v[6:9], v[154:157], v[170:173], v[6:9]
	v_mfma_f32_16x16x32_bf16 v[26:29], v[146:149], v[192:195], v[26:29]
	v_mfma_f32_16x16x32_bf16 v[2:5], v[154:157], v[192:195], v[2:5]
	v_mfma_f32_16x16x32_bf16 v[54:57], v[146:149], v[200:203], v[54:57]
	v_mfma_f32_16x16x32_bf16 v[18:21], v[154:157], v[200:203], v[18:21]
	v_mfma_f32_16x16x32_bf16 v[46:49], v[150:153], v[166:169], v[46:49]
	v_mfma_f32_16x16x32_bf16 v[22:25], v[158:161], v[166:169], v[22:25]
	v_mfma_f32_16x16x32_bf16 v[30:33], v[150:153], v[174:177], v[30:33]
	v_mfma_f32_16x16x32_bf16 v[6:9], v[158:161], v[174:177], v[6:9]
	v_mfma_f32_16x16x32_bf16 v[26:29], v[150:153], v[196:199], v[26:29]
	v_mfma_f32_16x16x32_bf16 v[2:5], v[158:161], v[196:199], v[2:5]
	v_mfma_f32_16x16x32_bf16 v[54:57], v[150:153], v[204:207], v[54:57]
	v_mfma_f32_16x16x32_bf16 v[18:21], v[158:161], v[204:207], v[18:21]
	s_barrier
	s_add_i32 s82, s82, 2
	s_add_u32 s80, s80, 0x100
	s_addc_u32 s81, s81, 0
	s_add_u32 s12, s12, 0x100
	s_addc_u32 s13, s13, 0
	s_cmp_gt_u32 s82, 61
	s_cbranch_scc0 .LBB0_825
	s_and_b64 vcc, exec, s[40:41]
	s_cbranch_vccz .LBB0_828
	s_barrier

; #define PG8_STAGE(bufoff, gbase, voff) do { _Pragma("unroll") for (int _i = 0; _i < 2; ++_i) \
;         __builtin_amdgcn_global_load_lds((const unsigned*)((const char*)(gbase) + (voff)[_i]), (PG8_LAS unsigned*)(lds + (bufoff) + ldsw + _i * 8192), 16, 0, 0); } while (0)
; #define PG8_LDA(dst, b, h) do { _Pragma("unroll") for (int m = 0; m < 4; ++m) _Pragma("unroll") for (int k = 0; k < 2; ++k) dst[m][k] = *(const PG8_LAS bf16x8*)(lds + PG8_SA(b, h) + aoff + m * 2048 + k * 1024); } while (0)
; #define PG8_LDB(dst, b, h) do { _Pragma("unroll") for (int n = 0; n < 2; ++n) _Pragma("unroll") for (int k = 0; k < 2; ++k) dst[n][k] = *(const PG8_LAS bf16x8*)(lds + PG8_SB(b, h) + boff + n * 2048 + k * 1024); } while (0)
; #define PG8_WAIT_V(n) asm volatile("s_waitcnt vmcnt(" #n ")" ::: "memory")
; #define PG8_WAIT_L(n) asm volatile("s_waitcnt lgkmcnt(" #n ")" ::: "memory")
; #define PG8_BAR __builtin_amdgcn_s_barrier()
; #define PG8_SCHED __builtin_amdgcn_sched_barrier(0)
; template <class Epi, class Sched, bool ALIGN_EPI = false, bool SP2 = false, bool F8 = false>
; __device__ __forceinline__ void gemm_phase(PG8_LAS unsigned char* lds, const Gemm g, const Sched& S, const Epi& E) {
;     ...
;             PG8_LDB(B0, 0, 0); PG8_LDB(B1, 0, 1); PG8_SCHED; PG8_LDA(At, 0, 0); PG8_STAGE(PG8_SA(1, 1), a1 + hA, voffA);
;             PG8_WAIT_V(8); PG8_WAIT_L(0); PG8_BAR; PG8_MMA(0, 0, At, B0); PG8_MMA(0, 1, At, B1); PG8_BAR; PG8_SCHED;
;             PG8_LDA(At, 0, 1); PG8_STAGE(PG8_SB(0, 0), b2, voffB); PG8_STAGE(PG8_SB(0, 1), b2 + hB, voffB); PG8_STAGE(PG8_SA(0, 0), a2, voffA);
;             PG8_WAIT_V(8); PG8_WAIT_L(0); PG8_BAR; PG8_MMA(1, 0, At, B0); PG8_MMA(1, 1, At, B1); PG8_BAR; PG8_SCHED;
.LBB0_883:
	ds_read_b128 v[130:133], v247
	ds_read_b128 v[134:137], v247 offset:1024
	ds_read_b128 v[138:141], v247 offset:2048
	ds_read_b128 v[142:145], v247 offset:3072
	ds_read_b128 v[146:149], v248
	ds_read_b128 v[150:153], v248 offset:1024
	ds_read_b128 v[154:157], v248 offset:2048
	ds_read_b128 v[158:161], v248 offset:3072
	s_add_u32 s14, s10, 0xfff00080
	s_addc_u32 s15, s11, -1
	s_cmp_eq_u32 s88, 12
	s_cselect_b32 s17, s13, s15
	s_cselect_b32 s16, s77, s14
	s_cselect_b32 s15, s79, s87
	s_cselect_b32 s14, s85, s86
	v_lshl_add_u64 v[212:213], s[10:11], 0, v[194:195]
	s_add_i32 m0, s6, 0xc000
	ds_read_b128 v[162:165], v249
	ds_read_b128 v[166:169], v249 offset:1024
	ds_read_b128 v[170:173], v249 offset:2048
	ds_read_b128 v[174:177], v249 offset:3072
	ds_read_b128 v[178:181], v249 offset:4096
	ds_read_b128 v[200:203], v249 offset:5120
	ds_read_b128 v[204:207], v249 offset:6144
	ds_read_b128 v[208:211], v249 offset:7168
	global_load_lds_dwordx4 v[212:213], off
	v_lshl_add_u64 v[212:213], s[10:11], 0, v[192:193]
	s_add_i32 m0, s6, 0xe000
	s_nop 0
	global_load_lds_dwordx4 v[212:213], off
	s_waitcnt vmcnt(8)
	s_waitcnt lgkmcnt(0)
	s_barrier
	v_mfma_f32_16x16x32_bf16 v[126:129], v[130:133], v[162:165], v[126:129]
	v_mfma_f32_16x16x32_bf16 v[122:125], v[138:141], v[162:165], v[122:125]
	v_mfma_f32_16x16x32_bf16 v[118:121], v[130:133], v[170:173], v[118:121]
	v_mfma_f32_16x16x32_bf16 v[114:117], v[138:141], v[170:173], v[114:117]
	v_mfma_f32_16x16x32_bf16 v[110:113], v[130:133], v[178:181], v[110:113]
	v_mfma_f32_16x16x32_bf16 v[106:109], v[138:141], v[178:181], v[106:109]
	v_mfma_f32_16x16x32_bf16 v[102:105], v[130:133], v[204:207], v[102:105]
	v_mfma_f32_16x16x32_bf16 v[98:101], v[138:141], v[204:207], v[98:101]
	v_mfma_f32_16x16x32_bf16 v[126:129], v[134:137], v[166:169], v[126:129]
	v_mfma_f32_16x16x32_bf16 v[122:125], v[142:145], v[166:169], v[122:125]
	v_mfma_f32_16x16x32_bf16 v[118:121], v[134:137], v[174:177], v[118:121]
	v_mfma_f32_16x16x32_bf16 v[114:117], v[142:145], v[174:177], v[114:117]
	v_mfma_f32_16x16x32_bf16 v[110:113], v[134:137], v[200:203], v[110:113]
	v_mfma_f32_16x16x32_bf16 v[106:109], v[142:145], v[200:203], v[106:109]
	v_mfma_f32_16x16x32_bf16 v[102:105], v[134:137], v[208:211], v[102:105]
	v_mfma_f32_16x16x32_bf16 v[98:101], v[142:145], v[208:211], v[98:101]
	v_mfma_f32_16x16x32_bf16 v[82:85], v[146:149], v[162:165], v[82:85]
	v_mfma_f32_16x16x32_bf16 v[74:77], v[154:157], v[162:165], v[74:77]
	v_mfma_f32_16x16x32_bf16 v[94:97], v[146:149], v[170:173], v[94:97]
	v_mfma_f32_16x16x32_bf16 v[90:93], v[154:157], v[170:173], v[90:93]
	v_mfma_f32_16x16x32_bf16 v[86:89], v[146:149], v[178:181], v[86:89]
	v_mfma_f32_16x16x32_bf16 v[78:81], v[154:157], v[178:181], v[78:81]
	v_mfma_f32_16x16x32_bf16 v[70:73], v[146:149], v[204:207], v[70:73]
	v_mfma_f32_16x16x32_bf16 v[62:65], v[154:157], v[204:207], v[62:65]
	v_mfma_f32_16x16x32_bf16 v[82:85], v[150:153], v[166:169], v[82:85]
	v_mfma_f32_16x16x32_bf16 v[74:77], v[158:161], v[166:169], v[74:77]
	v_mfma_f32_16x16x32_bf16 v[94:97], v[150:153], v[174:177], v[94:97]
	v_mfma_f32_16x16x32_bf16 v[90:93], v[158:161], v[174:177], v[90:93]
	v_mfma_f32_16x16x32_bf16 v[86:89], v[150:153], v[200:203], v[86:89]
	v_mfma_f32_16x16x32_bf16 v[78:81], v[158:161], v[200:203], v[78:81]
	v_mfma_f32_16x16x32_bf16 v[70:73], v[150:153], v[208:211], v[70:73]
	v_mfma_f32_16x16x32_bf16 v[62:65], v[158:161], v[208:211], v[62:65]
	s_barrier
	s_add_i32 s89, s54, s96
	v_lshl_add_u64 v[212:213], s[14:15], 0, v[184:185]
	s_mov_b32 m0, s89
	ds_read_b128 v[162:165], v249 offset:16384
	ds_read_b128 v[166:169], v249 offset:17408
	ds_read_b128 v[170:173], v249 offset:18432
	ds_read_b128 v[174:177], v249 offset:19456
	ds_read_b128 v[178:181], v249 offset:20480
	ds_read_b128 v[200:203], v249 offset:21504
	ds_read_b128 v[204:207], v249 offset:22528
	ds_read_b128 v[208:211], v249 offset:23552
	global_load_lds_dwordx4 v[212:213], off
	s_add_i32 m0, s89, 0x2000
	s_add_u32 s90, s14, 0x100000
	v_lshl_add_u64 v[214:215], s[14:15], 0, v[188:189]
	s_addc_u32 s91, s15, 0
	s_add_i32 s89, s55, s96
	global_load_lds_dwordx4 v[214:215], off
	v_lshl_add_u64 v[216:217], s[90:91], 0, v[184:185]
	s_mov_b32 m0, s89
	v_lshl_add_u64 v[218:219], s[16:17], 0, v[186:187]
	global_load_lds_dwordx4 v[216:217], off
	v_lshl_add_u64 v[216:217], s[90:91], 0, v[188:189]
	s_add_i32 m0, s89, 0x2000
	s_nop 0
	global_load_lds_dwordx4 v[216:217], off
	v_lshl_add_u64 v[216:217], s[16:17], 0, v[182:183]
	s_mov_b32 m0, s6
	s_nop 0
	global_load_lds_dwordx4 v[216:217], off
	s_mov_b32 m0, s7
	s_nop 0
	global_load_lds_dwordx4 v[218:219], off
	s_waitcnt vmcnt(8)
	s_waitcnt lgkmcnt(0)
	s_barrier
; #define PG8_STAGE(bufoff, gbase, voff) do { _Pragma("unroll") for (int _i = 0; _i < 2; ++_i) \
;         __builtin_amdgcn_global_load_lds((const unsigned*)((const char*)(gbase) + (voff)[_i]), (PG8_LAS unsigned*)(lds + (bufoff) + ldsw + _i * 8192), 16, 0, 0); } while (0)
; #define PG8_LDA(dst, b, h) do { _Pragma("unroll") for (int m = 0; m < 4; ++m) _Pragma("unroll") for (int k = 0; k < 2; ++k) dst[m][k] = *(const PG8_LAS bf16x8*)(lds + PG8_SA(b, h) + aoff + m * 2048 + k * 1024); } while (0)
; #define PG8_LDB(dst, b, h) do { _Pragma("unroll") for (int n = 0; n < 2; ++n) _Pragma("unroll") for (int k = 0; k < 2; ++k) dst[n][k] = *(const PG8_LAS bf16x8*)(lds + PG8_SB(b, h) + boff + n * 2048 + k * 1024); } while (0)
; #define PG8_WAIT_V(n) asm volatile("s_waitcnt vmcnt(" #n ")" ::: "memory")
; #define PG8_WAIT_L(n) asm volatile("s_waitcnt lgkmcnt(" #n ")" ::: "memory")
; #define PG8_BAR __builtin_amdgcn_s_barrier()
; #define PG8_SCHED __builtin_amdgcn_sched_barrier(0)
; template <class Epi, class Sched, bool ALIGN_EPI = false, bool SP2 = false, bool F8 = false>
; __device__ __forceinline__ void gemm_phase(PG8_LAS unsigned char* lds, const Gemm g, const Sched& S, const Epi& E) {
;     ...
;             PG8_WAIT_V(8); PG8_WAIT_L(0); PG8_BAR; PG8_MMA(1, 0, At, B0); PG8_MMA(1, 1, At, B1); PG8_BAR; PG8_SCHED;
;             PG8_LDB(B0, 1, 0); PG8_LDB(B1, 1, 1); PG8_SCHED; PG8_LDA(At, 1, 0); PG8_STAGE(PG8_SA(0, 1), a2 + hA, voffA);
;             PG8_WAIT_V(8); PG8_WAIT_L(0); PG8_BAR; PG8_MMA(0, 0, At, B0); PG8_MMA(0, 1, At, B1); PG8_BAR; PG8_SCHED;
	v_mfma_f32_16x16x32_bf16 v[66:69], v[130:133], v[162:165], v[66:69]
	v_mfma_f32_16x16x32_bf16 v[58:61], v[138:141], v[162:165], v[58:61]
	v_mfma_f32_16x16x32_bf16 v[54:57], v[130:133], v[170:173], v[54:57]
	v_mfma_f32_16x16x32_bf16 v[50:53], v[138:141], v[170:173], v[50:53]
	v_mfma_f32_16x16x32_bf16 v[46:49], v[130:133], v[178:181], v[46:49]
	v_mfma_f32_16x16x32_bf16 v[42:45], v[138:141], v[178:181], v[42:45]
	v_mfma_f32_16x16x32_bf16 v[38:41], v[130:133], v[204:207], v[38:41]
	v_mfma_f32_16x16x32_bf16 v[34:37], v[138:141], v[204:207], v[34:37]
	v_mfma_f32_16x16x32_bf16 v[66:69], v[134:137], v[166:169], v[66:69]
	v_mfma_f32_16x16x32_bf16 v[58:61], v[142:145], v[166:169], v[58:61]
	v_mfma_f32_16x16x32_bf16 v[54:57], v[134:137], v[174:177], v[54:57]
	v_mfma_f32_16x16x32_bf16 v[50:53], v[142:145], v[174:177], v[50:53]
	v_mfma_f32_16x16x32_bf16 v[46:49], v[134:137], v[200:203], v[46:49]
	v_mfma_f32_16x16x32_bf16 v[42:45], v[142:145], v[200:203], v[42:45]
	v_mfma_f32_16x16x32_bf16 v[38:41], v[134:137], v[208:211], v[38:41]
	v_mfma_f32_16x16x32_bf16 v[34:37], v[142:145], v[208:211], v[34:37]
	v_mfma_f32_16x16x32_bf16 v[30:33], v[146:149], v[162:165], v[30:33]
	v_mfma_f32_16x16x32_bf16 v[18:21], v[154:157], v[162:165], v[18:21]
	v_mfma_f32_16x16x32_bf16 v[26:29], v[146:149], v[170:173], v[26:29]
	v_mfma_f32_16x16x32_bf16 v[22:25], v[154:157], v[170:173], v[22:25]
	v_mfma_f32_16x16x32_bf16 v[14:17], v[146:149], v[178:181], v[14:17]
	v_mfma_f32_16x16x32_bf16 v[10:13], v[154:157], v[178:181], v[10:13]
	v_mfma_f32_16x16x32_bf16 v[6:9], v[146:149], v[204:207], v[6:9]
	v_mfma_f32_16x16x32_bf16 v[2:5], v[154:157], v[204:207], v[2:5]
	v_mfma_f32_16x16x32_bf16 v[30:33], v[150:153], v[166:169], v[30:33]
	v_mfma_f32_16x16x32_bf16 v[18:21], v[158:161], v[166:169], v[18:21]
	v_mfma_f32_16x16x32_bf16 v[26:29], v[150:153], v[174:177], v[26:29]
	v_mfma_f32_16x16x32_bf16 v[22:25], v[158:161], v[174:177], v[22:25]
	v_mfma_f32_16x16x32_bf16 v[14:17], v[150:153], v[200:203], v[14:17]
	v_mfma_f32_16x16x32_bf16 v[10:13], v[158:161], v[200:203], v[10:13]
	v_mfma_f32_16x16x32_bf16 v[6:9], v[150:153], v[208:211], v[6:9]
	v_mfma_f32_16x16x32_bf16 v[2:5], v[158:161], v[208:211], v[2:5]
	s_barrier
	s_add_i32 s89, 0, 0x18000
	s_add_i32 s90, 0, 0x1c000
	v_add_u32_e32 v142, s89, v245
	v_add_u32_e32 v158, s90, v245
	ds_read_b128 v[130:133], v142
	ds_read_b128 v[134:137], v142 offset:1024
	ds_read_b128 v[138:141], v142 offset:2048
	ds_read_b128 v[142:145], v142 offset:3072
	ds_read_b128 v[146:149], v158
	ds_read_b128 v[150:153], v158 offset:1024
	ds_read_b128 v[154:157], v158 offset:2048
	ds_read_b128 v[158:161], v158 offset:3072
	s_add_u32 s16, s16, 0x100000
	s_addc_u32 s17, s17, 0
	s_mov_b32 m0, s5
	v_lshl_add_u64 v[220:221], s[16:17], 0, v[182:183]
	ds_read_b128 v[162:165], v249 offset:32768
	ds_read_b128 v[166:169], v249 offset:33792
	ds_read_b128 v[170:173], v249 offset:34816
	ds_read_b128 v[174:177], v249 offset:35840
	ds_read_b128 v[178:181], v249 offset:36864
	ds_read_b128 v[200:203], v249 offset:37888
	ds_read_b128 v[204:207], v249 offset:38912
	ds_read_b128 v[208:211], v249 offset:39936
	global_load_lds_dwordx4 v[220:221], off
	v_lshl_add_u64 v[220:221], s[16:17], 0, v[186:187]
	s_mov_b32 m0, s18
	s_nop 0
	global_load_lds_dwordx4 v[220:221], off
	s_waitcnt vmcnt(8)
	s_waitcnt lgkmcnt(0)
	s_barrier
	v_mfma_f32_16x16x32_bf16 v[126:129], v[130:133], v[162:165], v[126:129]
	v_mfma_f32_16x16x32_bf16 v[122:125], v[138:141], v[162:165], v[122:125]
	v_mfma_f32_16x16x32_bf16 v[118:121], v[130:133], v[170:173], v[118:121]
	v_mfma_f32_16x16x32_bf16 v[114:117], v[138:141], v[170:173], v[114:117]
	v_mfma_f32_16x16x32_bf16 v[110:113], v[130:133], v[178:181], v[110:113]
	v_mfma_f32_16x16x32_bf16 v[106:109], v[138:141], v[178:181], v[106:109]
	v_mfma_f32_16x16x32_bf16 v[102:105], v[130:133], v[204:207], v[102:105]
	v_mfma_f32_16x16x32_bf16 v[98:101], v[138:141], v[204:207], v[98:101]
	v_mfma_f32_16x16x32_bf16 v[126:129], v[134:137], v[166:169], v[126:129]
	v_mfma_f32_16x16x32_bf16 v[122:125], v[142:145], v[166:169], v[122:125]
	v_mfma_f32_16x16x32_bf16 v[118:121], v[134:137], v[174:177], v[118:121]
	v_mfma_f32_16x16x32_bf16 v[114:117], v[142:145], v[174:177], v[114:117]
	v_mfma_f32_16x16x32_bf16 v[110:113], v[134:137], v[200:203], v[110:113]
	v_mfma_f32_16x16x32_bf16 v[106:109], v[142:145], v[200:203], v[106:109]
	v_mfma_f32_16x16x32_bf16 v[102:105], v[134:137], v[208:211], v[102:105]
	v_mfma_f32_16x16x32_bf16 v[98:101], v[142:145], v[208:211], v[98:101]
	v_mfma_f32_16x16x32_bf16 v[82:85], v[146:149], v[162:165], v[82:85]
	v_mfma_f32_16x16x32_bf16 v[74:77], v[154:157], v[162:165], v[74:77]
	v_mfma_f32_16x16x32_bf16 v[94:97], v[146:149], v[170:173], v[94:97]
	v_mfma_f32_16x16x32_bf16 v[90:93], v[154:157], v[170:173], v[90:93]
	v_mfma_f32_16x16x32_bf16 v[86:89], v[146:149], v[178:181], v[86:89]
	v_mfma_f32_16x16x32_bf16 v[78:81], v[154:157], v[178:181], v[78:81]
	v_mfma_f32_16x16x32_bf16 v[70:73], v[146:149], v[204:207], v[70:73]
	v_mfma_f32_16x16x32_bf16 v[62:65], v[154:157], v[204:207], v[62:65]
	v_mfma_f32_16x16x32_bf16 v[82:85], v[150:153], v[166:169], v[82:85]
	v_mfma_f32_16x16x32_bf16 v[74:77], v[158:161], v[166:169], v[74:77]
	v_mfma_f32_16x16x32_bf16 v[94:97], v[150:153], v[174:177], v[94:97]
	v_mfma_f32_16x16x32_bf16 v[90:93], v[158:161], v[174:177], v[90:93]
	v_mfma_f32_16x16x32_bf16 v[86:89], v[150:153], v[200:203], v[86:89]
	v_mfma_f32_16x16x32_bf16 v[78:81], v[158:161], v[200:203], v[78:81]
	v_mfma_f32_16x16x32_bf16 v[70:73], v[150:153], v[208:211], v[70:73]
	v_mfma_f32_16x16x32_bf16 v[62:65], v[158:161], v[208:211], v[62:65]
	s_barrier
; #define PG8_STAGE(bufoff, gbase, voff) do { _Pragma("unroll") for (int _i = 0; _i < 2; ++_i) \
;         __builtin_amdgcn_global_load_lds((const unsigned*)((const char*)(gbase) + (voff)[_i]), (PG8_LAS unsigned*)(lds + (bufoff) + ldsw + _i * 8192), 16, 0, 0); } while (0)
; #define PG8_LDA(dst, b, h) do { _Pragma("unroll") for (int m = 0; m < 4; ++m) _Pragma("unroll") for (int k = 0; k < 2; ++k) dst[m][k] = *(const PG8_LAS bf16x8*)(lds + PG8_SA(b, h) + aoff + m * 2048 + k * 1024); } while (0)
; #define PG8_LDB(dst, b, h) do { _Pragma("unroll") for (int n = 0; n < 2; ++n) _Pragma("unroll") for (int k = 0; k < 2; ++k) dst[n][k] = *(const PG8_LAS bf16x8*)(lds + PG8_SB(b, h) + boff + n * 2048 + k * 1024); } while (0)
; template <class Epi, class Sched, bool ALIGN_EPI = false, bool SP2 = false, bool F8 = false>
; __device__ __forceinline__ void gemm_phase(PG8_LAS unsigned char* lds, const Gemm g, const Sched& S, const Epi& E) {
;     ...
;         for (int t = 0; t < nt; t += 2) {
;             const bool last = (t == nt - 2);
;             const char* a1 = cA + (size_t)(t + 1) * kstep;
;             const char* a2 = last ? nA : cA + (size_t)(t + 2) * kstep; const char* b2 = last ? nB : cB + (size_t)(t + 2) * kstep;
;             const char* a3 = a2 + kstep; const char* b3 = b2 + kstep;
;             if (last && has_next) S.a_ready(nxt);
;             if constexpr (SP2) {
;             PG8_LDB(B0, 0, 0); PG8_LDB(B1, 0, 1); PG8_SCHED; PG8_LDA(At, 0, 0); PG8_STAGE(PG8_SA(1, 1), a1 + hA, voffA);
;             PG8_WAIT_V(8); PG8_WAIT_L(0); PG8_BAR; PG8_MMA(0, 0, At, B0); PG8_MMA(0, 1, At, B1); PG8_BAR; PG8_SCHED;
;             PG8_LDA(At, 0, 1); PG8_STAGE(PG8_SB(0, 0), b2, voffB); PG8_STAGE(PG8_SB(0, 1), b2 + hB, voffB); PG8_STAGE(PG8_SA(0, 0), a2, voffA);
;             PG8_WAIT_V(8); PG8_WAIT_L(0); PG8_BAR; PG8_MMA(1, 0, At, B0); PG8_MMA(1, 1, At, B1); PG8_BAR; PG8_SCHED;
;             PG8_LDB(B0, 1, 0); PG8_LDB(B1, 1, 1); PG8_SCHED; PG8_LDA(At, 1, 0); PG8_STAGE(PG8_SA(0, 1), a2 + hA, voffA);
;             PG8_WAIT_V(8); PG8_WAIT_L(0); PG8_BAR; PG8_MMA(0, 0, At, B0); PG8_MMA(0, 1, At, B1); PG8_BAR; PG8_SCHED;
;             PG8_LDA(At, 1, 1); PG8_STAGE(PG8_SB(1, 0), b3, voffB); PG8_STAGE(PG8_SB(1, 1), b3 + hB, voffB); PG8_STAGE(PG8_SA(1, 0), a3, voffA);
;             PG8_WAIT_V(8); PG8_WAIT_L(0); PG8_BAR; PG8_MMA(1, 0, At, B0); PG8_MMA(1, 1, At, B1); PG8_BAR; PG8_SCHED;
	s_add_i32 s16, s89, s96
	v_lshl_add_u64 v[212:213], v[212:213], 0, s[34:35]
	s_mov_b32 m0, s16
	ds_read_b128 v[162:165], v249 offset:49152
	ds_read_b128 v[166:169], v249 offset:50176
	ds_read_b128 v[170:173], v249 offset:51200
	ds_read_b128 v[174:177], v249 offset:52224
	ds_read_b128 v[178:181], v249 offset:53248
	ds_read_b128 v[200:203], v249 offset:54272
	ds_read_b128 v[204:207], v249 offset:55296
	ds_read_b128 v[208:211], v249 offset:56320
	global_load_lds_dwordx4 v[212:213], off
	s_add_i32 m0, s16, 0x2000
	s_add_u32 s14, s14, 0x100080
	v_lshl_add_u64 v[212:213], v[214:215], 0, s[34:35]
	s_addc_u32 s15, s15, 0
	s_add_i32 s16, s90, s96
	global_load_lds_dwordx4 v[212:213], off
	v_lshl_add_u64 v[212:213], s[14:15], 0, v[184:185]
	s_mov_b32 m0, s16
	s_nop 0
	global_load_lds_dwordx4 v[212:213], off
	v_lshl_add_u64 v[212:213], s[14:15], 0, v[188:189]
	s_add_i32 m0, s16, 0x2000
	s_nop 0
	global_load_lds_dwordx4 v[212:213], off
	v_lshl_add_u64 v[212:213], v[216:217], 0, s[34:35]
	s_mov_b32 m0, s31
	s_nop 0
	global_load_lds_dwordx4 v[212:213], off
	v_lshl_add_u64 v[212:213], v[218:219], 0, s[34:35]
	s_mov_b32 m0, s50
	s_nop 0
	global_load_lds_dwordx4 v[212:213], off
	s_waitcnt vmcnt(8)
	s_waitcnt lgkmcnt(0)
	s_barrier
	v_mfma_f32_16x16x32_bf16 v[66:69], v[130:133], v[162:165], v[66:69]
	v_mfma_f32_16x16x32_bf16 v[58:61], v[138:141], v[162:165], v[58:61]
	v_mfma_f32_16x16x32_bf16 v[54:57], v[130:133], v[170:173], v[54:57]
	v_mfma_f32_16x16x32_bf16 v[50:53], v[138:141], v[170:173], v[50:53]
	v_mfma_f32_16x16x32_bf16 v[46:49], v[130:133], v[178:181], v[46:49]
	v_mfma_f32_16x16x32_bf16 v[42:45], v[138:141], v[178:181], v[42:45]
	v_mfma_f32_16x16x32_bf16 v[38:41], v[130:133], v[204:207], v[38:41]
	v_mfma_f32_16x16x32_bf16 v[34:37], v[138:141], v[204:207], v[34:37]
	v_mfma_f32_16x16x32_bf16 v[66:69], v[134:137], v[166:169], v[66:69]
	v_mfma_f32_16x16x32_bf16 v[58:61], v[142:145], v[166:169], v[58:61]
	v_mfma_f32_16x16x32_bf16 v[54:57], v[134:137], v[174:177], v[54:57]
	v_mfma_f32_16x16x32_bf16 v[50:53], v[142:145], v[174:177], v[50:53]
	v_mfma_f32_16x16x32_bf16 v[46:49], v[134:137], v[200:203], v[46:49]
	v_mfma_f32_16x16x32_bf16 v[42:45], v[142:145], v[200:203], v[42:45]
	v_mfma_f32_16x16x32_bf16 v[38:41], v[134:137], v[208:211], v[38:41]
	v_mfma_f32_16x16x32_bf16 v[34:37], v[142:145], v[208:211], v[34:37]
	v_mfma_f32_16x16x32_bf16 v[30:33], v[146:149], v[162:165], v[30:33]
	v_mfma_f32_16x16x32_bf16 v[18:21], v[154:157], v[162:165], v[18:21]
	v_mfma_f32_16x16x32_bf16 v[26:29], v[146:149], v[170:173], v[26:29]
	v_mfma_f32_16x16x32_bf16 v[22:25], v[154:157], v[170:173], v[22:25]
	v_mfma_f32_16x16x32_bf16 v[14:17], v[146:149], v[178:181], v[14:17]
	v_mfma_f32_16x16x32_bf16 v[10:13], v[154:157], v[178:181], v[10:13]
	v_mfma_f32_16x16x32_bf16 v[6:9], v[146:149], v[204:207], v[6:9]
	v_mfma_f32_16x16x32_bf16 v[2:5], v[154:157], v[204:207], v[2:5]
	v_mfma_f32_16x16x32_bf16 v[30:33], v[150:153], v[166:169], v[30:33]
	v_mfma_f32_16x16x32_bf16 v[18:21], v[158:161], v[166:169], v[18:21]
	v_mfma_f32_16x16x32_bf16 v[26:29], v[150:153], v[174:177], v[26:29]
	v_mfma_f32_16x16x32_bf16 v[22:25], v[158:161], v[174:177], v[22:25]
	v_mfma_f32_16x16x32_bf16 v[14:17], v[150:153], v[200:203], v[14:17]
	v_mfma_f32_16x16x32_bf16 v[10:13], v[158:161], v[200:203], v[10:13]
	v_mfma_f32_16x16x32_bf16 v[6:9], v[150:153], v[208:211], v[6:9]
	v_mfma_f32_16x16x32_bf16 v[2:5], v[158:161], v[208:211], v[2:5]
	s_barrier
	s_add_i32 s88, s88, 2
	s_add_u32 s86, s86, 0x100
	s_addc_u32 s87, s87, 0
	s_add_u32 s10, s10, 0x100
	s_addc_u32 s11, s11, 0
	s_cmp_gt_u32 s88, 13
	s_cbranch_scc0 .LBB0_883
	s_and_b64 vcc, exec, s[36:37]
	s_cbranch_vccz .LBB0_886
	s_barrier

; #define PG8_STAGE(bufoff, gbase, voff) do { _Pragma("unroll") for (int _i = 0; _i < 2; ++_i) \
;         __builtin_amdgcn_global_load_lds((const unsigned*)((const char*)(gbase) + (voff)[_i]), (PG8_LAS unsigned*)(lds + (bufoff) + ldsw + _i * 8192), 16, 0, 0); } while (0)
; #define PG8_LDA(dst, b, h) do { _Pragma("unroll") for (int m = 0; m < 4; ++m) _Pragma("unroll") for (int k = 0; k < 2; ++k) dst[m][k] = *(const PG8_LAS bf16x8*)(lds + PG8_SA(b, h) + aoff + m * 2048 + k * 1024); } while (0)
; #define PG8_LDB(dst, b, h) do { _Pragma("unroll") for (int n = 0; n < 2; ++n) _Pragma("unroll") for (int k = 0; k < 2; ++k) dst[n][k] = *(const PG8_LAS bf16x8*)(lds + PG8_SB(b, h) + boff + n * 2048 + k * 1024); } while (0)
; #define PG8_WAIT_V(n) asm volatile("s_waitcnt vmcnt(" #n ")" ::: "memory")
; #define PG8_WAIT_L(n) asm volatile("s_waitcnt lgkmcnt(" #n ")" ::: "memory")
; #define PG8_BAR __builtin_amdgcn_s_barrier()
; #define PG8_SCHED __builtin_amdgcn_sched_barrier(0)
; template <class Epi, class Sched, bool ALIGN_EPI = false, bool SP2 = false, bool F8 = false>
; __device__ __forceinline__ void gemm_phase(PG8_LAS unsigned char* lds, const Gemm g, const Sched& S, const Epi& E) {
;     ...
;         for (int t = 0; t < nt; t += 2) {
;             const bool last = (t == nt - 2);
;             const char* a1 = cA + (size_t)(t + 1) * kstep;
;             const char* a2 = last ? nA : cA + (size_t)(t + 2) * kstep; const char* b2 = last ? nB : cB + (size_t)(t + 2) * kstep;
;             const char* a3 = a2 + kstep; const char* b3 = b2 + kstep;
;             if (last && has_next) S.a_ready(nxt);
;             if constexpr (SP2) {
;             PG8_LDB(B0, 0, 0); PG8_LDB(B1, 0, 1); PG8_SCHED; PG8_LDA(At, 0, 0); PG8_STAGE(PG8_SA(1, 1), a1 + hA, voffA);
;             PG8_WAIT_V(8); PG8_WAIT_L(0); PG8_BAR; PG8_MMA(0, 0, At, B0); PG8_MMA(0, 1, At, B1); PG8_BAR; PG8_SCHED;
;             PG8_LDA(At, 0, 1); PG8_STAGE(PG8_SB(0, 0), b2, voffB); PG8_STAGE(PG8_SB(0, 1), b2 + hB, voffB); PG8_STAGE(PG8_SA(0, 0), a2, voffA);
;             PG8_WAIT_V(8); PG8_WAIT_L(0); PG8_BAR; PG8_MMA(1, 0, At, B0); PG8_MMA(1, 1, At, B1); PG8_BAR; PG8_SCHED;
;             PG8_LDB(B0, 1, 0); PG8_LDB(B1, 1, 1); PG8_SCHED; PG8_LDA(At, 1, 0); PG8_STAGE(PG8_SA(0, 1), a2 + hA, voffA);
.LBB0_1078:
	ds_read_b128 v[130:133], v197
	ds_read_b128 v[134:137], v197 offset:1024
	ds_read_b128 v[138:141], v197 offset:2048
	ds_read_b128 v[142:145], v197 offset:3072
	ds_read_b128 v[146:149], v198
	ds_read_b128 v[150:153], v198 offset:1024
	ds_read_b128 v[154:157], v198 offset:2048
	ds_read_b128 v[158:161], v198 offset:3072
	s_add_u32 s28, s26, 0x100
	s_addc_u32 s29, s27, 0
	s_cmpk_eq_i32 s55, 0xa8
	s_cselect_b32 s35, s7, s29
	s_cselect_b32 s34, s6, s28
	s_cselect_b32 s31, s9, s54
	s_cselect_b32 s30, s8, s53
	v_lshl_add_u64 v[216:217], s[26:27], 0, v[176:177]
	s_add_i32 m0, s39, 0xc000
	ds_read_b128 v[162:165], v199
	ds_read_b128 v[182:185], v199 offset:1024
	ds_read_b128 v[186:189], v199 offset:2048
	ds_read_b128 v[190:193], v199 offset:3072
	ds_read_b128 v[200:203], v199 offset:4096
	ds_read_b128 v[204:207], v199 offset:5120
	ds_read_b128 v[208:211], v199 offset:6144
	ds_read_b128 v[212:215], v199 offset:7168
	global_load_lds_dwordx4 v[216:217], off
	v_lshl_add_u64 v[216:217], s[26:27], 0, v[174:175]
	s_add_i32 m0, s39, 0xe000
	s_nop 0
	global_load_lds_dwordx4 v[216:217], off
	s_waitcnt vmcnt(8)
	s_waitcnt lgkmcnt(0)
	s_barrier
	v_mfma_f32_16x16x32_bf16 v[126:129], v[130:133], v[162:165], v[126:129]
	v_mfma_f32_16x16x32_bf16 v[122:125], v[138:141], v[162:165], v[122:125]
	v_mfma_f32_16x16x32_bf16 v[118:121], v[130:133], v[186:189], v[118:121]
	v_mfma_f32_16x16x32_bf16 v[106:109], v[138:141], v[186:189], v[106:109]
	v_mfma_f32_16x16x32_bf16 v[98:101], v[130:133], v[200:203], v[98:101]
	v_mfma_f32_16x16x32_bf16 v[90:93], v[138:141], v[200:203], v[90:93]
	v_mfma_f32_16x16x32_bf16 v[82:85], v[130:133], v[208:211], v[82:85]
	v_mfma_f32_16x16x32_bf16 v[74:77], v[138:141], v[208:211], v[74:77]
	v_mfma_f32_16x16x32_bf16 v[126:129], v[134:137], v[182:185], v[126:129]
	v_mfma_f32_16x16x32_bf16 v[122:125], v[142:145], v[182:185], v[122:125]
	v_mfma_f32_16x16x32_bf16 v[118:121], v[134:137], v[190:193], v[118:121]
	v_mfma_f32_16x16x32_bf16 v[106:109], v[142:145], v[190:193], v[106:109]
	v_mfma_f32_16x16x32_bf16 v[98:101], v[134:137], v[204:207], v[98:101]
	v_mfma_f32_16x16x32_bf16 v[90:93], v[142:145], v[204:207], v[90:93]
	v_mfma_f32_16x16x32_bf16 v[82:85], v[134:137], v[212:215], v[82:85]
	v_mfma_f32_16x16x32_bf16 v[74:77], v[142:145], v[212:215], v[74:77]
	v_mfma_f32_16x16x32_bf16 v[114:117], v[146:149], v[162:165], v[114:117]
	v_mfma_f32_16x16x32_bf16 v[110:113], v[154:157], v[162:165], v[110:113]
	v_mfma_f32_16x16x32_bf16 v[102:105], v[146:149], v[186:189], v[102:105]
	v_mfma_f32_16x16x32_bf16 v[94:97], v[154:157], v[186:189], v[94:97]
	v_mfma_f32_16x16x32_bf16 v[86:89], v[146:149], v[200:203], v[86:89]
	v_mfma_f32_16x16x32_bf16 v[78:81], v[154:157], v[200:203], v[78:81]
	v_mfma_f32_16x16x32_bf16 v[70:73], v[146:149], v[208:211], v[70:73]
	v_mfma_f32_16x16x32_bf16 v[66:69], v[154:157], v[208:211], v[66:69]
	v_mfma_f32_16x16x32_bf16 v[114:117], v[150:153], v[182:185], v[114:117]
	v_mfma_f32_16x16x32_bf16 v[110:113], v[158:161], v[182:185], v[110:113]
	v_mfma_f32_16x16x32_bf16 v[102:105], v[150:153], v[190:193], v[102:105]
	v_mfma_f32_16x16x32_bf16 v[94:97], v[158:161], v[190:193], v[94:97]
	v_mfma_f32_16x16x32_bf16 v[86:89], v[150:153], v[204:207], v[86:89]
	v_mfma_f32_16x16x32_bf16 v[78:81], v[158:161], v[204:207], v[78:81]
	v_mfma_f32_16x16x32_bf16 v[70:73], v[150:153], v[212:215], v[70:73]
	v_mfma_f32_16x16x32_bf16 v[66:69], v[158:161], v[212:215], v[66:69]
	s_barrier
	s_add_i32 s26, s47, s36
	v_lshl_add_u64 v[216:217], s[30:31], 0, v[170:171]
	s_mov_b32 m0, s26
	ds_read_b128 v[162:165], v199 offset:16384
	ds_read_b128 v[182:185], v199 offset:17408
	ds_read_b128 v[186:189], v199 offset:18432
	ds_read_b128 v[190:193], v199 offset:19456
	ds_read_b128 v[200:203], v199 offset:20480
	ds_read_b128 v[204:207], v199 offset:21504
	ds_read_b128 v[208:211], v199 offset:22528
	ds_read_b128 v[212:215], v199 offset:23552
	global_load_lds_dwordx4 v[216:217], off
	s_add_i32 m0, s26, 0x2000
	s_add_u32 s26, s30, 0x2b0000
	v_lshl_add_u64 v[218:219], s[30:31], 0, v[166:167]
	s_addc_u32 s27, s31, 0
	s_add_i32 s56, s48, s36
	global_load_lds_dwordx4 v[218:219], off
	v_lshl_add_u64 v[220:221], s[26:27], 0, v[170:171]
	s_mov_b32 m0, s56
	v_lshl_add_u64 v[222:223], s[34:35], 0, v[168:169]
	global_load_lds_dwordx4 v[220:221], off
	v_lshl_add_u64 v[220:221], s[26:27], 0, v[166:167]
	s_add_i32 m0, s56, 0x2000
	s_nop 0
	global_load_lds_dwordx4 v[220:221], off
	v_lshl_add_u64 v[220:221], s[34:35], 0, v[172:173]
	s_mov_b32 m0, s39
	s_nop 0
	global_load_lds_dwordx4 v[220:221], off
	s_mov_b32 m0, s40
	s_nop 0
	global_load_lds_dwordx4 v[222:223], off
	s_waitcnt vmcnt(8)
	s_waitcnt lgkmcnt(0)
	s_barrier
; #define PG8_STAGE(bufoff, gbase, voff) do { _Pragma("unroll") for (int _i = 0; _i < 2; ++_i) \
;         __builtin_amdgcn_global_load_lds((const unsigned*)((const char*)(gbase) + (voff)[_i]), (PG8_LAS unsigned*)(lds + (bufoff) + ldsw + _i * 8192), 16, 0, 0); } while (0)
; #define PG8_LDA(dst, b, h) do { _Pragma("unroll") for (int m = 0; m < 4; ++m) _Pragma("unroll") for (int k = 0; k < 2; ++k) dst[m][k] = *(const PG8_LAS bf16x8*)(lds + PG8_SA(b, h) + aoff + m * 2048 + k * 1024); } while (0)
; #define PG8_LDB(dst, b, h) do { _Pragma("unroll") for (int n = 0; n < 2; ++n) _Pragma("unroll") for (int k = 0; k < 2; ++k) dst[n][k] = *(const PG8_LAS bf16x8*)(lds + PG8_SB(b, h) + boff + n * 2048 + k * 1024); } while (0)
; #define PG8_WAIT_V(n) asm volatile("s_waitcnt vmcnt(" #n ")" ::: "memory")
; #define PG8_WAIT_L(n) asm volatile("s_waitcnt lgkmcnt(" #n ")" ::: "memory")
; #define PG8_BAR __builtin_amdgcn_s_barrier()
; #define PG8_SCHED __builtin_amdgcn_sched_barrier(0)
; template <class Epi, class Sched, bool ALIGN_EPI = false, bool SP2 = false, bool F8 = false>
; __device__ __forceinline__ void gemm_phase(PG8_LAS unsigned char* lds, const Gemm g, const Sched& S, const Epi& E) {
;     ...
;             PG8_WAIT_V(8); PG8_WAIT_L(0); PG8_BAR; PG8_MMA(1, 0, At, B0); PG8_MMA(1, 1, At, B1); PG8_BAR; PG8_SCHED;
;             PG8_LDB(B0, 1, 0); PG8_LDB(B1, 1, 1); PG8_SCHED; PG8_LDA(At, 1, 0); PG8_STAGE(PG8_SA(0, 1), a2 + hA, voffA);
;             PG8_WAIT_V(8); PG8_WAIT_L(0); PG8_BAR; PG8_MMA(0, 0, At, B0); PG8_MMA(0, 1, At, B1); PG8_BAR; PG8_SCHED;
	v_mfma_f32_16x16x32_bf16 v[62:65], v[130:133], v[162:165], v[62:65]
	v_mfma_f32_16x16x32_bf16 v[58:61], v[138:141], v[162:165], v[58:61]
	v_mfma_f32_16x16x32_bf16 v[50:53], v[130:133], v[186:189], v[50:53]
	v_mfma_f32_16x16x32_bf16 v[42:45], v[138:141], v[186:189], v[42:45]
	v_mfma_f32_16x16x32_bf16 v[34:37], v[130:133], v[200:203], v[34:37]
	v_mfma_f32_16x16x32_bf16 v[26:29], v[138:141], v[200:203], v[26:29]
	v_mfma_f32_16x16x32_bf16 v[18:21], v[130:133], v[208:211], v[18:21]
	v_mfma_f32_16x16x32_bf16 v[10:13], v[138:141], v[208:211], v[10:13]
	v_mfma_f32_16x16x32_bf16 v[62:65], v[134:137], v[182:185], v[62:65]
	v_mfma_f32_16x16x32_bf16 v[58:61], v[142:145], v[182:185], v[58:61]
	v_mfma_f32_16x16x32_bf16 v[50:53], v[134:137], v[190:193], v[50:53]
	v_mfma_f32_16x16x32_bf16 v[42:45], v[142:145], v[190:193], v[42:45]
	v_mfma_f32_16x16x32_bf16 v[34:37], v[134:137], v[204:207], v[34:37]
	v_mfma_f32_16x16x32_bf16 v[26:29], v[142:145], v[204:207], v[26:29]
	v_mfma_f32_16x16x32_bf16 v[18:21], v[134:137], v[212:215], v[18:21]
	v_mfma_f32_16x16x32_bf16 v[10:13], v[142:145], v[212:215], v[10:13]
	v_mfma_f32_16x16x32_bf16 v[54:57], v[146:149], v[162:165], v[54:57]
	v_mfma_f32_16x16x32_bf16 v[46:49], v[154:157], v[162:165], v[46:49]
	v_mfma_f32_16x16x32_bf16 v[38:41], v[146:149], v[186:189], v[38:41]
	v_mfma_f32_16x16x32_bf16 v[30:33], v[154:157], v[186:189], v[30:33]
	v_mfma_f32_16x16x32_bf16 v[22:25], v[146:149], v[200:203], v[22:25]
	v_mfma_f32_16x16x32_bf16 v[14:17], v[154:157], v[200:203], v[14:17]
	v_mfma_f32_16x16x32_bf16 v[6:9], v[146:149], v[208:211], v[6:9]
	v_mfma_f32_16x16x32_bf16 v[2:5], v[154:157], v[208:211], v[2:5]
	v_mfma_f32_16x16x32_bf16 v[54:57], v[150:153], v[182:185], v[54:57]
	v_mfma_f32_16x16x32_bf16 v[46:49], v[158:161], v[182:185], v[46:49]
	v_mfma_f32_16x16x32_bf16 v[38:41], v[150:153], v[190:193], v[38:41]
	v_mfma_f32_16x16x32_bf16 v[30:33], v[158:161], v[190:193], v[30:33]
	v_mfma_f32_16x16x32_bf16 v[22:25], v[150:153], v[204:207], v[22:25]
	v_mfma_f32_16x16x32_bf16 v[14:17], v[158:161], v[204:207], v[14:17]
	v_mfma_f32_16x16x32_bf16 v[6:9], v[150:153], v[212:215], v[6:9]
	v_mfma_f32_16x16x32_bf16 v[2:5], v[158:161], v[212:215], v[2:5]
	s_barrier
	s_add_i32 s56, 0, 0x18000
	s_add_i32 s57, 0, 0x1c000
	v_add_u32_e32 v142, s56, v195
	v_add_u32_e32 v158, s57, v195
	ds_read_b128 v[130:133], v142
	ds_read_b128 v[134:137], v142 offset:1024
	ds_read_b128 v[138:141], v142 offset:2048
	ds_read_b128 v[142:145], v142 offset:3072
	ds_read_b128 v[146:149], v158
	ds_read_b128 v[150:153], v158 offset:1024
	ds_read_b128 v[154:157], v158 offset:2048
	ds_read_b128 v[158:161], v158 offset:3072
	s_add_u32 s26, s34, 0x2b0000
	s_addc_u32 s27, s35, 0
	s_mov_b32 m0, s41
	v_lshl_add_u64 v[224:225], s[26:27], 0, v[172:173]
	ds_read_b128 v[162:165], v199 offset:32768
	ds_read_b128 v[182:185], v199 offset:33792
	ds_read_b128 v[186:189], v199 offset:34816
	ds_read_b128 v[190:193], v199 offset:35840
	ds_read_b128 v[200:203], v199 offset:36864
	ds_read_b128 v[204:207], v199 offset:37888
	ds_read_b128 v[208:211], v199 offset:38912
	ds_read_b128 v[212:215], v199 offset:39936
	global_load_lds_dwordx4 v[224:225], off
	v_lshl_add_u64 v[224:225], s[26:27], 0, v[168:169]
	s_mov_b32 m0, s42
	s_nop 0
	global_load_lds_dwordx4 v[224:225], off
	s_waitcnt vmcnt(8)
	s_waitcnt lgkmcnt(0)
	s_barrier
	v_mfma_f32_16x16x32_bf16 v[126:129], v[130:133], v[162:165], v[126:129]
	v_mfma_f32_16x16x32_bf16 v[122:125], v[138:141], v[162:165], v[122:125]
	v_mfma_f32_16x16x32_bf16 v[118:121], v[130:133], v[186:189], v[118:121]
	v_mfma_f32_16x16x32_bf16 v[106:109], v[138:141], v[186:189], v[106:109]
	v_mfma_f32_16x16x32_bf16 v[98:101], v[130:133], v[200:203], v[98:101]
	v_mfma_f32_16x16x32_bf16 v[90:93], v[138:141], v[200:203], v[90:93]
	v_mfma_f32_16x16x32_bf16 v[82:85], v[130:133], v[208:211], v[82:85]
	v_mfma_f32_16x16x32_bf16 v[74:77], v[138:141], v[208:211], v[74:77]
	v_mfma_f32_16x16x32_bf16 v[126:129], v[134:137], v[182:185], v[126:129]
	v_mfma_f32_16x16x32_bf16 v[122:125], v[142:145], v[182:185], v[122:125]
	v_mfma_f32_16x16x32_bf16 v[118:121], v[134:137], v[190:193], v[118:121]
	v_mfma_f32_16x16x32_bf16 v[106:109], v[142:145], v[190:193], v[106:109]
	v_mfma_f32_16x16x32_bf16 v[98:101], v[134:137], v[204:207], v[98:101]
	v_mfma_f32_16x16x32_bf16 v[90:93], v[142:145], v[204:207], v[90:93]
	v_mfma_f32_16x16x32_bf16 v[82:85], v[134:137], v[212:215], v[82:85]
	v_mfma_f32_16x16x32_bf16 v[74:77], v[142:145], v[212:215], v[74:77]
	v_mfma_f32_16x16x32_bf16 v[114:117], v[146:149], v[162:165], v[114:117]
	v_mfma_f32_16x16x32_bf16 v[110:113], v[154:157], v[162:165], v[110:113]
	v_mfma_f32_16x16x32_bf16 v[102:105], v[146:149], v[186:189], v[102:105]
	v_mfma_f32_16x16x32_bf16 v[94:97], v[154:157], v[186:189], v[94:97]
	v_mfma_f32_16x16x32_bf16 v[86:89], v[146:149], v[200:203], v[86:89]
	v_mfma_f32_16x16x32_bf16 v[78:81], v[154:157], v[200:203], v[78:81]
	v_mfma_f32_16x16x32_bf16 v[70:73], v[146:149], v[208:211], v[70:73]
	v_mfma_f32_16x16x32_bf16 v[66:69], v[154:157], v[208:211], v[66:69]
	v_mfma_f32_16x16x32_bf16 v[114:117], v[150:153], v[182:185], v[114:117]
	v_mfma_f32_16x16x32_bf16 v[110:113], v[158:161], v[182:185], v[110:113]
	v_mfma_f32_16x16x32_bf16 v[102:105], v[150:153], v[190:193], v[102:105]
	v_mfma_f32_16x16x32_bf16 v[94:97], v[158:161], v[190:193], v[94:97]
	v_mfma_f32_16x16x32_bf16 v[86:89], v[150:153], v[204:207], v[86:89]
	v_mfma_f32_16x16x32_bf16 v[78:81], v[158:161], v[204:207], v[78:81]
	v_mfma_f32_16x16x32_bf16 v[70:73], v[150:153], v[212:215], v[70:73]
	v_mfma_f32_16x16x32_bf16 v[66:69], v[158:161], v[212:215], v[66:69]
	s_barrier
; #define PG8_GAS __attribute__((address_space(1)))
; #define PG8_STAGE(bufoff, gbase, voff) do { _Pragma("unroll") for (int _i = 0; _i < 2; ++_i) \
;         __builtin_amdgcn_global_load_lds((const unsigned*)((const char*)(gbase) + (voff)[_i]), (PG8_LAS unsigned*)(lds + (bufoff) + ldsw + _i * 8192), 16, 0, 0); } while (0)
; #define PG8_LDA(dst, b, h) do { _Pragma("unroll") for (int m = 0; m < 4; ++m) _Pragma("unroll") for (int k = 0; k < 2; ++k) dst[m][k] = *(const PG8_LAS bf16x8*)(lds + PG8_SA(b, h) + aoff + m * 2048 + k * 1024); } while (0)
; #define PG8_WAIT_V(n) asm volatile("s_waitcnt vmcnt(" #n ")" ::: "memory")
; #define PG8_WAIT_L(n) asm volatile("s_waitcnt lgkmcnt(" #n ")" ::: "memory")
; #define PG8_BAR __builtin_amdgcn_s_barrier()
; #define PG8_SCHED __builtin_amdgcn_sched_barrier(0)
;     __device__ __forceinline__ void operator()(const f32x4 (&acc)[2][2][4][2], const Unit& un, int wr, int wc, int fr, int fq) const {
;         const int row0 = un.pm * BM + wr * 64 + fr, col0 = un.pn * BM + wc * 32 + 8 * fq;
;         u32x4 rr[2][4][2];
; #pragma unroll
;         for (int ai = 0; ai < 2; ++ai)
; #pragma unroll
;             for (int m = 0; m < 4; ++m)
; #pragma unroll
;                 for (int bj = 0; bj < 2; ++bj) rr[ai][m][bj] = *(const PG8_GAS u32x4*)((PG8_GAS bf16_t*)h + (size_t)(row0 + ai * HALF + m * 16) * 4096 + col0 + bj * HALF);
; template <class Epi, class Sched, bool ALIGN_EPI = false, bool SP2 = false, bool F8 = false>
; __device__ __forceinline__ void gemm_phase(PG8_LAS unsigned char* lds, const Gemm g, const Sched& S, const Epi& E) {
;     ...
;             PG8_LDA(At, 1, 1); PG8_STAGE(PG8_SB(1, 0), b3, voffB); PG8_STAGE(PG8_SB(1, 1), b3 + hB, voffB); PG8_STAGE(PG8_SA(1, 0), a3, voffA);
;             PG8_WAIT_V(8); PG8_WAIT_L(0); PG8_BAR; PG8_MMA(1, 0, At, B0); PG8_MMA(1, 1, At, B1); PG8_BAR; PG8_SCHED;
	s_add_i32 s26, s56, s36
	v_lshl_add_u64 v[216:217], v[216:217], 0, s[14:15]
	s_mov_b32 m0, s26
	ds_read_b128 v[162:165], v199 offset:49152
	ds_read_b128 v[182:185], v199 offset:50176
	ds_read_b128 v[186:189], v199 offset:51200
	ds_read_b128 v[190:193], v199 offset:52224
	ds_read_b128 v[200:203], v199 offset:53248
	ds_read_b128 v[204:207], v199 offset:54272
	ds_read_b128 v[208:211], v199 offset:55296
	ds_read_b128 v[212:215], v199 offset:56320
	global_load_lds_dwordx4 v[216:217], off
	s_add_i32 m0, s26, 0x2000
	s_add_u32 s26, s30, 0x2b0080
	v_lshl_add_u64 v[216:217], v[218:219], 0, s[14:15]
	s_addc_u32 s27, s31, 0
	s_add_i32 s30, s57, s36
	global_load_lds_dwordx4 v[216:217], off
	v_lshl_add_u64 v[216:217], s[26:27], 0, v[170:171]
	s_mov_b32 m0, s30
	s_nop 0
	global_load_lds_dwordx4 v[216:217], off
	v_lshl_add_u64 v[216:217], s[26:27], 0, v[166:167]
	s_add_i32 m0, s30, 0x2000
	s_nop 0
	global_load_lds_dwordx4 v[216:217], off
	v_lshl_add_u64 v[216:217], v[220:221], 0, s[14:15]
	s_mov_b32 m0, s44
	s_nop 0
	global_load_lds_dwordx4 v[216:217], off
	v_lshl_add_u64 v[216:217], v[222:223], 0, s[14:15]
	s_mov_b32 m0, s45
	s_nop 0
	global_load_lds_dwordx4 v[216:217], off
	s_waitcnt vmcnt(8)
	s_waitcnt lgkmcnt(0)
	s_barrier
	v_mfma_f32_16x16x32_bf16 v[62:65], v[130:133], v[162:165], v[62:65]
	v_mfma_f32_16x16x32_bf16 v[58:61], v[138:141], v[162:165], v[58:61]
	v_mfma_f32_16x16x32_bf16 v[50:53], v[130:133], v[186:189], v[50:53]
	v_mfma_f32_16x16x32_bf16 v[42:45], v[138:141], v[186:189], v[42:45]
	v_mfma_f32_16x16x32_bf16 v[34:37], v[130:133], v[200:203], v[34:37]
	v_mfma_f32_16x16x32_bf16 v[26:29], v[138:141], v[200:203], v[26:29]
	v_mfma_f32_16x16x32_bf16 v[18:21], v[130:133], v[208:211], v[18:21]
	v_mfma_f32_16x16x32_bf16 v[10:13], v[138:141], v[208:211], v[10:13]
	v_mfma_f32_16x16x32_bf16 v[62:65], v[134:137], v[182:185], v[62:65]
	v_mfma_f32_16x16x32_bf16 v[58:61], v[142:145], v[182:185], v[58:61]
	v_mfma_f32_16x16x32_bf16 v[50:53], v[134:137], v[190:193], v[50:53]
	v_mfma_f32_16x16x32_bf16 v[42:45], v[142:145], v[190:193], v[42:45]
	v_mfma_f32_16x16x32_bf16 v[34:37], v[134:137], v[204:207], v[34:37]
	v_mfma_f32_16x16x32_bf16 v[26:29], v[142:145], v[204:207], v[26:29]
	v_mfma_f32_16x16x32_bf16 v[18:21], v[134:137], v[212:215], v[18:21]
	v_mfma_f32_16x16x32_bf16 v[10:13], v[142:145], v[212:215], v[10:13]
	v_mfma_f32_16x16x32_bf16 v[54:57], v[146:149], v[162:165], v[54:57]
	v_mfma_f32_16x16x32_bf16 v[46:49], v[154:157], v[162:165], v[46:49]
	v_mfma_f32_16x16x32_bf16 v[38:41], v[146:149], v[186:189], v[38:41]
	v_mfma_f32_16x16x32_bf16 v[30:33], v[154:157], v[186:189], v[30:33]
	v_mfma_f32_16x16x32_bf16 v[22:25], v[146:149], v[200:203], v[22:25]
	v_mfma_f32_16x16x32_bf16 v[14:17], v[154:157], v[200:203], v[14:17]
	v_mfma_f32_16x16x32_bf16 v[6:9], v[146:149], v[208:211], v[6:9]
	v_mfma_f32_16x16x32_bf16 v[2:5], v[154:157], v[208:211], v[2:5]
	v_mfma_f32_16x16x32_bf16 v[54:57], v[150:153], v[182:185], v[54:57]
	v_mfma_f32_16x16x32_bf16 v[46:49], v[158:161], v[182:185], v[46:49]
	v_mfma_f32_16x16x32_bf16 v[38:41], v[150:153], v[190:193], v[38:41]
	v_mfma_f32_16x16x32_bf16 v[30:33], v[158:161], v[190:193], v[30:33]
	v_mfma_f32_16x16x32_bf16 v[22:25], v[150:153], v[204:207], v[22:25]
	v_mfma_f32_16x16x32_bf16 v[14:17], v[158:161], v[204:207], v[14:17]
	v_mfma_f32_16x16x32_bf16 v[6:9], v[150:153], v[212:215], v[6:9]
	v_mfma_f32_16x16x32_bf16 v[2:5], v[158:161], v[212:215], v[2:5]
	s_barrier
	s_add_i32 s55, s55, 2
	s_add_u32 s53, s53, 0x100
	s_addc_u32 s54, s54, 0
	s_cmpk_gt_u32 s55, 0xa9
	s_mov_b64 s[26:27], s[28:29]
	s_cbranch_scc0 .LBB0_1078
	v_lshl_or_b32 v132, s52, 8, v196
	v_lshl_add_u32 v130, s51, 8, v194
	v_ashrrev_i32_e32 v133, 31, v132
	v_lshlrev_b64 v[182:183], 1, v[132:133]
	v_ashrrev_i32_e32 v131, 31, v130
	v_lshl_add_u64 v[132:133], s[12:13], 0, v[182:183]
	v_lshlrev_b64 v[134:135], 13, v[130:131]
	v_lshl_add_u64 v[136:137], v[132:133], 0, v[134:135]
	global_load_dwordx4 v[200:203], v[136:137], off
	global_load_dwordx4 v[204:207], v[136:137], off offset:256
	v_or_b32_e32 v136, 16, v130
	v_ashrrev_i32_e32 v137, 31, v136
	v_lshlrev_b64 v[228:229], 13, v[136:137]
	v_lshl_add_u64 v[136:137], v[132:133], 0, v[228:229]
	global_load_dwordx4 v[208:211], v[136:137], off
	global_load_dwordx4 v[212:215], v[136:137], off offset:256
	v_or_b32_e32 v138, 32, v130
	v_or_b32_e32 v130, 48, v130
	v_ashrrev_i32_e32 v139, 31, v138
	v_ashrrev_i32_e32 v131, 31, v130
	v_lshlrev_b64 v[230:231], 13, v[138:139]
	v_lshlrev_b64 v[192:193], 13, v[130:131]
	v_lshl_add_u64 v[190:191], v[134:135], 0, s[16:17]
	v_lshl_add_u64 v[188:189], v[134:135], 0, s[20:21]
	v_lshl_add_u64 v[186:187], v[134:135], 0, s[22:23]
	v_lshl_add_u64 v[184:185], v[134:135], 0, s[24:25]
	v_lshl_add_u64 v[130:131], s[12:13], 0, v[134:135]
	v_lshl_add_u64 v[134:135], v[132:133], 0, v[230:231]
	v_lshl_add_u64 v[136:137], v[132:133], 0, v[192:193]
	v_lshl_add_u64 v[138:139], v[132:133], 0, v[190:191]
	v_lshl_add_u64 v[140:141], v[132:133], 0, v[188:189]
	v_lshl_add_u64 v[232:233], v[132:133], 0, v[186:187]
	v_lshl_add_u64 v[132:133], v[132:133], 0, v[184:185]
	v_lshl_add_u64 v[234:235], v[130:131], 0, v[182:183]
	global_load_dwordx4 v[216:219], v[134:135], off
	global_load_dwordx4 v[220:223], v[134:135], off offset:256
	global_load_dwordx4 v[224:227], v[136:137], off
	global_load_dwordx4 v[162:165], v[136:137], off offset:256
	global_load_dwordx4 v[158:161], v[138:139], off
	global_load_dwordx4 v[154:157], v[138:139], off offset:256
	global_load_dwordx4 v[150:153], v[140:141], off
	global_load_dwordx4 v[146:149], v[140:141], off offset:256
	global_load_dwordx4 v[142:145], v[232:233], off
	s_nop 0
	global_load_dwordx4 v[138:141], v[232:233], off offset:256
	global_load_dwordx4 v[134:137], v[132:133], off
	s_nop 0
	global_load_dwordx4 v[130:133], v[132:133], off offset:256
	s_and_b64 vcc, exec, s[4:5]
	s_mov_b32 s52, s49
	s_mov_b32 s51, s50
	s_mov_b64 s[28:29], s[8:9]
	s_mov_b64 s[26:27], s[6:7]
	s_waitcnt vmcnt(0)
; #define PG8_GAS __attribute__((address_space(1)))
; __device__ __forceinline__ unsigned cvt_pk_bf16(float lo, float hi) { const f32x2c v = {lo, hi}; return __builtin_bit_cast(unsigned, __builtin_convertvector(v, bf16x2c)); }
; __device__ __forceinline__ float bf_lo(unsigned w) { return __uint_as_float(w << 16); }
; __device__ __forceinline__ float bf_hi(unsigned w) { return __uint_as_float(w & 0xffff0000u); }
;     __device__ __forceinline__ void operator()(const f32x4 (&acc)[2][2][4][2], const Unit& un, int wr, int wc, int fr, int fq) const {
;     ...
; #pragma unroll
;         for (int ai = 0; ai < 2; ++ai)
; #pragma unroll
;             for (int m = 0; m < 4; ++m)
; #pragma unroll
;                 for (int bj = 0; bj < 2; ++bj) { const u32x4 r = rr[ai][m][bj]; const f32x4 v0 = acc[ai][bj][m][0], v1 = acc[ai][bj][m][1];
;                     u32x4 w; w.x = cvt_pk_bf16(v0[0] + bf_lo(r.x), v0[1] + bf_hi(r.x)); w.y = cvt_pk_bf16(v0[2] + bf_lo(r.y), v0[3] + bf_hi(r.y));
;                     w.z = cvt_pk_bf16(v1[0] + bf_lo(r.z), v1[1] + bf_hi(r.z)); w.w = cvt_pk_bf16(v1[2] + bf_lo(r.w), v1[3] + bf_hi(r.w));
;                     *(PG8_GAS u32x4*)((PG8_GAS bf16_t*)h + (size_t)(row0 + ai * HALF + m * 16) * 4096 + col0 + bj * HALF) = w; }
	v_lshlrev_b32_e32 v232, 16, v200
	v_and_b32_e32 v233, 0xffff0000, v200
	v_lshlrev_b32_e32 v200, 16, v201
	v_and_b32_e32 v201, 0xffff0000, v201
	v_lshlrev_b32_e32 v236, 16, v202
	v_and_b32_e32 v237, 0xffff0000, v202
	v_lshlrev_b32_e32 v202, 16, v203
	v_and_b32_e32 v203, 0xffff0000, v203
	v_lshlrev_b32_e32 v238, 16, v204
	v_and_b32_e32 v239, 0xffff0000, v204
	v_lshlrev_b32_e32 v204, 16, v205
	v_and_b32_e32 v205, 0xffff0000, v205
	v_lshlrev_b32_e32 v240, 16, v206
	v_and_b32_e32 v241, 0xffff0000, v206
	v_lshlrev_b32_e32 v206, 16, v207
	v_and_b32_e32 v207, 0xffff0000, v207
	v_pk_add_f32 v[126:127], v[126:127], v[232:233]
	v_pk_add_f32 v[128:129], v[128:129], v[200:201]
	v_pk_add_f32 v[122:123], v[122:123], v[236:237]
	v_pk_add_f32 v[124:125], v[124:125], v[202:203]
	v_pk_add_f32 v[114:115], v[114:115], v[238:239]
	v_pk_add_f32 v[116:117], v[116:117], v[204:205]
	v_pk_add_f32 v[200:201], v[110:111], v[240:241]
	v_pk_add_f32 v[202:203], v[112:113], v[206:207]
	v_cvt_pk_bf16_f32 v110, v126, v127
	v_cvt_pk_bf16_f32 v111, v128, v129
	v_cvt_pk_bf16_f32 v112, v122, v123
	v_cvt_pk_bf16_f32 v113, v124, v125
	v_lshlrev_b32_e32 v242, 16, v208
	v_and_b32_e32 v243, 0xffff0000, v208
	v_lshlrev_b32_e32 v208, 16, v209
	v_and_b32_e32 v209, 0xffff0000, v209
	v_cvt_pk_bf16_f32 v114, v114, v115
	v_cvt_pk_bf16_f32 v115, v116, v117
	v_cvt_pk_bf16_f32 v116, v200, v201
	v_cvt_pk_bf16_f32 v117, v202, v203
	global_store_dwordx4 v[234:235], v[110:113], off
	global_store_dwordx4 v[234:235], v[114:117], off offset:256
	v_pk_add_f32 v[118:119], v[118:119], v[242:243]
	v_lshlrev_b32_e32 v110, 16, v210
	v_and_b32_e32 v111, 0xffff0000, v210
	v_pk_add_f32 v[120:121], v[120:121], v[208:209]
	v_pk_add_f32 v[106:107], v[106:107], v[110:111]
	v_cvt_pk_bf16_f32 v118, v118, v119
	v_cvt_pk_bf16_f32 v119, v120, v121
	v_cvt_pk_bf16_f32 v120, v106, v107
	v_lshlrev_b32_e32 v106, 16, v211
	v_and_b32_e32 v107, 0xffff0000, v211
	v_pk_add_f32 v[106:107], v[108:109], v[106:107]
	v_lshlrev_b32_e32 v108, 16, v212
	v_and_b32_e32 v109, 0xffff0000, v212
	v_pk_add_f32 v[102:103], v[102:103], v[108:109]
	v_lshlrev_b32_e32 v108, 16, v213
	v_and_b32_e32 v109, 0xffff0000, v213
	v_pk_add_f32 v[104:105], v[104:105], v[108:109]
	v_cvt_pk_bf16_f32 v102, v102, v103
	v_cvt_pk_bf16_f32 v103, v104, v105
	v_lshlrev_b32_e32 v104, 16, v214
	v_and_b32_e32 v105, 0xffff0000, v214
	v_pk_add_f32 v[94:95], v[94:95], v[104:105]
	v_cvt_pk_bf16_f32 v121, v106, v107
	v_cvt_pk_bf16_f32 v104, v94, v95
	v_lshlrev_b32_e32 v94, 16, v215
	v_and_b32_e32 v95, 0xffff0000, v215
	v_pk_add_f32 v[94:95], v[96:97], v[94:95]
	v_lshlrev_b32_e32 v96, 16, v217
	v_cvt_pk_bf16_f32 v105, v94, v95
	v_lshlrev_b32_e32 v94, 16, v216
	v_and_b32_e32 v95, 0xffff0000, v216
	v_and_b32_e32 v97, 0xffff0000, v217
	v_pk_add_f32 v[94:95], v[98:99], v[94:95]
	v_pk_add_f32 v[96:97], v[100:101], v[96:97]
	v_cvt_pk_bf16_f32 v94, v94, v95
	v_cvt_pk_bf16_f32 v95, v96, v97
	v_lshlrev_b32_e32 v96, 16, v218
	v_and_b32_e32 v97, 0xffff0000, v218
	v_pk_add_f32 v[90:91], v[90:91], v[96:97]
	v_lshl_add_u64 v[106:107], s[12:13], 0, v[228:229]
	v_cvt_pk_bf16_f32 v96, v90, v91
	v_lshlrev_b32_e32 v90, 16, v219
	v_and_b32_e32 v91, 0xffff0000, v219
	v_pk_add_f32 v[90:91], v[92:93], v[90:91]
	v_lshlrev_b32_e32 v92, 16, v220
	v_and_b32_e32 v93, 0xffff0000, v220
	v_pk_add_f32 v[86:87], v[86:87], v[92:93]
	v_lshlrev_b32_e32 v92, 16, v221
	v_and_b32_e32 v93, 0xffff0000, v221
	v_pk_add_f32 v[88:89], v[88:89], v[92:93]
	v_cvt_pk_bf16_f32 v86, v86, v87
	v_cvt_pk_bf16_f32 v87, v88, v89
	v_lshlrev_b32_e32 v88, 16, v222
	v_and_b32_e32 v89, 0xffff0000, v222
	v_pk_add_f32 v[78:79], v[78:79], v[88:89]
	v_cvt_pk_bf16_f32 v97, v90, v91
	v_cvt_pk_bf16_f32 v88, v78, v79
	v_lshlrev_b32_e32 v78, 16, v223
	v_and_b32_e32 v79, 0xffff0000, v223
	v_pk_add_f32 v[78:79], v[80:81], v[78:79]
	v_lshlrev_b32_e32 v80, 16, v225
	v_cvt_pk_bf16_f32 v89, v78, v79
	v_lshlrev_b32_e32 v78, 16, v224
	v_and_b32_e32 v79, 0xffff0000, v224
	v_and_b32_e32 v81, 0xffff0000, v225
	v_pk_add_f32 v[78:79], v[82:83], v[78:79]
	v_pk_add_f32 v[80:81], v[84:85], v[80:81]
	v_cvt_pk_bf16_f32 v78, v78, v79
	v_cvt_pk_bf16_f32 v79, v80, v81
	v_lshlrev_b32_e32 v80, 16, v226
	v_and_b32_e32 v81, 0xffff0000, v226
	v_pk_add_f32 v[74:75], v[74:75], v[80:81]
	v_lshl_add_u64 v[90:91], s[12:13], 0, v[230:231]
	v_cvt_pk_bf16_f32 v80, v74, v75
	v_lshlrev_b32_e32 v74, 16, v227
	v_and_b32_e32 v75, 0xffff0000, v227
	v_pk_add_f32 v[74:75], v[76:77], v[74:75]
	v_lshlrev_b32_e32 v76, 16, v162
	v_and_b32_e32 v77, 0xffff0000, v162
	v_pk_add_f32 v[70:71], v[70:71], v[76:77]
	v_lshlrev_b32_e32 v76, 16, v163
	v_and_b32_e32 v77, 0xffff0000, v163
	v_pk_add_f32 v[72:73], v[72:73], v[76:77]
	v_cvt_pk_bf16_f32 v70, v70, v71
	v_cvt_pk_bf16_f32 v71, v72, v73
	v_lshlrev_b32_e32 v72, 16, v164
	v_and_b32_e32 v73, 0xffff0000, v164
	v_pk_add_f32 v[66:67], v[66:67], v[72:73]
	v_cvt_pk_bf16_f32 v81, v74, v75
	v_cvt_pk_bf16_f32 v72, v66, v67
	v_lshlrev_b32_e32 v66, 16, v165
	v_and_b32_e32 v67, 0xffff0000, v165
	v_pk_add_f32 v[66:67], v[68:69], v[66:67]
	v_lshl_add_u64 v[74:75], s[12:13], 0, v[192:193]
	v_cvt_pk_bf16_f32 v73, v66, v67
	v_lshlrev_b32_e32 v66, 16, v158
	v_and_b32_e32 v67, 0xffff0000, v158
	v_pk_add_f32 v[62:63], v[62:63], v[66:67]
	v_lshlrev_b32_e32 v66, 16, v159
	v_and_b32_e32 v67, 0xffff0000, v159
	v_pk_add_f32 v[64:65], v[64:65], v[66:67]
	v_cvt_pk_bf16_f32 v62, v62, v63
	v_cvt_pk_bf16_f32 v63, v64, v65
	v_lshlrev_b32_e32 v64, 16, v160
	v_and_b32_e32 v65, 0xffff0000, v160
	v_pk_add_f32 v[58:59], v[58:59], v[64:65]
	v_lshl_add_u64 v[106:107], v[106:107], 0, v[182:183]
; #define PG8_GAS __attribute__((address_space(1)))
; __device__ __forceinline__ unsigned cvt_pk_bf16(float lo, float hi) { const f32x2c v = {lo, hi}; return __builtin_bit_cast(unsigned, __builtin_convertvector(v, bf16x2c)); }
; __device__ __forceinline__ float bf_lo(unsigned w) { return __uint_as_float(w << 16); }
; __device__ __forceinline__ float bf_hi(unsigned w) { return __uint_as_float(w & 0xffff0000u); }
; #define PG8_WAIT_V(n) asm volatile("s_waitcnt vmcnt(" #n ")" ::: "memory")
; #define PG8_BAR __builtin_amdgcn_s_barrier()
;     __device__ __forceinline__ void operator()(const f32x4 (&acc)[2][2][4][2], const Unit& un, int wr, int wc, int fr, int fq) const {
;     ...
; #pragma unroll
;         for (int ai = 0; ai < 2; ++ai)
; #pragma unroll
;             for (int m = 0; m < 4; ++m)
; #pragma unroll
;                 for (int bj = 0; bj < 2; ++bj) { const u32x4 r = rr[ai][m][bj]; const f32x4 v0 = acc[ai][bj][m][0], v1 = acc[ai][bj][m][1];
;                     u32x4 w; w.x = cvt_pk_bf16(v0[0] + bf_lo(r.x), v0[1] + bf_hi(r.x)); w.y = cvt_pk_bf16(v0[2] + bf_lo(r.y), v0[3] + bf_hi(r.y));
;                     w.z = cvt_pk_bf16(v1[0] + bf_lo(r.z), v1[1] + bf_hi(r.z)); w.w = cvt_pk_bf16(v1[2] + bf_lo(r.w), v1[3] + bf_hi(r.w));
;                     *(PG8_GAS u32x4*)((PG8_GAS bf16_t*)h + (size_t)(row0 + ai * HALF + m * 16) * 4096 + col0 + bj * HALF) = w; }
; template <class Epi, class Sched, bool ALIGN_EPI = false, bool SP2 = false, bool F8 = false>
; __device__ __forceinline__ void gemm_phase(PG8_LAS unsigned char* lds, const Gemm g, const Sched& S, const Epi& E) {
;     ...
;     PG8_WAIT_V(0);
;     if constexpr (!ALIGN_EPI) { if (wr == 0) PG8_BAR; }
;     PG8_BAR;
	v_cvt_pk_bf16_f32 v64, v58, v59
	v_lshlrev_b32_e32 v58, 16, v161
	v_and_b32_e32 v59, 0xffff0000, v161
	v_pk_add_f32 v[58:59], v[60:61], v[58:59]
	v_lshlrev_b32_e32 v60, 16, v154
	v_and_b32_e32 v61, 0xffff0000, v154
	v_pk_add_f32 v[54:55], v[54:55], v[60:61]
	v_lshlrev_b32_e32 v60, 16, v155
	v_and_b32_e32 v61, 0xffff0000, v155
	v_pk_add_f32 v[56:57], v[56:57], v[60:61]
	v_cvt_pk_bf16_f32 v54, v54, v55
	v_cvt_pk_bf16_f32 v55, v56, v57
	v_lshlrev_b32_e32 v56, 16, v156
	v_and_b32_e32 v57, 0xffff0000, v156
	v_pk_add_f32 v[46:47], v[46:47], v[56:57]
	v_cvt_pk_bf16_f32 v65, v58, v59
	v_cvt_pk_bf16_f32 v56, v46, v47
	v_lshlrev_b32_e32 v46, 16, v157
	v_and_b32_e32 v47, 0xffff0000, v157
	v_pk_add_f32 v[46:47], v[48:49], v[46:47]
	v_lshlrev_b32_e32 v48, 16, v151
	v_cvt_pk_bf16_f32 v57, v46, v47
	v_lshlrev_b32_e32 v46, 16, v150
	v_and_b32_e32 v47, 0xffff0000, v150
	v_and_b32_e32 v49, 0xffff0000, v151
	v_pk_add_f32 v[46:47], v[50:51], v[46:47]
	v_pk_add_f32 v[48:49], v[52:53], v[48:49]
	v_cvt_pk_bf16_f32 v46, v46, v47
	v_cvt_pk_bf16_f32 v47, v48, v49
	v_lshlrev_b32_e32 v48, 16, v152
	v_and_b32_e32 v49, 0xffff0000, v152
	v_pk_add_f32 v[42:43], v[42:43], v[48:49]
	v_lshl_add_u64 v[58:59], s[12:13], 0, v[190:191]
	v_cvt_pk_bf16_f32 v48, v42, v43
	v_lshlrev_b32_e32 v42, 16, v153
	v_and_b32_e32 v43, 0xffff0000, v153
	v_pk_add_f32 v[42:43], v[44:45], v[42:43]
	v_lshlrev_b32_e32 v44, 16, v146
	v_and_b32_e32 v45, 0xffff0000, v146
	v_pk_add_f32 v[38:39], v[38:39], v[44:45]
	v_lshlrev_b32_e32 v44, 16, v147
	v_and_b32_e32 v45, 0xffff0000, v147
	v_pk_add_f32 v[40:41], v[40:41], v[44:45]
	v_cvt_pk_bf16_f32 v38, v38, v39
	v_cvt_pk_bf16_f32 v39, v40, v41
	v_lshlrev_b32_e32 v40, 16, v148
	v_and_b32_e32 v41, 0xffff0000, v148
	v_pk_add_f32 v[30:31], v[30:31], v[40:41]
	v_cvt_pk_bf16_f32 v49, v42, v43
	v_cvt_pk_bf16_f32 v40, v30, v31
	v_lshlrev_b32_e32 v30, 16, v149
	v_and_b32_e32 v31, 0xffff0000, v149
	v_pk_add_f32 v[30:31], v[32:33], v[30:31]
	v_lshlrev_b32_e32 v32, 16, v143
	v_cvt_pk_bf16_f32 v41, v30, v31
	v_lshlrev_b32_e32 v30, 16, v142
	v_and_b32_e32 v31, 0xffff0000, v142
	v_and_b32_e32 v33, 0xffff0000, v143
	v_pk_add_f32 v[30:31], v[34:35], v[30:31]
	v_pk_add_f32 v[32:33], v[36:37], v[32:33]
	v_cvt_pk_bf16_f32 v30, v30, v31
	v_cvt_pk_bf16_f32 v31, v32, v33
	v_lshlrev_b32_e32 v32, 16, v144
	v_and_b32_e32 v33, 0xffff0000, v144
	v_pk_add_f32 v[26:27], v[26:27], v[32:33]
	v_lshl_add_u64 v[42:43], s[12:13], 0, v[188:189]
	v_cvt_pk_bf16_f32 v32, v26, v27
	v_lshlrev_b32_e32 v26, 16, v145
	v_and_b32_e32 v27, 0xffff0000, v145
	v_pk_add_f32 v[26:27], v[28:29], v[26:27]
	v_lshlrev_b32_e32 v28, 16, v138
	v_and_b32_e32 v29, 0xffff0000, v138
	v_pk_add_f32 v[22:23], v[22:23], v[28:29]
	v_lshlrev_b32_e32 v28, 16, v139
	v_and_b32_e32 v29, 0xffff0000, v139
	v_pk_add_f32 v[24:25], v[24:25], v[28:29]
	v_cvt_pk_bf16_f32 v22, v22, v23
	v_cvt_pk_bf16_f32 v23, v24, v25
	v_lshlrev_b32_e32 v24, 16, v140
	v_and_b32_e32 v25, 0xffff0000, v140
	v_pk_add_f32 v[14:15], v[14:15], v[24:25]
	v_cvt_pk_bf16_f32 v33, v26, v27
	v_cvt_pk_bf16_f32 v24, v14, v15
	v_lshlrev_b32_e32 v14, 16, v141
	v_and_b32_e32 v15, 0xffff0000, v141
	v_pk_add_f32 v[14:15], v[16:17], v[14:15]
	v_lshlrev_b32_e32 v16, 16, v135
	v_cvt_pk_bf16_f32 v25, v14, v15
	v_lshlrev_b32_e32 v14, 16, v134
	v_and_b32_e32 v15, 0xffff0000, v134
	v_and_b32_e32 v17, 0xffff0000, v135
	v_pk_add_f32 v[14:15], v[18:19], v[14:15]
	v_pk_add_f32 v[16:17], v[20:21], v[16:17]
	v_cvt_pk_bf16_f32 v14, v14, v15
	v_cvt_pk_bf16_f32 v15, v16, v17
	v_lshlrev_b32_e32 v16, 16, v136
	v_and_b32_e32 v17, 0xffff0000, v136
	v_pk_add_f32 v[10:11], v[10:11], v[16:17]
	v_lshl_add_u64 v[26:27], s[12:13], 0, v[186:187]
	v_cvt_pk_bf16_f32 v16, v10, v11
	v_lshlrev_b32_e32 v10, 16, v137
	v_and_b32_e32 v11, 0xffff0000, v137
	v_pk_add_f32 v[10:11], v[12:13], v[10:11]
	v_lshlrev_b32_e32 v12, 16, v130
	v_and_b32_e32 v13, 0xffff0000, v130
	v_pk_add_f32 v[6:7], v[6:7], v[12:13]
	v_lshlrev_b32_e32 v12, 16, v131
	v_and_b32_e32 v13, 0xffff0000, v131
	v_pk_add_f32 v[8:9], v[8:9], v[12:13]
	v_cvt_pk_bf16_f32 v6, v6, v7
	v_cvt_pk_bf16_f32 v7, v8, v9
	v_lshlrev_b32_e32 v8, 16, v132
	v_and_b32_e32 v9, 0xffff0000, v132
	v_pk_add_f32 v[2:3], v[2:3], v[8:9]
	v_cvt_pk_bf16_f32 v17, v10, v11
	v_cvt_pk_bf16_f32 v8, v2, v3
	v_lshlrev_b32_e32 v2, 16, v133
	v_and_b32_e32 v3, 0xffff0000, v133
	v_lshl_add_u64 v[10:11], s[12:13], 0, v[184:185]
	v_pk_add_f32 v[2:3], v[4:5], v[2:3]
	v_lshl_add_u64 v[90:91], v[90:91], 0, v[182:183]
	v_lshl_add_u64 v[74:75], v[74:75], 0, v[182:183]
	v_lshl_add_u64 v[58:59], v[58:59], 0, v[182:183]
	v_lshl_add_u64 v[42:43], v[42:43], 0, v[182:183]
	v_lshl_add_u64 v[26:27], v[26:27], 0, v[182:183]
	v_lshl_add_u64 v[10:11], v[10:11], 0, v[182:183]
	v_cvt_pk_bf16_f32 v9, v2, v3
	global_store_dwordx4 v[106:107], v[118:121], off
	global_store_dwordx4 v[106:107], v[102:105], off offset:256
	global_store_dwordx4 v[90:91], v[94:97], off
	global_store_dwordx4 v[90:91], v[86:89], off offset:256
	global_store_dwordx4 v[74:75], v[78:81], off
	global_store_dwordx4 v[74:75], v[70:73], off offset:256
	global_store_dwordx4 v[58:59], v[62:65], off
	global_store_dwordx4 v[58:59], v[54:57], off offset:256
	global_store_dwordx4 v[42:43], v[46:49], off
	global_store_dwordx4 v[42:43], v[38:41], off offset:256
	global_store_dwordx4 v[26:27], v[30:33], off
	global_store_dwordx4 v[26:27], v[22:25], off offset:256
	global_store_dwordx4 v[10:11], v[14:17], off
	global_store_dwordx4 v[10:11], v[6:9], off offset:256
	s_cbranch_vccz .LBB0_1071
	s_waitcnt vmcnt(0)
	s_cmpk_gt_u32 s18, 0xff
	s_cbranch_scc1 .LBB0_1082
	s_barrier
